# GEMM main loops: LDS-DMA loads in SGPR-base+VGPR-offset form (no per-load 64-bit VALU adds) + half-tile last round
# speedup vs baseline: 1.0144x; 1.0069x over previous
; #define PG8_STAGE(bufoff, gbase, voff) do { _Pragma("unroll") for (int _i = 0; _i < 2; ++_i) \
;         __builtin_amdgcn_global_load_lds((const unsigned*)((const char*)(gbase) + (voff)[_i]), (PG8_LAS unsigned*)(lds + (bufoff) + ldsw + _i * 8192), 16, 0, 0); } while (0)
; #define PG8_LDA(dst, b, h) do { _Pragma("unroll") for (int m = 0; m < 4; ++m) _Pragma("unroll") for (int k = 0; k < 2; ++k) dst[m][k] = *(const PG8_LAS bf16x8*)(lds + PG8_SA(b, h) + aoff + m * 2048 + k * 1024); } while (0)
; #define PG8_LDB(dst, b, h) do { _Pragma("unroll") for (int n = 0; n < 2; ++n) _Pragma("unroll") for (int k = 0; k < 2; ++k) dst[n][k] = *(const PG8_LAS bf16x8*)(lds + PG8_SB(b, h) + boff + n * 2048 + k * 1024); } while (0)
; #define PG8_MMA(ai, bj, At, Bt) do { __builtin_amdgcn_s_setprio(1); _Pragma("unroll") for (int m = 0; m < 4; ++m) _Pragma("unroll") for (int n = 0; n < 2; ++n) _Pragma("unroll") for (int k = 0; k < 2; ++k) \
;         acc[ai][bj][m][n] = __builtin_amdgcn_mfma_f32_16x16x32_bf16(Bt[n][k], At[m][k], acc[ai][bj][m][n], 0, 0, 0); __builtin_amdgcn_s_setprio(0); } while (0)
; #define PG8_WAIT_V(n) asm volatile("s_waitcnt vmcnt(" #n ")" ::: "memory")
; #define PG8_WAIT_L(n) asm volatile("s_waitcnt lgkmcnt(" #n ")" ::: "memory")
; #define PG8_BAR __builtin_amdgcn_s_barrier()
; #define PG8_SCHED __builtin_amdgcn_sched_barrier(0)
; template <class Epi, class Sched, bool STAMP = false>
; __device__ __forceinline__ void gemm_phase(PG8_LAS unsigned char* lds, const Gemm g, const Sched& S, const Epi& E, unsigned long long* stamps) {
;     ...
;             PG8_LDB(B0, 0, 0); PG8_SCHED; PG8_LDA(At, 0, 0); PG8_STAGE(PG8_SA(1, 1), a1 + hstep, voffA);
;             PG8_WAIT_L(8); PG8_BAR; PG8_WAIT_L(0); PG8_MMA(0, 0, At, B0); PG8_BAR; PG8_SCHED;
;             PG8_LDB(B1, 0, 1); PG8_STAGE(PG8_SB(0, 0), b2, voffB);
;             PG8_BAR; PG8_WAIT_L(0); PG8_MMA(0, 1, At, B1); PG8_BAR;
;             PG8_LDA(At, 0, 1); PG8_STAGE(PG8_SA(0, 0), a2, voffA);
;             PG8_BAR; PG8_WAIT_L(0); PG8_MMA(1, 0, At, B0); PG8_BAR; PG8_SCHED;
;             PG8_STAGE(PG8_SB(0, 1), b2 + hstep, voffB);
;             PG8_WAIT_V(6); PG8_BAR; PG8_MMA(1, 1, At, B1); PG8_BAR;
.LBB0_63:
	ds_read_b128 v[140:143], v148
	ds_read_b128 v[166:169], v149
	ds_read_b128 v[170:173], v150
	ds_read_b128 v[174:177], v151
	s_add_u32 s16, s14, 0x100
	s_addc_u32 s17, s15, 0
	s_cmp_eq_u32 s77, 12
	s_cselect_b32 s29, s5, s17
	s_cselect_b32 s28, s4, s16
	s_cselect_b32 s19, s1, s76
	s_cselect_b32 s18, s0, s75
	s_mov_b32 m0, s68
	ds_read_b128 v[178:181], v146
	ds_read_b128 v[182:185], v146 offset:1024
	ds_read_b128 v[186:189], v146 offset:2048
	ds_read_b128 v[190:193], v146 offset:3072
	ds_read_b128 v[194:197], v146 offset:4096
	ds_read_b128 v[198:201], v146 offset:5120
	ds_read_b128 v[202:205], v146 offset:6144
	ds_read_b128 v[206:209], v146 offset:7168
	global_load_lds_dwordx4 v132, s[14:15]
	s_mov_b32 m0, s69
	s_nop 0
	global_load_lds_dwordx4 v134, s[14:15]
	s_waitcnt lgkmcnt(8)
	s_barrier
	s_waitcnt lgkmcnt(0)
	s_setprio 1
	s_waitcnt lgkmcnt(0)
	v_mfma_f32_16x16x32_bf16 v[124:127], v[140:143], v[178:181], v[124:127]
	v_mfma_f32_16x16x32_bf16 v[120:123], v[170:173], v[178:181], v[120:123]
	v_mfma_f32_16x16x32_bf16 v[108:111], v[140:143], v[186:189], v[108:111]
	v_mfma_f32_16x16x32_bf16 v[104:107], v[170:173], v[186:189], v[104:107]
	v_mfma_f32_16x16x32_bf16 v[92:95], v[140:143], v[194:197], v[92:95]
	v_mfma_f32_16x16x32_bf16 v[88:91], v[170:173], v[194:197], v[88:91]
	v_mfma_f32_16x16x32_bf16 v[76:79], v[140:143], v[202:205], v[76:79]
	v_mfma_f32_16x16x32_bf16 v[72:75], v[170:173], v[202:205], v[72:75]
	v_mfma_f32_16x16x32_bf16 v[124:127], v[166:169], v[182:185], v[124:127]
	v_mfma_f32_16x16x32_bf16 v[120:123], v[174:177], v[182:185], v[120:123]
	v_mfma_f32_16x16x32_bf16 v[108:111], v[166:169], v[190:193], v[108:111]
	v_mfma_f32_16x16x32_bf16 v[104:107], v[174:177], v[190:193], v[104:107]
	v_mfma_f32_16x16x32_bf16 v[92:95], v[166:169], v[198:201], v[92:95]
	v_mfma_f32_16x16x32_bf16 v[88:91], v[174:177], v[198:201], v[88:91]
	v_mfma_f32_16x16x32_bf16 v[76:79], v[166:169], v[206:209], v[76:79]
	v_mfma_f32_16x16x32_bf16 v[72:75], v[174:177], v[206:209], v[72:75]
	s_setprio 0
	s_barrier
	s_mov_b32 m0, s52
	ds_read_b128 v[210:213], v152
	ds_read_b128 v[214:217], v153
	ds_read_b128 v[218:221], v154
	ds_read_b128 v[222:225], v155
	global_load_lds_dwordx4 v130, s[18:19]
	s_mov_b32 m0, s53
	s_nop 0
	global_load_lds_dwordx4 v128, s[18:19]
	s_barrier
	s_waitcnt lgkmcnt(0)
	s_setprio 1
	s_waitcnt lgkmcnt(0)
	v_mfma_f32_16x16x32_bf16 v[116:119], v[210:213], v[178:181], v[116:119]
	v_mfma_f32_16x16x32_bf16 v[112:115], v[218:221], v[178:181], v[112:115]
	v_mfma_f32_16x16x32_bf16 v[100:103], v[210:213], v[186:189], v[100:103]
	v_mfma_f32_16x16x32_bf16 v[96:99], v[218:221], v[186:189], v[96:99]
	v_mfma_f32_16x16x32_bf16 v[84:87], v[210:213], v[194:197], v[84:87]
	v_mfma_f32_16x16x32_bf16 v[80:83], v[218:221], v[194:197], v[80:83]
	v_mfma_f32_16x16x32_bf16 v[68:71], v[210:213], v[202:205], v[68:71]
	v_mfma_f32_16x16x32_bf16 v[64:67], v[218:221], v[202:205], v[64:67]
	v_mfma_f32_16x16x32_bf16 v[116:119], v[214:217], v[182:185], v[116:119]
	v_mfma_f32_16x16x32_bf16 v[112:115], v[222:225], v[182:185], v[112:115]
	v_mfma_f32_16x16x32_bf16 v[100:103], v[214:217], v[190:193], v[100:103]
	v_mfma_f32_16x16x32_bf16 v[96:99], v[222:225], v[190:193], v[96:99]
	v_mfma_f32_16x16x32_bf16 v[84:87], v[214:217], v[198:201], v[84:87]
	v_mfma_f32_16x16x32_bf16 v[80:83], v[222:225], v[198:201], v[80:83]
	v_mfma_f32_16x16x32_bf16 v[68:71], v[214:217], v[206:209], v[68:71]
	v_mfma_f32_16x16x32_bf16 v[64:67], v[222:225], v[206:209], v[64:67]
	s_setprio 0
	s_mov_b32 m0, s33
	s_barrier
	ds_read_b128 v[178:181], v146 offset:16384
	ds_read_b128 v[182:185], v146 offset:17408
	ds_read_b128 v[186:189], v146 offset:18432
	ds_read_b128 v[190:193], v146 offset:19456
	ds_read_b128 v[194:197], v146 offset:20480
	ds_read_b128 v[198:201], v146 offset:21504
	ds_read_b128 v[202:205], v146 offset:22528
	ds_read_b128 v[206:209], v146 offset:23552
	global_load_lds_dwordx4 v130, s[28:29]
	s_mov_b32 m0, s54
	s_nop 0
	global_load_lds_dwordx4 v128, s[28:29]
	s_barrier
	s_waitcnt lgkmcnt(0)
	s_setprio 1
	s_waitcnt lgkmcnt(0)
	v_mfma_f32_16x16x32_bf16 v[60:63], v[140:143], v[178:181], v[60:63]
	v_mfma_f32_16x16x32_bf16 v[56:59], v[170:173], v[178:181], v[56:59]
	v_mfma_f32_16x16x32_bf16 v[44:47], v[140:143], v[186:189], v[44:47]
	v_mfma_f32_16x16x32_bf16 v[40:43], v[170:173], v[186:189], v[40:43]
	v_mfma_f32_16x16x32_bf16 v[28:31], v[140:143], v[194:197], v[28:31]
	v_mfma_f32_16x16x32_bf16 v[24:27], v[170:173], v[194:197], v[24:27]
	v_mfma_f32_16x16x32_bf16 v[12:15], v[140:143], v[202:205], v[12:15]
	v_mfma_f32_16x16x32_bf16 v[8:11], v[170:173], v[202:205], v[8:11]
	v_mfma_f32_16x16x32_bf16 v[60:63], v[166:169], v[182:185], v[60:63]
	v_mfma_f32_16x16x32_bf16 v[56:59], v[174:177], v[182:185], v[56:59]
	v_mfma_f32_16x16x32_bf16 v[44:47], v[166:169], v[190:193], v[44:47]
	v_mfma_f32_16x16x32_bf16 v[40:43], v[174:177], v[190:193], v[40:43]
	v_mfma_f32_16x16x32_bf16 v[28:31], v[166:169], v[198:201], v[28:31]
	v_mfma_f32_16x16x32_bf16 v[24:27], v[174:177], v[198:201], v[24:27]
	v_mfma_f32_16x16x32_bf16 v[12:15], v[166:169], v[206:209], v[12:15]
	v_mfma_f32_16x16x32_bf16 v[8:11], v[174:177], v[206:209], v[8:11]
	s_setprio 0
	s_barrier
	s_add_u32 s14, s18, 0x44000
	s_addc_u32 s15, s19, 0
	s_mov_b32 m0, s55
	s_nop 0
	global_load_lds_dwordx4 v130, s[14:15]
	s_mov_b32 m0, s56
	s_nop 0
	global_load_lds_dwordx4 v128, s[14:15]
	s_waitcnt vmcnt(6)
	s_barrier
; #define PG8_STAGE(bufoff, gbase, voff) do { _Pragma("unroll") for (int _i = 0; _i < 2; ++_i) \
;         __builtin_amdgcn_global_load_lds((const unsigned*)((const char*)(gbase) + (voff)[_i]), (PG8_LAS unsigned*)(lds + (bufoff) + ldsw + _i * 8192), 16, 0, 0); } while (0)
; #define PG8_LDA(dst, b, h) do { _Pragma("unroll") for (int m = 0; m < 4; ++m) _Pragma("unroll") for (int k = 0; k < 2; ++k) dst[m][k] = *(const PG8_LAS bf16x8*)(lds + PG8_SA(b, h) + aoff + m * 2048 + k * 1024); } while (0)
; #define PG8_LDB(dst, b, h) do { _Pragma("unroll") for (int n = 0; n < 2; ++n) _Pragma("unroll") for (int k = 0; k < 2; ++k) dst[n][k] = *(const PG8_LAS bf16x8*)(lds + PG8_SB(b, h) + boff + n * 2048 + k * 1024); } while (0)
; #define PG8_MMA(ai, bj, At, Bt) do { __builtin_amdgcn_s_setprio(1); _Pragma("unroll") for (int m = 0; m < 4; ++m) _Pragma("unroll") for (int n = 0; n < 2; ++n) _Pragma("unroll") for (int k = 0; k < 2; ++k) \
;         acc[ai][bj][m][n] = __builtin_amdgcn_mfma_f32_16x16x32_bf16(Bt[n][k], At[m][k], acc[ai][bj][m][n], 0, 0, 0); __builtin_amdgcn_s_setprio(0); } while (0)
; #define PG8_WAIT_V(n) asm volatile("s_waitcnt vmcnt(" #n ")" ::: "memory")
; #define PG8_WAIT_L(n) asm volatile("s_waitcnt lgkmcnt(" #n ")" ::: "memory")
; #define PG8_BAR __builtin_amdgcn_s_barrier()
; #define PG8_SCHED __builtin_amdgcn_sched_barrier(0)
; template <class Epi, class Sched, bool STAMP = false>
; __device__ __forceinline__ void gemm_phase(PG8_LAS unsigned char* lds, const Gemm g, const Sched& S, const Epi& E, unsigned long long* stamps) {
;     ...
;             PG8_WAIT_V(6); PG8_BAR; PG8_MMA(1, 1, At, B1); PG8_BAR;
;             PG8_LDB(B0, 1, 0); PG8_SCHED; PG8_LDA(At, 1, 0); PG8_STAGE(PG8_SA(0, 1), a2 + hstep, voffA);
;             PG8_WAIT_L(8); PG8_BAR; PG8_WAIT_L(0); PG8_MMA(0, 0, At, B0); PG8_BAR; PG8_SCHED;
;             PG8_LDB(B1, 1, 1); PG8_STAGE(PG8_SB(1, 0), b3, voffB);
;             PG8_BAR; PG8_WAIT_L(0); PG8_MMA(0, 1, At, B1); PG8_BAR;
;             PG8_LDA(At, 1, 1); PG8_STAGE(PG8_SA(1, 0), a3, voffA);
	s_setprio 1
	v_mfma_f32_16x16x32_bf16 v[52:55], v[210:213], v[178:181], v[52:55]
	v_mfma_f32_16x16x32_bf16 v[48:51], v[218:221], v[178:181], v[48:51]
	v_mfma_f32_16x16x32_bf16 v[36:39], v[210:213], v[186:189], v[36:39]
	v_mfma_f32_16x16x32_bf16 v[32:35], v[218:221], v[186:189], v[32:35]
	v_mfma_f32_16x16x32_bf16 v[20:23], v[210:213], v[194:197], v[20:23]
	v_mfma_f32_16x16x32_bf16 v[16:19], v[218:221], v[194:197], v[16:19]
	v_mfma_f32_16x16x32_bf16 v[4:7], v[210:213], v[202:205], v[4:7]
	v_mfma_f32_16x16x32_bf16 v[0:3], v[218:221], v[202:205], v[0:3]
	v_mfma_f32_16x16x32_bf16 v[52:55], v[214:217], v[182:185], v[52:55]
	v_mfma_f32_16x16x32_bf16 v[48:51], v[222:225], v[182:185], v[48:51]
	v_mfma_f32_16x16x32_bf16 v[36:39], v[214:217], v[190:193], v[36:39]
	v_mfma_f32_16x16x32_bf16 v[32:35], v[222:225], v[190:193], v[32:35]
	v_mfma_f32_16x16x32_bf16 v[20:23], v[214:217], v[198:201], v[20:23]
	v_mfma_f32_16x16x32_bf16 v[16:19], v[222:225], v[198:201], v[16:19]
	v_mfma_f32_16x16x32_bf16 v[4:7], v[214:217], v[206:209], v[4:7]
	v_mfma_f32_16x16x32_bf16 v[0:3], v[222:225], v[206:209], v[0:3]
	s_setprio 0
	s_barrier
	ds_read_b128 v[140:143], v156
	ds_read_b128 v[166:169], v157
	ds_read_b128 v[170:173], v159
	ds_read_b128 v[174:177], v160
	s_add_u32 s14, s28, 0x44000
	s_addc_u32 s15, s29, 0
	s_mov_b32 m0, s57
	ds_read_b128 v[178:181], v146 offset:32768
	ds_read_b128 v[182:185], v146 offset:33792
	ds_read_b128 v[186:189], v146 offset:34816
	ds_read_b128 v[190:193], v146 offset:35840
	ds_read_b128 v[194:197], v146 offset:36864
	ds_read_b128 v[198:201], v146 offset:37888
	ds_read_b128 v[202:205], v146 offset:38912
	ds_read_b128 v[206:209], v146 offset:39936
	global_load_lds_dwordx4 v130, s[14:15]
	s_mov_b32 m0, s58
	s_nop 0
	global_load_lds_dwordx4 v128, s[14:15]
	s_waitcnt lgkmcnt(8)
	s_barrier
	s_waitcnt lgkmcnt(0)
	s_setprio 1
	s_waitcnt lgkmcnt(0)
	v_mfma_f32_16x16x32_bf16 v[124:127], v[140:143], v[178:181], v[124:127]
	v_mfma_f32_16x16x32_bf16 v[120:123], v[170:173], v[178:181], v[120:123]
	v_mfma_f32_16x16x32_bf16 v[108:111], v[140:143], v[186:189], v[108:111]
	v_mfma_f32_16x16x32_bf16 v[104:107], v[170:173], v[186:189], v[104:107]
	v_mfma_f32_16x16x32_bf16 v[92:95], v[140:143], v[194:197], v[92:95]
	v_mfma_f32_16x16x32_bf16 v[88:91], v[170:173], v[194:197], v[88:91]
	v_mfma_f32_16x16x32_bf16 v[76:79], v[140:143], v[202:205], v[76:79]
	v_mfma_f32_16x16x32_bf16 v[72:75], v[170:173], v[202:205], v[72:75]
	v_mfma_f32_16x16x32_bf16 v[124:127], v[166:169], v[182:185], v[124:127]
	v_mfma_f32_16x16x32_bf16 v[120:123], v[174:177], v[182:185], v[120:123]
	v_mfma_f32_16x16x32_bf16 v[108:111], v[166:169], v[190:193], v[108:111]
	v_mfma_f32_16x16x32_bf16 v[104:107], v[174:177], v[190:193], v[104:107]
	v_mfma_f32_16x16x32_bf16 v[92:95], v[166:169], v[198:201], v[92:95]
	v_mfma_f32_16x16x32_bf16 v[88:91], v[174:177], v[198:201], v[88:91]
	v_mfma_f32_16x16x32_bf16 v[76:79], v[166:169], v[206:209], v[76:79]
	v_mfma_f32_16x16x32_bf16 v[72:75], v[174:177], v[206:209], v[72:75]
	s_setprio 0
	s_barrier
	s_mov_b32 m0, s61
	ds_read_b128 v[210:213], v161
	ds_read_b128 v[214:217], v162
	ds_read_b128 v[218:221], v163
	ds_read_b128 v[222:225], v164
	s_add_u32 s100, s18, 0x80
	s_addc_u32 s101, s19, 0
	global_load_lds_dwordx4 v130, s[100:101]
	s_mov_b32 m0, s62
	s_nop 0
	global_load_lds_dwordx4 v128, s[100:101]
	s_barrier
	s_waitcnt lgkmcnt(0)
	s_setprio 1
	s_waitcnt lgkmcnt(0)
	v_mfma_f32_16x16x32_bf16 v[116:119], v[210:213], v[178:181], v[116:119]
	v_mfma_f32_16x16x32_bf16 v[112:115], v[218:221], v[178:181], v[112:115]
	v_mfma_f32_16x16x32_bf16 v[100:103], v[210:213], v[186:189], v[100:103]
	v_mfma_f32_16x16x32_bf16 v[96:99], v[218:221], v[186:189], v[96:99]
	v_mfma_f32_16x16x32_bf16 v[84:87], v[210:213], v[194:197], v[84:87]
	v_mfma_f32_16x16x32_bf16 v[80:83], v[218:221], v[194:197], v[80:83]
	v_mfma_f32_16x16x32_bf16 v[68:71], v[210:213], v[202:205], v[68:71]
	v_mfma_f32_16x16x32_bf16 v[64:67], v[218:221], v[202:205], v[64:67]
	v_mfma_f32_16x16x32_bf16 v[116:119], v[214:217], v[182:185], v[116:119]
	v_mfma_f32_16x16x32_bf16 v[112:115], v[222:225], v[182:185], v[112:115]
	v_mfma_f32_16x16x32_bf16 v[100:103], v[214:217], v[190:193], v[100:103]
	v_mfma_f32_16x16x32_bf16 v[96:99], v[222:225], v[190:193], v[96:99]
	v_mfma_f32_16x16x32_bf16 v[84:87], v[214:217], v[198:201], v[84:87]
	v_mfma_f32_16x16x32_bf16 v[80:83], v[222:225], v[198:201], v[80:83]
	v_mfma_f32_16x16x32_bf16 v[68:71], v[214:217], v[206:209], v[68:71]
	v_mfma_f32_16x16x32_bf16 v[64:67], v[222:225], v[206:209], v[64:67]
	s_setprio 0
	s_mov_b32 m0, s63
	s_barrier
	ds_read_b128 v[178:181], v146 offset:49152
	ds_read_b128 v[182:185], v146 offset:50176
	ds_read_b128 v[186:189], v146 offset:51200
	ds_read_b128 v[190:193], v146 offset:52224
	ds_read_b128 v[194:197], v146 offset:53248
	ds_read_b128 v[198:201], v146 offset:54272
	ds_read_b128 v[202:205], v146 offset:55296
	ds_read_b128 v[206:209], v146 offset:56320
	s_add_u32 s100, s28, 0x80
	s_addc_u32 s101, s29, 0
	global_load_lds_dwordx4 v130, s[100:101]
	s_mov_b32 m0, s64
	s_nop 0
	global_load_lds_dwordx4 v128, s[100:101]
	s_barrier
; DI float ex2(float x) { return __builtin_amdgcn_exp2f(x); }
; #define PG8_STAGE(bufoff, gbase, voff) do { _Pragma("unroll") for (int _i = 0; _i < 2; ++_i) \
;         __builtin_amdgcn_global_load_lds((const unsigned*)((const char*)(gbase) + (voff)[_i]), (PG8_LAS unsigned*)(lds + (bufoff) + ldsw + _i * 8192), 16, 0, 0); } while (0)
; #define PG8_MMA(ai, bj, At, Bt) do { __builtin_amdgcn_s_setprio(1); _Pragma("unroll") for (int m = 0; m < 4; ++m) _Pragma("unroll") for (int n = 0; n < 2; ++n) _Pragma("unroll") for (int k = 0; k < 2; ++k) \
;         acc[ai][bj][m][n] = __builtin_amdgcn_mfma_f32_16x16x32_bf16(Bt[n][k], At[m][k], acc[ai][bj][m][n], 0, 0, 0); __builtin_amdgcn_s_setprio(0); } while (0)
; #define PG8_WAIT_V(n) asm volatile("s_waitcnt vmcnt(" #n ")" ::: "memory")
; #define PG8_WAIT_L(n) asm volatile("s_waitcnt lgkmcnt(" #n ")" ::: "memory")
; #define PG8_BAR __builtin_amdgcn_s_barrier()
; #define PG8_SCHED __builtin_amdgcn_sched_barrier(0)
;     DI void operator()(const f32x4 (&acc)[2][2][4][2], const Unit& u, int wr, int wc, int fr, int fq) const {
;         const int row0 = u.pm * BM + wr * 64 + fr, hcol0 = ((u.pn * BM + wc * 32) >> 1) + 4 * fq;
; #pragma unroll
;         for (int ai = 0; ai < 2; ++ai)
; #pragma unroll
;             for (int m = 0; m < 4; ++m) { u16* rowp = O + (size_t)(row0 + ai * HALF + m * 16) * ldc + hcol0;
; #pragma unroll
;                 for (int bj = 0; bj < 2; ++bj) { const f32x4 g = acc[ai][bj][m][0], up = acc[ai][bj][m][1]; float r[4];
; #pragma unroll
;                     for (int j = 0; j < 4; ++j) r[j] = g[j] * up[j] * __builtin_amdgcn_rcpf(1.f + ex2(-LOG2E * g[j]));
;                     uint2 w = {pack2(r[0], r[1]), pack2(r[2], r[3])}; *(uint2*)(rowp + bj * (HALF / 2)) = w; } }
; template <class Epi, class Sched, bool STAMP = false>
; __device__ __forceinline__ void gemm_phase(PG8_LAS unsigned char* lds, const Gemm g, const Sched& S, const Epi& E, unsigned long long* stamps) {
;     ...
;             PG8_BAR; PG8_WAIT_L(0); PG8_MMA(1, 0, At, B0); PG8_BAR; PG8_SCHED;
;             PG8_STAGE(PG8_SB(1, 1), b3 + hstep, voffB);
;             PG8_WAIT_V(6); PG8_BAR; PG8_MMA(1, 1, At, B1); PG8_BAR;
;         }
	s_waitcnt lgkmcnt(0)
	s_setprio 1
	s_waitcnt lgkmcnt(0)
	v_mfma_f32_16x16x32_bf16 v[60:63], v[140:143], v[178:181], v[60:63]
	v_mfma_f32_16x16x32_bf16 v[56:59], v[170:173], v[178:181], v[56:59]
	v_mfma_f32_16x16x32_bf16 v[44:47], v[140:143], v[186:189], v[44:47]
	v_mfma_f32_16x16x32_bf16 v[40:43], v[170:173], v[186:189], v[40:43]
	v_mfma_f32_16x16x32_bf16 v[28:31], v[140:143], v[194:197], v[28:31]
	v_mfma_f32_16x16x32_bf16 v[24:27], v[170:173], v[194:197], v[24:27]
	v_mfma_f32_16x16x32_bf16 v[12:15], v[140:143], v[202:205], v[12:15]
	v_mfma_f32_16x16x32_bf16 v[8:11], v[170:173], v[202:205], v[8:11]
	v_mfma_f32_16x16x32_bf16 v[60:63], v[166:169], v[182:185], v[60:63]
	v_mfma_f32_16x16x32_bf16 v[56:59], v[174:177], v[182:185], v[56:59]
	v_mfma_f32_16x16x32_bf16 v[44:47], v[166:169], v[190:193], v[44:47]
	v_mfma_f32_16x16x32_bf16 v[40:43], v[174:177], v[190:193], v[40:43]
	v_mfma_f32_16x16x32_bf16 v[28:31], v[166:169], v[198:201], v[28:31]
	v_mfma_f32_16x16x32_bf16 v[24:27], v[174:177], v[198:201], v[24:27]
	v_mfma_f32_16x16x32_bf16 v[12:15], v[166:169], v[206:209], v[12:15]
	v_mfma_f32_16x16x32_bf16 v[8:11], v[174:177], v[206:209], v[8:11]
	s_setprio 0
	s_barrier
	s_add_u32 s14, s18, 0x44080
	s_addc_u32 s15, s19, 0
	s_mov_b32 m0, s65
	s_nop 0
	global_load_lds_dwordx4 v130, s[14:15]
	s_mov_b32 m0, s66
	s_nop 0
	global_load_lds_dwordx4 v128, s[14:15]
	s_waitcnt vmcnt(6)
	s_barrier
	s_setprio 1
	v_mfma_f32_16x16x32_bf16 v[52:55], v[210:213], v[178:181], v[52:55]
	v_mfma_f32_16x16x32_bf16 v[48:51], v[218:221], v[178:181], v[48:51]
	v_mfma_f32_16x16x32_bf16 v[36:39], v[210:213], v[186:189], v[36:39]
	v_mfma_f32_16x16x32_bf16 v[32:35], v[218:221], v[186:189], v[32:35]
	v_mfma_f32_16x16x32_bf16 v[20:23], v[210:213], v[194:197], v[20:23]
	v_mfma_f32_16x16x32_bf16 v[16:19], v[218:221], v[194:197], v[16:19]
	v_mfma_f32_16x16x32_bf16 v[4:7], v[210:213], v[202:205], v[4:7]
	v_mfma_f32_16x16x32_bf16 v[0:3], v[218:221], v[202:205], v[0:3]
	v_mfma_f32_16x16x32_bf16 v[52:55], v[214:217], v[182:185], v[52:55]
	v_mfma_f32_16x16x32_bf16 v[48:51], v[222:225], v[182:185], v[48:51]
	v_mfma_f32_16x16x32_bf16 v[36:39], v[214:217], v[190:193], v[36:39]
	v_mfma_f32_16x16x32_bf16 v[32:35], v[222:225], v[190:193], v[32:35]
	v_mfma_f32_16x16x32_bf16 v[20:23], v[214:217], v[198:201], v[20:23]
	v_mfma_f32_16x16x32_bf16 v[16:19], v[222:225], v[198:201], v[16:19]
	v_mfma_f32_16x16x32_bf16 v[4:7], v[214:217], v[206:209], v[4:7]
	v_mfma_f32_16x16x32_bf16 v[0:3], v[222:225], v[206:209], v[0:3]
	s_setprio 0
	s_add_i32 s77, s77, 2
	s_add_u32 s75, s75, 0x100
	s_addc_u32 s76, s76, 0
	s_cmp_gt_u32 s77, 13
	s_mov_b64 s[14:15], s[16:17]
	s_barrier
	s_cbranch_scc0 .LBB0_63
	v_mul_f32_e32 v168, 0xbfb8aa3b, v124
	v_mul_f32_e32 v169, 0xbfb8aa3b, v125
	v_mul_f32_e32 v170, 0xbfb8aa3b, v126
	v_mul_f32_e32 v171, 0xbfb8aa3b, v127
	v_exp_f32_e32 v168, v168
	v_exp_f32_e32 v169, v169
	v_exp_f32_e32 v170, v170
	v_exp_f32_e32 v171, v171
	v_add_f32_e32 v168, 1.0, v168
	v_add_f32_e32 v169, 1.0, v169
	v_add_f32_e32 v170, 1.0, v170
	v_add_f32_e32 v171, 1.0, v171
	v_rcp_f32_e32 v168, v168
	v_rcp_f32_e32 v169, v169
	v_rcp_f32_e32 v170, v170
	v_rcp_f32_e32 v171, v171
	s_lshl_b32 s10, s74, 8
	v_pk_mul_f32 v[122:123], v[126:127], v[122:123]
	v_pk_mul_f32 v[120:121], v[124:125], v[120:121]
	s_or_b32 s10, s10, s60
	v_pk_mul_f32 v[120:121], v[120:121], v[168:169]
	v_pk_mul_f32 v[122:123], v[122:123], v[170:171]
	s_ashr_i32 s10, s10, 1
	v_cvt_pk_bf16_f32 v120, v120, v121
	v_cvt_pk_bf16_f32 v121, v122, v123
	v_mul_f32_e32 v122, 0xbfb8aa3b, v116
	v_mul_f32_e32 v123, 0xbfb8aa3b, v117
	v_or_b32_e32 v140, s10, v147
	v_exp_f32_e32 v122, v122
	v_exp_f32_e32 v123, v123
	v_lshl_add_u32 v165, s73, 8, v145
	v_ashrrev_i32_e32 v141, 31, v140
	v_mov_b64_e32 v[142:143], s[12:13]
	v_mad_i64_i32 v[166:167], s[14:15], v165, s70, v[142:143]
	v_lshlrev_b64 v[140:141], 1, v[140:141]
	v_lshl_add_u64 v[166:167], v[166:167], 0, v[140:141]
	global_store_dwordx2 v[166:167], v[120:121], off
	v_add_f32_e32 v120, 1.0, v122
	v_add_f32_e32 v121, 1.0, v123
	v_mul_f32_e32 v122, 0xbfb8aa3b, v118
	v_mul_f32_e32 v123, 0xbfb8aa3b, v119
	v_exp_f32_e32 v122, v122
	v_exp_f32_e32 v123, v123
	v_rcp_f32_e32 v120, v120
	v_rcp_f32_e32 v121, v121
	v_add_f32_e32 v122, 1.0, v122
	v_add_f32_e32 v123, 1.0, v123
	v_rcp_f32_e32 v122, v122
	v_rcp_f32_e32 v123, v123
	v_pk_mul_f32 v[114:115], v[118:119], v[114:115]
	v_pk_mul_f32 v[112:113], v[116:117], v[112:113]
	v_mul_f32_e32 v116, 0xbfb8aa3b, v110
	v_pk_mul_f32 v[112:113], v[112:113], v[120:121]
	v_pk_mul_f32 v[114:115], v[114:115], v[122:123]
	v_cvt_pk_bf16_f32 v112, v112, v113
	v_cvt_pk_bf16_f32 v113, v114, v115
	v_mul_f32_e32 v114, 0xbfb8aa3b, v108
	v_mul_f32_e32 v115, 0xbfb8aa3b, v109
	v_mul_f32_e32 v117, 0xbfb8aa3b, v111
	v_exp_f32_e32 v114, v114
	v_exp_f32_e32 v115, v115
	v_exp_f32_e32 v116, v116
	v_exp_f32_e32 v117, v117
	v_add_f32_e32 v114, 1.0, v114
	v_add_f32_e32 v115, 1.0, v115
	v_add_f32_e32 v116, 1.0, v116
	v_add_f32_e32 v117, 1.0, v117
	v_rcp_f32_e32 v114, v114
	v_rcp_f32_e32 v115, v115
	v_rcp_f32_e32 v116, v116
	v_rcp_f32_e32 v117, v117
	v_pk_mul_f32 v[106:107], v[110:111], v[106:107]
	v_pk_mul_f32 v[104:105], v[108:109], v[104:105]
	global_store_dwordx2 v[166:167], v[112:113], off offset:128
	v_pk_mul_f32 v[104:105], v[104:105], v[114:115]
	v_pk_mul_f32 v[106:107], v[106:107], v[116:117]
	v_cvt_pk_bf16_f32 v104, v104, v105
	v_cvt_pk_bf16_f32 v105, v106, v107
	v_mul_f32_e32 v106, 0xbfb8aa3b, v100
	v_mul_f32_e32 v107, 0xbfb8aa3b, v101
	v_exp_f32_e32 v106, v106
	v_exp_f32_e32 v107, v107
	v_or_b32_e32 v112, 16, v165
	v_mad_i64_i32 v[112:113], s[14:15], v112, s70, v[142:143]
; DI float ex2(float x) { return __builtin_amdgcn_exp2f(x); }
;     DI void operator()(const f32x4 (&acc)[2][2][4][2], const Unit& u, int wr, int wc, int fr, int fq) const {
;         const int row0 = u.pm * BM + wr * 64 + fr, hcol0 = ((u.pn * BM + wc * 32) >> 1) + 4 * fq;
; #pragma unroll
;         for (int ai = 0; ai < 2; ++ai)
; #pragma unroll
;             for (int m = 0; m < 4; ++m) { u16* rowp = O + (size_t)(row0 + ai * HALF + m * 16) * ldc + hcol0;
; #pragma unroll
;                 for (int bj = 0; bj < 2; ++bj) { const f32x4 g = acc[ai][bj][m][0], up = acc[ai][bj][m][1]; float r[4];
; #pragma unroll
;                     for (int j = 0; j < 4; ++j) r[j] = g[j] * up[j] * __builtin_amdgcn_rcpf(1.f + ex2(-LOG2E * g[j]));
;                     uint2 w = {pack2(r[0], r[1]), pack2(r[2], r[3])}; *(uint2*)(rowp + bj * (HALF / 2)) = w; } }
	v_lshl_add_u64 v[112:113], v[112:113], 0, v[140:141]
	global_store_dwordx2 v[112:113], v[104:105], off
	v_add_f32_e32 v104, 1.0, v106
	v_add_f32_e32 v105, 1.0, v107
	v_mul_f32_e32 v106, 0xbfb8aa3b, v102
	v_mul_f32_e32 v107, 0xbfb8aa3b, v103
	v_exp_f32_e32 v106, v106
	v_exp_f32_e32 v107, v107
	v_rcp_f32_e32 v104, v104
	v_rcp_f32_e32 v105, v105
	v_add_f32_e32 v106, 1.0, v106
	v_add_f32_e32 v107, 1.0, v107
	v_rcp_f32_e32 v106, v106
	v_rcp_f32_e32 v107, v107
	v_pk_mul_f32 v[98:99], v[102:103], v[98:99]
	v_pk_mul_f32 v[96:97], v[100:101], v[96:97]
	v_mul_f32_e32 v100, 0xbfb8aa3b, v94
	v_pk_mul_f32 v[96:97], v[96:97], v[104:105]
	v_pk_mul_f32 v[98:99], v[98:99], v[106:107]
	v_cvt_pk_bf16_f32 v96, v96, v97
	v_cvt_pk_bf16_f32 v97, v98, v99
	v_mul_f32_e32 v98, 0xbfb8aa3b, v92
	v_mul_f32_e32 v99, 0xbfb8aa3b, v93
	v_mul_f32_e32 v101, 0xbfb8aa3b, v95
	v_exp_f32_e32 v98, v98
	v_exp_f32_e32 v99, v99
	v_exp_f32_e32 v100, v100
	v_exp_f32_e32 v101, v101
	v_add_f32_e32 v98, 1.0, v98
	v_add_f32_e32 v99, 1.0, v99
	v_add_f32_e32 v100, 1.0, v100
	v_add_f32_e32 v101, 1.0, v101
	v_rcp_f32_e32 v98, v98
	v_rcp_f32_e32 v99, v99
	v_rcp_f32_e32 v100, v100
	v_rcp_f32_e32 v101, v101
	v_pk_mul_f32 v[90:91], v[94:95], v[90:91]
	v_pk_mul_f32 v[88:89], v[92:93], v[88:89]
	global_store_dwordx2 v[112:113], v[96:97], off offset:128
	v_pk_mul_f32 v[88:89], v[88:89], v[98:99]
	v_pk_mul_f32 v[90:91], v[90:91], v[100:101]
	v_cvt_pk_bf16_f32 v88, v88, v89
	v_cvt_pk_bf16_f32 v89, v90, v91
	v_mul_f32_e32 v90, 0xbfb8aa3b, v84
	v_mul_f32_e32 v91, 0xbfb8aa3b, v85
	v_exp_f32_e32 v90, v90
	v_exp_f32_e32 v91, v91
	v_or_b32_e32 v96, 32, v165
	v_mad_i64_i32 v[96:97], s[14:15], v96, s70, v[142:143]
	v_lshl_add_u64 v[96:97], v[96:97], 0, v[140:141]
	global_store_dwordx2 v[96:97], v[88:89], off
	v_add_f32_e32 v88, 1.0, v90
	v_add_f32_e32 v89, 1.0, v91
	v_mul_f32_e32 v90, 0xbfb8aa3b, v86
	v_mul_f32_e32 v91, 0xbfb8aa3b, v87
	v_exp_f32_e32 v90, v90
	v_exp_f32_e32 v91, v91
	v_rcp_f32_e32 v88, v88
	v_rcp_f32_e32 v89, v89
	v_add_f32_e32 v90, 1.0, v90
	v_add_f32_e32 v91, 1.0, v91
	v_rcp_f32_e32 v90, v90
	v_rcp_f32_e32 v91, v91
	v_pk_mul_f32 v[82:83], v[86:87], v[82:83]
	v_pk_mul_f32 v[80:81], v[84:85], v[80:81]
	v_mul_f32_e32 v84, 0xbfb8aa3b, v78
	v_pk_mul_f32 v[80:81], v[80:81], v[88:89]
	v_pk_mul_f32 v[82:83], v[82:83], v[90:91]
	v_cvt_pk_bf16_f32 v80, v80, v81
	v_cvt_pk_bf16_f32 v81, v82, v83
	v_mul_f32_e32 v82, 0xbfb8aa3b, v76
	v_mul_f32_e32 v83, 0xbfb8aa3b, v77
	v_mul_f32_e32 v85, 0xbfb8aa3b, v79
	v_exp_f32_e32 v82, v82
	v_exp_f32_e32 v83, v83
	v_exp_f32_e32 v84, v84
	v_exp_f32_e32 v85, v85
	v_add_f32_e32 v82, 1.0, v82
	v_add_f32_e32 v83, 1.0, v83
	v_add_f32_e32 v84, 1.0, v84
	v_add_f32_e32 v85, 1.0, v85
	v_rcp_f32_e32 v82, v82
	v_rcp_f32_e32 v83, v83
	v_rcp_f32_e32 v84, v84
	v_rcp_f32_e32 v85, v85
	v_pk_mul_f32 v[74:75], v[78:79], v[74:75]
	v_pk_mul_f32 v[72:73], v[76:77], v[72:73]
	global_store_dwordx2 v[96:97], v[80:81], off offset:128
	v_pk_mul_f32 v[72:73], v[72:73], v[82:83]
	v_pk_mul_f32 v[74:75], v[74:75], v[84:85]
	v_cvt_pk_bf16_f32 v72, v72, v73
	v_cvt_pk_bf16_f32 v73, v74, v75
	v_mul_f32_e32 v74, 0xbfb8aa3b, v68
	v_mul_f32_e32 v75, 0xbfb8aa3b, v69
	v_exp_f32_e32 v74, v74
	v_exp_f32_e32 v75, v75
	v_or_b32_e32 v80, 48, v165
	v_mad_i64_i32 v[80:81], s[14:15], v80, s70, v[142:143]
	v_lshl_add_u64 v[80:81], v[80:81], 0, v[140:141]
	global_store_dwordx2 v[80:81], v[72:73], off
	v_add_f32_e32 v72, 1.0, v74
	v_add_f32_e32 v73, 1.0, v75
	v_mul_f32_e32 v74, 0xbfb8aa3b, v70
	v_mul_f32_e32 v75, 0xbfb8aa3b, v71
	v_exp_f32_e32 v74, v74
	v_exp_f32_e32 v75, v75
	v_rcp_f32_e32 v72, v72
	v_rcp_f32_e32 v73, v73
	v_add_f32_e32 v74, 1.0, v74
	v_add_f32_e32 v75, 1.0, v75
	v_rcp_f32_e32 v74, v74
	v_rcp_f32_e32 v75, v75
	v_pk_mul_f32 v[66:67], v[70:71], v[66:67]
	v_pk_mul_f32 v[64:65], v[68:69], v[64:65]
	v_mul_f32_e32 v68, 0xbfb8aa3b, v62
	v_pk_mul_f32 v[64:65], v[64:65], v[72:73]
	v_pk_mul_f32 v[66:67], v[66:67], v[74:75]
	v_cvt_pk_bf16_f32 v64, v64, v65
	v_cvt_pk_bf16_f32 v65, v66, v67
	v_mul_f32_e32 v66, 0xbfb8aa3b, v60
	v_mul_f32_e32 v67, 0xbfb8aa3b, v61
	v_mul_f32_e32 v69, 0xbfb8aa3b, v63
	v_exp_f32_e32 v66, v66
	v_exp_f32_e32 v67, v67
	v_exp_f32_e32 v68, v68
	v_exp_f32_e32 v69, v69
	v_add_f32_e32 v66, 1.0, v66
	v_add_f32_e32 v67, 1.0, v67
	v_add_f32_e32 v68, 1.0, v68
	v_add_f32_e32 v69, 1.0, v69
	v_rcp_f32_e32 v66, v66
	v_rcp_f32_e32 v67, v67
	v_rcp_f32_e32 v68, v68
	v_rcp_f32_e32 v69, v69
	v_pk_mul_f32 v[58:59], v[62:63], v[58:59]
	v_pk_mul_f32 v[56:57], v[60:61], v[56:57]
	global_store_dwordx2 v[80:81], v[64:65], off offset:128
	v_pk_mul_f32 v[56:57], v[56:57], v[66:67]
	v_pk_mul_f32 v[58:59], v[58:59], v[68:69]
	v_cvt_pk_bf16_f32 v56, v56, v57
	v_cvt_pk_bf16_f32 v57, v58, v59
	v_mul_f32_e32 v58, 0xbfb8aa3b, v52
	v_mul_f32_e32 v59, 0xbfb8aa3b, v53
	v_exp_f32_e32 v58, v58
	v_exp_f32_e32 v59, v59
	v_add_u32_e32 v64, 0x80, v165
	v_mad_i64_i32 v[64:65], s[14:15], v64, s70, v[142:143]
	v_lshl_add_u64 v[64:65], v[64:65], 0, v[140:141]
	global_store_dwordx2 v[64:65], v[56:57], off
	v_add_f32_e32 v56, 1.0, v58
	v_add_f32_e32 v57, 1.0, v59
	v_mul_f32_e32 v58, 0xbfb8aa3b, v54
	v_mul_f32_e32 v59, 0xbfb8aa3b, v55
	v_exp_f32_e32 v58, v58
	v_exp_f32_e32 v59, v59
	v_rcp_f32_e32 v56, v56
	v_rcp_f32_e32 v57, v57
	v_add_f32_e32 v58, 1.0, v58
	v_add_f32_e32 v59, 1.0, v59
	v_rcp_f32_e32 v58, v58
	v_rcp_f32_e32 v59, v59
	v_pk_mul_f32 v[50:51], v[54:55], v[50:51]
	v_pk_mul_f32 v[48:49], v[52:53], v[48:49]
	v_mul_f32_e32 v52, 0xbfb8aa3b, v46
	v_pk_mul_f32 v[48:49], v[48:49], v[56:57]
	v_pk_mul_f32 v[50:51], v[50:51], v[58:59]
	v_cvt_pk_bf16_f32 v48, v48, v49
	v_cvt_pk_bf16_f32 v49, v50, v51
	v_mul_f32_e32 v50, 0xbfb8aa3b, v44
; DI float ex2(float x) { return __builtin_amdgcn_exp2f(x); }
;     DI void operator()(const f32x4 (&acc)[2][2][4][2], const Unit& u, int wr, int wc, int fr, int fq) const {
;         const int row0 = u.pm * BM + wr * 64 + fr, hcol0 = ((u.pn * BM + wc * 32) >> 1) + 4 * fq;
; #pragma unroll
;         for (int ai = 0; ai < 2; ++ai)
; #pragma unroll
;             for (int m = 0; m < 4; ++m) { u16* rowp = O + (size_t)(row0 + ai * HALF + m * 16) * ldc + hcol0;
; #pragma unroll
;                 for (int bj = 0; bj < 2; ++bj) { const f32x4 g = acc[ai][bj][m][0], up = acc[ai][bj][m][1]; float r[4];
; #pragma unroll
;                     for (int j = 0; j < 4; ++j) r[j] = g[j] * up[j] * __builtin_amdgcn_rcpf(1.f + ex2(-LOG2E * g[j]));
;                     uint2 w = {pack2(r[0], r[1]), pack2(r[2], r[3])}; *(uint2*)(rowp + bj * (HALF / 2)) = w; } }
	v_mul_f32_e32 v51, 0xbfb8aa3b, v45
	v_mul_f32_e32 v53, 0xbfb8aa3b, v47
	v_exp_f32_e32 v50, v50
	v_exp_f32_e32 v51, v51
	v_exp_f32_e32 v52, v52
	v_exp_f32_e32 v53, v53
	v_add_f32_e32 v50, 1.0, v50
	v_add_f32_e32 v51, 1.0, v51
	v_add_f32_e32 v52, 1.0, v52
	v_add_f32_e32 v53, 1.0, v53
	v_rcp_f32_e32 v50, v50
	v_rcp_f32_e32 v51, v51
	v_rcp_f32_e32 v52, v52
	v_rcp_f32_e32 v53, v53
	v_pk_mul_f32 v[42:43], v[46:47], v[42:43]
	v_pk_mul_f32 v[40:41], v[44:45], v[40:41]
	global_store_dwordx2 v[64:65], v[48:49], off offset:128
	v_pk_mul_f32 v[40:41], v[40:41], v[50:51]
	v_pk_mul_f32 v[42:43], v[42:43], v[52:53]
	v_cvt_pk_bf16_f32 v40, v40, v41
	v_cvt_pk_bf16_f32 v41, v42, v43
	v_mul_f32_e32 v42, 0xbfb8aa3b, v36
	v_mul_f32_e32 v43, 0xbfb8aa3b, v37
	v_exp_f32_e32 v42, v42
	v_exp_f32_e32 v43, v43
	v_add_u32_e32 v48, 0x90, v165
	v_mad_i64_i32 v[48:49], s[14:15], v48, s70, v[142:143]
	v_lshl_add_u64 v[48:49], v[48:49], 0, v[140:141]
	global_store_dwordx2 v[48:49], v[40:41], off
	v_add_f32_e32 v40, 1.0, v42
	v_add_f32_e32 v41, 1.0, v43
	v_mul_f32_e32 v42, 0xbfb8aa3b, v38
	v_mul_f32_e32 v43, 0xbfb8aa3b, v39
	v_exp_f32_e32 v42, v42
	v_exp_f32_e32 v43, v43
	v_rcp_f32_e32 v40, v40
	v_rcp_f32_e32 v41, v41
	v_add_f32_e32 v42, 1.0, v42
	v_add_f32_e32 v43, 1.0, v43
	v_rcp_f32_e32 v42, v42
	v_rcp_f32_e32 v43, v43
	v_pk_mul_f32 v[34:35], v[38:39], v[34:35]
	v_pk_mul_f32 v[32:33], v[36:37], v[32:33]
	v_mul_f32_e32 v36, 0xbfb8aa3b, v30
	v_pk_mul_f32 v[32:33], v[32:33], v[40:41]
	v_pk_mul_f32 v[34:35], v[34:35], v[42:43]
	v_cvt_pk_bf16_f32 v32, v32, v33
	v_cvt_pk_bf16_f32 v33, v34, v35
	v_mul_f32_e32 v34, 0xbfb8aa3b, v28
	v_mul_f32_e32 v35, 0xbfb8aa3b, v29
	v_mul_f32_e32 v37, 0xbfb8aa3b, v31
	v_exp_f32_e32 v34, v34
	v_exp_f32_e32 v35, v35
	v_exp_f32_e32 v36, v36
	v_exp_f32_e32 v37, v37
	v_add_f32_e32 v34, 1.0, v34
	v_add_f32_e32 v35, 1.0, v35
	v_add_f32_e32 v36, 1.0, v36
	v_add_f32_e32 v37, 1.0, v37
	v_rcp_f32_e32 v34, v34
	v_rcp_f32_e32 v35, v35
	v_rcp_f32_e32 v36, v36
	v_rcp_f32_e32 v37, v37
	v_pk_mul_f32 v[26:27], v[30:31], v[26:27]
	v_pk_mul_f32 v[24:25], v[28:29], v[24:25]
	global_store_dwordx2 v[48:49], v[32:33], off offset:128
	v_pk_mul_f32 v[24:25], v[24:25], v[34:35]
	v_pk_mul_f32 v[26:27], v[26:27], v[36:37]
	v_cvt_pk_bf16_f32 v24, v24, v25
	v_cvt_pk_bf16_f32 v25, v26, v27
	v_mul_f32_e32 v26, 0xbfb8aa3b, v20
	v_mul_f32_e32 v27, 0xbfb8aa3b, v21
	v_exp_f32_e32 v26, v26
	v_exp_f32_e32 v27, v27
	v_add_u32_e32 v32, 0xa0, v165
	v_mad_i64_i32 v[32:33], s[14:15], v32, s70, v[142:143]
	v_lshl_add_u64 v[32:33], v[32:33], 0, v[140:141]
	global_store_dwordx2 v[32:33], v[24:25], off
	v_add_f32_e32 v24, 1.0, v26
	v_add_f32_e32 v25, 1.0, v27
	v_mul_f32_e32 v26, 0xbfb8aa3b, v22
	v_mul_f32_e32 v27, 0xbfb8aa3b, v23
	v_exp_f32_e32 v26, v26
	v_exp_f32_e32 v27, v27
	v_rcp_f32_e32 v24, v24
	v_rcp_f32_e32 v25, v25
	v_add_f32_e32 v26, 1.0, v26
	v_add_f32_e32 v27, 1.0, v27
	v_rcp_f32_e32 v26, v26
	v_rcp_f32_e32 v27, v27
	v_pk_mul_f32 v[18:19], v[22:23], v[18:19]
	v_pk_mul_f32 v[16:17], v[20:21], v[16:17]
	v_mul_f32_e32 v20, 0xbfb8aa3b, v14
	v_pk_mul_f32 v[16:17], v[16:17], v[24:25]
	v_pk_mul_f32 v[18:19], v[18:19], v[26:27]
	v_cvt_pk_bf16_f32 v16, v16, v17
	v_cvt_pk_bf16_f32 v17, v18, v19
	v_mul_f32_e32 v18, 0xbfb8aa3b, v12
	v_mul_f32_e32 v19, 0xbfb8aa3b, v13
	v_mul_f32_e32 v21, 0xbfb8aa3b, v15
	v_exp_f32_e32 v18, v18
	v_exp_f32_e32 v19, v19
	v_exp_f32_e32 v20, v20
	v_exp_f32_e32 v21, v21
	v_add_f32_e32 v18, 1.0, v18
	v_add_f32_e32 v19, 1.0, v19
	v_add_f32_e32 v20, 1.0, v20
	v_add_f32_e32 v21, 1.0, v21
	v_rcp_f32_e32 v18, v18
	v_rcp_f32_e32 v19, v19
	v_rcp_f32_e32 v20, v20
	v_rcp_f32_e32 v21, v21
	v_pk_mul_f32 v[10:11], v[14:15], v[10:11]
	v_pk_mul_f32 v[8:9], v[12:13], v[8:9]
	global_store_dwordx2 v[32:33], v[16:17], off offset:128
	v_pk_mul_f32 v[8:9], v[8:9], v[18:19]
	v_pk_mul_f32 v[10:11], v[10:11], v[20:21]
	v_cvt_pk_bf16_f32 v8, v8, v9
	v_cvt_pk_bf16_f32 v9, v10, v11
	v_mul_f32_e32 v10, 0xbfb8aa3b, v4
	v_mul_f32_e32 v11, 0xbfb8aa3b, v5
	v_exp_f32_e32 v10, v10
	v_exp_f32_e32 v11, v11
	v_add_u32_e32 v16, 0xb0, v165
	v_mad_i64_i32 v[16:17], s[14:15], v16, s70, v[142:143]
	v_lshl_add_u64 v[16:17], v[16:17], 0, v[140:141]
	global_store_dwordx2 v[16:17], v[8:9], off
	v_add_f32_e32 v8, 1.0, v10
	v_add_f32_e32 v9, 1.0, v11
	v_mul_f32_e32 v10, 0xbfb8aa3b, v6
	v_mul_f32_e32 v11, 0xbfb8aa3b, v7
	v_exp_f32_e32 v10, v10
	v_exp_f32_e32 v11, v11
	v_rcp_f32_e32 v8, v8
	v_rcp_f32_e32 v9, v9
	v_add_f32_e32 v10, 1.0, v10
	v_add_f32_e32 v11, 1.0, v11
	v_rcp_f32_e32 v10, v10
	v_rcp_f32_e32 v11, v11
	v_pk_mul_f32 v[2:3], v[6:7], v[2:3]
	v_pk_mul_f32 v[0:1], v[4:5], v[0:1]
	s_and_b64 vcc, exec, s[2:3]
	v_pk_mul_f32 v[0:1], v[0:1], v[8:9]
	v_pk_mul_f32 v[2:3], v[2:3], v[10:11]
	v_cvt_pk_bf16_f32 v0, v0, v1
	v_cvt_pk_bf16_f32 v1, v2, v3
	s_mov_b32 s74, s71
	s_mov_b32 s73, s72
	s_mov_b64 s[16:17], s[0:1]
	s_mov_b64 s[14:15], s[4:5]
	global_store_dwordx2 v[16:17], v[0:1], off offset:128
	s_cbranch_vccz .LBB0_56
	s_branch .Lgu1_done
; #define PG8_STAGE(bufoff, gbase, voff) do { _Pragma("unroll") for (int _i = 0; _i < 2; ++_i) \
;         __builtin_amdgcn_global_load_lds((const unsigned*)((const char*)(gbase) + (voff)[_i]), (PG8_LAS unsigned*)(lds + (bufoff) + ldsw + _i * 8192), 16, 0, 0); } while (0)
; #define PG8_LDA(dst, b, h) do { _Pragma("unroll") for (int m = 0; m < 4; ++m) _Pragma("unroll") for (int k = 0; k < 2; ++k) dst[m][k] = *(const PG8_LAS bf16x8*)(lds + PG8_SA(b, h) + aoff + m * 2048 + k * 1024); } while (0)
; #define PG8_LDB(dst, b, h) do { _Pragma("unroll") for (int n = 0; n < 2; ++n) _Pragma("unroll") for (int k = 0; k < 2; ++k) dst[n][k] = *(const PG8_LAS bf16x8*)(lds + PG8_SB(b, h) + boff + n * 2048 + k * 1024); } while (0)
; #define PG8_MMA(ai, bj, At, Bt) do { __builtin_amdgcn_s_setprio(1); _Pragma("unroll") for (int m = 0; m < 4; ++m) _Pragma("unroll") for (int n = 0; n < 2; ++n) _Pragma("unroll") for (int k = 0; k < 2; ++k) \
;         acc[ai][bj][m][n] = __builtin_amdgcn_mfma_f32_16x16x32_bf16(Bt[n][k], At[m][k], acc[ai][bj][m][n], 0, 0, 0); __builtin_amdgcn_s_setprio(0); } while (0)
; #define PG8_WAIT_V(n) asm volatile("s_waitcnt vmcnt(" #n ")" ::: "memory")
; #define PG8_WAIT_L(n) asm volatile("s_waitcnt lgkmcnt(" #n ")" ::: "memory")
; #define PG8_BAR __builtin_amdgcn_s_barrier()
; template <class Epi, class Sched, bool STAMP = false>
; __device__ __forceinline__ void gemm_phase(PG8_LAS unsigned char* lds, const Gemm g, const Sched& S, const Epi& E, unsigned long long* stamps) {
;     ...
;             PG8_LDB(B0, 0, 0); PG8_SCHED; PG8_LDA(At, 0, 0); PG8_STAGE(PG8_SA(1, 1), a1 + hstep, voffA);
;             PG8_WAIT_L(8); PG8_BAR; PG8_WAIT_L(0); PG8_MMA(0, 0, At, B0); PG8_BAR; PG8_SCHED;
;             PG8_LDB(B1, 0, 1); PG8_STAGE(PG8_SB(0, 0), b2, voffB);
;             PG8_BAR; PG8_WAIT_L(0); PG8_MMA(0, 1, At, B1); PG8_BAR;
;             PG8_LDA(At, 0, 1); PG8_STAGE(PG8_SA(0, 0), a2, voffA);
;             PG8_BAR; PG8_WAIT_L(0); PG8_MMA(1, 0, At, B0); PG8_BAR; PG8_SCHED;
;             PG8_STAGE(PG8_SB(0, 1), b2 + hstep, voffB);
;             PG8_WAIT_V(6); PG8_BAR; PG8_MMA(1, 1, At, B1); PG8_BAR;
;             PG8_LDB(B0, 1, 0); PG8_SCHED; PG8_LDA(At, 1, 0); PG8_STAGE(PG8_SA(0, 1), a2 + hstep, voffA);
;             PG8_WAIT_L(8); PG8_BAR; PG8_WAIT_L(0); PG8_MMA(0, 0, At, B0); PG8_BAR; PG8_SCHED;
;             PG8_LDB(B1, 1, 1); PG8_STAGE(PG8_SB(1, 0), b3, voffB);
.Lgu1_half_loop:
	ds_read_b128 v[140:143], v148
	ds_read_b128 v[166:169], v149
	ds_read_b128 v[170:173], v150
	ds_read_b128 v[174:177], v151
	s_add_u32 s16, s14, 0x100
	s_addc_u32 s17, s15, 0
	s_cmp_eq_u32 s77, 12
	s_cselect_b32 s29, s5, s17
	s_cselect_b32 s28, s4, s16
	s_cselect_b32 s19, s1, s76
	s_cselect_b32 s18, s0, s75
	s_mov_b32 m0, s68
	ds_read_b128 v[178:181], v146
	ds_read_b128 v[182:185], v146 offset:1024
	ds_read_b128 v[186:189], v146 offset:2048
	ds_read_b128 v[190:193], v146 offset:3072
	ds_read_b128 v[194:197], v146 offset:4096
	ds_read_b128 v[198:201], v146 offset:5120
	ds_read_b128 v[202:205], v146 offset:6144
	ds_read_b128 v[206:209], v146 offset:7168
	global_load_lds_dwordx4 v132, s[14:15]
	s_mov_b32 m0, s69
	s_nop 0
	global_load_lds_dwordx4 v134, s[14:15]
	s_waitcnt lgkmcnt(8)
	s_barrier
	s_waitcnt lgkmcnt(0)
	s_setprio 1
	s_waitcnt lgkmcnt(0)
	v_mfma_f32_16x16x32_bf16 v[124:127], v[140:143], v[178:181], v[124:127]
	v_mfma_f32_16x16x32_bf16 v[120:123], v[170:173], v[178:181], v[120:123]
	v_mfma_f32_16x16x32_bf16 v[108:111], v[140:143], v[186:189], v[108:111]
	v_mfma_f32_16x16x32_bf16 v[104:107], v[170:173], v[186:189], v[104:107]
	v_mfma_f32_16x16x32_bf16 v[92:95], v[140:143], v[194:197], v[92:95]
	v_mfma_f32_16x16x32_bf16 v[88:91], v[170:173], v[194:197], v[88:91]
	v_mfma_f32_16x16x32_bf16 v[76:79], v[140:143], v[202:205], v[76:79]
	v_mfma_f32_16x16x32_bf16 v[72:75], v[170:173], v[202:205], v[72:75]
	v_mfma_f32_16x16x32_bf16 v[124:127], v[166:169], v[182:185], v[124:127]
	v_mfma_f32_16x16x32_bf16 v[120:123], v[174:177], v[182:185], v[120:123]
	v_mfma_f32_16x16x32_bf16 v[108:111], v[166:169], v[190:193], v[108:111]
	v_mfma_f32_16x16x32_bf16 v[104:107], v[174:177], v[190:193], v[104:107]
	v_mfma_f32_16x16x32_bf16 v[92:95], v[166:169], v[198:201], v[92:95]
	v_mfma_f32_16x16x32_bf16 v[88:91], v[174:177], v[198:201], v[88:91]
	v_mfma_f32_16x16x32_bf16 v[76:79], v[166:169], v[206:209], v[76:79]
	v_mfma_f32_16x16x32_bf16 v[72:75], v[174:177], v[206:209], v[72:75]
	s_setprio 0
	s_barrier
	s_mov_b32 m0, s52
	s_nop 0
	global_load_lds_dwordx4 v130, s[18:19]
	s_mov_b32 m0, s53
	s_nop 0
	global_load_lds_dwordx4 v128, s[18:19]
	s_barrier
	s_waitcnt lgkmcnt(0)
	s_setprio 1
	s_waitcnt lgkmcnt(0)
	s_setprio 0
	s_mov_b32 m0, s33
	s_barrier
	ds_read_b128 v[178:181], v146 offset:16384
	ds_read_b128 v[182:185], v146 offset:17408
	ds_read_b128 v[186:189], v146 offset:18432
	ds_read_b128 v[190:193], v146 offset:19456
	ds_read_b128 v[194:197], v146 offset:20480
	ds_read_b128 v[198:201], v146 offset:21504
	ds_read_b128 v[202:205], v146 offset:22528
	ds_read_b128 v[206:209], v146 offset:23552
	global_load_lds_dwordx4 v130, s[28:29]
	s_mov_b32 m0, s54
	s_nop 0
	global_load_lds_dwordx4 v128, s[28:29]
	s_barrier
	s_waitcnt lgkmcnt(0)
	s_setprio 1
	s_waitcnt lgkmcnt(0)
	v_mfma_f32_16x16x32_bf16 v[60:63], v[140:143], v[178:181], v[60:63]
	v_mfma_f32_16x16x32_bf16 v[56:59], v[170:173], v[178:181], v[56:59]
	v_mfma_f32_16x16x32_bf16 v[44:47], v[140:143], v[186:189], v[44:47]
	v_mfma_f32_16x16x32_bf16 v[40:43], v[170:173], v[186:189], v[40:43]
	v_mfma_f32_16x16x32_bf16 v[28:31], v[140:143], v[194:197], v[28:31]
	v_mfma_f32_16x16x32_bf16 v[24:27], v[170:173], v[194:197], v[24:27]
	v_mfma_f32_16x16x32_bf16 v[12:15], v[140:143], v[202:205], v[12:15]
	v_mfma_f32_16x16x32_bf16 v[8:11], v[170:173], v[202:205], v[8:11]
	v_mfma_f32_16x16x32_bf16 v[60:63], v[166:169], v[182:185], v[60:63]
	v_mfma_f32_16x16x32_bf16 v[56:59], v[174:177], v[182:185], v[56:59]
	v_mfma_f32_16x16x32_bf16 v[44:47], v[166:169], v[190:193], v[44:47]
	v_mfma_f32_16x16x32_bf16 v[40:43], v[174:177], v[190:193], v[40:43]
	v_mfma_f32_16x16x32_bf16 v[28:31], v[166:169], v[198:201], v[28:31]
	v_mfma_f32_16x16x32_bf16 v[24:27], v[174:177], v[198:201], v[24:27]
	v_mfma_f32_16x16x32_bf16 v[12:15], v[166:169], v[206:209], v[12:15]
	v_mfma_f32_16x16x32_bf16 v[8:11], v[174:177], v[206:209], v[8:11]
	s_setprio 0
	s_barrier
	s_add_u32 s14, s18, 0x44000
	s_addc_u32 s15, s19, 0
	s_mov_b32 m0, s55
	s_nop 0
	global_load_lds_dwordx4 v130, s[14:15]
	s_mov_b32 m0, s56
	s_nop 0
	global_load_lds_dwordx4 v128, s[14:15]
	s_waitcnt vmcnt(6)
	s_barrier
	s_setprio 1
	s_setprio 0
	s_barrier
	ds_read_b128 v[140:143], v156
	ds_read_b128 v[166:169], v157
	ds_read_b128 v[170:173], v159
	ds_read_b128 v[174:177], v160
	s_add_u32 s14, s28, 0x44000
	s_addc_u32 s15, s29, 0
	s_mov_b32 m0, s57
	ds_read_b128 v[178:181], v146 offset:32768
	ds_read_b128 v[182:185], v146 offset:33792
	ds_read_b128 v[186:189], v146 offset:34816
	ds_read_b128 v[190:193], v146 offset:35840
	ds_read_b128 v[194:197], v146 offset:36864
	ds_read_b128 v[198:201], v146 offset:37888
	ds_read_b128 v[202:205], v146 offset:38912
	ds_read_b128 v[206:209], v146 offset:39936
	global_load_lds_dwordx4 v130, s[14:15]
	s_mov_b32 m0, s58
	s_nop 0
	global_load_lds_dwordx4 v128, s[14:15]
	s_waitcnt lgkmcnt(8)
	s_barrier
	s_waitcnt lgkmcnt(0)
	s_setprio 1
	s_waitcnt lgkmcnt(0)
	v_mfma_f32_16x16x32_bf16 v[124:127], v[140:143], v[178:181], v[124:127]
	v_mfma_f32_16x16x32_bf16 v[120:123], v[170:173], v[178:181], v[120:123]
	v_mfma_f32_16x16x32_bf16 v[108:111], v[140:143], v[186:189], v[108:111]
	v_mfma_f32_16x16x32_bf16 v[104:107], v[170:173], v[186:189], v[104:107]
	v_mfma_f32_16x16x32_bf16 v[92:95], v[140:143], v[194:197], v[92:95]
	v_mfma_f32_16x16x32_bf16 v[88:91], v[170:173], v[194:197], v[88:91]
	v_mfma_f32_16x16x32_bf16 v[76:79], v[140:143], v[202:205], v[76:79]
	v_mfma_f32_16x16x32_bf16 v[72:75], v[170:173], v[202:205], v[72:75]
	v_mfma_f32_16x16x32_bf16 v[124:127], v[166:169], v[182:185], v[124:127]
	v_mfma_f32_16x16x32_bf16 v[120:123], v[174:177], v[182:185], v[120:123]
	v_mfma_f32_16x16x32_bf16 v[108:111], v[166:169], v[190:193], v[108:111]
	v_mfma_f32_16x16x32_bf16 v[104:107], v[174:177], v[190:193], v[104:107]
	v_mfma_f32_16x16x32_bf16 v[92:95], v[166:169], v[198:201], v[92:95]
	v_mfma_f32_16x16x32_bf16 v[88:91], v[174:177], v[198:201], v[88:91]
	v_mfma_f32_16x16x32_bf16 v[76:79], v[166:169], v[206:209], v[76:79]
	v_mfma_f32_16x16x32_bf16 v[72:75], v[174:177], v[206:209], v[72:75]
	s_setprio 0
	s_barrier
; DI float ex2(float x) { return __builtin_amdgcn_exp2f(x); }
; #define PG8_STAGE(bufoff, gbase, voff) do { _Pragma("unroll") for (int _i = 0; _i < 2; ++_i) \
;         __builtin_amdgcn_global_load_lds((const unsigned*)((const char*)(gbase) + (voff)[_i]), (PG8_LAS unsigned*)(lds + (bufoff) + ldsw + _i * 8192), 16, 0, 0); } while (0)
; #define PG8_LDA(dst, b, h) do { _Pragma("unroll") for (int m = 0; m < 4; ++m) _Pragma("unroll") for (int k = 0; k < 2; ++k) dst[m][k] = *(const PG8_LAS bf16x8*)(lds + PG8_SA(b, h) + aoff + m * 2048 + k * 1024); } while (0)
; #define PG8_LDB(dst, b, h) do { _Pragma("unroll") for (int n = 0; n < 2; ++n) _Pragma("unroll") for (int k = 0; k < 2; ++k) dst[n][k] = *(const PG8_LAS bf16x8*)(lds + PG8_SB(b, h) + boff + n * 2048 + k * 1024); } while (0)
; #define PG8_WAIT_V(n) asm volatile("s_waitcnt vmcnt(" #n ")" ::: "memory")
; #define PG8_WAIT_L(n) asm volatile("s_waitcnt lgkmcnt(" #n ")" ::: "memory")
;     DI void operator()(const f32x4 (&acc)[2][2][4][2], const Unit& u, int wr, int wc, int fr, int fq) const {
;         const int row0 = u.pm * BM + wr * 64 + fr, hcol0 = ((u.pn * BM + wc * 32) >> 1) + 4 * fq;
; #pragma unroll
;         for (int ai = 0; ai < 2; ++ai)
; #pragma unroll
;             for (int m = 0; m < 4; ++m) { u16* rowp = O + (size_t)(row0 + ai * HALF + m * 16) * ldc + hcol0;
; #pragma unroll
;                 for (int bj = 0; bj < 2; ++bj) { const f32x4 g = acc[ai][bj][m][0], up = acc[ai][bj][m][1]; float r[4];
; #pragma unroll
;                     for (int j = 0; j < 4; ++j) r[j] = g[j] * up[j] * __builtin_amdgcn_rcpf(1.f + ex2(-LOG2E * g[j]));
;                     uint2 w = {pack2(r[0], r[1]), pack2(r[2], r[3])}; *(uint2*)(rowp + bj * (HALF / 2)) = w; } }
; template <class Epi, class Sched, bool STAMP = false>
; __device__ __forceinline__ void gemm_phase(PG8_LAS unsigned char* lds, const Gemm g, const Sched& S, const Epi& E, unsigned long long* stamps) {
;     ...
;             PG8_LDB(B1, 1, 1); PG8_STAGE(PG8_SB(1, 0), b3, voffB);
;             PG8_BAR; PG8_WAIT_L(0); PG8_MMA(0, 1, At, B1); PG8_BAR;
;             PG8_LDA(At, 1, 1); PG8_STAGE(PG8_SA(1, 0), a3, voffA);
;             PG8_BAR; PG8_WAIT_L(0); PG8_MMA(1, 0, At, B0); PG8_BAR; PG8_SCHED;
;             PG8_STAGE(PG8_SB(1, 1), b3 + hstep, voffB);
;             PG8_WAIT_V(6); PG8_BAR; PG8_MMA(1, 1, At, B1); PG8_BAR;
;         }
	s_mov_b32 m0, s61
	s_add_u32 s100, s18, 0x80
	s_addc_u32 s101, s19, 0
	global_load_lds_dwordx4 v130, s[100:101]
	s_mov_b32 m0, s62
	s_nop 0
	global_load_lds_dwordx4 v128, s[100:101]
	s_barrier
	s_waitcnt lgkmcnt(0)
	s_setprio 1
	s_waitcnt lgkmcnt(0)
	s_setprio 0
	s_mov_b32 m0, s63
	s_barrier
	ds_read_b128 v[178:181], v146 offset:49152
	ds_read_b128 v[182:185], v146 offset:50176
	ds_read_b128 v[186:189], v146 offset:51200
	ds_read_b128 v[190:193], v146 offset:52224
	ds_read_b128 v[194:197], v146 offset:53248
	ds_read_b128 v[198:201], v146 offset:54272
	ds_read_b128 v[202:205], v146 offset:55296
	ds_read_b128 v[206:209], v146 offset:56320
	s_add_u32 s100, s28, 0x80
	s_addc_u32 s101, s29, 0
	global_load_lds_dwordx4 v130, s[100:101]
	s_mov_b32 m0, s64
	s_nop 0
	global_load_lds_dwordx4 v128, s[100:101]
	s_barrier
	s_waitcnt lgkmcnt(0)
	s_setprio 1
	s_waitcnt lgkmcnt(0)
	v_mfma_f32_16x16x32_bf16 v[60:63], v[140:143], v[178:181], v[60:63]
	v_mfma_f32_16x16x32_bf16 v[56:59], v[170:173], v[178:181], v[56:59]
	v_mfma_f32_16x16x32_bf16 v[44:47], v[140:143], v[186:189], v[44:47]
	v_mfma_f32_16x16x32_bf16 v[40:43], v[170:173], v[186:189], v[40:43]
	v_mfma_f32_16x16x32_bf16 v[28:31], v[140:143], v[194:197], v[28:31]
	v_mfma_f32_16x16x32_bf16 v[24:27], v[170:173], v[194:197], v[24:27]
	v_mfma_f32_16x16x32_bf16 v[12:15], v[140:143], v[202:205], v[12:15]
	v_mfma_f32_16x16x32_bf16 v[8:11], v[170:173], v[202:205], v[8:11]
	v_mfma_f32_16x16x32_bf16 v[60:63], v[166:169], v[182:185], v[60:63]
	v_mfma_f32_16x16x32_bf16 v[56:59], v[174:177], v[182:185], v[56:59]
	v_mfma_f32_16x16x32_bf16 v[44:47], v[166:169], v[190:193], v[44:47]
	v_mfma_f32_16x16x32_bf16 v[40:43], v[174:177], v[190:193], v[40:43]
	v_mfma_f32_16x16x32_bf16 v[28:31], v[166:169], v[198:201], v[28:31]
	v_mfma_f32_16x16x32_bf16 v[24:27], v[174:177], v[198:201], v[24:27]
	v_mfma_f32_16x16x32_bf16 v[12:15], v[166:169], v[206:209], v[12:15]
	v_mfma_f32_16x16x32_bf16 v[8:11], v[174:177], v[206:209], v[8:11]
	s_setprio 0
	s_barrier
	s_add_u32 s14, s18, 0x44080
	s_addc_u32 s15, s19, 0
	s_mov_b32 m0, s65
	s_nop 0
	global_load_lds_dwordx4 v130, s[14:15]
	s_mov_b32 m0, s66
	s_nop 0
	global_load_lds_dwordx4 v128, s[14:15]
	s_waitcnt vmcnt(6)
	s_barrier
	s_setprio 1
	s_setprio 0
	s_add_i32 s77, s77, 2
	s_add_u32 s75, s75, 0x100
	s_addc_u32 s76, s76, 0
	s_cmp_gt_u32 s77, 13
	s_mov_b64 s[14:15], s[16:17]
	s_barrier
	s_cbranch_scc0 .Lgu1_half_loop
	v_mul_f32_e32 v168, 0xbfb8aa3b, v124
	v_mul_f32_e32 v169, 0xbfb8aa3b, v125
	v_mul_f32_e32 v170, 0xbfb8aa3b, v126
	v_mul_f32_e32 v171, 0xbfb8aa3b, v127
	v_exp_f32_e32 v168, v168
	v_exp_f32_e32 v169, v169
	v_exp_f32_e32 v170, v170
	v_exp_f32_e32 v171, v171
	v_add_f32_e32 v168, 1.0, v168
	v_add_f32_e32 v169, 1.0, v169
	v_add_f32_e32 v170, 1.0, v170
	v_add_f32_e32 v171, 1.0, v171
	v_rcp_f32_e32 v168, v168
	v_rcp_f32_e32 v169, v169
	v_rcp_f32_e32 v170, v170
	v_rcp_f32_e32 v171, v171
	s_lshl_b32 s10, s74, 8
	v_pk_mul_f32 v[122:123], v[126:127], v[122:123]
	v_pk_mul_f32 v[120:121], v[124:125], v[120:121]
	s_or_b32 s10, s10, s60
	s_or_b32 s10, s10, s98
	v_pk_mul_f32 v[120:121], v[120:121], v[168:169]
	v_pk_mul_f32 v[122:123], v[122:123], v[170:171]
	s_ashr_i32 s10, s10, 1
	v_cvt_pk_bf16_f32 v120, v120, v121
	v_cvt_pk_bf16_f32 v121, v122, v123
	v_or_b32_e32 v140, s10, v147
	v_lshl_add_u32 v165, s73, 8, v145
	v_ashrrev_i32_e32 v141, 31, v140
	v_mov_b64_e32 v[142:143], s[12:13]
	v_mad_i64_i32 v[166:167], s[14:15], v165, s70, v[142:143]
	v_lshlrev_b64 v[140:141], 1, v[140:141]
	v_lshl_add_u64 v[166:167], v[166:167], 0, v[140:141]
	global_store_dwordx2 v[166:167], v[120:121], off
	v_mul_f32_e32 v116, 0xbfb8aa3b, v110
	v_mul_f32_e32 v114, 0xbfb8aa3b, v108
	v_mul_f32_e32 v115, 0xbfb8aa3b, v109
	v_mul_f32_e32 v117, 0xbfb8aa3b, v111
	v_exp_f32_e32 v114, v114
	v_exp_f32_e32 v115, v115
	v_exp_f32_e32 v116, v116
	v_exp_f32_e32 v117, v117
	v_add_f32_e32 v114, 1.0, v114
	v_add_f32_e32 v115, 1.0, v115
	v_add_f32_e32 v116, 1.0, v116
	v_add_f32_e32 v117, 1.0, v117
	v_rcp_f32_e32 v114, v114
	v_rcp_f32_e32 v115, v115
	v_rcp_f32_e32 v116, v116
	v_rcp_f32_e32 v117, v117
	v_pk_mul_f32 v[106:107], v[110:111], v[106:107]
	v_pk_mul_f32 v[104:105], v[108:109], v[104:105]
	v_pk_mul_f32 v[104:105], v[104:105], v[114:115]
	v_pk_mul_f32 v[106:107], v[106:107], v[116:117]
	v_cvt_pk_bf16_f32 v104, v104, v105
	v_cvt_pk_bf16_f32 v105, v106, v107
	v_or_b32_e32 v112, 16, v165
	v_mad_i64_i32 v[112:113], s[14:15], v112, s70, v[142:143]
	v_lshl_add_u64 v[112:113], v[112:113], 0, v[140:141]
	global_store_dwordx2 v[112:113], v[104:105], off
	v_mul_f32_e32 v100, 0xbfb8aa3b, v94
	v_mul_f32_e32 v98, 0xbfb8aa3b, v92
	v_mul_f32_e32 v99, 0xbfb8aa3b, v93
	v_mul_f32_e32 v101, 0xbfb8aa3b, v95
	v_exp_f32_e32 v98, v98
	v_exp_f32_e32 v99, v99
	v_exp_f32_e32 v100, v100
	v_exp_f32_e32 v101, v101
	v_add_f32_e32 v98, 1.0, v98
	v_add_f32_e32 v99, 1.0, v99
	v_add_f32_e32 v100, 1.0, v100
	v_add_f32_e32 v101, 1.0, v101
	v_rcp_f32_e32 v98, v98
	v_rcp_f32_e32 v99, v99
; DI float ex2(float x) { return __builtin_amdgcn_exp2f(x); }
;     DI void operator()(const f32x4 (&acc)[2][2][4][2], const Unit& u, int wr, int wc, int fr, int fq) const {
;         const int row0 = u.pm * BM + wr * 64 + fr, hcol0 = ((u.pn * BM + wc * 32) >> 1) + 4 * fq;
; #pragma unroll
;         for (int ai = 0; ai < 2; ++ai)
; #pragma unroll
;             for (int m = 0; m < 4; ++m) { u16* rowp = O + (size_t)(row0 + ai * HALF + m * 16) * ldc + hcol0;
; #pragma unroll
;                 for (int bj = 0; bj < 2; ++bj) { const f32x4 g = acc[ai][bj][m][0], up = acc[ai][bj][m][1]; float r[4];
; #pragma unroll
;                     for (int j = 0; j < 4; ++j) r[j] = g[j] * up[j] * __builtin_amdgcn_rcpf(1.f + ex2(-LOG2E * g[j]));
;                     uint2 w = {pack2(r[0], r[1]), pack2(r[2], r[3])}; *(uint2*)(rowp + bj * (HALF / 2)) = w; } }
	v_rcp_f32_e32 v100, v100
	v_rcp_f32_e32 v101, v101
	v_pk_mul_f32 v[90:91], v[94:95], v[90:91]
	v_pk_mul_f32 v[88:89], v[92:93], v[88:89]
	v_pk_mul_f32 v[88:89], v[88:89], v[98:99]
	v_pk_mul_f32 v[90:91], v[90:91], v[100:101]
	v_cvt_pk_bf16_f32 v88, v88, v89
	v_cvt_pk_bf16_f32 v89, v90, v91
	v_or_b32_e32 v96, 32, v165
	v_mad_i64_i32 v[96:97], s[14:15], v96, s70, v[142:143]
	v_lshl_add_u64 v[96:97], v[96:97], 0, v[140:141]
	global_store_dwordx2 v[96:97], v[88:89], off
	v_mul_f32_e32 v84, 0xbfb8aa3b, v78
	v_mul_f32_e32 v82, 0xbfb8aa3b, v76
	v_mul_f32_e32 v83, 0xbfb8aa3b, v77
	v_mul_f32_e32 v85, 0xbfb8aa3b, v79
	v_exp_f32_e32 v82, v82
	v_exp_f32_e32 v83, v83
	v_exp_f32_e32 v84, v84
	v_exp_f32_e32 v85, v85
	v_add_f32_e32 v82, 1.0, v82
	v_add_f32_e32 v83, 1.0, v83
	v_add_f32_e32 v84, 1.0, v84
	v_add_f32_e32 v85, 1.0, v85
	v_rcp_f32_e32 v82, v82
	v_rcp_f32_e32 v83, v83
	v_rcp_f32_e32 v84, v84
	v_rcp_f32_e32 v85, v85
	v_pk_mul_f32 v[74:75], v[78:79], v[74:75]
	v_pk_mul_f32 v[72:73], v[76:77], v[72:73]
	v_pk_mul_f32 v[72:73], v[72:73], v[82:83]
	v_pk_mul_f32 v[74:75], v[74:75], v[84:85]
	v_cvt_pk_bf16_f32 v72, v72, v73
	v_cvt_pk_bf16_f32 v73, v74, v75
	v_or_b32_e32 v80, 48, v165
	v_mad_i64_i32 v[80:81], s[14:15], v80, s70, v[142:143]
	v_lshl_add_u64 v[80:81], v[80:81], 0, v[140:141]
	global_store_dwordx2 v[80:81], v[72:73], off
	v_mul_f32_e32 v68, 0xbfb8aa3b, v62
	v_mul_f32_e32 v66, 0xbfb8aa3b, v60
	v_mul_f32_e32 v67, 0xbfb8aa3b, v61
	v_mul_f32_e32 v69, 0xbfb8aa3b, v63
	v_exp_f32_e32 v66, v66
	v_exp_f32_e32 v67, v67
	v_exp_f32_e32 v68, v68
	v_exp_f32_e32 v69, v69
	v_add_f32_e32 v66, 1.0, v66
	v_add_f32_e32 v67, 1.0, v67
	v_add_f32_e32 v68, 1.0, v68
	v_add_f32_e32 v69, 1.0, v69
	v_rcp_f32_e32 v66, v66
	v_rcp_f32_e32 v67, v67
	v_rcp_f32_e32 v68, v68
	v_rcp_f32_e32 v69, v69
	v_pk_mul_f32 v[58:59], v[62:63], v[58:59]
	v_pk_mul_f32 v[56:57], v[60:61], v[56:57]
	v_pk_mul_f32 v[56:57], v[56:57], v[66:67]
	v_pk_mul_f32 v[58:59], v[58:59], v[68:69]
	v_cvt_pk_bf16_f32 v56, v56, v57
	v_cvt_pk_bf16_f32 v57, v58, v59
	v_add_u32_e32 v64, 0x80, v165
	v_mad_i64_i32 v[64:65], s[14:15], v64, s70, v[142:143]
	v_lshl_add_u64 v[64:65], v[64:65], 0, v[140:141]
	global_store_dwordx2 v[64:65], v[56:57], off
	v_mul_f32_e32 v52, 0xbfb8aa3b, v46
	v_mul_f32_e32 v50, 0xbfb8aa3b, v44
	v_mul_f32_e32 v51, 0xbfb8aa3b, v45
	v_mul_f32_e32 v53, 0xbfb8aa3b, v47
	v_exp_f32_e32 v50, v50
	v_exp_f32_e32 v51, v51
	v_exp_f32_e32 v52, v52
	v_exp_f32_e32 v53, v53
	v_add_f32_e32 v50, 1.0, v50
	v_add_f32_e32 v51, 1.0, v51
	v_add_f32_e32 v52, 1.0, v52
	v_add_f32_e32 v53, 1.0, v53
	v_rcp_f32_e32 v50, v50
	v_rcp_f32_e32 v51, v51
	v_rcp_f32_e32 v52, v52
	v_rcp_f32_e32 v53, v53
	v_pk_mul_f32 v[42:43], v[46:47], v[42:43]
	v_pk_mul_f32 v[40:41], v[44:45], v[40:41]
	v_pk_mul_f32 v[40:41], v[40:41], v[50:51]
	v_pk_mul_f32 v[42:43], v[42:43], v[52:53]
	v_cvt_pk_bf16_f32 v40, v40, v41
	v_cvt_pk_bf16_f32 v41, v42, v43
	v_add_u32_e32 v48, 0x90, v165
	v_mad_i64_i32 v[48:49], s[14:15], v48, s70, v[142:143]
	v_lshl_add_u64 v[48:49], v[48:49], 0, v[140:141]
	global_store_dwordx2 v[48:49], v[40:41], off
	v_mul_f32_e32 v36, 0xbfb8aa3b, v30
	v_mul_f32_e32 v34, 0xbfb8aa3b, v28
	v_mul_f32_e32 v35, 0xbfb8aa3b, v29
	v_mul_f32_e32 v37, 0xbfb8aa3b, v31
	v_exp_f32_e32 v34, v34
	v_exp_f32_e32 v35, v35
	v_exp_f32_e32 v36, v36
	v_exp_f32_e32 v37, v37
	v_add_f32_e32 v34, 1.0, v34
	v_add_f32_e32 v35, 1.0, v35
	v_add_f32_e32 v36, 1.0, v36
	v_add_f32_e32 v37, 1.0, v37
	v_rcp_f32_e32 v34, v34
	v_rcp_f32_e32 v35, v35
	v_rcp_f32_e32 v36, v36
	v_rcp_f32_e32 v37, v37
	v_pk_mul_f32 v[26:27], v[30:31], v[26:27]
	v_pk_mul_f32 v[24:25], v[28:29], v[24:25]
	v_pk_mul_f32 v[24:25], v[24:25], v[34:35]
	v_pk_mul_f32 v[26:27], v[26:27], v[36:37]
	v_cvt_pk_bf16_f32 v24, v24, v25
	v_cvt_pk_bf16_f32 v25, v26, v27
	v_add_u32_e32 v32, 0xa0, v165
	v_mad_i64_i32 v[32:33], s[14:15], v32, s70, v[142:143]
	v_lshl_add_u64 v[32:33], v[32:33], 0, v[140:141]
	global_store_dwordx2 v[32:33], v[24:25], off
	v_mul_f32_e32 v20, 0xbfb8aa3b, v14
	v_mul_f32_e32 v18, 0xbfb8aa3b, v12
	v_mul_f32_e32 v19, 0xbfb8aa3b, v13
	v_mul_f32_e32 v21, 0xbfb8aa3b, v15
	v_exp_f32_e32 v18, v18
	v_exp_f32_e32 v19, v19
	v_exp_f32_e32 v20, v20
	v_exp_f32_e32 v21, v21
	v_add_f32_e32 v18, 1.0, v18
	v_add_f32_e32 v19, 1.0, v19
	v_add_f32_e32 v20, 1.0, v20
	v_add_f32_e32 v21, 1.0, v21
	v_rcp_f32_e32 v18, v18
	v_rcp_f32_e32 v19, v19
	v_rcp_f32_e32 v20, v20
	v_rcp_f32_e32 v21, v21
	v_pk_mul_f32 v[10:11], v[14:15], v[10:11]
	v_pk_mul_f32 v[8:9], v[12:13], v[8:9]
	v_pk_mul_f32 v[8:9], v[8:9], v[18:19]
	v_pk_mul_f32 v[10:11], v[10:11], v[20:21]
	v_cvt_pk_bf16_f32 v8, v8, v9
	v_cvt_pk_bf16_f32 v9, v10, v11
	v_add_u32_e32 v16, 0xb0, v165
	v_mad_i64_i32 v[16:17], s[14:15], v16, s70, v[142:143]
	v_lshl_add_u64 v[16:17], v[16:17], 0, v[140:141]
	global_store_dwordx2 v[16:17], v[8:9], off
	s_and_b64 vcc, exec, s[2:3]
	s_mov_b32 s74, s71
	s_mov_b32 s73, s72
	s_mov_b64 s[16:17], s[0:1]
	s_mov_b64 s[14:15], s[4:5]

; #define PG8_STAGE(bufoff, gbase, voff) do { _Pragma("unroll") for (int _i = 0; _i < 2; ++_i) \
;         __builtin_amdgcn_global_load_lds((const unsigned*)((const char*)(gbase) + (voff)[_i]), (PG8_LAS unsigned*)(lds + (bufoff) + ldsw + _i * 8192), 16, 0, 0); } while (0)
; #define PG8_LDA(dst, b, h) do { _Pragma("unroll") for (int m = 0; m < 4; ++m) _Pragma("unroll") for (int k = 0; k < 2; ++k) dst[m][k] = *(const PG8_LAS bf16x8*)(lds + PG8_SA(b, h) + aoff + m * 2048 + k * 1024); } while (0)
; #define PG8_LDB(dst, b, h) do { _Pragma("unroll") for (int n = 0; n < 2; ++n) _Pragma("unroll") for (int k = 0; k < 2; ++k) dst[n][k] = *(const PG8_LAS bf16x8*)(lds + PG8_SB(b, h) + boff + n * 2048 + k * 1024); } while (0)
; #define PG8_MMA(ai, bj, At, Bt) do { __builtin_amdgcn_s_setprio(1); _Pragma("unroll") for (int m = 0; m < 4; ++m) _Pragma("unroll") for (int n = 0; n < 2; ++n) _Pragma("unroll") for (int k = 0; k < 2; ++k) \
;         acc[ai][bj][m][n] = __builtin_amdgcn_mfma_f32_16x16x32_bf16(Bt[n][k], At[m][k], acc[ai][bj][m][n], 0, 0, 0); __builtin_amdgcn_s_setprio(0); } while (0)
; #define PG8_WAIT_V(n) asm volatile("s_waitcnt vmcnt(" #n ")" ::: "memory")
; #define PG8_WAIT_L(n) asm volatile("s_waitcnt lgkmcnt(" #n ")" ::: "memory")
; #define PG8_BAR __builtin_amdgcn_s_barrier()
; #define PG8_SCHED __builtin_amdgcn_sched_barrier(0)
; template <class Epi, class Sched, bool STAMP = false>
; __device__ __forceinline__ void gemm_phase(PG8_LAS unsigned char* lds, const Gemm g, const Sched& S, const Epi& E, unsigned long long* stamps) {
;     ...
;             PG8_LDB(B0, 0, 0); PG8_SCHED; PG8_LDA(At, 0, 0); PG8_STAGE(PG8_SA(1, 1), a1 + hstep, voffA);
;             PG8_WAIT_L(8); PG8_BAR; PG8_WAIT_L(0); PG8_MMA(0, 0, At, B0); PG8_BAR; PG8_SCHED;
;             PG8_LDB(B1, 0, 1); PG8_STAGE(PG8_SB(0, 0), b2, voffB);
;             PG8_BAR; PG8_WAIT_L(0); PG8_MMA(0, 1, At, B1); PG8_BAR;
;             PG8_LDA(At, 0, 1); PG8_STAGE(PG8_SA(0, 0), a2, voffA);
;             PG8_BAR; PG8_WAIT_L(0); PG8_MMA(1, 0, At, B0); PG8_BAR; PG8_SCHED;
;             PG8_STAGE(PG8_SB(0, 1), b2 + hstep, voffB);
;             PG8_WAIT_V(6); PG8_BAR; PG8_MMA(1, 1, At, B1); PG8_BAR;
.LBB0_97:
	ds_read_b128 v[166:169], v148
	ds_read_b128 v[170:173], v149
	ds_read_b128 v[174:177], v150
	ds_read_b128 v[178:181], v151
	s_add_u32 s52, s34, 0x100
	s_addc_u32 s53, s35, 0
	s_cmp_eq_u32 s90, 40
	s_cselect_b32 s57, s5, s53
	s_cselect_b32 s56, s4, s52
	s_cselect_b32 s55, s1, s89
	s_cselect_b32 s54, s0, s88
	s_mov_b32 m0, s76
	ds_read_b128 v[182:185], v146
	ds_read_b128 v[186:189], v146 offset:1024
	ds_read_b128 v[190:193], v146 offset:2048
	ds_read_b128 v[194:197], v146 offset:3072
	ds_read_b128 v[198:201], v146 offset:4096
	ds_read_b128 v[202:205], v146 offset:5120
	ds_read_b128 v[206:209], v146 offset:6144
	ds_read_b128 v[210:213], v146 offset:7168
	global_load_lds_dwordx4 v136, s[34:35]
	s_mov_b32 m0, s77
	s_nop 0
	global_load_lds_dwordx4 v138, s[34:35]
	s_waitcnt lgkmcnt(8)
	s_barrier
	s_waitcnt lgkmcnt(0)
	s_setprio 1
	s_waitcnt lgkmcnt(0)
	v_mfma_f32_16x16x32_bf16 v[124:127], v[166:169], v[182:185], v[124:127]
	v_mfma_f32_16x16x32_bf16 v[120:123], v[174:177], v[182:185], v[120:123]
	v_mfma_f32_16x16x32_bf16 v[116:119], v[166:169], v[190:193], v[116:119]
	v_mfma_f32_16x16x32_bf16 v[112:115], v[174:177], v[190:193], v[112:115]
	v_mfma_f32_16x16x32_bf16 v[100:103], v[166:169], v[198:201], v[100:103]
	v_mfma_f32_16x16x32_bf16 v[96:99], v[174:177], v[198:201], v[96:99]
	v_mfma_f32_16x16x32_bf16 v[84:87], v[166:169], v[206:209], v[84:87]
	v_mfma_f32_16x16x32_bf16 v[80:83], v[174:177], v[206:209], v[80:83]
	v_mfma_f32_16x16x32_bf16 v[124:127], v[170:173], v[186:189], v[124:127]
	v_mfma_f32_16x16x32_bf16 v[120:123], v[178:181], v[186:189], v[120:123]
	v_mfma_f32_16x16x32_bf16 v[116:119], v[170:173], v[194:197], v[116:119]
	v_mfma_f32_16x16x32_bf16 v[112:115], v[178:181], v[194:197], v[112:115]
	v_mfma_f32_16x16x32_bf16 v[100:103], v[170:173], v[202:205], v[100:103]
	v_mfma_f32_16x16x32_bf16 v[96:99], v[178:181], v[202:205], v[96:99]
	v_mfma_f32_16x16x32_bf16 v[84:87], v[170:173], v[210:213], v[84:87]
	v_mfma_f32_16x16x32_bf16 v[80:83], v[178:181], v[210:213], v[80:83]
	s_setprio 0
	s_barrier
	s_mov_b32 m0, s61
	ds_read_b128 v[214:217], v152
	ds_read_b128 v[218:221], v153
	ds_read_b128 v[222:225], v154
	ds_read_b128 v[226:229], v155
	global_load_lds_dwordx4 v130, s[54:55]
	s_mov_b32 m0, s62
	s_nop 0
	global_load_lds_dwordx4 v134, s[54:55]
	s_barrier
	s_waitcnt lgkmcnt(0)
	s_setprio 1
	s_waitcnt lgkmcnt(0)
	v_mfma_f32_16x16x32_bf16 v[108:111], v[214:217], v[182:185], v[108:111]
	v_mfma_f32_16x16x32_bf16 v[104:107], v[222:225], v[182:185], v[104:107]
	v_mfma_f32_16x16x32_bf16 v[92:95], v[214:217], v[190:193], v[92:95]
	v_mfma_f32_16x16x32_bf16 v[88:91], v[222:225], v[190:193], v[88:91]
	v_mfma_f32_16x16x32_bf16 v[76:79], v[214:217], v[198:201], v[76:79]
	v_mfma_f32_16x16x32_bf16 v[72:75], v[222:225], v[198:201], v[72:75]
	v_mfma_f32_16x16x32_bf16 v[68:71], v[214:217], v[206:209], v[68:71]
	v_mfma_f32_16x16x32_bf16 v[64:67], v[222:225], v[206:209], v[64:67]
	v_mfma_f32_16x16x32_bf16 v[108:111], v[218:221], v[186:189], v[108:111]
	v_mfma_f32_16x16x32_bf16 v[104:107], v[226:229], v[186:189], v[104:107]
	v_mfma_f32_16x16x32_bf16 v[92:95], v[218:221], v[194:197], v[92:95]
	v_mfma_f32_16x16x32_bf16 v[88:91], v[226:229], v[194:197], v[88:91]
	v_mfma_f32_16x16x32_bf16 v[76:79], v[218:221], v[202:205], v[76:79]
	v_mfma_f32_16x16x32_bf16 v[72:75], v[226:229], v[202:205], v[72:75]
	v_mfma_f32_16x16x32_bf16 v[68:71], v[218:221], v[210:213], v[68:71]
	v_mfma_f32_16x16x32_bf16 v[64:67], v[226:229], v[210:213], v[64:67]
	s_setprio 0
	s_mov_b32 m0, s60
	s_barrier
	ds_read_b128 v[182:185], v146 offset:16384
	ds_read_b128 v[186:189], v146 offset:17408
	ds_read_b128 v[190:193], v146 offset:18432
	ds_read_b128 v[194:197], v146 offset:19456
	ds_read_b128 v[198:201], v146 offset:20480
	ds_read_b128 v[202:205], v146 offset:21504
	ds_read_b128 v[206:209], v146 offset:22528
	ds_read_b128 v[210:213], v146 offset:23552
	global_load_lds_dwordx4 v128, s[56:57]
	s_mov_b32 m0, s63
	s_nop 0
	global_load_lds_dwordx4 v132, s[56:57]
	s_barrier
	s_waitcnt lgkmcnt(0)
	s_setprio 1
	s_waitcnt lgkmcnt(0)
	v_mfma_f32_16x16x32_bf16 v[60:63], v[166:169], v[182:185], v[60:63]
	v_mfma_f32_16x16x32_bf16 v[56:59], v[174:177], v[182:185], v[56:59]
	v_mfma_f32_16x16x32_bf16 v[52:55], v[166:169], v[190:193], v[52:55]
	v_mfma_f32_16x16x32_bf16 v[48:51], v[174:177], v[190:193], v[48:51]
	v_mfma_f32_16x16x32_bf16 v[36:39], v[166:169], v[198:201], v[36:39]
	v_mfma_f32_16x16x32_bf16 v[32:35], v[174:177], v[198:201], v[32:35]
	v_mfma_f32_16x16x32_bf16 v[20:23], v[166:169], v[206:209], v[20:23]
	v_mfma_f32_16x16x32_bf16 v[16:19], v[174:177], v[206:209], v[16:19]
	v_mfma_f32_16x16x32_bf16 v[60:63], v[170:173], v[186:189], v[60:63]
	v_mfma_f32_16x16x32_bf16 v[56:59], v[178:181], v[186:189], v[56:59]
	v_mfma_f32_16x16x32_bf16 v[52:55], v[170:173], v[194:197], v[52:55]
	v_mfma_f32_16x16x32_bf16 v[48:51], v[178:181], v[194:197], v[48:51]
	v_mfma_f32_16x16x32_bf16 v[36:39], v[170:173], v[202:205], v[36:39]
	v_mfma_f32_16x16x32_bf16 v[32:35], v[178:181], v[202:205], v[32:35]
	v_mfma_f32_16x16x32_bf16 v[20:23], v[170:173], v[210:213], v[20:23]
	v_mfma_f32_16x16x32_bf16 v[16:19], v[178:181], v[210:213], v[16:19]
	s_setprio 0
	s_barrier
	s_add_u32 s34, s54, 0xb4000
	s_addc_u32 s35, s55, 0
	s_mov_b32 m0, s64
	s_nop 0
	global_load_lds_dwordx4 v130, s[34:35]
	s_mov_b32 m0, s65
	s_nop 0
	global_load_lds_dwordx4 v134, s[34:35]
	s_waitcnt vmcnt(6)
	s_barrier
; #define PG8_STAGE(bufoff, gbase, voff) do { _Pragma("unroll") for (int _i = 0; _i < 2; ++_i) \
;         __builtin_amdgcn_global_load_lds((const unsigned*)((const char*)(gbase) + (voff)[_i]), (PG8_LAS unsigned*)(lds + (bufoff) + ldsw + _i * 8192), 16, 0, 0); } while (0)
; #define PG8_LDA(dst, b, h) do { _Pragma("unroll") for (int m = 0; m < 4; ++m) _Pragma("unroll") for (int k = 0; k < 2; ++k) dst[m][k] = *(const PG8_LAS bf16x8*)(lds + PG8_SA(b, h) + aoff + m * 2048 + k * 1024); } while (0)
; #define PG8_LDB(dst, b, h) do { _Pragma("unroll") for (int n = 0; n < 2; ++n) _Pragma("unroll") for (int k = 0; k < 2; ++k) dst[n][k] = *(const PG8_LAS bf16x8*)(lds + PG8_SB(b, h) + boff + n * 2048 + k * 1024); } while (0)
; #define PG8_MMA(ai, bj, At, Bt) do { __builtin_amdgcn_s_setprio(1); _Pragma("unroll") for (int m = 0; m < 4; ++m) _Pragma("unroll") for (int n = 0; n < 2; ++n) _Pragma("unroll") for (int k = 0; k < 2; ++k) \
;         acc[ai][bj][m][n] = __builtin_amdgcn_mfma_f32_16x16x32_bf16(Bt[n][k], At[m][k], acc[ai][bj][m][n], 0, 0, 0); __builtin_amdgcn_s_setprio(0); } while (0)
; #define PG8_WAIT_V(n) asm volatile("s_waitcnt vmcnt(" #n ")" ::: "memory")
; #define PG8_WAIT_L(n) asm volatile("s_waitcnt lgkmcnt(" #n ")" ::: "memory")
; #define PG8_BAR __builtin_amdgcn_s_barrier()
; #define PG8_SCHED __builtin_amdgcn_sched_barrier(0)
; template <class Epi, class Sched, bool STAMP = false>
; __device__ __forceinline__ void gemm_phase(PG8_LAS unsigned char* lds, const Gemm g, const Sched& S, const Epi& E, unsigned long long* stamps) {
;     ...
;             PG8_WAIT_V(6); PG8_BAR; PG8_MMA(1, 1, At, B1); PG8_BAR;
;             PG8_LDB(B0, 1, 0); PG8_SCHED; PG8_LDA(At, 1, 0); PG8_STAGE(PG8_SA(0, 1), a2 + hstep, voffA);
;             PG8_WAIT_L(8); PG8_BAR; PG8_WAIT_L(0); PG8_MMA(0, 0, At, B0); PG8_BAR; PG8_SCHED;
;             PG8_LDB(B1, 1, 1); PG8_STAGE(PG8_SB(1, 0), b3, voffB);
;             PG8_BAR; PG8_WAIT_L(0); PG8_MMA(0, 1, At, B1); PG8_BAR;
;             PG8_LDA(At, 1, 1); PG8_STAGE(PG8_SA(1, 0), a3, voffA);
	s_setprio 1
	v_mfma_f32_16x16x32_bf16 v[44:47], v[214:217], v[182:185], v[44:47]
	v_mfma_f32_16x16x32_bf16 v[40:43], v[222:225], v[182:185], v[40:43]
	v_mfma_f32_16x16x32_bf16 v[28:31], v[214:217], v[190:193], v[28:31]
	v_mfma_f32_16x16x32_bf16 v[24:27], v[222:225], v[190:193], v[24:27]
	v_mfma_f32_16x16x32_bf16 v[12:15], v[214:217], v[198:201], v[12:15]
	v_mfma_f32_16x16x32_bf16 v[8:11], v[222:225], v[198:201], v[8:11]
	v_mfma_f32_16x16x32_bf16 v[4:7], v[214:217], v[206:209], v[4:7]
	v_mfma_f32_16x16x32_bf16 v[0:3], v[222:225], v[206:209], v[0:3]
	v_mfma_f32_16x16x32_bf16 v[44:47], v[218:221], v[186:189], v[44:47]
	v_mfma_f32_16x16x32_bf16 v[40:43], v[226:229], v[186:189], v[40:43]
	v_mfma_f32_16x16x32_bf16 v[28:31], v[218:221], v[194:197], v[28:31]
	v_mfma_f32_16x16x32_bf16 v[24:27], v[226:229], v[194:197], v[24:27]
	v_mfma_f32_16x16x32_bf16 v[12:15], v[218:221], v[202:205], v[12:15]
	v_mfma_f32_16x16x32_bf16 v[8:11], v[226:229], v[202:205], v[8:11]
	v_mfma_f32_16x16x32_bf16 v[4:7], v[218:221], v[210:213], v[4:7]
	v_mfma_f32_16x16x32_bf16 v[0:3], v[226:229], v[210:213], v[0:3]
	s_setprio 0
	s_barrier
	ds_read_b128 v[166:169], v156
	ds_read_b128 v[170:173], v157
	ds_read_b128 v[174:177], v159
	ds_read_b128 v[178:181], v160
	s_add_u32 s34, s56, 0xb4000
	s_addc_u32 s35, s57, 0
	s_mov_b32 m0, s66
	ds_read_b128 v[182:185], v146 offset:32768
	ds_read_b128 v[186:189], v146 offset:33792
	ds_read_b128 v[190:193], v146 offset:34816
	ds_read_b128 v[194:197], v146 offset:35840
	ds_read_b128 v[198:201], v146 offset:36864
	ds_read_b128 v[202:205], v146 offset:37888
	ds_read_b128 v[206:209], v146 offset:38912
	ds_read_b128 v[210:213], v146 offset:39936
	global_load_lds_dwordx4 v128, s[34:35]
	s_mov_b32 m0, s67
	s_nop 0
	global_load_lds_dwordx4 v132, s[34:35]
	s_waitcnt lgkmcnt(8)
	s_barrier
	s_waitcnt lgkmcnt(0)
	s_setprio 1
	s_waitcnt lgkmcnt(0)
	v_mfma_f32_16x16x32_bf16 v[124:127], v[166:169], v[182:185], v[124:127]
	v_mfma_f32_16x16x32_bf16 v[120:123], v[174:177], v[182:185], v[120:123]
	v_mfma_f32_16x16x32_bf16 v[116:119], v[166:169], v[190:193], v[116:119]
	v_mfma_f32_16x16x32_bf16 v[112:115], v[174:177], v[190:193], v[112:115]
	v_mfma_f32_16x16x32_bf16 v[100:103], v[166:169], v[198:201], v[100:103]
	v_mfma_f32_16x16x32_bf16 v[96:99], v[174:177], v[198:201], v[96:99]
	v_mfma_f32_16x16x32_bf16 v[84:87], v[166:169], v[206:209], v[84:87]
	v_mfma_f32_16x16x32_bf16 v[80:83], v[174:177], v[206:209], v[80:83]
	v_mfma_f32_16x16x32_bf16 v[124:127], v[170:173], v[186:189], v[124:127]
	v_mfma_f32_16x16x32_bf16 v[120:123], v[178:181], v[186:189], v[120:123]
	v_mfma_f32_16x16x32_bf16 v[116:119], v[170:173], v[194:197], v[116:119]
	v_mfma_f32_16x16x32_bf16 v[112:115], v[178:181], v[194:197], v[112:115]
	v_mfma_f32_16x16x32_bf16 v[100:103], v[170:173], v[202:205], v[100:103]
	v_mfma_f32_16x16x32_bf16 v[96:99], v[178:181], v[202:205], v[96:99]
	v_mfma_f32_16x16x32_bf16 v[84:87], v[170:173], v[210:213], v[84:87]
	v_mfma_f32_16x16x32_bf16 v[80:83], v[178:181], v[210:213], v[80:83]
	s_setprio 0
	s_barrier
	s_mov_b32 m0, s68
	ds_read_b128 v[214:217], v161
	ds_read_b128 v[218:221], v162
	ds_read_b128 v[222:225], v163
	ds_read_b128 v[226:229], v164
	s_add_u32 s100, s54, 0x80
	s_addc_u32 s101, s55, 0
	global_load_lds_dwordx4 v130, s[100:101]
	s_mov_b32 m0, s69
	s_nop 0
	global_load_lds_dwordx4 v134, s[100:101]
	s_barrier
	s_waitcnt lgkmcnt(0)
	s_setprio 1
	s_waitcnt lgkmcnt(0)
	v_mfma_f32_16x16x32_bf16 v[108:111], v[214:217], v[182:185], v[108:111]
	v_mfma_f32_16x16x32_bf16 v[104:107], v[222:225], v[182:185], v[104:107]
	v_mfma_f32_16x16x32_bf16 v[92:95], v[214:217], v[190:193], v[92:95]
	v_mfma_f32_16x16x32_bf16 v[88:91], v[222:225], v[190:193], v[88:91]
	v_mfma_f32_16x16x32_bf16 v[76:79], v[214:217], v[198:201], v[76:79]
	v_mfma_f32_16x16x32_bf16 v[72:75], v[222:225], v[198:201], v[72:75]
	v_mfma_f32_16x16x32_bf16 v[68:71], v[214:217], v[206:209], v[68:71]
	v_mfma_f32_16x16x32_bf16 v[64:67], v[222:225], v[206:209], v[64:67]
	v_mfma_f32_16x16x32_bf16 v[108:111], v[218:221], v[186:189], v[108:111]
	v_mfma_f32_16x16x32_bf16 v[104:107], v[226:229], v[186:189], v[104:107]
	v_mfma_f32_16x16x32_bf16 v[92:95], v[218:221], v[194:197], v[92:95]
	v_mfma_f32_16x16x32_bf16 v[88:91], v[226:229], v[194:197], v[88:91]
	v_mfma_f32_16x16x32_bf16 v[76:79], v[218:221], v[202:205], v[76:79]
	v_mfma_f32_16x16x32_bf16 v[72:75], v[226:229], v[202:205], v[72:75]
	v_mfma_f32_16x16x32_bf16 v[68:71], v[218:221], v[210:213], v[68:71]
	v_mfma_f32_16x16x32_bf16 v[64:67], v[226:229], v[210:213], v[64:67]
	s_setprio 0
	s_mov_b32 m0, s70
	s_barrier
	ds_read_b128 v[182:185], v146 offset:49152
	ds_read_b128 v[186:189], v146 offset:50176
	ds_read_b128 v[190:193], v146 offset:51200
	ds_read_b128 v[194:197], v146 offset:52224
	ds_read_b128 v[198:201], v146 offset:53248
	ds_read_b128 v[202:205], v146 offset:54272
	ds_read_b128 v[206:209], v146 offset:55296
	ds_read_b128 v[210:213], v146 offset:56320
	s_add_u32 s100, s56, 0x80
	s_addc_u32 s101, s57, 0
	global_load_lds_dwordx4 v128, s[100:101]
	s_mov_b32 m0, s71
	s_nop 0
	global_load_lds_dwordx4 v132, s[100:101]
	s_barrier
; #define PG8_STAGE(bufoff, gbase, voff) do { _Pragma("unroll") for (int _i = 0; _i < 2; ++_i) \
;         __builtin_amdgcn_global_load_lds((const unsigned*)((const char*)(gbase) + (voff)[_i]), (PG8_LAS unsigned*)(lds + (bufoff) + ldsw + _i * 8192), 16, 0, 0); } while (0)
; #define PG8_MMA(ai, bj, At, Bt) do { __builtin_amdgcn_s_setprio(1); _Pragma("unroll") for (int m = 0; m < 4; ++m) _Pragma("unroll") for (int n = 0; n < 2; ++n) _Pragma("unroll") for (int k = 0; k < 2; ++k) \
;         acc[ai][bj][m][n] = __builtin_amdgcn_mfma_f32_16x16x32_bf16(Bt[n][k], At[m][k], acc[ai][bj][m][n], 0, 0, 0); __builtin_amdgcn_s_setprio(0); } while (0)
; #define PG8_WAIT_V(n) asm volatile("s_waitcnt vmcnt(" #n ")" ::: "memory")
; #define PG8_WAIT_L(n) asm volatile("s_waitcnt lgkmcnt(" #n ")" ::: "memory")
; #define PG8_BAR __builtin_amdgcn_s_barrier()
; #define PG8_SCHED __builtin_amdgcn_sched_barrier(0)
; template <class Epi, class Sched, bool STAMP = false>
; __device__ __forceinline__ void gemm_phase(PG8_LAS unsigned char* lds, const Gemm g, const Sched& S, const Epi& E, unsigned long long* stamps) {
;     ...
;             PG8_BAR; PG8_WAIT_L(0); PG8_MMA(1, 0, At, B0); PG8_BAR; PG8_SCHED;
;             PG8_STAGE(PG8_SB(1, 1), b3 + hstep, voffB);
;             PG8_WAIT_V(6); PG8_BAR; PG8_MMA(1, 1, At, B1); PG8_BAR;
;         }
	s_waitcnt lgkmcnt(0)
	s_setprio 1
	s_waitcnt lgkmcnt(0)
	v_mfma_f32_16x16x32_bf16 v[60:63], v[166:169], v[182:185], v[60:63]
	v_mfma_f32_16x16x32_bf16 v[56:59], v[174:177], v[182:185], v[56:59]
	v_mfma_f32_16x16x32_bf16 v[52:55], v[166:169], v[190:193], v[52:55]
	v_mfma_f32_16x16x32_bf16 v[48:51], v[174:177], v[190:193], v[48:51]
	v_mfma_f32_16x16x32_bf16 v[36:39], v[166:169], v[198:201], v[36:39]
	v_mfma_f32_16x16x32_bf16 v[32:35], v[174:177], v[198:201], v[32:35]
	v_mfma_f32_16x16x32_bf16 v[20:23], v[166:169], v[206:209], v[20:23]
	v_mfma_f32_16x16x32_bf16 v[16:19], v[174:177], v[206:209], v[16:19]
	v_mfma_f32_16x16x32_bf16 v[60:63], v[170:173], v[186:189], v[60:63]
	v_mfma_f32_16x16x32_bf16 v[56:59], v[178:181], v[186:189], v[56:59]
	v_mfma_f32_16x16x32_bf16 v[52:55], v[170:173], v[194:197], v[52:55]
	v_mfma_f32_16x16x32_bf16 v[48:51], v[178:181], v[194:197], v[48:51]
	v_mfma_f32_16x16x32_bf16 v[36:39], v[170:173], v[202:205], v[36:39]
	v_mfma_f32_16x16x32_bf16 v[32:35], v[178:181], v[202:205], v[32:35]
	v_mfma_f32_16x16x32_bf16 v[20:23], v[170:173], v[210:213], v[20:23]
	v_mfma_f32_16x16x32_bf16 v[16:19], v[178:181], v[210:213], v[16:19]
	s_setprio 0
	s_barrier
	s_add_u32 s34, s54, 0xb4080
	s_addc_u32 s35, s55, 0
	s_mov_b32 m0, s72
	s_nop 0
	global_load_lds_dwordx4 v130, s[34:35]
	s_mov_b32 m0, s73
	s_nop 0
	global_load_lds_dwordx4 v134, s[34:35]
	s_waitcnt vmcnt(6)
	s_barrier
	s_setprio 1
	v_mfma_f32_16x16x32_bf16 v[44:47], v[214:217], v[182:185], v[44:47]
	v_mfma_f32_16x16x32_bf16 v[40:43], v[222:225], v[182:185], v[40:43]
	v_mfma_f32_16x16x32_bf16 v[28:31], v[214:217], v[190:193], v[28:31]
	v_mfma_f32_16x16x32_bf16 v[24:27], v[222:225], v[190:193], v[24:27]
	v_mfma_f32_16x16x32_bf16 v[12:15], v[214:217], v[198:201], v[12:15]
	v_mfma_f32_16x16x32_bf16 v[8:11], v[222:225], v[198:201], v[8:11]
	v_mfma_f32_16x16x32_bf16 v[4:7], v[214:217], v[206:209], v[4:7]
	v_mfma_f32_16x16x32_bf16 v[0:3], v[222:225], v[206:209], v[0:3]
	v_mfma_f32_16x16x32_bf16 v[44:47], v[218:221], v[186:189], v[44:47]
	v_mfma_f32_16x16x32_bf16 v[40:43], v[226:229], v[186:189], v[40:43]
	v_mfma_f32_16x16x32_bf16 v[28:31], v[218:221], v[194:197], v[28:31]
	v_mfma_f32_16x16x32_bf16 v[24:27], v[226:229], v[194:197], v[24:27]
	v_mfma_f32_16x16x32_bf16 v[12:15], v[218:221], v[202:205], v[12:15]
	v_mfma_f32_16x16x32_bf16 v[8:11], v[226:229], v[202:205], v[8:11]
	v_mfma_f32_16x16x32_bf16 v[4:7], v[218:221], v[210:213], v[4:7]
	v_mfma_f32_16x16x32_bf16 v[0:3], v[226:229], v[210:213], v[0:3]
	s_setprio 0
	s_add_i32 s90, s90, 2
	s_add_u32 s88, s88, 0x100
	s_addc_u32 s89, s89, 0
	s_cmp_gt_u32 s90, 41
	s_mov_b64 s[34:35], s[52:53]
	s_barrier
	s_cbranch_scc0 .LBB0_97
; #define PG8_STAMP() do { if (STAMP && wid == 0 && nts < 64) { const unsigned long long _c = 0ull; \
;         ts_lo = (lane == nts) ? (int)(unsigned)_c : ts_lo; ts_hi = (lane == nts) ? (int)(unsigned)(_c >> 32) : ts_hi; ++nts; } } while (0)
; #define PG8_WAIT_V(n) asm volatile("s_waitcnt vmcnt(" #n ")" ::: "memory")
; #define PG8_BAR __builtin_amdgcn_s_barrier()
;     DI void operator()(const f32x4 (&acc)[2][2][4][2], const Unit& u, int wr, int wc, int fr, int fq) const {
;         const int row0 = u.pm * BM + wr * 64 + fr, col0 = u.pn * BM + wc * 32 + 8 * fq;
; #pragma unroll
;         for (int ai = 0; ai < 2; ++ai)
; #pragma unroll
;             for (int m = 0; m < 4; ++m) { u16* rowp = O + (size_t)(row0 + ai * HALF + m * 16) * ldc + col0;
; #pragma unroll
;                 for (int bj = 0; bj < 2; ++bj) { const f32x4 v0 = acc[ai][bj][m][0], v1 = acc[ai][bj][m][1];
;                     uint4 w = {pack2(v0[0], v0[1]), pack2(v0[2], v0[3]), pack2(v1[0], v1[1]), pack2(v1[2], v1[3])}; *(uint4*)(rowp + bj * HALF) = w; } }
; template <class Epi, class Sched, bool STAMP = false>
; __device__ __forceinline__ void gemm_phase(PG8_LAS unsigned char* lds, const Gemm g, const Sched& S, const Epi& E, unsigned long long* stamps) {
;     ...
;         if constexpr (!Epi::AFTER_DRAIN) { E(acc, cur, wr, wc, fr, fq); S.done(cur); }
;         PG8_STAMP();
;         if (!has_next) break;
; #pragma unroll
;         for (int a = 0; a < 2; ++a)
; #pragma unroll
;             for (int b = 0; b < 2; ++b)
; #pragma unroll
;                 for (int m = 0; m < 4; ++m)
; #pragma unroll
;                     for (int n = 0; n < 2; ++n) acc[a][b][m][n] = (f32x4){0.f, 0.f, 0.f, 0.f};
;         cur = nxt; cA = nA; cB = nB; ++ui;
;     }
;     PG8_WAIT_V(0);
;     if (wr == 0) PG8_BAR;
;     PG8_BAR;
	v_lshl_add_u32 v166, s84, 8, v145
	v_lshl_or_b32 v168, s87, 8, v147
	v_ashrrev_i32_e32 v167, 31, v166
	v_ashrrev_i32_e32 v169, 31, v168
	v_lshlrev_b64 v[170:171], 11, v[166:167]
	v_lshl_add_u64 v[170:171], s[14:15], 0, v[170:171]
	v_lshlrev_b64 v[168:169], 1, v[168:169]
	v_lshl_add_u64 v[170:171], v[170:171], 0, v[168:169]
	v_cvt_pk_bf16_f32 v60, v60, v61
	v_cvt_pk_bf16_f32 v61, v62, v63
	v_cvt_pk_bf16_f32 v62, v56, v57
	v_add_co_u32_e32 v56, vcc, s78, v170
	v_cvt_pk_bf16_f32 v68, v68, v69
	v_cvt_pk_bf16_f32 v69, v70, v71
	v_cvt_pk_bf16_f32 v70, v64, v65
	v_lshl_add_u64 v[64:65], v[170:171], 0, s[16:17]
	v_addc_co_u32_e32 v57, vcc, 0, v171, vcc
	v_cvt_pk_bf16_f32 v44, v44, v45
	v_cvt_pk_bf16_f32 v45, v46, v47
	v_cvt_pk_bf16_f32 v46, v40, v41
	v_cvt_pk_bf16_f32 v47, v42, v43
	v_cvt_pk_bf16_f32 v108, v108, v109
	v_cvt_pk_bf16_f32 v109, v110, v111
	v_cvt_pk_bf16_f32 v110, v104, v105
	v_or_b32_e32 v104, 16, v166
	global_store_dwordx4 v[64:65], v[44:47], off offset:256
	v_ashrrev_i32_e32 v105, 31, v104
	v_cvt_pk_bf16_f32 v92, v92, v93
	v_add_co_u32_e32 v46, vcc, s79, v170
	v_cvt_pk_bf16_f32 v93, v94, v95
	v_cvt_pk_bf16_f32 v94, v88, v89
	v_or_b32_e32 v88, 32, v166
	v_lshl_add_u64 v[44:45], v[170:171], 0, s[18:19]
	v_addc_co_u32_e32 v47, vcc, 0, v171, vcc
	v_cvt_pk_bf16_f32 v28, v28, v29
	v_cvt_pk_bf16_f32 v29, v30, v31
	v_cvt_pk_bf16_f32 v30, v24, v25
	v_cvt_pk_bf16_f32 v31, v26, v27
	v_lshlrev_b64 v[104:105], 11, v[104:105]
	v_ashrrev_i32_e32 v89, 31, v88
	v_cvt_pk_bf16_f32 v76, v76, v77
	v_cvt_pk_bf16_f32 v77, v78, v79
	v_cvt_pk_bf16_f32 v78, v72, v73
	v_or_b32_e32 v72, 48, v166
	global_store_dwordx4 v[44:45], v[28:31], off offset:256
	v_cvt_pk_bf16_f32 v111, v106, v107
	v_lshl_add_u64 v[104:105], s[14:15], 0, v[104:105]
	v_add_co_u32_e32 v30, vcc, s82, v170
	v_lshlrev_b64 v[88:89], 11, v[88:89]
	v_ashrrev_i32_e32 v73, 31, v72
	v_lshl_add_u64 v[28:29], v[170:171], 0, s[28:29]
	v_addc_co_u32_e32 v31, vcc, 0, v171, vcc
	v_cvt_pk_bf16_f32 v12, v12, v13
	v_cvt_pk_bf16_f32 v13, v14, v15
	v_cvt_pk_bf16_f32 v14, v8, v9
	v_cvt_pk_bf16_f32 v15, v10, v11
	global_store_dwordx4 v[170:171], v[108:111], off offset:256
	v_cvt_pk_bf16_f32 v95, v90, v91
	v_lshl_add_u64 v[88:89], s[14:15], 0, v[88:89]
	v_lshl_add_u64 v[108:109], v[104:105], 0, v[168:169]
	v_lshlrev_b64 v[72:73], 11, v[72:73]
	global_store_dwordx4 v[28:29], v[12:15], off offset:256
	global_store_dwordx4 v[108:109], v[92:95], off offset:256
	v_cvt_pk_bf16_f32 v79, v74, v75
	v_add_co_u32_e32 v14, vcc, s83, v170
	v_lshl_add_u64 v[92:93], v[88:89], 0, v[168:169]
	v_lshl_add_u64 v[72:73], s[14:15], 0, v[72:73]
	v_addc_co_u32_e32 v15, vcc, 0, v171, vcc
	v_cvt_pk_bf16_f32 v124, v124, v125
	v_cvt_pk_bf16_f32 v125, v126, v127
	v_cvt_pk_bf16_f32 v126, v120, v121
	v_cvt_pk_bf16_f32 v127, v122, v123
	v_cvt_pk_bf16_f32 v104, v116, v117
	v_cvt_pk_bf16_f32 v105, v118, v119
	v_cvt_pk_bf16_f32 v106, v112, v113
	v_cvt_pk_bf16_f32 v107, v114, v115
	v_cvt_pk_bf16_f32 v88, v100, v101
	v_cvt_pk_bf16_f32 v89, v102, v103
	v_cvt_pk_bf16_f32 v90, v96, v97
	v_cvt_pk_bf16_f32 v91, v98, v99
	global_store_dwordx4 v[92:93], v[76:79], off offset:256
	v_cvt_pk_bf16_f32 v74, v80, v81
	v_cvt_pk_bf16_f32 v75, v82, v83
	v_lshl_add_u64 v[76:77], v[72:73], 0, v[168:169]
	v_cvt_pk_bf16_f32 v72, v84, v85
	v_cvt_pk_bf16_f32 v73, v86, v87
	v_cvt_pk_bf16_f32 v71, v66, v67
	v_cvt_pk_bf16_f32 v63, v58, v59
	v_cvt_pk_bf16_f32 v40, v52, v53
	v_cvt_pk_bf16_f32 v41, v54, v55
	v_cvt_pk_bf16_f32 v42, v48, v49
	v_cvt_pk_bf16_f32 v43, v50, v51
	v_cvt_pk_bf16_f32 v24, v36, v37
	v_cvt_pk_bf16_f32 v25, v38, v39
	v_cvt_pk_bf16_f32 v26, v32, v33
	v_cvt_pk_bf16_f32 v27, v34, v35
	v_lshl_add_u64 v[12:13], v[170:171], 0, s[30:31]
	v_cvt_pk_bf16_f32 v8, v20, v21
	v_cvt_pk_bf16_f32 v9, v22, v23
	v_cvt_pk_bf16_f32 v10, v16, v17
	v_cvt_pk_bf16_f32 v11, v18, v19
	v_cvt_pk_bf16_f32 v4, v4, v5
	v_cvt_pk_bf16_f32 v5, v6, v7
	v_cvt_pk_bf16_f32 v6, v0, v1
	v_cvt_pk_bf16_f32 v7, v2, v3
	s_and_b64 vcc, exec, s[2:3]
	s_mov_b32 s87, s85
	s_mov_b32 s84, s86
	s_mov_b64 s[52:53], s[0:1]
	s_mov_b64 s[34:35], s[4:5]
	global_store_dwordx4 v[170:171], v[124:127], off
	global_store_dwordx4 v[108:109], v[104:107], off
	global_store_dwordx4 v[92:93], v[88:91], off
	global_store_dwordx4 v[76:77], v[72:75], off
	global_store_dwordx4 v[76:77], v[68:71], off offset:256
	global_store_dwordx4 v[56:57], v[60:63], off
	global_store_dwordx4 v[46:47], v[40:43], off
	global_store_dwordx4 v[30:31], v[24:27], off
	global_store_dwordx4 v[14:15], v[8:11], off
	global_store_dwordx4 v[12:13], v[4:7], off offset:256
	s_cbranch_vccz .LBB0_86
	s_waitcnt vmcnt(0)
	s_cmpk_gt_u32 s58, 0xff
	s_cbranch_scc1 .LBB0_101
	s_barrier

; #define PG8_STAGE(bufoff, gbase, voff) do { _Pragma("unroll") for (int _i = 0; _i < 2; ++_i) \
;         __builtin_amdgcn_global_load_lds((const unsigned*)((const char*)(gbase) + (voff)[_i]), (PG8_LAS unsigned*)(lds + (bufoff) + ldsw + _i * 8192), 16, 0, 0); } while (0)
; #define PG8_LDA(dst, b, h) do { _Pragma("unroll") for (int m = 0; m < 4; ++m) _Pragma("unroll") for (int k = 0; k < 2; ++k) dst[m][k] = *(const PG8_LAS bf16x8*)(lds + PG8_SA(b, h) + aoff + m * 2048 + k * 1024); } while (0)
; #define PG8_LDB(dst, b, h) do { _Pragma("unroll") for (int n = 0; n < 2; ++n) _Pragma("unroll") for (int k = 0; k < 2; ++k) dst[n][k] = *(const PG8_LAS bf16x8*)(lds + PG8_SB(b, h) + boff + n * 2048 + k * 1024); } while (0)
; #define PG8_MMA(ai, bj, At, Bt) do { __builtin_amdgcn_s_setprio(1); _Pragma("unroll") for (int m = 0; m < 4; ++m) _Pragma("unroll") for (int n = 0; n < 2; ++n) _Pragma("unroll") for (int k = 0; k < 2; ++k) \
;         acc[ai][bj][m][n] = __builtin_amdgcn_mfma_f32_16x16x32_bf16(Bt[n][k], At[m][k], acc[ai][bj][m][n], 0, 0, 0); __builtin_amdgcn_s_setprio(0); } while (0)
; #define PG8_WAIT_V(n) asm volatile("s_waitcnt vmcnt(" #n ")" ::: "memory")
; #define PG8_WAIT_L(n) asm volatile("s_waitcnt lgkmcnt(" #n ")" ::: "memory")
; #define PG8_BAR __builtin_amdgcn_s_barrier()
; #define PG8_SCHED __builtin_amdgcn_sched_barrier(0)
; template <class Epi, class Sched, bool STAMP = false>
; __device__ __forceinline__ void gemm_phase(PG8_LAS unsigned char* lds, const Gemm g, const Sched& S, const Epi& E, unsigned long long* stamps) {
;     ...
;             PG8_LDB(B0, 0, 0); PG8_SCHED; PG8_LDA(At, 0, 0); PG8_STAGE(PG8_SA(1, 1), a1 + hstep, voffA);
;             PG8_WAIT_L(8); PG8_BAR; PG8_WAIT_L(0); PG8_MMA(0, 0, At, B0); PG8_BAR; PG8_SCHED;
;             PG8_LDB(B1, 0, 1); PG8_STAGE(PG8_SB(0, 0), b2, voffB);
;             PG8_BAR; PG8_WAIT_L(0); PG8_MMA(0, 1, At, B1); PG8_BAR;
;             PG8_LDA(At, 0, 1); PG8_STAGE(PG8_SA(0, 0), a2, voffA);
;             PG8_BAR; PG8_WAIT_L(0); PG8_MMA(1, 0, At, B0); PG8_BAR; PG8_SCHED;
;             PG8_STAGE(PG8_SB(0, 1), b2 + hstep, voffB);
;             PG8_WAIT_V(6); PG8_BAR; PG8_MMA(1, 1, At, B1); PG8_BAR;
.LBB0_138:
	ds_read_b128 v[166:169], v148
	ds_read_b128 v[170:173], v149
	ds_read_b128 v[174:177], v150
	ds_read_b128 v[178:181], v151
	s_add_u32 s34, s28, 0x100
	s_addc_u32 s35, s29, 0
	s_cmp_eq_u32 s85, 12
	s_cselect_b32 s53, s7, s35
	s_cselect_b32 s52, s6, s34
	s_cselect_b32 s37, s1, s84
	s_cselect_b32 s36, s0, s83
	s_mov_b32 m0, s74
	ds_read_b128 v[182:185], v146
	ds_read_b128 v[186:189], v146 offset:1024
	ds_read_b128 v[190:193], v146 offset:2048
	ds_read_b128 v[194:197], v146 offset:3072
	ds_read_b128 v[198:201], v146 offset:4096
	ds_read_b128 v[202:205], v146 offset:5120
	ds_read_b128 v[206:209], v146 offset:6144
	ds_read_b128 v[210:213], v146 offset:7168
	global_load_lds_dwordx4 v136, s[28:29]
	s_mov_b32 m0, s75
	s_nop 0
	global_load_lds_dwordx4 v138, s[28:29]
	s_waitcnt lgkmcnt(8)
	s_barrier
	s_waitcnt lgkmcnt(0)
	s_setprio 1
	s_waitcnt lgkmcnt(0)
	v_mfma_f32_16x16x32_bf16 v[124:127], v[166:169], v[182:185], v[124:127]
	v_mfma_f32_16x16x32_bf16 v[120:123], v[174:177], v[182:185], v[120:123]
	v_mfma_f32_16x16x32_bf16 v[116:119], v[166:169], v[190:193], v[116:119]
	v_mfma_f32_16x16x32_bf16 v[112:115], v[174:177], v[190:193], v[112:115]
	v_mfma_f32_16x16x32_bf16 v[108:111], v[166:169], v[198:201], v[108:111]
	v_mfma_f32_16x16x32_bf16 v[104:107], v[174:177], v[198:201], v[104:107]
	v_mfma_f32_16x16x32_bf16 v[100:103], v[166:169], v[206:209], v[100:103]
	v_mfma_f32_16x16x32_bf16 v[96:99], v[174:177], v[206:209], v[96:99]
	v_mfma_f32_16x16x32_bf16 v[124:127], v[170:173], v[186:189], v[124:127]
	v_mfma_f32_16x16x32_bf16 v[120:123], v[178:181], v[186:189], v[120:123]
	v_mfma_f32_16x16x32_bf16 v[116:119], v[170:173], v[194:197], v[116:119]
	v_mfma_f32_16x16x32_bf16 v[112:115], v[178:181], v[194:197], v[112:115]
	v_mfma_f32_16x16x32_bf16 v[108:111], v[170:173], v[202:205], v[108:111]
	v_mfma_f32_16x16x32_bf16 v[104:107], v[178:181], v[202:205], v[104:107]
	v_mfma_f32_16x16x32_bf16 v[100:103], v[170:173], v[210:213], v[100:103]
	v_mfma_f32_16x16x32_bf16 v[96:99], v[178:181], v[210:213], v[96:99]
	s_setprio 0
	s_barrier
	s_mov_b32 m0, s58
	ds_read_b128 v[214:217], v152
	ds_read_b128 v[218:221], v153
	ds_read_b128 v[222:225], v154
	ds_read_b128 v[226:229], v155
	global_load_lds_dwordx4 v132, s[36:37]
	s_mov_b32 m0, s59
	s_nop 0
	global_load_lds_dwordx4 v128, s[36:37]
	s_barrier
	s_waitcnt lgkmcnt(0)
	s_setprio 1
	s_waitcnt lgkmcnt(0)
	v_mfma_f32_16x16x32_bf16 v[60:63], v[214:217], v[182:185], v[60:63]
	v_mfma_f32_16x16x32_bf16 v[56:59], v[222:225], v[182:185], v[56:59]
	v_mfma_f32_16x16x32_bf16 v[52:55], v[214:217], v[190:193], v[52:55]
	v_mfma_f32_16x16x32_bf16 v[48:51], v[222:225], v[190:193], v[48:51]
	v_mfma_f32_16x16x32_bf16 v[44:47], v[214:217], v[198:201], v[44:47]
	v_mfma_f32_16x16x32_bf16 v[40:43], v[222:225], v[198:201], v[40:43]
	v_mfma_f32_16x16x32_bf16 v[36:39], v[214:217], v[206:209], v[36:39]
	v_mfma_f32_16x16x32_bf16 v[32:35], v[222:225], v[206:209], v[32:35]
	v_mfma_f32_16x16x32_bf16 v[60:63], v[218:221], v[186:189], v[60:63]
	v_mfma_f32_16x16x32_bf16 v[56:59], v[226:229], v[186:189], v[56:59]
	v_mfma_f32_16x16x32_bf16 v[52:55], v[218:221], v[194:197], v[52:55]
	v_mfma_f32_16x16x32_bf16 v[48:51], v[226:229], v[194:197], v[48:51]
	v_mfma_f32_16x16x32_bf16 v[44:47], v[218:221], v[202:205], v[44:47]
	v_mfma_f32_16x16x32_bf16 v[40:43], v[226:229], v[202:205], v[40:43]
	v_mfma_f32_16x16x32_bf16 v[36:39], v[218:221], v[210:213], v[36:39]
	v_mfma_f32_16x16x32_bf16 v[32:35], v[226:229], v[210:213], v[32:35]
	s_setprio 0
	s_mov_b32 m0, s55
	s_barrier
	ds_read_b128 v[182:185], v146 offset:16384
	ds_read_b128 v[186:189], v146 offset:17408
	ds_read_b128 v[190:193], v146 offset:18432
	ds_read_b128 v[194:197], v146 offset:19456
	ds_read_b128 v[198:201], v146 offset:20480
	ds_read_b128 v[202:205], v146 offset:21504
	ds_read_b128 v[206:209], v146 offset:22528
	ds_read_b128 v[210:213], v146 offset:23552
	global_load_lds_dwordx4 v134, s[52:53]
	s_mov_b32 m0, s60
	s_nop 0
	global_load_lds_dwordx4 v130, s[52:53]
	s_barrier
	s_waitcnt lgkmcnt(0)
	s_setprio 1
	s_waitcnt lgkmcnt(0)
	v_mfma_f32_16x16x32_bf16 v[92:95], v[166:169], v[182:185], v[92:95]
	v_mfma_f32_16x16x32_bf16 v[88:91], v[174:177], v[182:185], v[88:91]
	v_mfma_f32_16x16x32_bf16 v[84:87], v[166:169], v[190:193], v[84:87]
	v_mfma_f32_16x16x32_bf16 v[80:83], v[174:177], v[190:193], v[80:83]
	v_mfma_f32_16x16x32_bf16 v[76:79], v[166:169], v[198:201], v[76:79]
	v_mfma_f32_16x16x32_bf16 v[72:75], v[174:177], v[198:201], v[72:75]
	v_mfma_f32_16x16x32_bf16 v[68:71], v[166:169], v[206:209], v[68:71]
	v_mfma_f32_16x16x32_bf16 v[64:67], v[174:177], v[206:209], v[64:67]
	v_mfma_f32_16x16x32_bf16 v[92:95], v[170:173], v[186:189], v[92:95]
	v_mfma_f32_16x16x32_bf16 v[88:91], v[178:181], v[186:189], v[88:91]
	v_mfma_f32_16x16x32_bf16 v[84:87], v[170:173], v[194:197], v[84:87]
	v_mfma_f32_16x16x32_bf16 v[80:83], v[178:181], v[194:197], v[80:83]
	v_mfma_f32_16x16x32_bf16 v[76:79], v[170:173], v[202:205], v[76:79]
	v_mfma_f32_16x16x32_bf16 v[72:75], v[178:181], v[202:205], v[72:75]
	v_mfma_f32_16x16x32_bf16 v[68:71], v[170:173], v[210:213], v[68:71]
	v_mfma_f32_16x16x32_bf16 v[64:67], v[178:181], v[210:213], v[64:67]
	s_setprio 0
	s_barrier
	s_add_u32 s28, s36, 0x44000
	s_addc_u32 s29, s37, 0
	s_mov_b32 m0, s61
	s_nop 0
	global_load_lds_dwordx4 v132, s[28:29]
	s_mov_b32 m0, s62
	s_nop 0
	global_load_lds_dwordx4 v128, s[28:29]
	s_waitcnt vmcnt(6)
	s_barrier
; #define PG8_STAGE(bufoff, gbase, voff) do { _Pragma("unroll") for (int _i = 0; _i < 2; ++_i) \
;         __builtin_amdgcn_global_load_lds((const unsigned*)((const char*)(gbase) + (voff)[_i]), (PG8_LAS unsigned*)(lds + (bufoff) + ldsw + _i * 8192), 16, 0, 0); } while (0)
; #define PG8_LDA(dst, b, h) do { _Pragma("unroll") for (int m = 0; m < 4; ++m) _Pragma("unroll") for (int k = 0; k < 2; ++k) dst[m][k] = *(const PG8_LAS bf16x8*)(lds + PG8_SA(b, h) + aoff + m * 2048 + k * 1024); } while (0)
; #define PG8_LDB(dst, b, h) do { _Pragma("unroll") for (int n = 0; n < 2; ++n) _Pragma("unroll") for (int k = 0; k < 2; ++k) dst[n][k] = *(const PG8_LAS bf16x8*)(lds + PG8_SB(b, h) + boff + n * 2048 + k * 1024); } while (0)
; #define PG8_MMA(ai, bj, At, Bt) do { __builtin_amdgcn_s_setprio(1); _Pragma("unroll") for (int m = 0; m < 4; ++m) _Pragma("unroll") for (int n = 0; n < 2; ++n) _Pragma("unroll") for (int k = 0; k < 2; ++k) \
;         acc[ai][bj][m][n] = __builtin_amdgcn_mfma_f32_16x16x32_bf16(Bt[n][k], At[m][k], acc[ai][bj][m][n], 0, 0, 0); __builtin_amdgcn_s_setprio(0); } while (0)
; #define PG8_WAIT_V(n) asm volatile("s_waitcnt vmcnt(" #n ")" ::: "memory")
; #define PG8_WAIT_L(n) asm volatile("s_waitcnt lgkmcnt(" #n ")" ::: "memory")
; #define PG8_BAR __builtin_amdgcn_s_barrier()
; #define PG8_SCHED __builtin_amdgcn_sched_barrier(0)
; template <class Epi, class Sched, bool STAMP = false>
; __device__ __forceinline__ void gemm_phase(PG8_LAS unsigned char* lds, const Gemm g, const Sched& S, const Epi& E, unsigned long long* stamps) {
;     ...
;             PG8_WAIT_V(6); PG8_BAR; PG8_MMA(1, 1, At, B1); PG8_BAR;
;             PG8_LDB(B0, 1, 0); PG8_SCHED; PG8_LDA(At, 1, 0); PG8_STAGE(PG8_SA(0, 1), a2 + hstep, voffA);
;             PG8_WAIT_L(8); PG8_BAR; PG8_WAIT_L(0); PG8_MMA(0, 0, At, B0); PG8_BAR; PG8_SCHED;
;             PG8_LDB(B1, 1, 1); PG8_STAGE(PG8_SB(1, 0), b3, voffB);
;             PG8_BAR; PG8_WAIT_L(0); PG8_MMA(0, 1, At, B1); PG8_BAR;
;             PG8_LDA(At, 1, 1); PG8_STAGE(PG8_SA(1, 0), a3, voffA);
	s_setprio 1
	v_mfma_f32_16x16x32_bf16 v[28:31], v[214:217], v[182:185], v[28:31]
	v_mfma_f32_16x16x32_bf16 v[24:27], v[222:225], v[182:185], v[24:27]
	v_mfma_f32_16x16x32_bf16 v[20:23], v[214:217], v[190:193], v[20:23]
	v_mfma_f32_16x16x32_bf16 v[16:19], v[222:225], v[190:193], v[16:19]
	v_mfma_f32_16x16x32_bf16 v[12:15], v[214:217], v[198:201], v[12:15]
	v_mfma_f32_16x16x32_bf16 v[8:11], v[222:225], v[198:201], v[8:11]
	v_mfma_f32_16x16x32_bf16 v[4:7], v[214:217], v[206:209], v[4:7]
	v_mfma_f32_16x16x32_bf16 v[0:3], v[222:225], v[206:209], v[0:3]
	v_mfma_f32_16x16x32_bf16 v[28:31], v[218:221], v[186:189], v[28:31]
	v_mfma_f32_16x16x32_bf16 v[24:27], v[226:229], v[186:189], v[24:27]
	v_mfma_f32_16x16x32_bf16 v[20:23], v[218:221], v[194:197], v[20:23]
	v_mfma_f32_16x16x32_bf16 v[16:19], v[226:229], v[194:197], v[16:19]
	v_mfma_f32_16x16x32_bf16 v[12:15], v[218:221], v[202:205], v[12:15]
	v_mfma_f32_16x16x32_bf16 v[8:11], v[226:229], v[202:205], v[8:11]
	v_mfma_f32_16x16x32_bf16 v[4:7], v[218:221], v[210:213], v[4:7]
	v_mfma_f32_16x16x32_bf16 v[0:3], v[226:229], v[210:213], v[0:3]
	s_setprio 0
	s_barrier
	ds_read_b128 v[166:169], v156
	ds_read_b128 v[170:173], v157
	ds_read_b128 v[174:177], v159
	ds_read_b128 v[178:181], v160
	s_add_u32 s28, s52, 0x44000
	s_addc_u32 s29, s53, 0
	s_mov_b32 m0, s63
	ds_read_b128 v[182:185], v146 offset:32768
	ds_read_b128 v[186:189], v146 offset:33792
	ds_read_b128 v[190:193], v146 offset:34816
	ds_read_b128 v[194:197], v146 offset:35840
	ds_read_b128 v[198:201], v146 offset:36864
	ds_read_b128 v[202:205], v146 offset:37888
	ds_read_b128 v[206:209], v146 offset:38912
	ds_read_b128 v[210:213], v146 offset:39936
	global_load_lds_dwordx4 v134, s[28:29]
	s_mov_b32 m0, s64
	s_nop 0
	global_load_lds_dwordx4 v130, s[28:29]
	s_waitcnt lgkmcnt(8)
	s_barrier
	s_waitcnt lgkmcnt(0)
	s_setprio 1
	s_waitcnt lgkmcnt(0)
	v_mfma_f32_16x16x32_bf16 v[124:127], v[166:169], v[182:185], v[124:127]
	v_mfma_f32_16x16x32_bf16 v[120:123], v[174:177], v[182:185], v[120:123]
	v_mfma_f32_16x16x32_bf16 v[116:119], v[166:169], v[190:193], v[116:119]
	v_mfma_f32_16x16x32_bf16 v[112:115], v[174:177], v[190:193], v[112:115]
	v_mfma_f32_16x16x32_bf16 v[108:111], v[166:169], v[198:201], v[108:111]
	v_mfma_f32_16x16x32_bf16 v[104:107], v[174:177], v[198:201], v[104:107]
	v_mfma_f32_16x16x32_bf16 v[100:103], v[166:169], v[206:209], v[100:103]
	v_mfma_f32_16x16x32_bf16 v[96:99], v[174:177], v[206:209], v[96:99]
	v_mfma_f32_16x16x32_bf16 v[124:127], v[170:173], v[186:189], v[124:127]
	v_mfma_f32_16x16x32_bf16 v[120:123], v[178:181], v[186:189], v[120:123]
	v_mfma_f32_16x16x32_bf16 v[116:119], v[170:173], v[194:197], v[116:119]
	v_mfma_f32_16x16x32_bf16 v[112:115], v[178:181], v[194:197], v[112:115]
	v_mfma_f32_16x16x32_bf16 v[108:111], v[170:173], v[202:205], v[108:111]
	v_mfma_f32_16x16x32_bf16 v[104:107], v[178:181], v[202:205], v[104:107]
	v_mfma_f32_16x16x32_bf16 v[100:103], v[170:173], v[210:213], v[100:103]
	v_mfma_f32_16x16x32_bf16 v[96:99], v[178:181], v[210:213], v[96:99]
	s_setprio 0
	s_barrier
	s_mov_b32 m0, s67
	ds_read_b128 v[214:217], v161
	ds_read_b128 v[218:221], v162
	ds_read_b128 v[222:225], v163
	ds_read_b128 v[226:229], v164
	s_add_u32 s100, s36, 0x80
	s_addc_u32 s101, s37, 0
	global_load_lds_dwordx4 v132, s[100:101]
	s_mov_b32 m0, s68
	s_nop 0
	global_load_lds_dwordx4 v128, s[100:101]
	s_barrier
	s_waitcnt lgkmcnt(0)
	s_setprio 1
	s_waitcnt lgkmcnt(0)
	v_mfma_f32_16x16x32_bf16 v[60:63], v[214:217], v[182:185], v[60:63]
	v_mfma_f32_16x16x32_bf16 v[56:59], v[222:225], v[182:185], v[56:59]
	v_mfma_f32_16x16x32_bf16 v[52:55], v[214:217], v[190:193], v[52:55]
	v_mfma_f32_16x16x32_bf16 v[48:51], v[222:225], v[190:193], v[48:51]
	v_mfma_f32_16x16x32_bf16 v[44:47], v[214:217], v[198:201], v[44:47]
	v_mfma_f32_16x16x32_bf16 v[40:43], v[222:225], v[198:201], v[40:43]
	v_mfma_f32_16x16x32_bf16 v[36:39], v[214:217], v[206:209], v[36:39]
	v_mfma_f32_16x16x32_bf16 v[32:35], v[222:225], v[206:209], v[32:35]
	v_mfma_f32_16x16x32_bf16 v[60:63], v[218:221], v[186:189], v[60:63]
	v_mfma_f32_16x16x32_bf16 v[56:59], v[226:229], v[186:189], v[56:59]
	v_mfma_f32_16x16x32_bf16 v[52:55], v[218:221], v[194:197], v[52:55]
	v_mfma_f32_16x16x32_bf16 v[48:51], v[226:229], v[194:197], v[48:51]
	v_mfma_f32_16x16x32_bf16 v[44:47], v[218:221], v[202:205], v[44:47]
	v_mfma_f32_16x16x32_bf16 v[40:43], v[226:229], v[202:205], v[40:43]
	v_mfma_f32_16x16x32_bf16 v[36:39], v[218:221], v[210:213], v[36:39]
	v_mfma_f32_16x16x32_bf16 v[32:35], v[226:229], v[210:213], v[32:35]
	s_setprio 0
	s_mov_b32 m0, s69
	s_barrier
	ds_read_b128 v[182:185], v146 offset:49152
	ds_read_b128 v[186:189], v146 offset:50176
	ds_read_b128 v[190:193], v146 offset:51200
	ds_read_b128 v[194:197], v146 offset:52224
	ds_read_b128 v[198:201], v146 offset:53248
	ds_read_b128 v[202:205], v146 offset:54272
	ds_read_b128 v[206:209], v146 offset:55296
	ds_read_b128 v[210:213], v146 offset:56320
	s_add_u32 s100, s52, 0x80
	s_addc_u32 s101, s53, 0
	global_load_lds_dwordx4 v134, s[100:101]
	s_mov_b32 m0, s70
	s_nop 0
	global_load_lds_dwordx4 v130, s[100:101]
	s_barrier
; #define PG8_STAGE(bufoff, gbase, voff) do { _Pragma("unroll") for (int _i = 0; _i < 2; ++_i) \
;         __builtin_amdgcn_global_load_lds((const unsigned*)((const char*)(gbase) + (voff)[_i]), (PG8_LAS unsigned*)(lds + (bufoff) + ldsw + _i * 8192), 16, 0, 0); } while (0)
; #define PG8_MMA(ai, bj, At, Bt) do { __builtin_amdgcn_s_setprio(1); _Pragma("unroll") for (int m = 0; m < 4; ++m) _Pragma("unroll") for (int n = 0; n < 2; ++n) _Pragma("unroll") for (int k = 0; k < 2; ++k) \
;         acc[ai][bj][m][n] = __builtin_amdgcn_mfma_f32_16x16x32_bf16(Bt[n][k], At[m][k], acc[ai][bj][m][n], 0, 0, 0); __builtin_amdgcn_s_setprio(0); } while (0)
; #define PG8_WAIT_V(n) asm volatile("s_waitcnt vmcnt(" #n ")" ::: "memory")
; #define PG8_WAIT_L(n) asm volatile("s_waitcnt lgkmcnt(" #n ")" ::: "memory")
; #define PG8_BAR __builtin_amdgcn_s_barrier()
; #define PG8_SCHED __builtin_amdgcn_sched_barrier(0)
;     DI void operator()(const f32x4 (&acc)[2][2][4][2], const Unit& u, int wr, int wc, int fr, int fq) const {
;         const int row0 = u.pm * BM + wr * 64 + fr, col0 = u.pn * BM + wc * 32 + 8 * fq;
; #pragma unroll
;         for (int ai = 0; ai < 2; ++ai)
; #pragma unroll
;             for (int m = 0; m < 4; ++m) { u16* rowp = O + (size_t)(row0 + ai * HALF + m * 16) * ldc + col0;
; #pragma unroll
;                 for (int bj = 0; bj < 2; ++bj) { const f32x4 v0 = acc[ai][bj][m][0], v1 = acc[ai][bj][m][1];
;                     uint4 w = {pack2(v0[0], v0[1]), pack2(v0[2], v0[3]), pack2(v1[0], v1[1]), pack2(v1[2], v1[3])}; *(uint4*)(rowp + bj * HALF) = w; } }
; template <class Epi, class Sched, bool STAMP = false>
; __device__ __forceinline__ void gemm_phase(PG8_LAS unsigned char* lds, const Gemm g, const Sched& S, const Epi& E, unsigned long long* stamps) {
;     ...
;             PG8_BAR; PG8_WAIT_L(0); PG8_MMA(1, 0, At, B0); PG8_BAR; PG8_SCHED;
;             PG8_STAGE(PG8_SB(1, 1), b3 + hstep, voffB);
;             PG8_WAIT_V(6); PG8_BAR; PG8_MMA(1, 1, At, B1); PG8_BAR;
;         }
	s_waitcnt lgkmcnt(0)
	s_setprio 1
	s_waitcnt lgkmcnt(0)
	v_mfma_f32_16x16x32_bf16 v[92:95], v[166:169], v[182:185], v[92:95]
	v_mfma_f32_16x16x32_bf16 v[88:91], v[174:177], v[182:185], v[88:91]
	v_mfma_f32_16x16x32_bf16 v[84:87], v[166:169], v[190:193], v[84:87]
	v_mfma_f32_16x16x32_bf16 v[80:83], v[174:177], v[190:193], v[80:83]
	v_mfma_f32_16x16x32_bf16 v[76:79], v[166:169], v[198:201], v[76:79]
	v_mfma_f32_16x16x32_bf16 v[72:75], v[174:177], v[198:201], v[72:75]
	v_mfma_f32_16x16x32_bf16 v[68:71], v[166:169], v[206:209], v[68:71]
	v_mfma_f32_16x16x32_bf16 v[64:67], v[174:177], v[206:209], v[64:67]
	v_mfma_f32_16x16x32_bf16 v[92:95], v[170:173], v[186:189], v[92:95]
	v_mfma_f32_16x16x32_bf16 v[88:91], v[178:181], v[186:189], v[88:91]
	v_mfma_f32_16x16x32_bf16 v[84:87], v[170:173], v[194:197], v[84:87]
	v_mfma_f32_16x16x32_bf16 v[80:83], v[178:181], v[194:197], v[80:83]
	v_mfma_f32_16x16x32_bf16 v[76:79], v[170:173], v[202:205], v[76:79]
	v_mfma_f32_16x16x32_bf16 v[72:75], v[178:181], v[202:205], v[72:75]
	v_mfma_f32_16x16x32_bf16 v[68:71], v[170:173], v[210:213], v[68:71]
	v_mfma_f32_16x16x32_bf16 v[64:67], v[178:181], v[210:213], v[64:67]
	s_setprio 0
	s_barrier
	s_add_u32 s28, s36, 0x44080
	s_addc_u32 s29, s37, 0
	s_mov_b32 m0, s71
	s_nop 0
	global_load_lds_dwordx4 v132, s[28:29]
	s_mov_b32 m0, s72
	s_nop 0
	global_load_lds_dwordx4 v128, s[28:29]
	s_waitcnt vmcnt(6)
	s_barrier
	s_setprio 1
	v_mfma_f32_16x16x32_bf16 v[28:31], v[214:217], v[182:185], v[28:31]
	v_mfma_f32_16x16x32_bf16 v[24:27], v[222:225], v[182:185], v[24:27]
	v_mfma_f32_16x16x32_bf16 v[20:23], v[214:217], v[190:193], v[20:23]
	v_mfma_f32_16x16x32_bf16 v[16:19], v[222:225], v[190:193], v[16:19]
	v_mfma_f32_16x16x32_bf16 v[12:15], v[214:217], v[198:201], v[12:15]
	v_mfma_f32_16x16x32_bf16 v[8:11], v[222:225], v[198:201], v[8:11]
	v_mfma_f32_16x16x32_bf16 v[4:7], v[214:217], v[206:209], v[4:7]
	v_mfma_f32_16x16x32_bf16 v[0:3], v[222:225], v[206:209], v[0:3]
	v_mfma_f32_16x16x32_bf16 v[28:31], v[218:221], v[186:189], v[28:31]
	v_mfma_f32_16x16x32_bf16 v[24:27], v[226:229], v[186:189], v[24:27]
	v_mfma_f32_16x16x32_bf16 v[20:23], v[218:221], v[194:197], v[20:23]
	v_mfma_f32_16x16x32_bf16 v[16:19], v[226:229], v[194:197], v[16:19]
	v_mfma_f32_16x16x32_bf16 v[12:15], v[218:221], v[202:205], v[12:15]
	v_mfma_f32_16x16x32_bf16 v[8:11], v[226:229], v[202:205], v[8:11]
	v_mfma_f32_16x16x32_bf16 v[4:7], v[218:221], v[210:213], v[4:7]
	v_mfma_f32_16x16x32_bf16 v[0:3], v[226:229], v[210:213], v[0:3]
	s_setprio 0
	s_add_i32 s85, s85, 2
	s_add_u32 s83, s83, 0x100
	s_addc_u32 s84, s84, 0
	s_cmp_gt_u32 s85, 13
	s_mov_b64 s[28:29], s[34:35]
	s_barrier
	s_cbranch_scc0 .LBB0_138
	s_lshl_b32 s52, s79, 8
	v_or_b32_e32 v166, s52, v147
	v_lshl_add_u32 v176, s82, 8, v145
	v_ashrrev_i32_e32 v167, 31, v166
	v_mov_b64_e32 v[170:171], s[12:13]
	v_mad_i64_i32 v[168:169], s[28:29], v176, s76, v[170:171]
	v_lshlrev_b64 v[172:173], 1, v[166:167]
	v_lshl_add_u64 v[174:175], v[168:169], 0, v[172:173]
	v_cvt_pk_bf16_f32 v166, v124, v125
	v_cvt_pk_bf16_f32 v167, v126, v127
	v_cvt_pk_bf16_f32 v168, v120, v121
	v_cvt_pk_bf16_f32 v169, v122, v123
	global_store_dwordx4 v[174:175], v[166:169], off
	s_or_b32 s10, s52, s66
	s_nop 0
	v_cvt_pk_bf16_f32 v166, v60, v61
	v_cvt_pk_bf16_f32 v167, v62, v63
	v_cvt_pk_bf16_f32 v168, v56, v57
	v_cvt_pk_bf16_f32 v169, v58, v59
	global_store_dwordx4 v[174:175], v[166:169], off offset:256
	s_nop 1
	v_or_b32_e32 v166, 16, v176
	v_mad_i64_i32 v[166:167], s[28:29], v166, s76, v[170:171]
	v_lshl_add_u64 v[174:175], v[166:167], 0, v[172:173]
	v_cvt_pk_bf16_f32 v166, v116, v117
	v_cvt_pk_bf16_f32 v167, v118, v119
	v_cvt_pk_bf16_f32 v168, v112, v113
	v_cvt_pk_bf16_f32 v169, v114, v115
	global_store_dwordx4 v[174:175], v[166:169], off
	s_nop 1
	v_cvt_pk_bf16_f32 v166, v52, v53
	v_cvt_pk_bf16_f32 v167, v54, v55
	v_cvt_pk_bf16_f32 v168, v48, v49
	v_cvt_pk_bf16_f32 v169, v50, v51
	global_store_dwordx4 v[174:175], v[166:169], off offset:256
	s_nop 1
	v_or_b32_e32 v166, 32, v176
	v_mad_i64_i32 v[166:167], s[28:29], v166, s76, v[170:171]
	v_lshl_add_u64 v[174:175], v[166:167], 0, v[172:173]
	v_cvt_pk_bf16_f32 v166, v108, v109
	v_cvt_pk_bf16_f32 v167, v110, v111
	v_cvt_pk_bf16_f32 v168, v104, v105
	v_cvt_pk_bf16_f32 v169, v106, v107
	global_store_dwordx4 v[174:175], v[166:169], off
	s_nop 1
	v_cvt_pk_bf16_f32 v166, v44, v45
	v_cvt_pk_bf16_f32 v167, v46, v47
	v_cvt_pk_bf16_f32 v168, v40, v41
	v_cvt_pk_bf16_f32 v169, v42, v43
	global_store_dwordx4 v[174:175], v[166:169], off offset:256
	s_nop 1
	v_or_b32_e32 v166, 48, v176
	v_mad_i64_i32 v[166:167], s[28:29], v166, s76, v[170:171]
	v_lshl_add_u64 v[174:175], v[166:167], 0, v[172:173]
	v_cvt_pk_bf16_f32 v166, v100, v101
	v_cvt_pk_bf16_f32 v167, v102, v103
	v_cvt_pk_bf16_f32 v168, v96, v97
	v_cvt_pk_bf16_f32 v169, v98, v99
	global_store_dwordx4 v[174:175], v[166:169], off
	s_nop 1
	v_cvt_pk_bf16_f32 v166, v36, v37
	v_cvt_pk_bf16_f32 v167, v38, v39
	v_cvt_pk_bf16_f32 v168, v32, v33
	v_cvt_pk_bf16_f32 v169, v34, v35
	global_store_dwordx4 v[174:175], v[166:169], off offset:256
	s_nop 1
	v_add_u32_e32 v166, 0x80, v176
	v_mad_i64_i32 v[166:167], s[28:29], v166, s76, v[170:171]
	v_lshl_add_u64 v[174:175], v[166:167], 0, v[172:173]
	v_cvt_pk_bf16_f32 v166, v92, v93
	v_cvt_pk_bf16_f32 v167, v94, v95
	v_cvt_pk_bf16_f32 v168, v88, v89
	v_cvt_pk_bf16_f32 v169, v90, v91
	global_store_dwordx4 v[174:175], v[166:169], off
	s_nop 1
	v_cvt_pk_bf16_f32 v166, v28, v29
	v_cvt_pk_bf16_f32 v167, v30, v31
	v_cvt_pk_bf16_f32 v168, v24, v25
	v_cvt_pk_bf16_f32 v169, v26, v27
	global_store_dwordx4 v[174:175], v[166:169], off offset:256
	s_nop 1
	v_add_u32_e32 v166, 0x90, v176
;     DI void operator()(const f32x4 (&acc)[2][2][4][2], const Unit& u, int wr, int wc, int fr, int fq) const {
;         const int row0 = u.pm * BM + wr * 64 + fr, col0 = u.pn * BM + wc * 32 + 8 * fq;
; #pragma unroll
;         for (int ai = 0; ai < 2; ++ai)
; #pragma unroll
;             for (int m = 0; m < 4; ++m) { u16* rowp = O + (size_t)(row0 + ai * HALF + m * 16) * ldc + col0;
; #pragma unroll
;                 for (int bj = 0; bj < 2; ++bj) { const f32x4 v0 = acc[ai][bj][m][0], v1 = acc[ai][bj][m][1];
;                     uint4 w = {pack2(v0[0], v0[1]), pack2(v0[2], v0[3]), pack2(v1[0], v1[1]), pack2(v1[2], v1[3])}; *(uint4*)(rowp + bj * HALF) = w; } }
;         if (kmaxp) {
; #pragma unroll
;             for (int bj = 0; bj < 2; ++bj) {
;                 const int cb = u.pn * BM + bj * HALF + wc * 32;
;                 const bool isA = (cb >= 384 && cb < 768), isB = (cb >= 1408 && cb < 1664);
;                 if (isA || isB) {
;                     float mx = 0.f;
; #pragma unroll
;                     for (int ai = 0; ai < 2; ++ai)
; #pragma unroll
;                         for (int m = 0; m < 4; ++m) {
;                             const f32x4 a = acc[ai][bj][m][0], b = acc[ai][bj][m][1];
;                             float s0 = a[0] * a[0] + a[1] * a[1] + a[2] * a[2] + a[3] * a[3] + b[0] * b[0] + b[1] * b[1] + b[2] * b[2] + b[3] * b[3];
;                             s0 += __shfl_xor(s0, 16);
;                             s0 += __shfl_xor(s0, 32);
;                             mx = fmaxf(mx, s0);
;                         }
; #pragma unroll
;                     for (int o = 1; o <= 8; o <<= 1) mx = fmaxf(mx, __shfl_xor(mx, o));
;                     if ((threadIdx.x & 63) == 0) atomicMax((unsigned*)kmaxp + (isA ? ((cb - 384) >> 5) : (12 + ((cb - 1408) >> 5))), __float_as_uint(mx));
	v_mad_i64_i32 v[166:167], s[28:29], v166, s76, v[170:171]
	v_lshl_add_u64 v[174:175], v[166:167], 0, v[172:173]
	v_cvt_pk_bf16_f32 v166, v84, v85
	v_cvt_pk_bf16_f32 v167, v86, v87
	v_cvt_pk_bf16_f32 v168, v80, v81
	v_cvt_pk_bf16_f32 v169, v82, v83
	global_store_dwordx4 v[174:175], v[166:169], off
	s_nop 1
	v_cvt_pk_bf16_f32 v166, v20, v21
	v_cvt_pk_bf16_f32 v167, v22, v23
	v_cvt_pk_bf16_f32 v168, v16, v17
	v_cvt_pk_bf16_f32 v169, v18, v19
	global_store_dwordx4 v[174:175], v[166:169], off offset:256
	s_nop 1
	v_add_u32_e32 v166, 0xa0, v176
	v_mad_i64_i32 v[166:167], s[28:29], v166, s76, v[170:171]
	v_lshl_add_u64 v[174:175], v[166:167], 0, v[172:173]
	v_cvt_pk_bf16_f32 v166, v76, v77
	v_cvt_pk_bf16_f32 v167, v78, v79
	v_cvt_pk_bf16_f32 v168, v72, v73
	v_cvt_pk_bf16_f32 v169, v74, v75
	global_store_dwordx4 v[174:175], v[166:169], off
	s_nop 1
	v_cvt_pk_bf16_f32 v166, v12, v13
	v_cvt_pk_bf16_f32 v167, v14, v15
	v_cvt_pk_bf16_f32 v168, v8, v9
	v_cvt_pk_bf16_f32 v169, v10, v11
	global_store_dwordx4 v[174:175], v[166:169], off offset:256
	s_nop 1
	v_add_u32_e32 v166, 0xb0, v176
	v_mad_i64_i32 v[166:167], s[28:29], v166, s76, v[170:171]
	s_add_i32 s28, s52, 0xfffffe80
	s_cmpk_gt_u32 s28, 0x17f
	s_cselect_b64 s[28:29], -1, 0
	s_add_i32 s34, s52, 0xfffffa80
	s_cmpk_gt_u32 s34, 0xff
	s_cselect_b64 s[34:35], -1, 0
	v_lshl_add_u64 v[170:171], v[166:167], 0, v[172:173]
	v_cvt_pk_bf16_f32 v166, v68, v69
	v_cvt_pk_bf16_f32 v167, v70, v71
	v_cvt_pk_bf16_f32 v168, v64, v65
	v_cvt_pk_bf16_f32 v169, v66, v67
	s_and_b64 s[34:35], s[28:29], s[34:35]
	global_store_dwordx4 v[170:171], v[166:169], off
	s_and_b64 vcc, exec, s[34:35]
	s_nop 0
	v_cvt_pk_bf16_f32 v166, v4, v5
	v_cvt_pk_bf16_f32 v167, v6, v7
	v_cvt_pk_bf16_f32 v168, v0, v1
	v_cvt_pk_bf16_f32 v169, v2, v3
	global_store_dwordx4 v[170:171], v[166:169], off offset:256
	s_cbranch_vccnz .LBB0_150
	v_mul_f32_e32 v125, v125, v125
	v_mul_f32_e32 v117, v117, v117
	v_fmac_f32_e32 v125, v124, v124
	v_fmac_f32_e32 v117, v116, v116
	v_mul_f32_e32 v109, v109, v109
	v_mul_f32_e32 v101, v101, v101
	v_fmac_f32_e32 v125, v126, v126
	v_fmac_f32_e32 v117, v118, v118
	v_fmac_f32_e32 v109, v108, v108
	v_fmac_f32_e32 v101, v100, v100
	v_and_b32_e32 v167, 64, v165
	v_fmac_f32_e32 v125, v127, v127
	v_fmac_f32_e32 v117, v119, v119
	v_fmac_f32_e32 v109, v110, v110
	v_fmac_f32_e32 v101, v102, v102
	v_xor_b32_e32 v166, 16, v165
	v_add_u32_e32 v167, 64, v167
	v_fmac_f32_e32 v125, v120, v120
	v_fmac_f32_e32 v117, v112, v112
	v_fmac_f32_e32 v109, v111, v111
	v_fmac_f32_e32 v101, v103, v103
	v_cmp_lt_i32_e32 vcc, v166, v167
	v_fmac_f32_e32 v125, v121, v121
	v_fmac_f32_e32 v117, v113, v113
	v_fmac_f32_e32 v109, v104, v104
	v_fmac_f32_e32 v101, v96, v96
	v_cndmask_b32_e32 v166, v165, v166, vcc
	v_fmac_f32_e32 v125, v122, v122
	v_fmac_f32_e32 v117, v114, v114
	v_fmac_f32_e32 v109, v105, v105
	v_fmac_f32_e32 v101, v97, v97
	v_lshlrev_b32_e32 v166, 2, v166
	v_fmac_f32_e32 v125, v123, v123
	v_fmac_f32_e32 v117, v115, v115
	v_fmac_f32_e32 v109, v106, v106
	v_fmac_f32_e32 v101, v98, v98
	v_mul_f32_e32 v93, v93, v93
	v_mul_f32_e32 v85, v85, v85
	ds_bpermute_b32 v120, v166, v125
	ds_bpermute_b32 v112, v166, v117
	v_fmac_f32_e32 v109, v107, v107
	v_fmac_f32_e32 v101, v99, v99
	v_fmac_f32_e32 v93, v92, v92
	v_fmac_f32_e32 v85, v84, v84
	v_mul_f32_e32 v77, v77, v77
	v_mul_f32_e32 v69, v69, v69
	ds_bpermute_b32 v104, v166, v109
	ds_bpermute_b32 v96, v166, v101
	v_fmac_f32_e32 v93, v94, v94
	v_fmac_f32_e32 v85, v86, v86
	v_fmac_f32_e32 v77, v76, v76
	v_fmac_f32_e32 v69, v68, v68
	v_xor_b32_e32 v168, 32, v165
	v_fmac_f32_e32 v93, v95, v95
	v_fmac_f32_e32 v85, v87, v87
	v_fmac_f32_e32 v77, v78, v78
	v_fmac_f32_e32 v69, v70, v70
	v_cmp_lt_i32_e32 vcc, v168, v167
	v_fmac_f32_e32 v93, v88, v88
	v_fmac_f32_e32 v85, v80, v80
	v_fmac_f32_e32 v77, v79, v79
	v_fmac_f32_e32 v69, v71, v71
	v_cndmask_b32_e32 v113, v165, v168, vcc
	v_fmac_f32_e32 v93, v89, v89
	v_fmac_f32_e32 v85, v81, v81
	v_fmac_f32_e32 v77, v72, v72
	v_fmac_f32_e32 v69, v64, v64
	v_lshlrev_b32_e32 v113, 2, v113
	s_waitcnt lgkmcnt(0)
	v_add_f32_e32 v114, v125, v120
	v_add_f32_e32 v112, v117, v112
	v_fmac_f32_e32 v93, v90, v90
	v_fmac_f32_e32 v85, v82, v82
	v_fmac_f32_e32 v77, v73, v73
	v_fmac_f32_e32 v69, v65, v65
	ds_bpermute_b32 v115, v113, v114
	ds_bpermute_b32 v116, v113, v112
	v_add_f32_e32 v99, v109, v104
	v_add_f32_e32 v96, v101, v96
	v_fmac_f32_e32 v93, v91, v91
	v_fmac_f32_e32 v85, v83, v83
	v_fmac_f32_e32 v77, v74, v74
	v_fmac_f32_e32 v69, v66, v66
	ds_bpermute_b32 v100, v113, v99
	ds_bpermute_b32 v101, v113, v96
	ds_bpermute_b32 v88, v166, v93
	ds_bpermute_b32 v80, v166, v85
	v_fmac_f32_e32 v77, v75, v75
	v_fmac_f32_e32 v69, v67, v67
	ds_bpermute_b32 v72, v166, v77
	ds_bpermute_b32 v64, v166, v69
	s_waitcnt lgkmcnt(0)
	v_add_f32_e32 v97, v114, v115
	v_add_f32_e32 v98, v112, v116
	v_max3_f32 v89, v97, 0, v98
	v_add_f32_e32 v90, v99, v100
	v_add_f32_e32 v91, v96, v101
	v_add_f32_e32 v88, v93, v88
	v_add_f32_e32 v65, v85, v80
	v_max3_f32 v89, v89, v90, v91
	ds_bpermute_b32 v90, v113, v88
	ds_bpermute_b32 v66, v113, v65
	v_add_f32_e32 v67, v77, v72
	v_add_f32_e32 v64, v69, v64
	ds_bpermute_b32 v68, v113, v67
	ds_bpermute_b32 v69, v113, v64
	s_waitcnt lgkmcnt(0)
	v_add_f32_e32 v70, v88, v90
	v_add_f32_e32 v65, v65, v66
	v_max3_f32 v65, v89, v70, v65
	v_add_f32_e32 v66, v67, v68
	v_add_f32_e32 v64, v64, v69
	v_max3_f32 v64, v65, v66, v64
	v_xor_b32_e32 v65, 1, v165
	v_cmp_lt_i32_e32 vcc, v65, v167
	s_nop 1
	v_cndmask_b32_e32 v65, v165, v65, vcc
	v_lshlrev_b32_e32 v65, 2, v65
	ds_bpermute_b32 v65, v65, v64
	s_waitcnt lgkmcnt(0)
	v_max_f32_e32 v65, v65, v65
	v_max_f32_e32 v64, v64, v65
	v_xor_b32_e32 v65, 2, v165
	v_cmp_lt_i32_e32 vcc, v65, v167
	s_nop 1
	v_cndmask_b32_e32 v65, v165, v65, vcc
	v_lshlrev_b32_e32 v65, 2, v65
	ds_bpermute_b32 v65, v65, v64
	s_waitcnt lgkmcnt(0)
	v_max_f32_e32 v65, v65, v65
	v_max_f32_e32 v64, v64, v65
	v_xor_b32_e32 v65, 4, v165
	v_cmp_lt_i32_e32 vcc, v65, v167
	s_nop 1
	v_cndmask_b32_e32 v65, v165, v65, vcc
	v_lshlrev_b32_e32 v65, 2, v65
	ds_bpermute_b32 v65, v65, v64
	s_waitcnt lgkmcnt(0)
	v_max_f32_e32 v65, v65, v65
	v_max_f32_e32 v64, v64, v65
	v_xor_b32_e32 v65, 8, v165
	v_cmp_lt_i32_e32 vcc, v65, v167
	s_nop 1
	v_cndmask_b32_e32 v65, v165, v65, vcc
	v_lshlrev_b32_e32 v65, 2, v65
	ds_bpermute_b32 v65, v65, v64
	s_and_saveexec_b64 s[34:35], s[2:3]
	s_cbranch_execz .LBB0_149
	s_mov_b64 s[36:37], -1
	s_and_b64 vcc, exec, s[28:29]
	s_cbranch_vccz .LBB0_143
	s_add_i32 s28, s10, 0xfffffa80
	s_ashr_i32 s28, s28, 5
	s_add_i32 s28, s28, 12
	s_mov_b64 s[36:37], 0

; #define PG8_STAGE(bufoff, gbase, voff) do { _Pragma("unroll") for (int _i = 0; _i < 2; ++_i) \
;         __builtin_amdgcn_global_load_lds((const unsigned*)((const char*)(gbase) + (voff)[_i]), (PG8_LAS unsigned*)(lds + (bufoff) + ldsw + _i * 8192), 16, 0, 0); } while (0)
; #define PG8_LDA(dst, b, h) do { _Pragma("unroll") for (int m = 0; m < 4; ++m) _Pragma("unroll") for (int k = 0; k < 2; ++k) dst[m][k] = *(const PG8_LAS bf16x8*)(lds + PG8_SA(b, h) + aoff + m * 2048 + k * 1024); } while (0)
; #define PG8_LDB(dst, b, h) do { _Pragma("unroll") for (int n = 0; n < 2; ++n) _Pragma("unroll") for (int k = 0; k < 2; ++k) dst[n][k] = *(const PG8_LAS bf16x8*)(lds + PG8_SB(b, h) + boff + n * 2048 + k * 1024); } while (0)
; #define PG8_MMA(ai, bj, At, Bt) do { __builtin_amdgcn_s_setprio(1); _Pragma("unroll") for (int m = 0; m < 4; ++m) _Pragma("unroll") for (int n = 0; n < 2; ++n) _Pragma("unroll") for (int k = 0; k < 2; ++k) \
;         acc[ai][bj][m][n] = __builtin_amdgcn_mfma_f32_16x16x32_bf16(Bt[n][k], At[m][k], acc[ai][bj][m][n], 0, 0, 0); __builtin_amdgcn_s_setprio(0); } while (0)
; #define PG8_WAIT_V(n) asm volatile("s_waitcnt vmcnt(" #n ")" ::: "memory")
; #define PG8_WAIT_L(n) asm volatile("s_waitcnt lgkmcnt(" #n ")" ::: "memory")
; #define PG8_BAR __builtin_amdgcn_s_barrier()
; #define PG8_SCHED __builtin_amdgcn_sched_barrier(0)
; template <class Epi, class Sched, bool STAMP = false>
; __device__ __forceinline__ void gemm_phase(PG8_LAS unsigned char* lds, const Gemm g, const Sched& S, const Epi& E, unsigned long long* stamps) {
;     ...
;             PG8_LDB(B0, 0, 0); PG8_SCHED; PG8_LDA(At, 0, 0); PG8_STAGE(PG8_SA(1, 1), a1 + hstep, voffA);
;             PG8_WAIT_L(8); PG8_BAR; PG8_WAIT_L(0); PG8_MMA(0, 0, At, B0); PG8_BAR; PG8_SCHED;
;             PG8_LDB(B1, 0, 1); PG8_STAGE(PG8_SB(0, 0), b2, voffB);
;             PG8_BAR; PG8_WAIT_L(0); PG8_MMA(0, 1, At, B1); PG8_BAR;
;             PG8_LDA(At, 0, 1); PG8_STAGE(PG8_SA(0, 0), a2, voffA);
;             PG8_BAR; PG8_WAIT_L(0); PG8_MMA(1, 0, At, B0); PG8_BAR; PG8_SCHED;
;             PG8_STAGE(PG8_SB(0, 1), b2 + hstep, voffB);
;             PG8_WAIT_V(6); PG8_BAR; PG8_MMA(1, 1, At, B1); PG8_BAR;
.LBB0_312:
	ds_read_b128 v[170:173], v147
	ds_read_b128 v[174:177], v148
	ds_read_b128 v[178:181], v149
	ds_read_b128 v[182:185], v150
	s_add_u32 s58, s56, 0x100
	s_addc_u32 s59, s57, 0
	s_cmp_eq_u32 s96, 12
	s_cselect_b32 s63, s5, s59
	s_cselect_b32 s62, s4, s58
	s_cselect_b32 s61, s1, s95
	s_cselect_b32 s60, s0, s94
	s_mov_b32 m0, s84
	ds_read_b128 v[186:189], v145
	ds_read_b128 v[190:193], v145 offset:1024
	ds_read_b128 v[194:197], v145 offset:2048
	ds_read_b128 v[198:201], v145 offset:3072
	ds_read_b128 v[202:205], v145 offset:4096
	ds_read_b128 v[206:209], v145 offset:5120
	ds_read_b128 v[210:213], v145 offset:6144
	ds_read_b128 v[214:217], v145 offset:7168
	global_load_lds_dwordx4 v136, s[56:57]
	s_mov_b32 m0, s85
	s_nop 0
	global_load_lds_dwordx4 v138, s[56:57]
	s_waitcnt lgkmcnt(8)
	s_barrier
	s_waitcnt lgkmcnt(0)
	s_setprio 1
	s_waitcnt lgkmcnt(0)
	v_mfma_f32_16x16x32_bf16 v[124:127], v[170:173], v[186:189], v[124:127]
	v_mfma_f32_16x16x32_bf16 v[120:123], v[178:181], v[186:189], v[120:123]
	v_mfma_f32_16x16x32_bf16 v[116:119], v[170:173], v[194:197], v[116:119]
	v_mfma_f32_16x16x32_bf16 v[112:115], v[178:181], v[194:197], v[112:115]
	v_mfma_f32_16x16x32_bf16 v[100:103], v[170:173], v[202:205], v[100:103]
	v_mfma_f32_16x16x32_bf16 v[96:99], v[178:181], v[202:205], v[96:99]
	v_mfma_f32_16x16x32_bf16 v[84:87], v[170:173], v[210:213], v[84:87]
	v_mfma_f32_16x16x32_bf16 v[80:83], v[178:181], v[210:213], v[80:83]
	v_mfma_f32_16x16x32_bf16 v[124:127], v[174:177], v[190:193], v[124:127]
	v_mfma_f32_16x16x32_bf16 v[120:123], v[182:185], v[190:193], v[120:123]
	v_mfma_f32_16x16x32_bf16 v[116:119], v[174:177], v[198:201], v[116:119]
	v_mfma_f32_16x16x32_bf16 v[112:115], v[182:185], v[198:201], v[112:115]
	v_mfma_f32_16x16x32_bf16 v[100:103], v[174:177], v[206:209], v[100:103]
	v_mfma_f32_16x16x32_bf16 v[96:99], v[182:185], v[206:209], v[96:99]
	v_mfma_f32_16x16x32_bf16 v[84:87], v[174:177], v[214:217], v[84:87]
	v_mfma_f32_16x16x32_bf16 v[80:83], v[182:185], v[214:217], v[80:83]
	s_setprio 0
	s_barrier
	s_mov_b32 m0, s67
	ds_read_b128 v[218:221], v151
	ds_read_b128 v[222:225], v152
	ds_read_b128 v[226:229], v153
	ds_read_b128 v[230:233], v154
	global_load_lds_dwordx4 v130, s[60:61]
	s_mov_b32 m0, s68
	s_nop 0
	global_load_lds_dwordx4 v134, s[60:61]
	s_barrier
	s_waitcnt lgkmcnt(0)
	s_setprio 1
	s_waitcnt lgkmcnt(0)
	v_mfma_f32_16x16x32_bf16 v[108:111], v[218:221], v[186:189], v[108:111]
	v_mfma_f32_16x16x32_bf16 v[104:107], v[226:229], v[186:189], v[104:107]
	v_mfma_f32_16x16x32_bf16 v[92:95], v[218:221], v[194:197], v[92:95]
	v_mfma_f32_16x16x32_bf16 v[88:91], v[226:229], v[194:197], v[88:91]
	v_mfma_f32_16x16x32_bf16 v[76:79], v[218:221], v[202:205], v[76:79]
	v_mfma_f32_16x16x32_bf16 v[72:75], v[226:229], v[202:205], v[72:75]
	v_mfma_f32_16x16x32_bf16 v[68:71], v[218:221], v[210:213], v[68:71]
	v_mfma_f32_16x16x32_bf16 v[64:67], v[226:229], v[210:213], v[64:67]
	v_mfma_f32_16x16x32_bf16 v[108:111], v[222:225], v[190:193], v[108:111]
	v_mfma_f32_16x16x32_bf16 v[104:107], v[230:233], v[190:193], v[104:107]
	v_mfma_f32_16x16x32_bf16 v[92:95], v[222:225], v[198:201], v[92:95]
	v_mfma_f32_16x16x32_bf16 v[88:91], v[230:233], v[198:201], v[88:91]
	v_mfma_f32_16x16x32_bf16 v[76:79], v[222:225], v[206:209], v[76:79]
	v_mfma_f32_16x16x32_bf16 v[72:75], v[230:233], v[206:209], v[72:75]
	v_mfma_f32_16x16x32_bf16 v[68:71], v[222:225], v[214:217], v[68:71]
	v_mfma_f32_16x16x32_bf16 v[64:67], v[230:233], v[214:217], v[64:67]
	s_setprio 0
	s_mov_b32 m0, s66
	s_barrier
	ds_read_b128 v[186:189], v145 offset:16384
	ds_read_b128 v[190:193], v145 offset:17408
	ds_read_b128 v[194:197], v145 offset:18432
	ds_read_b128 v[198:201], v145 offset:19456
	ds_read_b128 v[202:205], v145 offset:20480
	ds_read_b128 v[206:209], v145 offset:21504
	ds_read_b128 v[210:213], v145 offset:22528
	ds_read_b128 v[214:217], v145 offset:23552
	global_load_lds_dwordx4 v128, s[62:63]
	s_mov_b32 m0, s69
	s_nop 0
	global_load_lds_dwordx4 v132, s[62:63]
	s_barrier
	s_waitcnt lgkmcnt(0)
	s_setprio 1
	s_waitcnt lgkmcnt(0)
	v_mfma_f32_16x16x32_bf16 v[60:63], v[170:173], v[186:189], v[60:63]
	v_mfma_f32_16x16x32_bf16 v[56:59], v[178:181], v[186:189], v[56:59]
	v_mfma_f32_16x16x32_bf16 v[52:55], v[170:173], v[194:197], v[52:55]
	v_mfma_f32_16x16x32_bf16 v[48:51], v[178:181], v[194:197], v[48:51]
	v_mfma_f32_16x16x32_bf16 v[36:39], v[170:173], v[202:205], v[36:39]
	v_mfma_f32_16x16x32_bf16 v[32:35], v[178:181], v[202:205], v[32:35]
	v_mfma_f32_16x16x32_bf16 v[20:23], v[170:173], v[210:213], v[20:23]
	v_mfma_f32_16x16x32_bf16 v[16:19], v[178:181], v[210:213], v[16:19]
	v_mfma_f32_16x16x32_bf16 v[60:63], v[174:177], v[190:193], v[60:63]
	v_mfma_f32_16x16x32_bf16 v[56:59], v[182:185], v[190:193], v[56:59]
	v_mfma_f32_16x16x32_bf16 v[52:55], v[174:177], v[198:201], v[52:55]
	v_mfma_f32_16x16x32_bf16 v[48:51], v[182:185], v[198:201], v[48:51]
	v_mfma_f32_16x16x32_bf16 v[36:39], v[174:177], v[206:209], v[36:39]
	v_mfma_f32_16x16x32_bf16 v[32:35], v[182:185], v[206:209], v[32:35]
	v_mfma_f32_16x16x32_bf16 v[20:23], v[174:177], v[214:217], v[20:23]
	v_mfma_f32_16x16x32_bf16 v[16:19], v[182:185], v[214:217], v[16:19]
	s_setprio 0
	s_barrier
	s_add_u32 s56, s60, 0x44000
	s_addc_u32 s57, s61, 0
	s_mov_b32 m0, s70
	s_nop 0
	global_load_lds_dwordx4 v130, s[56:57]
	s_mov_b32 m0, s71
	s_nop 0
	global_load_lds_dwordx4 v134, s[56:57]
	s_waitcnt vmcnt(6)
	s_barrier
; #define PG8_STAGE(bufoff, gbase, voff) do { _Pragma("unroll") for (int _i = 0; _i < 2; ++_i) \
;         __builtin_amdgcn_global_load_lds((const unsigned*)((const char*)(gbase) + (voff)[_i]), (PG8_LAS unsigned*)(lds + (bufoff) + ldsw + _i * 8192), 16, 0, 0); } while (0)
; #define PG8_LDA(dst, b, h) do { _Pragma("unroll") for (int m = 0; m < 4; ++m) _Pragma("unroll") for (int k = 0; k < 2; ++k) dst[m][k] = *(const PG8_LAS bf16x8*)(lds + PG8_SA(b, h) + aoff + m * 2048 + k * 1024); } while (0)
; #define PG8_LDB(dst, b, h) do { _Pragma("unroll") for (int n = 0; n < 2; ++n) _Pragma("unroll") for (int k = 0; k < 2; ++k) dst[n][k] = *(const PG8_LAS bf16x8*)(lds + PG8_SB(b, h) + boff + n * 2048 + k * 1024); } while (0)
; #define PG8_MMA(ai, bj, At, Bt) do { __builtin_amdgcn_s_setprio(1); _Pragma("unroll") for (int m = 0; m < 4; ++m) _Pragma("unroll") for (int n = 0; n < 2; ++n) _Pragma("unroll") for (int k = 0; k < 2; ++k) \
;         acc[ai][bj][m][n] = __builtin_amdgcn_mfma_f32_16x16x32_bf16(Bt[n][k], At[m][k], acc[ai][bj][m][n], 0, 0, 0); __builtin_amdgcn_s_setprio(0); } while (0)
; #define PG8_WAIT_V(n) asm volatile("s_waitcnt vmcnt(" #n ")" ::: "memory")
; #define PG8_WAIT_L(n) asm volatile("s_waitcnt lgkmcnt(" #n ")" ::: "memory")
; #define PG8_BAR __builtin_amdgcn_s_barrier()
; #define PG8_SCHED __builtin_amdgcn_sched_barrier(0)
; template <class Epi, class Sched, bool STAMP = false>
; __device__ __forceinline__ void gemm_phase(PG8_LAS unsigned char* lds, const Gemm g, const Sched& S, const Epi& E, unsigned long long* stamps) {
;     ...
;             PG8_WAIT_V(6); PG8_BAR; PG8_MMA(1, 1, At, B1); PG8_BAR;
;             PG8_LDB(B0, 1, 0); PG8_SCHED; PG8_LDA(At, 1, 0); PG8_STAGE(PG8_SA(0, 1), a2 + hstep, voffA);
;             PG8_WAIT_L(8); PG8_BAR; PG8_WAIT_L(0); PG8_MMA(0, 0, At, B0); PG8_BAR; PG8_SCHED;
;             PG8_LDB(B1, 1, 1); PG8_STAGE(PG8_SB(1, 0), b3, voffB);
;             PG8_BAR; PG8_WAIT_L(0); PG8_MMA(0, 1, At, B1); PG8_BAR;
;             PG8_LDA(At, 1, 1); PG8_STAGE(PG8_SA(1, 0), a3, voffA);
	s_setprio 1
	v_mfma_f32_16x16x32_bf16 v[44:47], v[218:221], v[186:189], v[44:47]
	v_mfma_f32_16x16x32_bf16 v[40:43], v[226:229], v[186:189], v[40:43]
	v_mfma_f32_16x16x32_bf16 v[28:31], v[218:221], v[194:197], v[28:31]
	v_mfma_f32_16x16x32_bf16 v[24:27], v[226:229], v[194:197], v[24:27]
	v_mfma_f32_16x16x32_bf16 v[12:15], v[218:221], v[202:205], v[12:15]
	v_mfma_f32_16x16x32_bf16 v[8:11], v[226:229], v[202:205], v[8:11]
	v_mfma_f32_16x16x32_bf16 v[4:7], v[218:221], v[210:213], v[4:7]
	v_mfma_f32_16x16x32_bf16 v[0:3], v[226:229], v[210:213], v[0:3]
	v_mfma_f32_16x16x32_bf16 v[44:47], v[222:225], v[190:193], v[44:47]
	v_mfma_f32_16x16x32_bf16 v[40:43], v[230:233], v[190:193], v[40:43]
	v_mfma_f32_16x16x32_bf16 v[28:31], v[222:225], v[198:201], v[28:31]
	v_mfma_f32_16x16x32_bf16 v[24:27], v[230:233], v[198:201], v[24:27]
	v_mfma_f32_16x16x32_bf16 v[12:15], v[222:225], v[206:209], v[12:15]
	v_mfma_f32_16x16x32_bf16 v[8:11], v[230:233], v[206:209], v[8:11]
	v_mfma_f32_16x16x32_bf16 v[4:7], v[222:225], v[214:217], v[4:7]
	v_mfma_f32_16x16x32_bf16 v[0:3], v[230:233], v[214:217], v[0:3]
	s_setprio 0
	s_barrier
	ds_read_b128 v[170:173], v155
	ds_read_b128 v[174:177], v156
	ds_read_b128 v[178:181], v157
	ds_read_b128 v[182:185], v165
	s_add_u32 s56, s62, 0x44000
	s_addc_u32 s57, s63, 0
	s_mov_b32 m0, s72
	ds_read_b128 v[186:189], v145 offset:32768
	ds_read_b128 v[190:193], v145 offset:33792
	ds_read_b128 v[194:197], v145 offset:34816
	ds_read_b128 v[198:201], v145 offset:35840
	ds_read_b128 v[202:205], v145 offset:36864
	ds_read_b128 v[206:209], v145 offset:37888
	ds_read_b128 v[210:213], v145 offset:38912
	ds_read_b128 v[214:217], v145 offset:39936
	global_load_lds_dwordx4 v128, s[56:57]
	s_mov_b32 m0, s73
	s_nop 0
	global_load_lds_dwordx4 v132, s[56:57]
	s_waitcnt lgkmcnt(8)
	s_barrier
	s_waitcnt lgkmcnt(0)
	s_setprio 1
	s_waitcnt lgkmcnt(0)
	v_mfma_f32_16x16x32_bf16 v[124:127], v[170:173], v[186:189], v[124:127]
	v_mfma_f32_16x16x32_bf16 v[120:123], v[178:181], v[186:189], v[120:123]
	v_mfma_f32_16x16x32_bf16 v[116:119], v[170:173], v[194:197], v[116:119]
	v_mfma_f32_16x16x32_bf16 v[112:115], v[178:181], v[194:197], v[112:115]
	v_mfma_f32_16x16x32_bf16 v[100:103], v[170:173], v[202:205], v[100:103]
	v_mfma_f32_16x16x32_bf16 v[96:99], v[178:181], v[202:205], v[96:99]
	v_mfma_f32_16x16x32_bf16 v[84:87], v[170:173], v[210:213], v[84:87]
	v_mfma_f32_16x16x32_bf16 v[80:83], v[178:181], v[210:213], v[80:83]
	v_mfma_f32_16x16x32_bf16 v[124:127], v[174:177], v[190:193], v[124:127]
	v_mfma_f32_16x16x32_bf16 v[120:123], v[182:185], v[190:193], v[120:123]
	v_mfma_f32_16x16x32_bf16 v[116:119], v[174:177], v[198:201], v[116:119]
	v_mfma_f32_16x16x32_bf16 v[112:115], v[182:185], v[198:201], v[112:115]
	v_mfma_f32_16x16x32_bf16 v[100:103], v[174:177], v[206:209], v[100:103]
	v_mfma_f32_16x16x32_bf16 v[96:99], v[182:185], v[206:209], v[96:99]
	v_mfma_f32_16x16x32_bf16 v[84:87], v[174:177], v[214:217], v[84:87]
	v_mfma_f32_16x16x32_bf16 v[80:83], v[182:185], v[214:217], v[80:83]
	s_setprio 0
	s_barrier
	s_mov_b32 m0, s74
	ds_read_b128 v[218:221], v166
	ds_read_b128 v[222:225], v167
	ds_read_b128 v[226:229], v168
	ds_read_b128 v[230:233], v169
	s_add_u32 s100, s60, 0x80
	s_addc_u32 s101, s61, 0
	global_load_lds_dwordx4 v130, s[100:101]
	s_mov_b32 m0, s75
	s_nop 0
	global_load_lds_dwordx4 v134, s[100:101]
	s_barrier
	s_waitcnt lgkmcnt(0)
	s_setprio 1
	s_waitcnt lgkmcnt(0)
	v_mfma_f32_16x16x32_bf16 v[108:111], v[218:221], v[186:189], v[108:111]
	v_mfma_f32_16x16x32_bf16 v[104:107], v[226:229], v[186:189], v[104:107]
	v_mfma_f32_16x16x32_bf16 v[92:95], v[218:221], v[194:197], v[92:95]
	v_mfma_f32_16x16x32_bf16 v[88:91], v[226:229], v[194:197], v[88:91]
	v_mfma_f32_16x16x32_bf16 v[76:79], v[218:221], v[202:205], v[76:79]
	v_mfma_f32_16x16x32_bf16 v[72:75], v[226:229], v[202:205], v[72:75]
	v_mfma_f32_16x16x32_bf16 v[68:71], v[218:221], v[210:213], v[68:71]
	v_mfma_f32_16x16x32_bf16 v[64:67], v[226:229], v[210:213], v[64:67]
	v_mfma_f32_16x16x32_bf16 v[108:111], v[222:225], v[190:193], v[108:111]
	v_mfma_f32_16x16x32_bf16 v[104:107], v[230:233], v[190:193], v[104:107]
	v_mfma_f32_16x16x32_bf16 v[92:95], v[222:225], v[198:201], v[92:95]
	v_mfma_f32_16x16x32_bf16 v[88:91], v[230:233], v[198:201], v[88:91]
	v_mfma_f32_16x16x32_bf16 v[76:79], v[222:225], v[206:209], v[76:79]
	v_mfma_f32_16x16x32_bf16 v[72:75], v[230:233], v[206:209], v[72:75]
	v_mfma_f32_16x16x32_bf16 v[68:71], v[222:225], v[214:217], v[68:71]
	v_mfma_f32_16x16x32_bf16 v[64:67], v[230:233], v[214:217], v[64:67]
	s_setprio 0
	s_mov_b32 m0, s76
	s_barrier
	ds_read_b128 v[186:189], v145 offset:49152
	ds_read_b128 v[190:193], v145 offset:50176
	ds_read_b128 v[194:197], v145 offset:51200
	ds_read_b128 v[198:201], v145 offset:52224
	ds_read_b128 v[202:205], v145 offset:53248
	ds_read_b128 v[206:209], v145 offset:54272
	ds_read_b128 v[210:213], v145 offset:55296
	ds_read_b128 v[214:217], v145 offset:56320
	s_add_u32 s100, s62, 0x80
	s_addc_u32 s101, s63, 0
	global_load_lds_dwordx4 v128, s[100:101]
	s_mov_b32 m0, s77
	s_nop 0
	global_load_lds_dwordx4 v132, s[100:101]
	s_barrier
; #define PG8_STAGE(bufoff, gbase, voff) do { _Pragma("unroll") for (int _i = 0; _i < 2; ++_i) \
;         __builtin_amdgcn_global_load_lds((const unsigned*)((const char*)(gbase) + (voff)[_i]), (PG8_LAS unsigned*)(lds + (bufoff) + ldsw + _i * 8192), 16, 0, 0); } while (0)
; #define PG8_MMA(ai, bj, At, Bt) do { __builtin_amdgcn_s_setprio(1); _Pragma("unroll") for (int m = 0; m < 4; ++m) _Pragma("unroll") for (int n = 0; n < 2; ++n) _Pragma("unroll") for (int k = 0; k < 2; ++k) \
;         acc[ai][bj][m][n] = __builtin_amdgcn_mfma_f32_16x16x32_bf16(Bt[n][k], At[m][k], acc[ai][bj][m][n], 0, 0, 0); __builtin_amdgcn_s_setprio(0); } while (0)
; #define PG8_WAIT_V(n) asm volatile("s_waitcnt vmcnt(" #n ")" ::: "memory")
; #define PG8_WAIT_L(n) asm volatile("s_waitcnt lgkmcnt(" #n ")" ::: "memory")
; #define PG8_BAR __builtin_amdgcn_s_barrier()
; #define PG8_SCHED __builtin_amdgcn_sched_barrier(0)
; template <class Epi, class Sched, bool STAMP = false>
; __device__ __forceinline__ void gemm_phase(PG8_LAS unsigned char* lds, const Gemm g, const Sched& S, const Epi& E, unsigned long long* stamps) {
;     ...
;             PG8_BAR; PG8_WAIT_L(0); PG8_MMA(1, 0, At, B0); PG8_BAR; PG8_SCHED;
;             PG8_STAGE(PG8_SB(1, 1), b3 + hstep, voffB);
;             PG8_WAIT_V(6); PG8_BAR; PG8_MMA(1, 1, At, B1); PG8_BAR;
;         }
	s_waitcnt lgkmcnt(0)
	s_setprio 1
	s_waitcnt lgkmcnt(0)
	v_mfma_f32_16x16x32_bf16 v[60:63], v[170:173], v[186:189], v[60:63]
	v_mfma_f32_16x16x32_bf16 v[56:59], v[178:181], v[186:189], v[56:59]
	v_mfma_f32_16x16x32_bf16 v[52:55], v[170:173], v[194:197], v[52:55]
	v_mfma_f32_16x16x32_bf16 v[48:51], v[178:181], v[194:197], v[48:51]
	v_mfma_f32_16x16x32_bf16 v[36:39], v[170:173], v[202:205], v[36:39]
	v_mfma_f32_16x16x32_bf16 v[32:35], v[178:181], v[202:205], v[32:35]
	v_mfma_f32_16x16x32_bf16 v[20:23], v[170:173], v[210:213], v[20:23]
	v_mfma_f32_16x16x32_bf16 v[16:19], v[178:181], v[210:213], v[16:19]
	v_mfma_f32_16x16x32_bf16 v[60:63], v[174:177], v[190:193], v[60:63]
	v_mfma_f32_16x16x32_bf16 v[56:59], v[182:185], v[190:193], v[56:59]
	v_mfma_f32_16x16x32_bf16 v[52:55], v[174:177], v[198:201], v[52:55]
	v_mfma_f32_16x16x32_bf16 v[48:51], v[182:185], v[198:201], v[48:51]
	v_mfma_f32_16x16x32_bf16 v[36:39], v[174:177], v[206:209], v[36:39]
	v_mfma_f32_16x16x32_bf16 v[32:35], v[182:185], v[206:209], v[32:35]
	v_mfma_f32_16x16x32_bf16 v[20:23], v[174:177], v[214:217], v[20:23]
	v_mfma_f32_16x16x32_bf16 v[16:19], v[182:185], v[214:217], v[16:19]
	s_setprio 0
	s_barrier
	s_add_u32 s56, s60, 0x44080
	s_addc_u32 s57, s61, 0
	s_mov_b32 m0, s78
	s_nop 0
	global_load_lds_dwordx4 v130, s[56:57]
	s_mov_b32 m0, s79
	s_nop 0
	global_load_lds_dwordx4 v134, s[56:57]
	s_waitcnt vmcnt(6)
	s_barrier
	s_setprio 1
	v_mfma_f32_16x16x32_bf16 v[44:47], v[218:221], v[186:189], v[44:47]
	v_mfma_f32_16x16x32_bf16 v[40:43], v[226:229], v[186:189], v[40:43]
	v_mfma_f32_16x16x32_bf16 v[28:31], v[218:221], v[194:197], v[28:31]
	v_mfma_f32_16x16x32_bf16 v[24:27], v[226:229], v[194:197], v[24:27]
	v_mfma_f32_16x16x32_bf16 v[12:15], v[218:221], v[202:205], v[12:15]
	v_mfma_f32_16x16x32_bf16 v[8:11], v[226:229], v[202:205], v[8:11]
	v_mfma_f32_16x16x32_bf16 v[4:7], v[218:221], v[210:213], v[4:7]
	v_mfma_f32_16x16x32_bf16 v[0:3], v[226:229], v[210:213], v[0:3]
	v_mfma_f32_16x16x32_bf16 v[44:47], v[222:225], v[190:193], v[44:47]
	v_mfma_f32_16x16x32_bf16 v[40:43], v[230:233], v[190:193], v[40:43]
	v_mfma_f32_16x16x32_bf16 v[28:31], v[222:225], v[198:201], v[28:31]
	v_mfma_f32_16x16x32_bf16 v[24:27], v[230:233], v[198:201], v[24:27]
	v_mfma_f32_16x16x32_bf16 v[12:15], v[222:225], v[206:209], v[12:15]
	v_mfma_f32_16x16x32_bf16 v[8:11], v[230:233], v[206:209], v[8:11]
	v_mfma_f32_16x16x32_bf16 v[4:7], v[222:225], v[214:217], v[4:7]
	v_mfma_f32_16x16x32_bf16 v[0:3], v[230:233], v[214:217], v[0:3]
	s_setprio 0
	s_add_i32 s96, s96, 2
	s_add_u32 s94, s94, 0x100
	s_addc_u32 s95, s95, 0
	s_cmp_gt_u32 s96, 13
	s_mov_b64 s[56:57], s[58:59]
	s_barrier
	s_cbranch_scc0 .LBB0_312
; #define PG8_WAIT_V(n) asm volatile("s_waitcnt vmcnt(" #n ")" ::: "memory")
; #define PG8_BAR __builtin_amdgcn_s_barrier()
;     DI void operator()(const f32x4 (&acc)[2][2][4][2], const Unit& u, int wr, int wc, int fr, int fq) const {
;         const int row0 = u.pm * BM + wr * 64 + fr, col0 = u.pn * BM + wc * 32 + 8 * fq;
; #pragma unroll
;         for (int ai = 0; ai < 2; ++ai)
; #pragma unroll
;             for (int m = 0; m < 4; ++m) { u16* rowp = O + (size_t)(row0 + ai * HALF + m * 16) * ldc + col0;
; #pragma unroll
;                 for (int bj = 0; bj < 2; ++bj) { const f32x4 v0 = acc[ai][bj][m][0], v1 = acc[ai][bj][m][1];
;                     uint4 w = {pack2(v0[0], v0[1]), pack2(v0[2], v0[3]), pack2(v1[0], v1[1]), pack2(v1[2], v1[3])}; *(uint4*)(rowp + bj * HALF) = w; } }
; template <class Epi, class Sched, bool STAMP = false>
; __device__ __forceinline__ void gemm_phase(PG8_LAS unsigned char* lds, const Gemm g, const Sched& S, const Epi& E, unsigned long long* stamps) {
;     ...
;         cur = nxt; cA = nA; cB = nB; ++ui;
;     }
;     PG8_WAIT_V(0);
;     if (wr == 0) PG8_BAR;
;     PG8_BAR;
	v_lshl_add_u32 v170, s90, 8, v144
	v_lshl_or_b32 v172, s93, 8, v146
	v_ashrrev_i32_e32 v171, 31, v170
	v_ashrrev_i32_e32 v173, 31, v172
	v_lshlrev_b64 v[174:175], 11, v[170:171]
	v_lshl_add_u64 v[174:175], s[14:15], 0, v[174:175]
	v_lshlrev_b64 v[172:173], 1, v[172:173]
	v_lshl_add_u64 v[174:175], v[174:175], 0, v[172:173]
	v_cvt_pk_bf16_f32 v60, v60, v61
	v_cvt_pk_bf16_f32 v61, v62, v63
	v_cvt_pk_bf16_f32 v62, v56, v57
	v_add_co_u32_e32 v56, vcc, s86, v174
	v_cvt_pk_bf16_f32 v68, v68, v69
	v_cvt_pk_bf16_f32 v69, v70, v71
	v_cvt_pk_bf16_f32 v70, v64, v65
	v_lshl_add_u64 v[64:65], v[174:175], 0, s[34:35]
	v_addc_co_u32_e32 v57, vcc, 0, v175, vcc
	v_cvt_pk_bf16_f32 v44, v44, v45
	v_cvt_pk_bf16_f32 v45, v46, v47
	v_cvt_pk_bf16_f32 v46, v40, v41
	v_cvt_pk_bf16_f32 v47, v42, v43
	v_cvt_pk_bf16_f32 v108, v108, v109
	v_cvt_pk_bf16_f32 v109, v110, v111
	v_cvt_pk_bf16_f32 v110, v104, v105
	v_or_b32_e32 v104, 16, v170
	global_store_dwordx4 v[64:65], v[44:47], off offset:256
	v_ashrrev_i32_e32 v105, 31, v104
	v_cvt_pk_bf16_f32 v92, v92, v93
	v_add_co_u32_e32 v46, vcc, s87, v174
	v_cvt_pk_bf16_f32 v93, v94, v95
	v_cvt_pk_bf16_f32 v94, v88, v89
	v_or_b32_e32 v88, 32, v170
	v_lshl_add_u64 v[44:45], v[174:175], 0, s[36:37]
	v_addc_co_u32_e32 v47, vcc, 0, v175, vcc
	v_cvt_pk_bf16_f32 v28, v28, v29
	v_cvt_pk_bf16_f32 v29, v30, v31
	v_cvt_pk_bf16_f32 v30, v24, v25
	v_cvt_pk_bf16_f32 v31, v26, v27
	v_lshlrev_b64 v[104:105], 11, v[104:105]
	v_ashrrev_i32_e32 v89, 31, v88
	v_cvt_pk_bf16_f32 v76, v76, v77
	v_cvt_pk_bf16_f32 v77, v78, v79
	v_cvt_pk_bf16_f32 v78, v72, v73
	v_or_b32_e32 v72, 48, v170
	global_store_dwordx4 v[44:45], v[28:31], off offset:256
	v_cvt_pk_bf16_f32 v111, v106, v107
	v_lshl_add_u64 v[104:105], s[14:15], 0, v[104:105]
	v_add_co_u32_e32 v30, vcc, s88, v174
	v_lshlrev_b64 v[88:89], 11, v[88:89]
	v_ashrrev_i32_e32 v73, 31, v72
	v_lshl_add_u64 v[28:29], v[174:175], 0, s[52:53]
	v_addc_co_u32_e32 v31, vcc, 0, v175, vcc
	v_cvt_pk_bf16_f32 v12, v12, v13
	v_cvt_pk_bf16_f32 v13, v14, v15
	v_cvt_pk_bf16_f32 v14, v8, v9
	v_cvt_pk_bf16_f32 v15, v10, v11
	global_store_dwordx4 v[174:175], v[108:111], off offset:256
	v_cvt_pk_bf16_f32 v95, v90, v91
	v_lshl_add_u64 v[88:89], s[14:15], 0, v[88:89]
	v_lshl_add_u64 v[108:109], v[104:105], 0, v[172:173]
	v_lshlrev_b64 v[72:73], 11, v[72:73]
	global_store_dwordx4 v[28:29], v[12:15], off offset:256
	global_store_dwordx4 v[108:109], v[92:95], off offset:256
	v_cvt_pk_bf16_f32 v79, v74, v75
	v_add_co_u32_e32 v14, vcc, s89, v174
	v_lshl_add_u64 v[92:93], v[88:89], 0, v[172:173]
	v_lshl_add_u64 v[72:73], s[14:15], 0, v[72:73]
	v_addc_co_u32_e32 v15, vcc, 0, v175, vcc
	v_cvt_pk_bf16_f32 v124, v124, v125
	v_cvt_pk_bf16_f32 v125, v126, v127
	v_cvt_pk_bf16_f32 v126, v120, v121
	v_cvt_pk_bf16_f32 v127, v122, v123
	v_cvt_pk_bf16_f32 v104, v116, v117
	v_cvt_pk_bf16_f32 v105, v118, v119
	v_cvt_pk_bf16_f32 v106, v112, v113
	v_cvt_pk_bf16_f32 v107, v114, v115
	v_cvt_pk_bf16_f32 v88, v100, v101
	v_cvt_pk_bf16_f32 v89, v102, v103
	v_cvt_pk_bf16_f32 v90, v96, v97
	v_cvt_pk_bf16_f32 v91, v98, v99
	global_store_dwordx4 v[92:93], v[76:79], off offset:256
	v_cvt_pk_bf16_f32 v74, v80, v81
	v_cvt_pk_bf16_f32 v75, v82, v83
	v_lshl_add_u64 v[76:77], v[72:73], 0, v[172:173]
	v_cvt_pk_bf16_f32 v72, v84, v85
	v_cvt_pk_bf16_f32 v73, v86, v87
	v_cvt_pk_bf16_f32 v71, v66, v67
	v_cvt_pk_bf16_f32 v63, v58, v59
	v_cvt_pk_bf16_f32 v40, v52, v53
	v_cvt_pk_bf16_f32 v41, v54, v55
	v_cvt_pk_bf16_f32 v42, v48, v49
	v_cvt_pk_bf16_f32 v43, v50, v51
	v_cvt_pk_bf16_f32 v24, v36, v37
	v_cvt_pk_bf16_f32 v25, v38, v39
	v_cvt_pk_bf16_f32 v26, v32, v33
	v_cvt_pk_bf16_f32 v27, v34, v35
	v_lshl_add_u64 v[12:13], v[174:175], 0, s[54:55]
	v_cvt_pk_bf16_f32 v8, v20, v21
	v_cvt_pk_bf16_f32 v9, v22, v23
	v_cvt_pk_bf16_f32 v10, v16, v17
	v_cvt_pk_bf16_f32 v11, v18, v19
	v_cvt_pk_bf16_f32 v4, v4, v5
	v_cvt_pk_bf16_f32 v5, v6, v7
	v_cvt_pk_bf16_f32 v6, v0, v1
	v_cvt_pk_bf16_f32 v7, v2, v3
	s_and_b64 vcc, exec, s[2:3]
	s_mov_b32 s93, s91
	s_mov_b32 s90, s92
	s_mov_b64 s[58:59], s[0:1]
	s_mov_b64 s[56:57], s[4:5]
	global_store_dwordx4 v[174:175], v[124:127], off
	global_store_dwordx4 v[108:109], v[104:107], off
	global_store_dwordx4 v[92:93], v[88:91], off
	global_store_dwordx4 v[76:77], v[72:75], off
	global_store_dwordx4 v[76:77], v[68:71], off offset:256
	global_store_dwordx4 v[56:57], v[60:63], off
	global_store_dwordx4 v[46:47], v[40:43], off
	global_store_dwordx4 v[30:31], v[24:27], off
	global_store_dwordx4 v[14:15], v[8:11], off
	global_store_dwordx4 v[12:13], v[4:7], off offset:256
	s_cbranch_vccz .LBB0_301
	s_waitcnt vmcnt(0)
	s_cmpk_gt_u32 s64, 0xff
	s_cbranch_scc1 .LBB0_316
	s_barrier

; #define PG8_STAGE(bufoff, gbase, voff) do { _Pragma("unroll") for (int _i = 0; _i < 2; ++_i) \
;         __builtin_amdgcn_global_load_lds((const unsigned*)((const char*)(gbase) + (voff)[_i]), (PG8_LAS unsigned*)(lds + (bufoff) + ldsw + _i * 8192), 16, 0, 0); } while (0)
; #define PG8_LDA(dst, b, h) do { _Pragma("unroll") for (int m = 0; m < 4; ++m) _Pragma("unroll") for (int k = 0; k < 2; ++k) dst[m][k] = *(const PG8_LAS bf16x8*)(lds + PG8_SA(b, h) + aoff + m * 2048 + k * 1024); } while (0)
; #define PG8_LDB(dst, b, h) do { _Pragma("unroll") for (int n = 0; n < 2; ++n) _Pragma("unroll") for (int k = 0; k < 2; ++k) dst[n][k] = *(const PG8_LAS bf16x8*)(lds + PG8_SB(b, h) + boff + n * 2048 + k * 1024); } while (0)
; #define PG8_MMA(ai, bj, At, Bt) do { __builtin_amdgcn_s_setprio(1); _Pragma("unroll") for (int m = 0; m < 4; ++m) _Pragma("unroll") for (int n = 0; n < 2; ++n) _Pragma("unroll") for (int k = 0; k < 2; ++k) \
;         acc[ai][bj][m][n] = __builtin_amdgcn_mfma_f32_16x16x32_bf16(Bt[n][k], At[m][k], acc[ai][bj][m][n], 0, 0, 0); __builtin_amdgcn_s_setprio(0); } while (0)
; #define PG8_WAIT_V(n) asm volatile("s_waitcnt vmcnt(" #n ")" ::: "memory")
; template <class Epi, class Sched, bool STAMP = false>
; __device__ __forceinline__ void gemm_phase(PG8_LAS unsigned char* lds, const Gemm g, const Sched& S, const Epi& E, unsigned long long* stamps) {
;     ...
;             const bool last = (t == nt - 2);
;             const char* a1 = cA + (size_t)(t + 1) * kstep;
;             const char* a2 = last ? nA : cA + (size_t)(t + 2) * kstep; const char* b2 = last ? nB : cB + (size_t)(t + 2) * kstep;
;             const char* a3 = a2 + kstep; const char* b3 = b2 + kstep;
;             if (last && has_next) S.a_ready(nxt);
;             PG8_LDB(B0, 0, 0); PG8_SCHED; PG8_LDA(At, 0, 0); PG8_STAGE(PG8_SA(1, 1), a1 + hstep, voffA);
;             PG8_WAIT_L(8); PG8_BAR; PG8_WAIT_L(0); PG8_MMA(0, 0, At, B0); PG8_BAR; PG8_SCHED;
;             PG8_LDB(B1, 0, 1); PG8_STAGE(PG8_SB(0, 0), b2, voffB);
;             PG8_BAR; PG8_WAIT_L(0); PG8_MMA(0, 1, At, B1); PG8_BAR;
;             PG8_LDA(At, 0, 1); PG8_STAGE(PG8_SA(0, 0), a2, voffA);
;             PG8_BAR; PG8_WAIT_L(0); PG8_MMA(1, 0, At, B0); PG8_BAR; PG8_SCHED;
;             PG8_STAGE(PG8_SB(0, 1), b2 + hstep, voffB);
;             PG8_WAIT_V(6); PG8_BAR; PG8_MMA(1, 1, At, B1); PG8_BAR;
.LBB0_351:
	ds_read_b128 v[140:143], v147
	ds_read_b128 v[170:173], v148
	ds_read_b128 v[174:177], v149
	ds_read_b128 v[178:181], v150
	s_add_u32 s36, s34, 0x100
	s_addc_u32 s37, s35, 0
	s_cmp_eq_u32 s89, 12
	s_cselect_b32 s55, s5, s37
	s_cselect_b32 s54, s4, s36
	s_cselect_b32 s53, s1, s88
	s_cselect_b32 s52, s0, s87
	s_mov_b32 m0, s78
	ds_read_b128 v[182:185], v145
	ds_read_b128 v[186:189], v145 offset:1024
	ds_read_b128 v[190:193], v145 offset:2048
	ds_read_b128 v[194:197], v145 offset:3072
	ds_read_b128 v[198:201], v145 offset:4096
	ds_read_b128 v[202:205], v145 offset:5120
	ds_read_b128 v[206:209], v145 offset:6144
	ds_read_b128 v[210:213], v145 offset:7168
	global_load_lds_dwordx4 v132, s[34:35]
	s_mov_b32 m0, s79
	s_nop 0
	global_load_lds_dwordx4 v134, s[34:35]
	s_waitcnt lgkmcnt(8)
	s_barrier
	s_waitcnt lgkmcnt(0)
	s_setprio 1
	s_waitcnt lgkmcnt(0)
	v_mfma_f32_16x16x32_bf16 v[124:127], v[140:143], v[182:185], v[124:127]
	v_mfma_f32_16x16x32_bf16 v[120:123], v[174:177], v[182:185], v[120:123]
	v_mfma_f32_16x16x32_bf16 v[108:111], v[140:143], v[190:193], v[108:111]
	v_mfma_f32_16x16x32_bf16 v[104:107], v[174:177], v[190:193], v[104:107]
	v_mfma_f32_16x16x32_bf16 v[92:95], v[140:143], v[198:201], v[92:95]
	v_mfma_f32_16x16x32_bf16 v[88:91], v[174:177], v[198:201], v[88:91]
	v_mfma_f32_16x16x32_bf16 v[76:79], v[140:143], v[206:209], v[76:79]
	v_mfma_f32_16x16x32_bf16 v[72:75], v[174:177], v[206:209], v[72:75]
	v_mfma_f32_16x16x32_bf16 v[124:127], v[170:173], v[186:189], v[124:127]
	v_mfma_f32_16x16x32_bf16 v[120:123], v[178:181], v[186:189], v[120:123]
	v_mfma_f32_16x16x32_bf16 v[108:111], v[170:173], v[194:197], v[108:111]
	v_mfma_f32_16x16x32_bf16 v[104:107], v[178:181], v[194:197], v[104:107]
	v_mfma_f32_16x16x32_bf16 v[92:95], v[170:173], v[202:205], v[92:95]
	v_mfma_f32_16x16x32_bf16 v[88:91], v[178:181], v[202:205], v[88:91]
	v_mfma_f32_16x16x32_bf16 v[76:79], v[170:173], v[210:213], v[76:79]
	v_mfma_f32_16x16x32_bf16 v[72:75], v[178:181], v[210:213], v[72:75]
	s_setprio 0
	s_barrier
	s_mov_b32 m0, s61
	ds_read_b128 v[214:217], v151
	ds_read_b128 v[218:221], v152
	ds_read_b128 v[222:225], v153
	ds_read_b128 v[226:229], v154
	global_load_lds_dwordx4 v130, s[52:53]
	s_mov_b32 m0, s62
	s_nop 0
	global_load_lds_dwordx4 v128, s[52:53]
	s_barrier
	s_waitcnt lgkmcnt(0)
	s_setprio 1
	s_waitcnt lgkmcnt(0)
	v_mfma_f32_16x16x32_bf16 v[116:119], v[214:217], v[182:185], v[116:119]
	v_mfma_f32_16x16x32_bf16 v[112:115], v[222:225], v[182:185], v[112:115]
	v_mfma_f32_16x16x32_bf16 v[100:103], v[214:217], v[190:193], v[100:103]
	v_mfma_f32_16x16x32_bf16 v[96:99], v[222:225], v[190:193], v[96:99]
	v_mfma_f32_16x16x32_bf16 v[84:87], v[214:217], v[198:201], v[84:87]
	v_mfma_f32_16x16x32_bf16 v[80:83], v[222:225], v[198:201], v[80:83]
	v_mfma_f32_16x16x32_bf16 v[68:71], v[214:217], v[206:209], v[68:71]
	v_mfma_f32_16x16x32_bf16 v[64:67], v[222:225], v[206:209], v[64:67]
	v_mfma_f32_16x16x32_bf16 v[116:119], v[218:221], v[186:189], v[116:119]
	v_mfma_f32_16x16x32_bf16 v[112:115], v[226:229], v[186:189], v[112:115]
	v_mfma_f32_16x16x32_bf16 v[100:103], v[218:221], v[194:197], v[100:103]
	v_mfma_f32_16x16x32_bf16 v[96:99], v[226:229], v[194:197], v[96:99]
	v_mfma_f32_16x16x32_bf16 v[84:87], v[218:221], v[202:205], v[84:87]
	v_mfma_f32_16x16x32_bf16 v[80:83], v[226:229], v[202:205], v[80:83]
	v_mfma_f32_16x16x32_bf16 v[68:71], v[218:221], v[210:213], v[68:71]
	v_mfma_f32_16x16x32_bf16 v[64:67], v[226:229], v[210:213], v[64:67]
	s_setprio 0
	s_mov_b32 m0, s58
	s_barrier
	ds_read_b128 v[182:185], v145 offset:16384
	ds_read_b128 v[186:189], v145 offset:17408
	ds_read_b128 v[190:193], v145 offset:18432
	ds_read_b128 v[194:197], v145 offset:19456
	ds_read_b128 v[198:201], v145 offset:20480
	ds_read_b128 v[202:205], v145 offset:21504
	ds_read_b128 v[206:209], v145 offset:22528
	ds_read_b128 v[210:213], v145 offset:23552
	global_load_lds_dwordx4 v130, s[54:55]
	s_mov_b32 m0, s63
	s_nop 0
	global_load_lds_dwordx4 v128, s[54:55]
	s_barrier
	s_waitcnt lgkmcnt(0)
	s_setprio 1
	s_waitcnt lgkmcnt(0)
	v_mfma_f32_16x16x32_bf16 v[60:63], v[140:143], v[182:185], v[60:63]
	v_mfma_f32_16x16x32_bf16 v[56:59], v[174:177], v[182:185], v[56:59]
	v_mfma_f32_16x16x32_bf16 v[44:47], v[140:143], v[190:193], v[44:47]
	v_mfma_f32_16x16x32_bf16 v[40:43], v[174:177], v[190:193], v[40:43]
	v_mfma_f32_16x16x32_bf16 v[28:31], v[140:143], v[198:201], v[28:31]
	v_mfma_f32_16x16x32_bf16 v[24:27], v[174:177], v[198:201], v[24:27]
	v_mfma_f32_16x16x32_bf16 v[12:15], v[140:143], v[206:209], v[12:15]
	v_mfma_f32_16x16x32_bf16 v[8:11], v[174:177], v[206:209], v[8:11]
	v_mfma_f32_16x16x32_bf16 v[60:63], v[170:173], v[186:189], v[60:63]
	v_mfma_f32_16x16x32_bf16 v[56:59], v[178:181], v[186:189], v[56:59]
	v_mfma_f32_16x16x32_bf16 v[44:47], v[170:173], v[194:197], v[44:47]
	v_mfma_f32_16x16x32_bf16 v[40:43], v[178:181], v[194:197], v[40:43]
	v_mfma_f32_16x16x32_bf16 v[28:31], v[170:173], v[202:205], v[28:31]
	v_mfma_f32_16x16x32_bf16 v[24:27], v[178:181], v[202:205], v[24:27]
	v_mfma_f32_16x16x32_bf16 v[12:15], v[170:173], v[210:213], v[12:15]
	v_mfma_f32_16x16x32_bf16 v[8:11], v[178:181], v[210:213], v[8:11]
	s_setprio 0
	s_barrier
	s_add_u32 s34, s52, 0x44000
	s_addc_u32 s35, s53, 0
	s_mov_b32 m0, s64
	s_nop 0
	global_load_lds_dwordx4 v130, s[34:35]
	s_mov_b32 m0, s65
	s_nop 0
	global_load_lds_dwordx4 v128, s[34:35]
	s_waitcnt vmcnt(6)
	s_barrier
; #define PG8_STAGE(bufoff, gbase, voff) do { _Pragma("unroll") for (int _i = 0; _i < 2; ++_i) \
;         __builtin_amdgcn_global_load_lds((const unsigned*)((const char*)(gbase) + (voff)[_i]), (PG8_LAS unsigned*)(lds + (bufoff) + ldsw + _i * 8192), 16, 0, 0); } while (0)
; #define PG8_LDA(dst, b, h) do { _Pragma("unroll") for (int m = 0; m < 4; ++m) _Pragma("unroll") for (int k = 0; k < 2; ++k) dst[m][k] = *(const PG8_LAS bf16x8*)(lds + PG8_SA(b, h) + aoff + m * 2048 + k * 1024); } while (0)
; #define PG8_LDB(dst, b, h) do { _Pragma("unroll") for (int n = 0; n < 2; ++n) _Pragma("unroll") for (int k = 0; k < 2; ++k) dst[n][k] = *(const PG8_LAS bf16x8*)(lds + PG8_SB(b, h) + boff + n * 2048 + k * 1024); } while (0)
; #define PG8_MMA(ai, bj, At, Bt) do { __builtin_amdgcn_s_setprio(1); _Pragma("unroll") for (int m = 0; m < 4; ++m) _Pragma("unroll") for (int n = 0; n < 2; ++n) _Pragma("unroll") for (int k = 0; k < 2; ++k) \
;         acc[ai][bj][m][n] = __builtin_amdgcn_mfma_f32_16x16x32_bf16(Bt[n][k], At[m][k], acc[ai][bj][m][n], 0, 0, 0); __builtin_amdgcn_s_setprio(0); } while (0)
; #define PG8_WAIT_V(n) asm volatile("s_waitcnt vmcnt(" #n ")" ::: "memory")
; #define PG8_WAIT_L(n) asm volatile("s_waitcnt lgkmcnt(" #n ")" ::: "memory")
; #define PG8_BAR __builtin_amdgcn_s_barrier()
; #define PG8_SCHED __builtin_amdgcn_sched_barrier(0)
; template <class Epi, class Sched, bool STAMP = false>
; __device__ __forceinline__ void gemm_phase(PG8_LAS unsigned char* lds, const Gemm g, const Sched& S, const Epi& E, unsigned long long* stamps) {
;     ...
;             PG8_WAIT_V(6); PG8_BAR; PG8_MMA(1, 1, At, B1); PG8_BAR;
;             PG8_LDB(B0, 1, 0); PG8_SCHED; PG8_LDA(At, 1, 0); PG8_STAGE(PG8_SA(0, 1), a2 + hstep, voffA);
;             PG8_WAIT_L(8); PG8_BAR; PG8_WAIT_L(0); PG8_MMA(0, 0, At, B0); PG8_BAR; PG8_SCHED;
;             PG8_LDB(B1, 1, 1); PG8_STAGE(PG8_SB(1, 0), b3, voffB);
;             PG8_BAR; PG8_WAIT_L(0); PG8_MMA(0, 1, At, B1); PG8_BAR;
;             PG8_LDA(At, 1, 1); PG8_STAGE(PG8_SA(1, 0), a3, voffA);
;             PG8_BAR; PG8_WAIT_L(0); PG8_MMA(1, 0, At, B0); PG8_BAR; PG8_SCHED;
	s_setprio 1
	v_mfma_f32_16x16x32_bf16 v[52:55], v[214:217], v[182:185], v[52:55]
	v_mfma_f32_16x16x32_bf16 v[48:51], v[222:225], v[182:185], v[48:51]
	v_mfma_f32_16x16x32_bf16 v[36:39], v[214:217], v[190:193], v[36:39]
	v_mfma_f32_16x16x32_bf16 v[32:35], v[222:225], v[190:193], v[32:35]
	v_mfma_f32_16x16x32_bf16 v[20:23], v[214:217], v[198:201], v[20:23]
	v_mfma_f32_16x16x32_bf16 v[16:19], v[222:225], v[198:201], v[16:19]
	v_mfma_f32_16x16x32_bf16 v[4:7], v[214:217], v[206:209], v[4:7]
	v_mfma_f32_16x16x32_bf16 v[0:3], v[222:225], v[206:209], v[0:3]
	v_mfma_f32_16x16x32_bf16 v[52:55], v[218:221], v[186:189], v[52:55]
	v_mfma_f32_16x16x32_bf16 v[48:51], v[226:229], v[186:189], v[48:51]
	v_mfma_f32_16x16x32_bf16 v[36:39], v[218:221], v[194:197], v[36:39]
	v_mfma_f32_16x16x32_bf16 v[32:35], v[226:229], v[194:197], v[32:35]
	v_mfma_f32_16x16x32_bf16 v[20:23], v[218:221], v[202:205], v[20:23]
	v_mfma_f32_16x16x32_bf16 v[16:19], v[226:229], v[202:205], v[16:19]
	v_mfma_f32_16x16x32_bf16 v[4:7], v[218:221], v[210:213], v[4:7]
	v_mfma_f32_16x16x32_bf16 v[0:3], v[226:229], v[210:213], v[0:3]
	s_setprio 0
	s_barrier
	ds_read_b128 v[140:143], v155
	ds_read_b128 v[170:173], v156
	ds_read_b128 v[174:177], v157
	ds_read_b128 v[178:181], v165
	s_add_u32 s34, s54, 0x44000
	s_addc_u32 s35, s55, 0
	s_mov_b32 m0, s66
	ds_read_b128 v[182:185], v145 offset:32768
	ds_read_b128 v[186:189], v145 offset:33792
	ds_read_b128 v[190:193], v145 offset:34816
	ds_read_b128 v[194:197], v145 offset:35840
	ds_read_b128 v[198:201], v145 offset:36864
	ds_read_b128 v[202:205], v145 offset:37888
	ds_read_b128 v[206:209], v145 offset:38912
	ds_read_b128 v[210:213], v145 offset:39936
	global_load_lds_dwordx4 v130, s[34:35]
	s_mov_b32 m0, s67
	s_nop 0
	global_load_lds_dwordx4 v128, s[34:35]
	s_waitcnt lgkmcnt(8)
	s_barrier
	s_waitcnt lgkmcnt(0)
	s_setprio 1
	s_waitcnt lgkmcnt(0)
	v_mfma_f32_16x16x32_bf16 v[124:127], v[140:143], v[182:185], v[124:127]
	v_mfma_f32_16x16x32_bf16 v[120:123], v[174:177], v[182:185], v[120:123]
	v_mfma_f32_16x16x32_bf16 v[108:111], v[140:143], v[190:193], v[108:111]
	v_mfma_f32_16x16x32_bf16 v[104:107], v[174:177], v[190:193], v[104:107]
	v_mfma_f32_16x16x32_bf16 v[92:95], v[140:143], v[198:201], v[92:95]
	v_mfma_f32_16x16x32_bf16 v[88:91], v[174:177], v[198:201], v[88:91]
	v_mfma_f32_16x16x32_bf16 v[76:79], v[140:143], v[206:209], v[76:79]
	v_mfma_f32_16x16x32_bf16 v[72:75], v[174:177], v[206:209], v[72:75]
	v_mfma_f32_16x16x32_bf16 v[124:127], v[170:173], v[186:189], v[124:127]
	v_mfma_f32_16x16x32_bf16 v[120:123], v[178:181], v[186:189], v[120:123]
	v_mfma_f32_16x16x32_bf16 v[108:111], v[170:173], v[194:197], v[108:111]
	v_mfma_f32_16x16x32_bf16 v[104:107], v[178:181], v[194:197], v[104:107]
	v_mfma_f32_16x16x32_bf16 v[92:95], v[170:173], v[202:205], v[92:95]
	v_mfma_f32_16x16x32_bf16 v[88:91], v[178:181], v[202:205], v[88:91]
	v_mfma_f32_16x16x32_bf16 v[76:79], v[170:173], v[210:213], v[76:79]
	v_mfma_f32_16x16x32_bf16 v[72:75], v[178:181], v[210:213], v[72:75]
	s_setprio 0
	s_barrier
	s_mov_b32 m0, s70
	ds_read_b128 v[214:217], v166
	ds_read_b128 v[218:221], v167
	ds_read_b128 v[222:225], v168
	ds_read_b128 v[226:229], v169
	s_add_u32 s100, s52, 0x80
	s_addc_u32 s101, s53, 0
	global_load_lds_dwordx4 v130, s[100:101]
	s_mov_b32 m0, s71
	s_nop 0
	global_load_lds_dwordx4 v128, s[100:101]
	s_barrier
	s_waitcnt lgkmcnt(0)
	s_setprio 1
	s_waitcnt lgkmcnt(0)
	v_mfma_f32_16x16x32_bf16 v[116:119], v[214:217], v[182:185], v[116:119]
	v_mfma_f32_16x16x32_bf16 v[112:115], v[222:225], v[182:185], v[112:115]
	v_mfma_f32_16x16x32_bf16 v[100:103], v[214:217], v[190:193], v[100:103]
	v_mfma_f32_16x16x32_bf16 v[96:99], v[222:225], v[190:193], v[96:99]
	v_mfma_f32_16x16x32_bf16 v[84:87], v[214:217], v[198:201], v[84:87]
	v_mfma_f32_16x16x32_bf16 v[80:83], v[222:225], v[198:201], v[80:83]
	v_mfma_f32_16x16x32_bf16 v[68:71], v[214:217], v[206:209], v[68:71]
	v_mfma_f32_16x16x32_bf16 v[64:67], v[222:225], v[206:209], v[64:67]
	v_mfma_f32_16x16x32_bf16 v[116:119], v[218:221], v[186:189], v[116:119]
	v_mfma_f32_16x16x32_bf16 v[112:115], v[226:229], v[186:189], v[112:115]
	v_mfma_f32_16x16x32_bf16 v[100:103], v[218:221], v[194:197], v[100:103]
	v_mfma_f32_16x16x32_bf16 v[96:99], v[226:229], v[194:197], v[96:99]
	v_mfma_f32_16x16x32_bf16 v[84:87], v[218:221], v[202:205], v[84:87]
	v_mfma_f32_16x16x32_bf16 v[80:83], v[226:229], v[202:205], v[80:83]
	v_mfma_f32_16x16x32_bf16 v[68:71], v[218:221], v[210:213], v[68:71]
	v_mfma_f32_16x16x32_bf16 v[64:67], v[226:229], v[210:213], v[64:67]
	s_setprio 0
	s_mov_b32 m0, s73
	s_barrier
	ds_read_b128 v[182:185], v145 offset:49152
	ds_read_b128 v[186:189], v145 offset:50176
	ds_read_b128 v[190:193], v145 offset:51200
	ds_read_b128 v[194:197], v145 offset:52224
	ds_read_b128 v[198:201], v145 offset:53248
	ds_read_b128 v[202:205], v145 offset:54272
	ds_read_b128 v[206:209], v145 offset:55296
	ds_read_b128 v[210:213], v145 offset:56320
	s_add_u32 s100, s54, 0x80
	s_addc_u32 s101, s55, 0
	global_load_lds_dwordx4 v130, s[100:101]
	s_mov_b32 m0, s74
	s_nop 0
	global_load_lds_dwordx4 v128, s[100:101]
	s_barrier
; DI float ex2(float x) { return __builtin_amdgcn_exp2f(x); }
; #define PG8_STAGE(bufoff, gbase, voff) do { _Pragma("unroll") for (int _i = 0; _i < 2; ++_i) \
;         __builtin_amdgcn_global_load_lds((const unsigned*)((const char*)(gbase) + (voff)[_i]), (PG8_LAS unsigned*)(lds + (bufoff) + ldsw + _i * 8192), 16, 0, 0); } while (0)
; #define PG8_MMA(ai, bj, At, Bt) do { __builtin_amdgcn_s_setprio(1); _Pragma("unroll") for (int m = 0; m < 4; ++m) _Pragma("unroll") for (int n = 0; n < 2; ++n) _Pragma("unroll") for (int k = 0; k < 2; ++k) \
;         acc[ai][bj][m][n] = __builtin_amdgcn_mfma_f32_16x16x32_bf16(Bt[n][k], At[m][k], acc[ai][bj][m][n], 0, 0, 0); __builtin_amdgcn_s_setprio(0); } while (0)
; #define PG8_WAIT_V(n) asm volatile("s_waitcnt vmcnt(" #n ")" ::: "memory")
; #define PG8_WAIT_L(n) asm volatile("s_waitcnt lgkmcnt(" #n ")" ::: "memory")
; #define PG8_BAR __builtin_amdgcn_s_barrier()
; #define PG8_SCHED __builtin_amdgcn_sched_barrier(0)
;     DI void operator()(const f32x4 (&acc)[2][2][4][2], const Unit& u, int wr, int wc, int fr, int fq) const {
;         const int row0 = u.pm * BM + wr * 64 + fr, hcol0 = ((u.pn * BM + wc * 32) >> 1) + 4 * fq;
; #pragma unroll
;         for (int ai = 0; ai < 2; ++ai)
; #pragma unroll
;             for (int m = 0; m < 4; ++m) { u16* rowp = O + (size_t)(row0 + ai * HALF + m * 16) * ldc + hcol0;
; #pragma unroll
;                 for (int bj = 0; bj < 2; ++bj) { const f32x4 g = acc[ai][bj][m][0], up = acc[ai][bj][m][1]; float r[4];
; #pragma unroll
;                     for (int j = 0; j < 4; ++j) r[j] = g[j] * up[j] * __builtin_amdgcn_rcpf(1.f + ex2(-LOG2E * g[j]));
;                     uint2 w = {pack2(r[0], r[1]), pack2(r[2], r[3])}; *(uint2*)(rowp + bj * (HALF / 2)) = w; } }
; template <class Epi, class Sched, bool STAMP = false>
; __device__ __forceinline__ void gemm_phase(PG8_LAS unsigned char* lds, const Gemm g, const Sched& S, const Epi& E, unsigned long long* stamps) {
;     ...
;             PG8_BAR; PG8_WAIT_L(0); PG8_MMA(1, 0, At, B0); PG8_BAR; PG8_SCHED;
;             PG8_STAGE(PG8_SB(1, 1), b3 + hstep, voffB);
;             PG8_WAIT_V(6); PG8_BAR; PG8_MMA(1, 1, At, B1); PG8_BAR;
;         }
	s_waitcnt lgkmcnt(0)
	s_setprio 1
	s_waitcnt lgkmcnt(0)
	v_mfma_f32_16x16x32_bf16 v[60:63], v[140:143], v[182:185], v[60:63]
	v_mfma_f32_16x16x32_bf16 v[56:59], v[174:177], v[182:185], v[56:59]
	v_mfma_f32_16x16x32_bf16 v[44:47], v[140:143], v[190:193], v[44:47]
	v_mfma_f32_16x16x32_bf16 v[40:43], v[174:177], v[190:193], v[40:43]
	v_mfma_f32_16x16x32_bf16 v[28:31], v[140:143], v[198:201], v[28:31]
	v_mfma_f32_16x16x32_bf16 v[24:27], v[174:177], v[198:201], v[24:27]
	v_mfma_f32_16x16x32_bf16 v[12:15], v[140:143], v[206:209], v[12:15]
	v_mfma_f32_16x16x32_bf16 v[8:11], v[174:177], v[206:209], v[8:11]
	v_mfma_f32_16x16x32_bf16 v[60:63], v[170:173], v[186:189], v[60:63]
	v_mfma_f32_16x16x32_bf16 v[56:59], v[178:181], v[186:189], v[56:59]
	v_mfma_f32_16x16x32_bf16 v[44:47], v[170:173], v[194:197], v[44:47]
	v_mfma_f32_16x16x32_bf16 v[40:43], v[178:181], v[194:197], v[40:43]
	v_mfma_f32_16x16x32_bf16 v[28:31], v[170:173], v[202:205], v[28:31]
	v_mfma_f32_16x16x32_bf16 v[24:27], v[178:181], v[202:205], v[24:27]
	v_mfma_f32_16x16x32_bf16 v[12:15], v[170:173], v[210:213], v[12:15]
	v_mfma_f32_16x16x32_bf16 v[8:11], v[178:181], v[210:213], v[8:11]
	s_setprio 0
	s_barrier
	s_add_u32 s34, s52, 0x44080
	s_addc_u32 s35, s53, 0
	s_mov_b32 m0, s75
	s_nop 0
	global_load_lds_dwordx4 v130, s[34:35]
	s_mov_b32 m0, s76
	s_nop 0
	global_load_lds_dwordx4 v128, s[34:35]
	s_waitcnt vmcnt(6)
	s_barrier
	s_setprio 1
	v_mfma_f32_16x16x32_bf16 v[52:55], v[214:217], v[182:185], v[52:55]
	v_mfma_f32_16x16x32_bf16 v[48:51], v[222:225], v[182:185], v[48:51]
	v_mfma_f32_16x16x32_bf16 v[36:39], v[214:217], v[190:193], v[36:39]
	v_mfma_f32_16x16x32_bf16 v[32:35], v[222:225], v[190:193], v[32:35]
	v_mfma_f32_16x16x32_bf16 v[20:23], v[214:217], v[198:201], v[20:23]
	v_mfma_f32_16x16x32_bf16 v[16:19], v[222:225], v[198:201], v[16:19]
	v_mfma_f32_16x16x32_bf16 v[4:7], v[214:217], v[206:209], v[4:7]
	v_mfma_f32_16x16x32_bf16 v[0:3], v[222:225], v[206:209], v[0:3]
	v_mfma_f32_16x16x32_bf16 v[52:55], v[218:221], v[186:189], v[52:55]
	v_mfma_f32_16x16x32_bf16 v[48:51], v[226:229], v[186:189], v[48:51]
	v_mfma_f32_16x16x32_bf16 v[36:39], v[218:221], v[194:197], v[36:39]
	v_mfma_f32_16x16x32_bf16 v[32:35], v[226:229], v[194:197], v[32:35]
	v_mfma_f32_16x16x32_bf16 v[20:23], v[218:221], v[202:205], v[20:23]
	v_mfma_f32_16x16x32_bf16 v[16:19], v[226:229], v[202:205], v[16:19]
	v_mfma_f32_16x16x32_bf16 v[4:7], v[218:221], v[210:213], v[4:7]
	v_mfma_f32_16x16x32_bf16 v[0:3], v[226:229], v[210:213], v[0:3]
	s_setprio 0
	s_add_i32 s89, s89, 2
	s_add_u32 s87, s87, 0x100
	s_addc_u32 s88, s88, 0
	s_cmp_gt_u32 s89, 13
	s_mov_b64 s[34:35], s[36:37]
	s_barrier
	s_cbranch_scc0 .LBB0_351
	v_mul_f32_e32 v171, 0xbfb8aa3b, v124
	v_exp_f32_e32 v171, v171
	v_mul_f32_e32 v174, 0xbfb8aa3b, v125
	v_exp_f32_e32 v175, v174
	s_lshl_b32 s10, s86, 8
	v_add_f32_e32 v171, 1.0, v171
	v_rcp_f32_e32 v174, v171
	v_add_f32_e32 v171, 1.0, v175
	v_mul_f32_e32 v175, 0xbfb8aa3b, v126
	v_exp_f32_e32 v176, v175
	v_mul_f32_e32 v175, 0xbfb8aa3b, v127
	v_exp_f32_e32 v177, v175
	v_rcp_f32_e32 v175, v171
	v_add_f32_e32 v171, 1.0, v176
	v_rcp_f32_e32 v176, v171
	v_add_f32_e32 v171, 1.0, v177
	v_rcp_f32_e32 v177, v171
	v_pk_mul_f32 v[122:123], v[126:127], v[122:123]
	v_pk_mul_f32 v[120:121], v[124:125], v[120:121]
	s_or_b32 s10, s10, s69
	v_pk_mul_f32 v[120:121], v[120:121], v[174:175]
	v_pk_mul_f32 v[122:123], v[122:123], v[176:177]
	s_ashr_i32 s10, s10, 1
	v_cvt_pk_bf16_f32 v120, v120, v121
	v_cvt_pk_bf16_f32 v121, v122, v123
	v_mul_f32_e32 v122, 0xbfb8aa3b, v116
	v_mul_f32_e32 v123, 0xbfb8aa3b, v117
	v_or_b32_e32 v140, s10, v146
	v_exp_f32_e32 v122, v122
	v_exp_f32_e32 v123, v123
	v_lshl_add_u32 v170, s85, 8, v144
	v_ashrrev_i32_e32 v141, 31, v140
	v_mov_b64_e32 v[142:143], s[12:13]
	v_mad_i64_i32 v[172:173], s[34:35], v170, s82, v[142:143]
	v_lshlrev_b64 v[140:141], 1, v[140:141]
	v_lshl_add_u64 v[172:173], v[172:173], 0, v[140:141]
	global_store_dwordx2 v[172:173], v[120:121], off
	v_add_f32_e32 v120, 1.0, v122
	v_add_f32_e32 v121, 1.0, v123
	v_mul_f32_e32 v122, 0xbfb8aa3b, v118
	v_mul_f32_e32 v123, 0xbfb8aa3b, v119
	v_exp_f32_e32 v122, v122
	v_exp_f32_e32 v123, v123
	v_rcp_f32_e32 v120, v120
	v_rcp_f32_e32 v121, v121
	v_add_f32_e32 v122, 1.0, v122
	v_add_f32_e32 v123, 1.0, v123
	v_rcp_f32_e32 v122, v122
	v_rcp_f32_e32 v123, v123
	v_pk_mul_f32 v[114:115], v[118:119], v[114:115]
	v_pk_mul_f32 v[112:113], v[116:117], v[112:113]
	v_mul_f32_e32 v116, 0xbfb8aa3b, v110
	v_pk_mul_f32 v[112:113], v[112:113], v[120:121]
	v_pk_mul_f32 v[114:115], v[114:115], v[122:123]
	v_cvt_pk_bf16_f32 v112, v112, v113
	v_cvt_pk_bf16_f32 v113, v114, v115
	v_mul_f32_e32 v114, 0xbfb8aa3b, v108
	v_mul_f32_e32 v115, 0xbfb8aa3b, v109
	v_mul_f32_e32 v117, 0xbfb8aa3b, v111
	v_exp_f32_e32 v114, v114
	v_exp_f32_e32 v115, v115
	v_exp_f32_e32 v116, v116
	v_exp_f32_e32 v117, v117
	v_add_f32_e32 v114, 1.0, v114
	v_add_f32_e32 v115, 1.0, v115
	v_add_f32_e32 v116, 1.0, v116
	v_add_f32_e32 v117, 1.0, v117
	v_rcp_f32_e32 v114, v114
	v_rcp_f32_e32 v115, v115
	v_rcp_f32_e32 v116, v116
	v_rcp_f32_e32 v117, v117
	v_pk_mul_f32 v[106:107], v[110:111], v[106:107]
	v_pk_mul_f32 v[104:105], v[108:109], v[104:105]
	global_store_dwordx2 v[172:173], v[112:113], off offset:128
	v_pk_mul_f32 v[104:105], v[104:105], v[114:115]
	v_pk_mul_f32 v[106:107], v[106:107], v[116:117]
	v_cvt_pk_bf16_f32 v104, v104, v105
	v_cvt_pk_bf16_f32 v105, v106, v107
	v_mul_f32_e32 v106, 0xbfb8aa3b, v100
	v_mul_f32_e32 v107, 0xbfb8aa3b, v101
	v_exp_f32_e32 v106, v106
	v_exp_f32_e32 v107, v107
	v_or_b32_e32 v112, 16, v170
	v_mad_i64_i32 v[112:113], s[34:35], v112, s82, v[142:143]
; DI float ex2(float x) { return __builtin_amdgcn_exp2f(x); }
;     DI void operator()(const f32x4 (&acc)[2][2][4][2], const Unit& u, int wr, int wc, int fr, int fq) const {
;         const int row0 = u.pm * BM + wr * 64 + fr, hcol0 = ((u.pn * BM + wc * 32) >> 1) + 4 * fq;
; #pragma unroll
;         for (int ai = 0; ai < 2; ++ai)
; #pragma unroll
;             for (int m = 0; m < 4; ++m) { u16* rowp = O + (size_t)(row0 + ai * HALF + m * 16) * ldc + hcol0;
; #pragma unroll
;                 for (int bj = 0; bj < 2; ++bj) { const f32x4 g = acc[ai][bj][m][0], up = acc[ai][bj][m][1]; float r[4];
; #pragma unroll
;                     for (int j = 0; j < 4; ++j) r[j] = g[j] * up[j] * __builtin_amdgcn_rcpf(1.f + ex2(-LOG2E * g[j]));
;                     uint2 w = {pack2(r[0], r[1]), pack2(r[2], r[3])}; *(uint2*)(rowp + bj * (HALF / 2)) = w; } }
	v_lshl_add_u64 v[112:113], v[112:113], 0, v[140:141]
	global_store_dwordx2 v[112:113], v[104:105], off
	v_add_f32_e32 v104, 1.0, v106
	v_add_f32_e32 v105, 1.0, v107
	v_mul_f32_e32 v106, 0xbfb8aa3b, v102
	v_mul_f32_e32 v107, 0xbfb8aa3b, v103
	v_exp_f32_e32 v106, v106
	v_exp_f32_e32 v107, v107
	v_rcp_f32_e32 v104, v104
	v_rcp_f32_e32 v105, v105
	v_add_f32_e32 v106, 1.0, v106
	v_add_f32_e32 v107, 1.0, v107
	v_rcp_f32_e32 v106, v106
	v_rcp_f32_e32 v107, v107
	v_pk_mul_f32 v[98:99], v[102:103], v[98:99]
	v_pk_mul_f32 v[96:97], v[100:101], v[96:97]
	v_mul_f32_e32 v100, 0xbfb8aa3b, v94
	v_pk_mul_f32 v[96:97], v[96:97], v[104:105]
	v_pk_mul_f32 v[98:99], v[98:99], v[106:107]
	v_cvt_pk_bf16_f32 v96, v96, v97
	v_cvt_pk_bf16_f32 v97, v98, v99
	v_mul_f32_e32 v98, 0xbfb8aa3b, v92
	v_mul_f32_e32 v99, 0xbfb8aa3b, v93
	v_mul_f32_e32 v101, 0xbfb8aa3b, v95
	v_exp_f32_e32 v98, v98
	v_exp_f32_e32 v99, v99
	v_exp_f32_e32 v100, v100
	v_exp_f32_e32 v101, v101
	v_add_f32_e32 v98, 1.0, v98
	v_add_f32_e32 v99, 1.0, v99
	v_add_f32_e32 v100, 1.0, v100
	v_add_f32_e32 v101, 1.0, v101
	v_rcp_f32_e32 v98, v98
	v_rcp_f32_e32 v99, v99
	v_rcp_f32_e32 v100, v100
	v_rcp_f32_e32 v101, v101
	v_pk_mul_f32 v[90:91], v[94:95], v[90:91]
	v_pk_mul_f32 v[88:89], v[92:93], v[88:89]
	global_store_dwordx2 v[112:113], v[96:97], off offset:128
	v_pk_mul_f32 v[88:89], v[88:89], v[98:99]
	v_pk_mul_f32 v[90:91], v[90:91], v[100:101]
	v_cvt_pk_bf16_f32 v88, v88, v89
	v_cvt_pk_bf16_f32 v89, v90, v91
	v_mul_f32_e32 v90, 0xbfb8aa3b, v84
	v_mul_f32_e32 v91, 0xbfb8aa3b, v85
	v_exp_f32_e32 v90, v90
	v_exp_f32_e32 v91, v91
	v_or_b32_e32 v96, 32, v170
	v_mad_i64_i32 v[96:97], s[34:35], v96, s82, v[142:143]
	v_lshl_add_u64 v[96:97], v[96:97], 0, v[140:141]
	global_store_dwordx2 v[96:97], v[88:89], off
	v_add_f32_e32 v88, 1.0, v90
	v_add_f32_e32 v89, 1.0, v91
	v_mul_f32_e32 v90, 0xbfb8aa3b, v86
	v_mul_f32_e32 v91, 0xbfb8aa3b, v87
	v_exp_f32_e32 v90, v90
	v_exp_f32_e32 v91, v91
	v_rcp_f32_e32 v88, v88
	v_rcp_f32_e32 v89, v89
	v_add_f32_e32 v90, 1.0, v90
	v_add_f32_e32 v91, 1.0, v91
	v_rcp_f32_e32 v90, v90
	v_rcp_f32_e32 v91, v91
	v_pk_mul_f32 v[82:83], v[86:87], v[82:83]
	v_pk_mul_f32 v[80:81], v[84:85], v[80:81]
	v_mul_f32_e32 v84, 0xbfb8aa3b, v78
	v_pk_mul_f32 v[80:81], v[80:81], v[88:89]
	v_pk_mul_f32 v[82:83], v[82:83], v[90:91]
	v_cvt_pk_bf16_f32 v80, v80, v81
	v_cvt_pk_bf16_f32 v81, v82, v83
	v_mul_f32_e32 v82, 0xbfb8aa3b, v76
	v_mul_f32_e32 v83, 0xbfb8aa3b, v77
	v_mul_f32_e32 v85, 0xbfb8aa3b, v79
	v_exp_f32_e32 v82, v82
	v_exp_f32_e32 v83, v83
	v_exp_f32_e32 v84, v84
	v_exp_f32_e32 v85, v85
	v_add_f32_e32 v82, 1.0, v82
	v_add_f32_e32 v83, 1.0, v83
	v_add_f32_e32 v84, 1.0, v84
	v_add_f32_e32 v85, 1.0, v85
	v_rcp_f32_e32 v82, v82
	v_rcp_f32_e32 v83, v83
	v_rcp_f32_e32 v84, v84
	v_rcp_f32_e32 v85, v85
	v_pk_mul_f32 v[74:75], v[78:79], v[74:75]
	v_pk_mul_f32 v[72:73], v[76:77], v[72:73]
	global_store_dwordx2 v[96:97], v[80:81], off offset:128
	v_pk_mul_f32 v[72:73], v[72:73], v[82:83]
	v_pk_mul_f32 v[74:75], v[74:75], v[84:85]
	v_cvt_pk_bf16_f32 v72, v72, v73
	v_cvt_pk_bf16_f32 v73, v74, v75
	v_mul_f32_e32 v74, 0xbfb8aa3b, v68
	v_mul_f32_e32 v75, 0xbfb8aa3b, v69
	v_exp_f32_e32 v74, v74
	v_exp_f32_e32 v75, v75
	v_or_b32_e32 v80, 48, v170
	v_mad_i64_i32 v[80:81], s[34:35], v80, s82, v[142:143]
	v_lshl_add_u64 v[80:81], v[80:81], 0, v[140:141]
	global_store_dwordx2 v[80:81], v[72:73], off
	v_add_f32_e32 v72, 1.0, v74
	v_add_f32_e32 v73, 1.0, v75
	v_mul_f32_e32 v74, 0xbfb8aa3b, v70
	v_mul_f32_e32 v75, 0xbfb8aa3b, v71
	v_exp_f32_e32 v74, v74
	v_exp_f32_e32 v75, v75
	v_rcp_f32_e32 v72, v72
	v_rcp_f32_e32 v73, v73
	v_add_f32_e32 v74, 1.0, v74
	v_add_f32_e32 v75, 1.0, v75
	v_rcp_f32_e32 v74, v74
	v_rcp_f32_e32 v75, v75
	v_pk_mul_f32 v[66:67], v[70:71], v[66:67]
	v_pk_mul_f32 v[64:65], v[68:69], v[64:65]
	v_mul_f32_e32 v68, 0xbfb8aa3b, v62
	v_pk_mul_f32 v[64:65], v[64:65], v[72:73]
	v_pk_mul_f32 v[66:67], v[66:67], v[74:75]
	v_cvt_pk_bf16_f32 v64, v64, v65
	v_cvt_pk_bf16_f32 v65, v66, v67
	v_mul_f32_e32 v66, 0xbfb8aa3b, v60
	v_mul_f32_e32 v67, 0xbfb8aa3b, v61
	v_mul_f32_e32 v69, 0xbfb8aa3b, v63
	v_exp_f32_e32 v66, v66
	v_exp_f32_e32 v67, v67
	v_exp_f32_e32 v68, v68
	v_exp_f32_e32 v69, v69
	v_add_f32_e32 v66, 1.0, v66
	v_add_f32_e32 v67, 1.0, v67
	v_add_f32_e32 v68, 1.0, v68
	v_add_f32_e32 v69, 1.0, v69
	v_rcp_f32_e32 v66, v66
	v_rcp_f32_e32 v67, v67
	v_rcp_f32_e32 v68, v68
	v_rcp_f32_e32 v69, v69
	v_pk_mul_f32 v[58:59], v[62:63], v[58:59]
	v_pk_mul_f32 v[56:57], v[60:61], v[56:57]
	global_store_dwordx2 v[80:81], v[64:65], off offset:128
	v_pk_mul_f32 v[56:57], v[56:57], v[66:67]
	v_pk_mul_f32 v[58:59], v[58:59], v[68:69]
	v_cvt_pk_bf16_f32 v56, v56, v57
	v_cvt_pk_bf16_f32 v57, v58, v59
	v_mul_f32_e32 v58, 0xbfb8aa3b, v52
	v_mul_f32_e32 v59, 0xbfb8aa3b, v53
	v_exp_f32_e32 v58, v58
	v_exp_f32_e32 v59, v59
	v_add_u32_e32 v64, 0x80, v170
	v_mad_i64_i32 v[64:65], s[34:35], v64, s82, v[142:143]
	v_lshl_add_u64 v[64:65], v[64:65], 0, v[140:141]
	global_store_dwordx2 v[64:65], v[56:57], off
	v_add_f32_e32 v56, 1.0, v58
	v_add_f32_e32 v57, 1.0, v59
	v_mul_f32_e32 v58, 0xbfb8aa3b, v54
	v_mul_f32_e32 v59, 0xbfb8aa3b, v55
	v_exp_f32_e32 v58, v58
	v_exp_f32_e32 v59, v59
	v_rcp_f32_e32 v56, v56
	v_rcp_f32_e32 v57, v57
	v_add_f32_e32 v58, 1.0, v58
	v_add_f32_e32 v59, 1.0, v59
	v_rcp_f32_e32 v58, v58
	v_rcp_f32_e32 v59, v59
	v_pk_mul_f32 v[50:51], v[54:55], v[50:51]
	v_pk_mul_f32 v[48:49], v[52:53], v[48:49]
	v_mul_f32_e32 v52, 0xbfb8aa3b, v46
	v_pk_mul_f32 v[48:49], v[48:49], v[56:57]
	v_pk_mul_f32 v[50:51], v[50:51], v[58:59]
	v_cvt_pk_bf16_f32 v48, v48, v49
	v_cvt_pk_bf16_f32 v49, v50, v51
	v_mul_f32_e32 v50, 0xbfb8aa3b, v44
; DI float ex2(float x) { return __builtin_amdgcn_exp2f(x); }
; #define PG8_STAMP() do { if (STAMP && wid == 0 && nts < 64) { const unsigned long long _c = 0ull; \
;         ts_lo = (lane == nts) ? (int)(unsigned)_c : ts_lo; ts_hi = (lane == nts) ? (int)(unsigned)(_c >> 32) : ts_hi; ++nts; } } while (0)
;     DI void operator()(const f32x4 (&acc)[2][2][4][2], const Unit& u, int wr, int wc, int fr, int fq) const {
;         const int row0 = u.pm * BM + wr * 64 + fr, hcol0 = ((u.pn * BM + wc * 32) >> 1) + 4 * fq;
; #pragma unroll
;         for (int ai = 0; ai < 2; ++ai)
; #pragma unroll
;             for (int m = 0; m < 4; ++m) { u16* rowp = O + (size_t)(row0 + ai * HALF + m * 16) * ldc + hcol0;
; #pragma unroll
;                 for (int bj = 0; bj < 2; ++bj) { const f32x4 g = acc[ai][bj][m][0], up = acc[ai][bj][m][1]; float r[4];
; #pragma unroll
;                     for (int j = 0; j < 4; ++j) r[j] = g[j] * up[j] * __builtin_amdgcn_rcpf(1.f + ex2(-LOG2E * g[j]));
;                     uint2 w = {pack2(r[0], r[1]), pack2(r[2], r[3])}; *(uint2*)(rowp + bj * (HALF / 2)) = w; } }
; template <class Epi, class Sched, bool STAMP = false>
; __device__ __forceinline__ void gemm_phase(PG8_LAS unsigned char* lds, const Gemm g, const Sched& S, const Epi& E, unsigned long long* stamps) {
;     ...
;         if constexpr (!Epi::AFTER_DRAIN) { E(acc, cur, wr, wc, fr, fq); S.done(cur); }
;         PG8_STAMP();
;         if (!has_next) break;
; #pragma unroll
;         for (int a = 0; a < 2; ++a)
	v_mul_f32_e32 v51, 0xbfb8aa3b, v45
	v_mul_f32_e32 v53, 0xbfb8aa3b, v47
	v_exp_f32_e32 v50, v50
	v_exp_f32_e32 v51, v51
	v_exp_f32_e32 v52, v52
	v_exp_f32_e32 v53, v53
	v_add_f32_e32 v50, 1.0, v50
	v_add_f32_e32 v51, 1.0, v51
	v_add_f32_e32 v52, 1.0, v52
	v_add_f32_e32 v53, 1.0, v53
	v_rcp_f32_e32 v50, v50
	v_rcp_f32_e32 v51, v51
	v_rcp_f32_e32 v52, v52
	v_rcp_f32_e32 v53, v53
	v_pk_mul_f32 v[42:43], v[46:47], v[42:43]
	v_pk_mul_f32 v[40:41], v[44:45], v[40:41]
	global_store_dwordx2 v[64:65], v[48:49], off offset:128
	v_pk_mul_f32 v[40:41], v[40:41], v[50:51]
	v_pk_mul_f32 v[42:43], v[42:43], v[52:53]
	v_cvt_pk_bf16_f32 v40, v40, v41
	v_cvt_pk_bf16_f32 v41, v42, v43
	v_mul_f32_e32 v42, 0xbfb8aa3b, v36
	v_mul_f32_e32 v43, 0xbfb8aa3b, v37
	v_exp_f32_e32 v42, v42
	v_exp_f32_e32 v43, v43
	v_add_u32_e32 v48, 0x90, v170
	v_mad_i64_i32 v[48:49], s[34:35], v48, s82, v[142:143]
	v_lshl_add_u64 v[48:49], v[48:49], 0, v[140:141]
	global_store_dwordx2 v[48:49], v[40:41], off
	v_add_f32_e32 v40, 1.0, v42
	v_add_f32_e32 v41, 1.0, v43
	v_mul_f32_e32 v42, 0xbfb8aa3b, v38
	v_mul_f32_e32 v43, 0xbfb8aa3b, v39
	v_exp_f32_e32 v42, v42
	v_exp_f32_e32 v43, v43
	v_rcp_f32_e32 v40, v40
	v_rcp_f32_e32 v41, v41
	v_add_f32_e32 v42, 1.0, v42
	v_add_f32_e32 v43, 1.0, v43
	v_rcp_f32_e32 v42, v42
	v_rcp_f32_e32 v43, v43
	v_pk_mul_f32 v[34:35], v[38:39], v[34:35]
	v_pk_mul_f32 v[32:33], v[36:37], v[32:33]
	v_mul_f32_e32 v36, 0xbfb8aa3b, v30
	v_pk_mul_f32 v[32:33], v[32:33], v[40:41]
	v_pk_mul_f32 v[34:35], v[34:35], v[42:43]
	v_cvt_pk_bf16_f32 v32, v32, v33
	v_cvt_pk_bf16_f32 v33, v34, v35
	v_mul_f32_e32 v34, 0xbfb8aa3b, v28
	v_mul_f32_e32 v35, 0xbfb8aa3b, v29
	v_mul_f32_e32 v37, 0xbfb8aa3b, v31
	v_exp_f32_e32 v34, v34
	v_exp_f32_e32 v35, v35
	v_exp_f32_e32 v36, v36
	v_exp_f32_e32 v37, v37
	v_add_f32_e32 v34, 1.0, v34
	v_add_f32_e32 v35, 1.0, v35
	v_add_f32_e32 v36, 1.0, v36
	v_add_f32_e32 v37, 1.0, v37
	v_rcp_f32_e32 v34, v34
	v_rcp_f32_e32 v35, v35
	v_rcp_f32_e32 v36, v36
	v_rcp_f32_e32 v37, v37
	v_pk_mul_f32 v[26:27], v[30:31], v[26:27]
	v_pk_mul_f32 v[24:25], v[28:29], v[24:25]
	global_store_dwordx2 v[48:49], v[32:33], off offset:128
	v_pk_mul_f32 v[24:25], v[24:25], v[34:35]
	v_pk_mul_f32 v[26:27], v[26:27], v[36:37]
	v_cvt_pk_bf16_f32 v24, v24, v25
	v_cvt_pk_bf16_f32 v25, v26, v27
	v_mul_f32_e32 v26, 0xbfb8aa3b, v20
	v_mul_f32_e32 v27, 0xbfb8aa3b, v21
	v_exp_f32_e32 v26, v26
	v_exp_f32_e32 v27, v27
	v_add_u32_e32 v32, 0xa0, v170
	v_mad_i64_i32 v[32:33], s[34:35], v32, s82, v[142:143]
	v_lshl_add_u64 v[32:33], v[32:33], 0, v[140:141]
	global_store_dwordx2 v[32:33], v[24:25], off
	v_add_f32_e32 v24, 1.0, v26
	v_add_f32_e32 v25, 1.0, v27
	v_mul_f32_e32 v26, 0xbfb8aa3b, v22
	v_mul_f32_e32 v27, 0xbfb8aa3b, v23
	v_exp_f32_e32 v26, v26
	v_exp_f32_e32 v27, v27
	v_rcp_f32_e32 v24, v24
	v_rcp_f32_e32 v25, v25
	v_add_f32_e32 v26, 1.0, v26
	v_add_f32_e32 v27, 1.0, v27
	v_rcp_f32_e32 v26, v26
	v_rcp_f32_e32 v27, v27
	v_pk_mul_f32 v[18:19], v[22:23], v[18:19]
	v_pk_mul_f32 v[16:17], v[20:21], v[16:17]
	v_mul_f32_e32 v20, 0xbfb8aa3b, v14
	v_pk_mul_f32 v[16:17], v[16:17], v[24:25]
	v_pk_mul_f32 v[18:19], v[18:19], v[26:27]
	v_cvt_pk_bf16_f32 v16, v16, v17
	v_cvt_pk_bf16_f32 v17, v18, v19
	v_mul_f32_e32 v18, 0xbfb8aa3b, v12
	v_mul_f32_e32 v19, 0xbfb8aa3b, v13
	v_mul_f32_e32 v21, 0xbfb8aa3b, v15
	v_exp_f32_e32 v18, v18
	v_exp_f32_e32 v19, v19
	v_exp_f32_e32 v20, v20
	v_exp_f32_e32 v21, v21
	v_add_f32_e32 v18, 1.0, v18
	v_add_f32_e32 v19, 1.0, v19
	v_add_f32_e32 v20, 1.0, v20
	v_add_f32_e32 v21, 1.0, v21
	v_rcp_f32_e32 v18, v18
	v_rcp_f32_e32 v19, v19
	v_rcp_f32_e32 v20, v20
	v_rcp_f32_e32 v21, v21
	v_pk_mul_f32 v[10:11], v[14:15], v[10:11]
	v_pk_mul_f32 v[8:9], v[12:13], v[8:9]
	global_store_dwordx2 v[32:33], v[16:17], off offset:128
	v_pk_mul_f32 v[8:9], v[8:9], v[18:19]
	v_pk_mul_f32 v[10:11], v[10:11], v[20:21]
	v_cvt_pk_bf16_f32 v8, v8, v9
	v_cvt_pk_bf16_f32 v9, v10, v11
	v_mul_f32_e32 v10, 0xbfb8aa3b, v4
	v_mul_f32_e32 v11, 0xbfb8aa3b, v5
	v_exp_f32_e32 v10, v10
	v_exp_f32_e32 v11, v11
	v_add_u32_e32 v16, 0xb0, v170
	v_mad_i64_i32 v[16:17], s[34:35], v16, s82, v[142:143]
	v_lshl_add_u64 v[16:17], v[16:17], 0, v[140:141]
	global_store_dwordx2 v[16:17], v[8:9], off
	v_add_f32_e32 v8, 1.0, v10
	v_add_f32_e32 v9, 1.0, v11
	v_mul_f32_e32 v10, 0xbfb8aa3b, v6
	v_mul_f32_e32 v11, 0xbfb8aa3b, v7
	v_exp_f32_e32 v10, v10
	v_exp_f32_e32 v11, v11
	v_rcp_f32_e32 v8, v8
	v_rcp_f32_e32 v9, v9
	v_add_f32_e32 v10, 1.0, v10
	v_add_f32_e32 v11, 1.0, v11
	v_rcp_f32_e32 v10, v10
	v_rcp_f32_e32 v11, v11
	v_pk_mul_f32 v[2:3], v[6:7], v[2:3]
	v_pk_mul_f32 v[0:1], v[4:5], v[0:1]
	s_and_b64 vcc, exec, s[2:3]
	v_pk_mul_f32 v[0:1], v[0:1], v[8:9]
	v_pk_mul_f32 v[2:3], v[2:3], v[10:11]
	v_cvt_pk_bf16_f32 v0, v0, v1
	v_cvt_pk_bf16_f32 v1, v2, v3
	s_mov_b32 s86, s83
	s_mov_b32 s85, s84
	s_mov_b64 s[36:37], s[0:1]
	s_mov_b64 s[34:35], s[4:5]
	global_store_dwordx2 v[16:17], v[0:1], off offset:128
	s_cbranch_vccz .LBB0_344
	s_branch .Lgu2_done
; #define PG8_STAGE(bufoff, gbase, voff) do { _Pragma("unroll") for (int _i = 0; _i < 2; ++_i) \
;         __builtin_amdgcn_global_load_lds((const unsigned*)((const char*)(gbase) + (voff)[_i]), (PG8_LAS unsigned*)(lds + (bufoff) + ldsw + _i * 8192), 16, 0, 0); } while (0)
; #define PG8_LDA(dst, b, h) do { _Pragma("unroll") for (int m = 0; m < 4; ++m) _Pragma("unroll") for (int k = 0; k < 2; ++k) dst[m][k] = *(const PG8_LAS bf16x8*)(lds + PG8_SA(b, h) + aoff + m * 2048 + k * 1024); } while (0)
; #define PG8_LDB(dst, b, h) do { _Pragma("unroll") for (int n = 0; n < 2; ++n) _Pragma("unroll") for (int k = 0; k < 2; ++k) dst[n][k] = *(const PG8_LAS bf16x8*)(lds + PG8_SB(b, h) + boff + n * 2048 + k * 1024); } while (0)
; #define PG8_WAIT_V(n) asm volatile("s_waitcnt vmcnt(" #n ")" ::: "memory")
; #define PG8_WAIT_L(n) asm volatile("s_waitcnt lgkmcnt(" #n ")" ::: "memory")
; #define PG8_BAR __builtin_amdgcn_s_barrier()
; #define PG8_SCHED __builtin_amdgcn_sched_barrier(0)
; template <class Epi, class Sched, bool STAMP = false>
; __device__ __forceinline__ void gemm_phase(PG8_LAS unsigned char* lds, const Gemm g, const Sched& S, const Epi& E, unsigned long long* stamps) {
;     ...
;             const bool last = (t == nt - 2);
;             const char* a1 = cA + (size_t)(t + 1) * kstep;
;             const char* a2 = last ? nA : cA + (size_t)(t + 2) * kstep; const char* b2 = last ? nB : cB + (size_t)(t + 2) * kstep;
;             const char* a3 = a2 + kstep; const char* b3 = b2 + kstep;
;             if (last && has_next) S.a_ready(nxt);
;             PG8_LDB(B0, 0, 0); PG8_SCHED; PG8_LDA(At, 0, 0); PG8_STAGE(PG8_SA(1, 1), a1 + hstep, voffA);
;             PG8_WAIT_L(8); PG8_BAR; PG8_WAIT_L(0); PG8_MMA(0, 0, At, B0); PG8_BAR; PG8_SCHED;
;             PG8_LDB(B1, 0, 1); PG8_STAGE(PG8_SB(0, 0), b2, voffB);
;             PG8_BAR; PG8_WAIT_L(0); PG8_MMA(0, 1, At, B1); PG8_BAR;
;             PG8_LDA(At, 0, 1); PG8_STAGE(PG8_SA(0, 0), a2, voffA);
;             PG8_BAR; PG8_WAIT_L(0); PG8_MMA(1, 0, At, B0); PG8_BAR; PG8_SCHED;
;             PG8_STAGE(PG8_SB(0, 1), b2 + hstep, voffB);
;             PG8_WAIT_V(6); PG8_BAR; PG8_MMA(1, 1, At, B1); PG8_BAR;
;             PG8_LDB(B0, 1, 0); PG8_SCHED; PG8_LDA(At, 1, 0); PG8_STAGE(PG8_SA(0, 1), a2 + hstep, voffA);
;             PG8_WAIT_L(8); PG8_BAR; PG8_WAIT_L(0); PG8_MMA(0, 0, At, B0); PG8_BAR; PG8_SCHED;
.Lgu2_half_loop:
	ds_read_b128 v[140:143], v147
	ds_read_b128 v[170:173], v148
	ds_read_b128 v[174:177], v149
	ds_read_b128 v[178:181], v150
	s_add_u32 s36, s34, 0x100
	s_addc_u32 s37, s35, 0
	s_cmp_eq_u32 s89, 12
	s_cselect_b32 s55, s5, s37
	s_cselect_b32 s54, s4, s36
	s_cselect_b32 s53, s1, s88
	s_cselect_b32 s52, s0, s87
	s_mov_b32 m0, s78
	ds_read_b128 v[182:185], v145
	ds_read_b128 v[186:189], v145 offset:1024
	ds_read_b128 v[190:193], v145 offset:2048
	ds_read_b128 v[194:197], v145 offset:3072
	ds_read_b128 v[198:201], v145 offset:4096
	ds_read_b128 v[202:205], v145 offset:5120
	ds_read_b128 v[206:209], v145 offset:6144
	ds_read_b128 v[210:213], v145 offset:7168
	global_load_lds_dwordx4 v132, s[34:35]
	s_mov_b32 m0, s79
	s_nop 0
	global_load_lds_dwordx4 v134, s[34:35]
	s_waitcnt lgkmcnt(8)
	s_barrier
	s_waitcnt lgkmcnt(0)
	s_setprio 1
	s_waitcnt lgkmcnt(0)
	v_mfma_f32_16x16x32_bf16 v[124:127], v[140:143], v[182:185], v[124:127]
	v_mfma_f32_16x16x32_bf16 v[120:123], v[174:177], v[182:185], v[120:123]
	v_mfma_f32_16x16x32_bf16 v[108:111], v[140:143], v[190:193], v[108:111]
	v_mfma_f32_16x16x32_bf16 v[104:107], v[174:177], v[190:193], v[104:107]
	v_mfma_f32_16x16x32_bf16 v[92:95], v[140:143], v[198:201], v[92:95]
	v_mfma_f32_16x16x32_bf16 v[88:91], v[174:177], v[198:201], v[88:91]
	v_mfma_f32_16x16x32_bf16 v[76:79], v[140:143], v[206:209], v[76:79]
	v_mfma_f32_16x16x32_bf16 v[72:75], v[174:177], v[206:209], v[72:75]
	v_mfma_f32_16x16x32_bf16 v[124:127], v[170:173], v[186:189], v[124:127]
	v_mfma_f32_16x16x32_bf16 v[120:123], v[178:181], v[186:189], v[120:123]
	v_mfma_f32_16x16x32_bf16 v[108:111], v[170:173], v[194:197], v[108:111]
	v_mfma_f32_16x16x32_bf16 v[104:107], v[178:181], v[194:197], v[104:107]
	v_mfma_f32_16x16x32_bf16 v[92:95], v[170:173], v[202:205], v[92:95]
	v_mfma_f32_16x16x32_bf16 v[88:91], v[178:181], v[202:205], v[88:91]
	v_mfma_f32_16x16x32_bf16 v[76:79], v[170:173], v[210:213], v[76:79]
	v_mfma_f32_16x16x32_bf16 v[72:75], v[178:181], v[210:213], v[72:75]
	s_setprio 0
	s_barrier
	s_mov_b32 m0, s61
	s_nop 0
	global_load_lds_dwordx4 v130, s[52:53]
	s_mov_b32 m0, s62
	s_nop 0
	global_load_lds_dwordx4 v128, s[52:53]
	s_barrier
	s_waitcnt lgkmcnt(0)
	s_setprio 1
	s_waitcnt lgkmcnt(0)
	s_setprio 0
	s_mov_b32 m0, s58
	s_barrier
	ds_read_b128 v[182:185], v145 offset:16384
	ds_read_b128 v[186:189], v145 offset:17408
	ds_read_b128 v[190:193], v145 offset:18432
	ds_read_b128 v[194:197], v145 offset:19456
	ds_read_b128 v[198:201], v145 offset:20480
	ds_read_b128 v[202:205], v145 offset:21504
	ds_read_b128 v[206:209], v145 offset:22528
	ds_read_b128 v[210:213], v145 offset:23552
	global_load_lds_dwordx4 v130, s[54:55]
	s_mov_b32 m0, s63
	s_nop 0
	global_load_lds_dwordx4 v128, s[54:55]
	s_barrier
	s_waitcnt lgkmcnt(0)
	s_setprio 1
	s_waitcnt lgkmcnt(0)
	v_mfma_f32_16x16x32_bf16 v[60:63], v[140:143], v[182:185], v[60:63]
	v_mfma_f32_16x16x32_bf16 v[56:59], v[174:177], v[182:185], v[56:59]
	v_mfma_f32_16x16x32_bf16 v[44:47], v[140:143], v[190:193], v[44:47]
	v_mfma_f32_16x16x32_bf16 v[40:43], v[174:177], v[190:193], v[40:43]
	v_mfma_f32_16x16x32_bf16 v[28:31], v[140:143], v[198:201], v[28:31]
	v_mfma_f32_16x16x32_bf16 v[24:27], v[174:177], v[198:201], v[24:27]
	v_mfma_f32_16x16x32_bf16 v[12:15], v[140:143], v[206:209], v[12:15]
	v_mfma_f32_16x16x32_bf16 v[8:11], v[174:177], v[206:209], v[8:11]
	v_mfma_f32_16x16x32_bf16 v[60:63], v[170:173], v[186:189], v[60:63]
	v_mfma_f32_16x16x32_bf16 v[56:59], v[178:181], v[186:189], v[56:59]
	v_mfma_f32_16x16x32_bf16 v[44:47], v[170:173], v[194:197], v[44:47]
	v_mfma_f32_16x16x32_bf16 v[40:43], v[178:181], v[194:197], v[40:43]
	v_mfma_f32_16x16x32_bf16 v[28:31], v[170:173], v[202:205], v[28:31]
	v_mfma_f32_16x16x32_bf16 v[24:27], v[178:181], v[202:205], v[24:27]
	v_mfma_f32_16x16x32_bf16 v[12:15], v[170:173], v[210:213], v[12:15]
	v_mfma_f32_16x16x32_bf16 v[8:11], v[178:181], v[210:213], v[8:11]
	s_setprio 0
	s_barrier
	s_add_u32 s34, s52, 0x44000
	s_addc_u32 s35, s53, 0
	s_mov_b32 m0, s64
	s_nop 0
	global_load_lds_dwordx4 v130, s[34:35]
	s_mov_b32 m0, s65
	s_nop 0
	global_load_lds_dwordx4 v128, s[34:35]
	s_waitcnt vmcnt(6)
	s_barrier
	s_setprio 1
	s_setprio 0
	s_barrier
	ds_read_b128 v[140:143], v155
	ds_read_b128 v[170:173], v156
	ds_read_b128 v[174:177], v157
	ds_read_b128 v[178:181], v165
	s_add_u32 s34, s54, 0x44000
	s_addc_u32 s35, s55, 0
	s_mov_b32 m0, s66
	ds_read_b128 v[182:185], v145 offset:32768
	ds_read_b128 v[186:189], v145 offset:33792
	ds_read_b128 v[190:193], v145 offset:34816
	ds_read_b128 v[194:197], v145 offset:35840
	ds_read_b128 v[198:201], v145 offset:36864
	ds_read_b128 v[202:205], v145 offset:37888
	ds_read_b128 v[206:209], v145 offset:38912
	ds_read_b128 v[210:213], v145 offset:39936
	global_load_lds_dwordx4 v130, s[34:35]
	s_mov_b32 m0, s67
	s_nop 0
	global_load_lds_dwordx4 v128, s[34:35]
	s_waitcnt lgkmcnt(8)
	s_barrier
	s_waitcnt lgkmcnt(0)
	s_setprio 1
	s_waitcnt lgkmcnt(0)
	v_mfma_f32_16x16x32_bf16 v[124:127], v[140:143], v[182:185], v[124:127]
	v_mfma_f32_16x16x32_bf16 v[120:123], v[174:177], v[182:185], v[120:123]
	v_mfma_f32_16x16x32_bf16 v[108:111], v[140:143], v[190:193], v[108:111]
	v_mfma_f32_16x16x32_bf16 v[104:107], v[174:177], v[190:193], v[104:107]
	v_mfma_f32_16x16x32_bf16 v[92:95], v[140:143], v[198:201], v[92:95]
	v_mfma_f32_16x16x32_bf16 v[88:91], v[174:177], v[198:201], v[88:91]
	v_mfma_f32_16x16x32_bf16 v[76:79], v[140:143], v[206:209], v[76:79]
	v_mfma_f32_16x16x32_bf16 v[72:75], v[174:177], v[206:209], v[72:75]
	v_mfma_f32_16x16x32_bf16 v[124:127], v[170:173], v[186:189], v[124:127]
	v_mfma_f32_16x16x32_bf16 v[120:123], v[178:181], v[186:189], v[120:123]
	v_mfma_f32_16x16x32_bf16 v[108:111], v[170:173], v[194:197], v[108:111]
	v_mfma_f32_16x16x32_bf16 v[104:107], v[178:181], v[194:197], v[104:107]
	v_mfma_f32_16x16x32_bf16 v[92:95], v[170:173], v[202:205], v[92:95]
	v_mfma_f32_16x16x32_bf16 v[88:91], v[178:181], v[202:205], v[88:91]
	v_mfma_f32_16x16x32_bf16 v[76:79], v[170:173], v[210:213], v[76:79]
	v_mfma_f32_16x16x32_bf16 v[72:75], v[178:181], v[210:213], v[72:75]
	s_setprio 0
	s_barrier
; DI float ex2(float x) { return __builtin_amdgcn_exp2f(x); }
; #define PG8_STAGE(bufoff, gbase, voff) do { _Pragma("unroll") for (int _i = 0; _i < 2; ++_i) \
;         __builtin_amdgcn_global_load_lds((const unsigned*)((const char*)(gbase) + (voff)[_i]), (PG8_LAS unsigned*)(lds + (bufoff) + ldsw + _i * 8192), 16, 0, 0); } while (0)
; #define PG8_LDA(dst, b, h) do { _Pragma("unroll") for (int m = 0; m < 4; ++m) _Pragma("unroll") for (int k = 0; k < 2; ++k) dst[m][k] = *(const PG8_LAS bf16x8*)(lds + PG8_SA(b, h) + aoff + m * 2048 + k * 1024); } while (0)
; #define PG8_LDB(dst, b, h) do { _Pragma("unroll") for (int n = 0; n < 2; ++n) _Pragma("unroll") for (int k = 0; k < 2; ++k) dst[n][k] = *(const PG8_LAS bf16x8*)(lds + PG8_SB(b, h) + boff + n * 2048 + k * 1024); } while (0)
; #define PG8_WAIT_V(n) asm volatile("s_waitcnt vmcnt(" #n ")" ::: "memory")
;     DI void operator()(const f32x4 (&acc)[2][2][4][2], const Unit& u, int wr, int wc, int fr, int fq) const {
;         const int row0 = u.pm * BM + wr * 64 + fr, hcol0 = ((u.pn * BM + wc * 32) >> 1) + 4 * fq;
; #pragma unroll
;         for (int ai = 0; ai < 2; ++ai)
; #pragma unroll
;             for (int m = 0; m < 4; ++m) { u16* rowp = O + (size_t)(row0 + ai * HALF + m * 16) * ldc + hcol0;
; #pragma unroll
;                 for (int bj = 0; bj < 2; ++bj) { const f32x4 g = acc[ai][bj][m][0], up = acc[ai][bj][m][1]; float r[4];
; #pragma unroll
;                     for (int j = 0; j < 4; ++j) r[j] = g[j] * up[j] * __builtin_amdgcn_rcpf(1.f + ex2(-LOG2E * g[j]));
;                     uint2 w = {pack2(r[0], r[1]), pack2(r[2], r[3])}; *(uint2*)(rowp + bj * (HALF / 2)) = w; } }
; template <class Epi, class Sched, bool STAMP = false>
; __device__ __forceinline__ void gemm_phase(PG8_LAS unsigned char* lds, const Gemm g, const Sched& S, const Epi& E, unsigned long long* stamps) {
;     ...
;             PG8_WAIT_L(8); PG8_BAR; PG8_WAIT_L(0); PG8_MMA(0, 0, At, B0); PG8_BAR; PG8_SCHED;
;             PG8_LDB(B1, 1, 1); PG8_STAGE(PG8_SB(1, 0), b3, voffB);
;             PG8_BAR; PG8_WAIT_L(0); PG8_MMA(0, 1, At, B1); PG8_BAR;
;             PG8_LDA(At, 1, 1); PG8_STAGE(PG8_SA(1, 0), a3, voffA);
;             PG8_BAR; PG8_WAIT_L(0); PG8_MMA(1, 0, At, B0); PG8_BAR; PG8_SCHED;
;             PG8_STAGE(PG8_SB(1, 1), b3 + hstep, voffB);
;             PG8_WAIT_V(6); PG8_BAR; PG8_MMA(1, 1, At, B1); PG8_BAR;
;         }
	s_mov_b32 m0, s70
	s_add_u32 s100, s52, 0x80
	s_addc_u32 s101, s53, 0
	global_load_lds_dwordx4 v130, s[100:101]
	s_mov_b32 m0, s71
	s_nop 0
	global_load_lds_dwordx4 v128, s[100:101]
	s_barrier
	s_waitcnt lgkmcnt(0)
	s_setprio 1
	s_waitcnt lgkmcnt(0)
	s_setprio 0
	s_mov_b32 m0, s73
	s_barrier
	ds_read_b128 v[182:185], v145 offset:49152
	ds_read_b128 v[186:189], v145 offset:50176
	ds_read_b128 v[190:193], v145 offset:51200
	ds_read_b128 v[194:197], v145 offset:52224
	ds_read_b128 v[198:201], v145 offset:53248
	ds_read_b128 v[202:205], v145 offset:54272
	ds_read_b128 v[206:209], v145 offset:55296
	ds_read_b128 v[210:213], v145 offset:56320
	s_add_u32 s100, s54, 0x80
	s_addc_u32 s101, s55, 0
	global_load_lds_dwordx4 v130, s[100:101]
	s_mov_b32 m0, s74
	s_nop 0
	global_load_lds_dwordx4 v128, s[100:101]
	s_barrier
	s_waitcnt lgkmcnt(0)
	s_setprio 1
	s_waitcnt lgkmcnt(0)
	v_mfma_f32_16x16x32_bf16 v[60:63], v[140:143], v[182:185], v[60:63]
	v_mfma_f32_16x16x32_bf16 v[56:59], v[174:177], v[182:185], v[56:59]
	v_mfma_f32_16x16x32_bf16 v[44:47], v[140:143], v[190:193], v[44:47]
	v_mfma_f32_16x16x32_bf16 v[40:43], v[174:177], v[190:193], v[40:43]
	v_mfma_f32_16x16x32_bf16 v[28:31], v[140:143], v[198:201], v[28:31]
	v_mfma_f32_16x16x32_bf16 v[24:27], v[174:177], v[198:201], v[24:27]
	v_mfma_f32_16x16x32_bf16 v[12:15], v[140:143], v[206:209], v[12:15]
	v_mfma_f32_16x16x32_bf16 v[8:11], v[174:177], v[206:209], v[8:11]
	v_mfma_f32_16x16x32_bf16 v[60:63], v[170:173], v[186:189], v[60:63]
	v_mfma_f32_16x16x32_bf16 v[56:59], v[178:181], v[186:189], v[56:59]
	v_mfma_f32_16x16x32_bf16 v[44:47], v[170:173], v[194:197], v[44:47]
	v_mfma_f32_16x16x32_bf16 v[40:43], v[178:181], v[194:197], v[40:43]
	v_mfma_f32_16x16x32_bf16 v[28:31], v[170:173], v[202:205], v[28:31]
	v_mfma_f32_16x16x32_bf16 v[24:27], v[178:181], v[202:205], v[24:27]
	v_mfma_f32_16x16x32_bf16 v[12:15], v[170:173], v[210:213], v[12:15]
	v_mfma_f32_16x16x32_bf16 v[8:11], v[178:181], v[210:213], v[8:11]
	s_setprio 0
	s_barrier
	s_add_u32 s34, s52, 0x44080
	s_addc_u32 s35, s53, 0
	s_mov_b32 m0, s75
	s_nop 0
	global_load_lds_dwordx4 v130, s[34:35]
	s_mov_b32 m0, s76
	s_nop 0
	global_load_lds_dwordx4 v128, s[34:35]
	s_waitcnt vmcnt(6)
	s_barrier
	s_setprio 1
	s_setprio 0
	s_add_i32 s89, s89, 2
	s_add_u32 s87, s87, 0x100
	s_addc_u32 s88, s88, 0
	s_cmp_gt_u32 s89, 13
	s_mov_b64 s[34:35], s[36:37]
	s_barrier
	s_cbranch_scc0 .Lgu2_half_loop
	v_mul_f32_e32 v171, 0xbfb8aa3b, v124
	v_exp_f32_e32 v171, v171
	v_mul_f32_e32 v174, 0xbfb8aa3b, v125
	v_exp_f32_e32 v175, v174
	s_lshl_b32 s10, s86, 8
	v_add_f32_e32 v171, 1.0, v171
	v_rcp_f32_e32 v174, v171
	v_add_f32_e32 v171, 1.0, v175
	v_mul_f32_e32 v175, 0xbfb8aa3b, v126
	v_exp_f32_e32 v176, v175
	v_mul_f32_e32 v175, 0xbfb8aa3b, v127
	v_exp_f32_e32 v177, v175
	v_rcp_f32_e32 v175, v171
	v_add_f32_e32 v171, 1.0, v176
	v_rcp_f32_e32 v176, v171
	v_add_f32_e32 v171, 1.0, v177
	v_rcp_f32_e32 v177, v171
	v_pk_mul_f32 v[122:123], v[126:127], v[122:123]
	v_pk_mul_f32 v[120:121], v[124:125], v[120:121]
	s_or_b32 s10, s10, s69
	s_or_b32 s10, s10, s98
	v_pk_mul_f32 v[120:121], v[120:121], v[174:175]
	v_pk_mul_f32 v[122:123], v[122:123], v[176:177]
	s_ashr_i32 s10, s10, 1
	v_cvt_pk_bf16_f32 v120, v120, v121
	v_cvt_pk_bf16_f32 v121, v122, v123
	v_or_b32_e32 v140, s10, v146
	v_lshl_add_u32 v170, s85, 8, v144
	v_ashrrev_i32_e32 v141, 31, v140
	v_mov_b64_e32 v[142:143], s[12:13]
	v_mad_i64_i32 v[172:173], s[34:35], v170, s82, v[142:143]
	v_lshlrev_b64 v[140:141], 1, v[140:141]
	v_lshl_add_u64 v[172:173], v[172:173], 0, v[140:141]
	global_store_dwordx2 v[172:173], v[120:121], off
	v_mul_f32_e32 v116, 0xbfb8aa3b, v110
	v_mul_f32_e32 v114, 0xbfb8aa3b, v108
	v_mul_f32_e32 v115, 0xbfb8aa3b, v109
	v_mul_f32_e32 v117, 0xbfb8aa3b, v111
	v_exp_f32_e32 v114, v114
	v_exp_f32_e32 v115, v115
	v_exp_f32_e32 v116, v116
	v_exp_f32_e32 v117, v117
	v_add_f32_e32 v114, 1.0, v114
	v_add_f32_e32 v115, 1.0, v115
	v_add_f32_e32 v116, 1.0, v116
	v_add_f32_e32 v117, 1.0, v117
	v_rcp_f32_e32 v114, v114
	v_rcp_f32_e32 v115, v115
	v_rcp_f32_e32 v116, v116
	v_rcp_f32_e32 v117, v117
	v_pk_mul_f32 v[106:107], v[110:111], v[106:107]
	v_pk_mul_f32 v[104:105], v[108:109], v[104:105]
	v_pk_mul_f32 v[104:105], v[104:105], v[114:115]
	v_pk_mul_f32 v[106:107], v[106:107], v[116:117]
	v_cvt_pk_bf16_f32 v104, v104, v105
	v_cvt_pk_bf16_f32 v105, v106, v107
	v_or_b32_e32 v112, 16, v170
	v_mad_i64_i32 v[112:113], s[34:35], v112, s82, v[142:143]
	v_lshl_add_u64 v[112:113], v[112:113], 0, v[140:141]
	global_store_dwordx2 v[112:113], v[104:105], off
	v_mul_f32_e32 v100, 0xbfb8aa3b, v94
	v_mul_f32_e32 v98, 0xbfb8aa3b, v92
	v_mul_f32_e32 v99, 0xbfb8aa3b, v93
	v_mul_f32_e32 v101, 0xbfb8aa3b, v95
	v_exp_f32_e32 v98, v98
	v_exp_f32_e32 v99, v99
	v_exp_f32_e32 v100, v100
	v_exp_f32_e32 v101, v101
	v_add_f32_e32 v98, 1.0, v98
	v_add_f32_e32 v99, 1.0, v99
	v_add_f32_e32 v100, 1.0, v100
	v_add_f32_e32 v101, 1.0, v101
	v_rcp_f32_e32 v98, v98
	v_rcp_f32_e32 v99, v99
; DI float ex2(float x) { return __builtin_amdgcn_exp2f(x); }
;     DI void operator()(const f32x4 (&acc)[2][2][4][2], const Unit& u, int wr, int wc, int fr, int fq) const {
;         const int row0 = u.pm * BM + wr * 64 + fr, hcol0 = ((u.pn * BM + wc * 32) >> 1) + 4 * fq;
; #pragma unroll
;         for (int ai = 0; ai < 2; ++ai)
; #pragma unroll
;             for (int m = 0; m < 4; ++m) { u16* rowp = O + (size_t)(row0 + ai * HALF + m * 16) * ldc + hcol0;
; #pragma unroll
;                 for (int bj = 0; bj < 2; ++bj) { const f32x4 g = acc[ai][bj][m][0], up = acc[ai][bj][m][1]; float r[4];
; #pragma unroll
;                     for (int j = 0; j < 4; ++j) r[j] = g[j] * up[j] * __builtin_amdgcn_rcpf(1.f + ex2(-LOG2E * g[j]));
;                     uint2 w = {pack2(r[0], r[1]), pack2(r[2], r[3])}; *(uint2*)(rowp + bj * (HALF / 2)) = w; } }
	v_rcp_f32_e32 v100, v100
	v_rcp_f32_e32 v101, v101
	v_pk_mul_f32 v[90:91], v[94:95], v[90:91]
	v_pk_mul_f32 v[88:89], v[92:93], v[88:89]
	v_pk_mul_f32 v[88:89], v[88:89], v[98:99]
	v_pk_mul_f32 v[90:91], v[90:91], v[100:101]
	v_cvt_pk_bf16_f32 v88, v88, v89
	v_cvt_pk_bf16_f32 v89, v90, v91
	v_or_b32_e32 v96, 32, v170
	v_mad_i64_i32 v[96:97], s[34:35], v96, s82, v[142:143]
	v_lshl_add_u64 v[96:97], v[96:97], 0, v[140:141]
	global_store_dwordx2 v[96:97], v[88:89], off
	v_mul_f32_e32 v84, 0xbfb8aa3b, v78
	v_mul_f32_e32 v82, 0xbfb8aa3b, v76
	v_mul_f32_e32 v83, 0xbfb8aa3b, v77
	v_mul_f32_e32 v85, 0xbfb8aa3b, v79
	v_exp_f32_e32 v82, v82
	v_exp_f32_e32 v83, v83
	v_exp_f32_e32 v84, v84
	v_exp_f32_e32 v85, v85
	v_add_f32_e32 v82, 1.0, v82
	v_add_f32_e32 v83, 1.0, v83
	v_add_f32_e32 v84, 1.0, v84
	v_add_f32_e32 v85, 1.0, v85
	v_rcp_f32_e32 v82, v82
	v_rcp_f32_e32 v83, v83
	v_rcp_f32_e32 v84, v84
	v_rcp_f32_e32 v85, v85
	v_pk_mul_f32 v[74:75], v[78:79], v[74:75]
	v_pk_mul_f32 v[72:73], v[76:77], v[72:73]
	v_pk_mul_f32 v[72:73], v[72:73], v[82:83]
	v_pk_mul_f32 v[74:75], v[74:75], v[84:85]
	v_cvt_pk_bf16_f32 v72, v72, v73
	v_cvt_pk_bf16_f32 v73, v74, v75
	v_or_b32_e32 v80, 48, v170
	v_mad_i64_i32 v[80:81], s[34:35], v80, s82, v[142:143]
	v_lshl_add_u64 v[80:81], v[80:81], 0, v[140:141]
	global_store_dwordx2 v[80:81], v[72:73], off
	v_mul_f32_e32 v68, 0xbfb8aa3b, v62
	v_mul_f32_e32 v66, 0xbfb8aa3b, v60
	v_mul_f32_e32 v67, 0xbfb8aa3b, v61
	v_mul_f32_e32 v69, 0xbfb8aa3b, v63
	v_exp_f32_e32 v66, v66
	v_exp_f32_e32 v67, v67
	v_exp_f32_e32 v68, v68
	v_exp_f32_e32 v69, v69
	v_add_f32_e32 v66, 1.0, v66
	v_add_f32_e32 v67, 1.0, v67
	v_add_f32_e32 v68, 1.0, v68
	v_add_f32_e32 v69, 1.0, v69
	v_rcp_f32_e32 v66, v66
	v_rcp_f32_e32 v67, v67
	v_rcp_f32_e32 v68, v68
	v_rcp_f32_e32 v69, v69
	v_pk_mul_f32 v[58:59], v[62:63], v[58:59]
	v_pk_mul_f32 v[56:57], v[60:61], v[56:57]
	v_pk_mul_f32 v[56:57], v[56:57], v[66:67]
	v_pk_mul_f32 v[58:59], v[58:59], v[68:69]
	v_cvt_pk_bf16_f32 v56, v56, v57
	v_cvt_pk_bf16_f32 v57, v58, v59
	v_add_u32_e32 v64, 0x80, v170
	v_mad_i64_i32 v[64:65], s[34:35], v64, s82, v[142:143]
	v_lshl_add_u64 v[64:65], v[64:65], 0, v[140:141]
	global_store_dwordx2 v[64:65], v[56:57], off
	v_mul_f32_e32 v52, 0xbfb8aa3b, v46
	v_mul_f32_e32 v50, 0xbfb8aa3b, v44
	v_mul_f32_e32 v51, 0xbfb8aa3b, v45
	v_mul_f32_e32 v53, 0xbfb8aa3b, v47
	v_exp_f32_e32 v50, v50
	v_exp_f32_e32 v51, v51
	v_exp_f32_e32 v52, v52
	v_exp_f32_e32 v53, v53
	v_add_f32_e32 v50, 1.0, v50
	v_add_f32_e32 v51, 1.0, v51
	v_add_f32_e32 v52, 1.0, v52
	v_add_f32_e32 v53, 1.0, v53
	v_rcp_f32_e32 v50, v50
	v_rcp_f32_e32 v51, v51
	v_rcp_f32_e32 v52, v52
	v_rcp_f32_e32 v53, v53
	v_pk_mul_f32 v[42:43], v[46:47], v[42:43]
	v_pk_mul_f32 v[40:41], v[44:45], v[40:41]
	v_pk_mul_f32 v[40:41], v[40:41], v[50:51]
	v_pk_mul_f32 v[42:43], v[42:43], v[52:53]
	v_cvt_pk_bf16_f32 v40, v40, v41
	v_cvt_pk_bf16_f32 v41, v42, v43
	v_add_u32_e32 v48, 0x90, v170
	v_mad_i64_i32 v[48:49], s[34:35], v48, s82, v[142:143]
	v_lshl_add_u64 v[48:49], v[48:49], 0, v[140:141]
	global_store_dwordx2 v[48:49], v[40:41], off
	v_mul_f32_e32 v36, 0xbfb8aa3b, v30
	v_mul_f32_e32 v34, 0xbfb8aa3b, v28
	v_mul_f32_e32 v35, 0xbfb8aa3b, v29
	v_mul_f32_e32 v37, 0xbfb8aa3b, v31
	v_exp_f32_e32 v34, v34
	v_exp_f32_e32 v35, v35
	v_exp_f32_e32 v36, v36
	v_exp_f32_e32 v37, v37
	v_add_f32_e32 v34, 1.0, v34
	v_add_f32_e32 v35, 1.0, v35
	v_add_f32_e32 v36, 1.0, v36
	v_add_f32_e32 v37, 1.0, v37
	v_rcp_f32_e32 v34, v34
	v_rcp_f32_e32 v35, v35
	v_rcp_f32_e32 v36, v36
	v_rcp_f32_e32 v37, v37
	v_pk_mul_f32 v[26:27], v[30:31], v[26:27]
	v_pk_mul_f32 v[24:25], v[28:29], v[24:25]
	v_pk_mul_f32 v[24:25], v[24:25], v[34:35]
	v_pk_mul_f32 v[26:27], v[26:27], v[36:37]
	v_cvt_pk_bf16_f32 v24, v24, v25
	v_cvt_pk_bf16_f32 v25, v26, v27
	v_add_u32_e32 v32, 0xa0, v170
	v_mad_i64_i32 v[32:33], s[34:35], v32, s82, v[142:143]
	v_lshl_add_u64 v[32:33], v[32:33], 0, v[140:141]
	global_store_dwordx2 v[32:33], v[24:25], off
	v_mul_f32_e32 v20, 0xbfb8aa3b, v14
	v_mul_f32_e32 v18, 0xbfb8aa3b, v12
	v_mul_f32_e32 v19, 0xbfb8aa3b, v13
	v_mul_f32_e32 v21, 0xbfb8aa3b, v15
	v_exp_f32_e32 v18, v18
	v_exp_f32_e32 v19, v19
	v_exp_f32_e32 v20, v20
	v_exp_f32_e32 v21, v21
	v_add_f32_e32 v18, 1.0, v18
	v_add_f32_e32 v19, 1.0, v19
	v_add_f32_e32 v20, 1.0, v20
	v_add_f32_e32 v21, 1.0, v21
	v_rcp_f32_e32 v18, v18
	v_rcp_f32_e32 v19, v19
	v_rcp_f32_e32 v20, v20
	v_rcp_f32_e32 v21, v21
	v_pk_mul_f32 v[10:11], v[14:15], v[10:11]
	v_pk_mul_f32 v[8:9], v[12:13], v[8:9]
	v_pk_mul_f32 v[8:9], v[8:9], v[18:19]
	v_pk_mul_f32 v[10:11], v[10:11], v[20:21]
	v_cvt_pk_bf16_f32 v8, v8, v9
	v_cvt_pk_bf16_f32 v9, v10, v11
	v_add_u32_e32 v16, 0xb0, v170
	v_mad_i64_i32 v[16:17], s[34:35], v16, s82, v[142:143]
	v_lshl_add_u64 v[16:17], v[16:17], 0, v[140:141]
	global_store_dwordx2 v[16:17], v[8:9], off
	s_and_b64 vcc, exec, s[2:3]
	s_mov_b32 s86, s83
	s_mov_b32 s85, s84
	s_mov_b64 s[36:37], s[0:1]
	s_mov_b64 s[34:35], s[4:5]

; #define PG8_STAGE(bufoff, gbase, voff) do { _Pragma("unroll") for (int _i = 0; _i < 2; ++_i) \
;         __builtin_amdgcn_global_load_lds((const unsigned*)((const char*)(gbase) + (voff)[_i]), (PG8_LAS unsigned*)(lds + (bufoff) + ldsw + _i * 8192), 16, 0, 0); } while (0)
; #define PG8_LDA(dst, b, h) do { _Pragma("unroll") for (int m = 0; m < 4; ++m) _Pragma("unroll") for (int k = 0; k < 2; ++k) dst[m][k] = *(const PG8_LAS bf16x8*)(lds + PG8_SA(b, h) + aoff + m * 2048 + k * 1024); } while (0)
; #define PG8_LDB(dst, b, h) do { _Pragma("unroll") for (int n = 0; n < 2; ++n) _Pragma("unroll") for (int k = 0; k < 2; ++k) dst[n][k] = *(const PG8_LAS bf16x8*)(lds + PG8_SB(b, h) + boff + n * 2048 + k * 1024); } while (0)
; #define PG8_MMA(ai, bj, At, Bt) do { __builtin_amdgcn_s_setprio(1); _Pragma("unroll") for (int m = 0; m < 4; ++m) _Pragma("unroll") for (int n = 0; n < 2; ++n) _Pragma("unroll") for (int k = 0; k < 2; ++k) \
;         acc[ai][bj][m][n] = __builtin_amdgcn_mfma_f32_16x16x32_bf16(Bt[n][k], At[m][k], acc[ai][bj][m][n], 0, 0, 0); __builtin_amdgcn_s_setprio(0); } while (0)
; #define PG8_WAIT_V(n) asm volatile("s_waitcnt vmcnt(" #n ")" ::: "memory")
; template <class Epi, class Sched, bool STAMP = false>
; __device__ __forceinline__ void gemm_phase(PG8_LAS unsigned char* lds, const Gemm g, const Sched& S, const Epi& E, unsigned long long* stamps) {
;     ...
;             const bool last = (t == nt - 2);
;             const char* a1 = cA + (size_t)(t + 1) * kstep;
;             const char* a2 = last ? nA : cA + (size_t)(t + 2) * kstep; const char* b2 = last ? nB : cB + (size_t)(t + 2) * kstep;
;             const char* a3 = a2 + kstep; const char* b3 = b2 + kstep;
;             if (last && has_next) S.a_ready(nxt);
;             PG8_LDB(B0, 0, 0); PG8_SCHED; PG8_LDA(At, 0, 0); PG8_STAGE(PG8_SA(1, 1), a1 + hstep, voffA);
;             PG8_WAIT_L(8); PG8_BAR; PG8_WAIT_L(0); PG8_MMA(0, 0, At, B0); PG8_BAR; PG8_SCHED;
;             PG8_LDB(B1, 0, 1); PG8_STAGE(PG8_SB(0, 0), b2, voffB);
;             PG8_BAR; PG8_WAIT_L(0); PG8_MMA(0, 1, At, B1); PG8_BAR;
;             PG8_LDA(At, 0, 1); PG8_STAGE(PG8_SA(0, 0), a2, voffA);
;             PG8_BAR; PG8_WAIT_L(0); PG8_MMA(1, 0, At, B0); PG8_BAR; PG8_SCHED;
;             PG8_STAGE(PG8_SB(0, 1), b2 + hstep, voffB);
;             PG8_WAIT_V(6); PG8_BAR; PG8_MMA(1, 1, At, B1); PG8_BAR;
.LBB0_385:
	ds_read_b128 v[170:173], v147
	ds_read_b128 v[174:177], v148
	ds_read_b128 v[178:181], v149
	ds_read_b128 v[182:185], v150
	s_add_u32 s58, s56, 0x100
	s_addc_u32 s59, s57, 0
	s_cmp_eq_u32 s10, 40
	s_cselect_b32 s63, s5, s59
	s_cselect_b32 s62, s4, s58
	s_cselect_b32 s61, s1, vcc_hi
	s_cselect_b32 s60, s0, vcc_lo
	s_mov_b32 m0, s88
	ds_read_b128 v[186:189], v145
	ds_read_b128 v[190:193], v145 offset:1024
	ds_read_b128 v[194:197], v145 offset:2048
	ds_read_b128 v[198:201], v145 offset:3072
	ds_read_b128 v[202:205], v145 offset:4096
	ds_read_b128 v[206:209], v145 offset:5120
	ds_read_b128 v[210:213], v145 offset:6144
	ds_read_b128 v[214:217], v145 offset:7168
	global_load_lds_dwordx4 v136, s[56:57]
	s_mov_b32 m0, s89
	s_nop 0
	global_load_lds_dwordx4 v138, s[56:57]
	s_waitcnt lgkmcnt(8)
	s_barrier
	s_waitcnt lgkmcnt(0)
	s_setprio 1
	s_waitcnt lgkmcnt(0)
	v_mfma_f32_16x16x32_bf16 v[124:127], v[170:173], v[186:189], v[124:127]
	v_mfma_f32_16x16x32_bf16 v[120:123], v[178:181], v[186:189], v[120:123]
	v_mfma_f32_16x16x32_bf16 v[116:119], v[170:173], v[194:197], v[116:119]
	v_mfma_f32_16x16x32_bf16 v[112:115], v[178:181], v[194:197], v[112:115]
	v_mfma_f32_16x16x32_bf16 v[100:103], v[170:173], v[202:205], v[100:103]
	v_mfma_f32_16x16x32_bf16 v[96:99], v[178:181], v[202:205], v[96:99]
	v_mfma_f32_16x16x32_bf16 v[84:87], v[170:173], v[210:213], v[84:87]
	v_mfma_f32_16x16x32_bf16 v[80:83], v[178:181], v[210:213], v[80:83]
	v_mfma_f32_16x16x32_bf16 v[124:127], v[174:177], v[190:193], v[124:127]
	v_mfma_f32_16x16x32_bf16 v[120:123], v[182:185], v[190:193], v[120:123]
	v_mfma_f32_16x16x32_bf16 v[116:119], v[174:177], v[198:201], v[116:119]
	v_mfma_f32_16x16x32_bf16 v[112:115], v[182:185], v[198:201], v[112:115]
	v_mfma_f32_16x16x32_bf16 v[100:103], v[174:177], v[206:209], v[100:103]
	v_mfma_f32_16x16x32_bf16 v[96:99], v[182:185], v[206:209], v[96:99]
	v_mfma_f32_16x16x32_bf16 v[84:87], v[174:177], v[214:217], v[84:87]
	v_mfma_f32_16x16x32_bf16 v[80:83], v[182:185], v[214:217], v[80:83]
	s_setprio 0
	s_barrier
	s_mov_b32 m0, s68
	ds_read_b128 v[218:221], v151
	ds_read_b128 v[222:225], v152
	ds_read_b128 v[226:229], v153
	ds_read_b128 v[230:233], v154
	global_load_lds_dwordx4 v130, s[60:61]
	s_mov_b32 m0, s69
	s_nop 0
	global_load_lds_dwordx4 v134, s[60:61]
	s_barrier
	s_waitcnt lgkmcnt(0)
	s_setprio 1
	s_waitcnt lgkmcnt(0)
	v_mfma_f32_16x16x32_bf16 v[108:111], v[218:221], v[186:189], v[108:111]
	v_mfma_f32_16x16x32_bf16 v[104:107], v[226:229], v[186:189], v[104:107]
	v_mfma_f32_16x16x32_bf16 v[92:95], v[218:221], v[194:197], v[92:95]
	v_mfma_f32_16x16x32_bf16 v[88:91], v[226:229], v[194:197], v[88:91]
	v_mfma_f32_16x16x32_bf16 v[76:79], v[218:221], v[202:205], v[76:79]
	v_mfma_f32_16x16x32_bf16 v[72:75], v[226:229], v[202:205], v[72:75]
	v_mfma_f32_16x16x32_bf16 v[68:71], v[218:221], v[210:213], v[68:71]
	v_mfma_f32_16x16x32_bf16 v[64:67], v[226:229], v[210:213], v[64:67]
	v_mfma_f32_16x16x32_bf16 v[108:111], v[222:225], v[190:193], v[108:111]
	v_mfma_f32_16x16x32_bf16 v[104:107], v[230:233], v[190:193], v[104:107]
	v_mfma_f32_16x16x32_bf16 v[92:95], v[222:225], v[198:201], v[92:95]
	v_mfma_f32_16x16x32_bf16 v[88:91], v[230:233], v[198:201], v[88:91]
	v_mfma_f32_16x16x32_bf16 v[76:79], v[222:225], v[206:209], v[76:79]
	v_mfma_f32_16x16x32_bf16 v[72:75], v[230:233], v[206:209], v[72:75]
	v_mfma_f32_16x16x32_bf16 v[68:71], v[222:225], v[214:217], v[68:71]
	v_mfma_f32_16x16x32_bf16 v[64:67], v[230:233], v[214:217], v[64:67]
	s_setprio 0
	s_mov_b32 m0, s67
	s_barrier
	ds_read_b128 v[186:189], v145 offset:16384
	ds_read_b128 v[190:193], v145 offset:17408
	ds_read_b128 v[194:197], v145 offset:18432
	ds_read_b128 v[198:201], v145 offset:19456
	ds_read_b128 v[202:205], v145 offset:20480
	ds_read_b128 v[206:209], v145 offset:21504
	ds_read_b128 v[210:213], v145 offset:22528
	ds_read_b128 v[214:217], v145 offset:23552
	global_load_lds_dwordx4 v128, s[62:63]
	s_mov_b32 m0, s70
	s_nop 0
	global_load_lds_dwordx4 v132, s[62:63]
	s_barrier
	s_waitcnt lgkmcnt(0)
	s_setprio 1
	s_waitcnt lgkmcnt(0)
	v_mfma_f32_16x16x32_bf16 v[60:63], v[170:173], v[186:189], v[60:63]
	v_mfma_f32_16x16x32_bf16 v[56:59], v[178:181], v[186:189], v[56:59]
	v_mfma_f32_16x16x32_bf16 v[52:55], v[170:173], v[194:197], v[52:55]
	v_mfma_f32_16x16x32_bf16 v[48:51], v[178:181], v[194:197], v[48:51]
	v_mfma_f32_16x16x32_bf16 v[36:39], v[170:173], v[202:205], v[36:39]
	v_mfma_f32_16x16x32_bf16 v[32:35], v[178:181], v[202:205], v[32:35]
	v_mfma_f32_16x16x32_bf16 v[20:23], v[170:173], v[210:213], v[20:23]
	v_mfma_f32_16x16x32_bf16 v[16:19], v[178:181], v[210:213], v[16:19]
	v_mfma_f32_16x16x32_bf16 v[60:63], v[174:177], v[190:193], v[60:63]
	v_mfma_f32_16x16x32_bf16 v[56:59], v[182:185], v[190:193], v[56:59]
	v_mfma_f32_16x16x32_bf16 v[52:55], v[174:177], v[198:201], v[52:55]
	v_mfma_f32_16x16x32_bf16 v[48:51], v[182:185], v[198:201], v[48:51]
	v_mfma_f32_16x16x32_bf16 v[36:39], v[174:177], v[206:209], v[36:39]
	v_mfma_f32_16x16x32_bf16 v[32:35], v[182:185], v[206:209], v[32:35]
	v_mfma_f32_16x16x32_bf16 v[20:23], v[174:177], v[214:217], v[20:23]
	v_mfma_f32_16x16x32_bf16 v[16:19], v[182:185], v[214:217], v[16:19]
	s_setprio 0
	s_barrier
	s_add_u32 s56, s60, 0xb4000
	s_addc_u32 s57, s61, 0
	s_mov_b32 m0, s71
	s_nop 0
	global_load_lds_dwordx4 v130, s[56:57]
	s_mov_b32 m0, s75
	s_nop 0
	global_load_lds_dwordx4 v134, s[56:57]
	s_waitcnt vmcnt(6)
	s_barrier
; #define PG8_STAGE(bufoff, gbase, voff) do { _Pragma("unroll") for (int _i = 0; _i < 2; ++_i) \
;         __builtin_amdgcn_global_load_lds((const unsigned*)((const char*)(gbase) + (voff)[_i]), (PG8_LAS unsigned*)(lds + (bufoff) + ldsw + _i * 8192), 16, 0, 0); } while (0)
; #define PG8_LDA(dst, b, h) do { _Pragma("unroll") for (int m = 0; m < 4; ++m) _Pragma("unroll") for (int k = 0; k < 2; ++k) dst[m][k] = *(const PG8_LAS bf16x8*)(lds + PG8_SA(b, h) + aoff + m * 2048 + k * 1024); } while (0)
; #define PG8_LDB(dst, b, h) do { _Pragma("unroll") for (int n = 0; n < 2; ++n) _Pragma("unroll") for (int k = 0; k < 2; ++k) dst[n][k] = *(const PG8_LAS bf16x8*)(lds + PG8_SB(b, h) + boff + n * 2048 + k * 1024); } while (0)
; #define PG8_MMA(ai, bj, At, Bt) do { __builtin_amdgcn_s_setprio(1); _Pragma("unroll") for (int m = 0; m < 4; ++m) _Pragma("unroll") for (int n = 0; n < 2; ++n) _Pragma("unroll") for (int k = 0; k < 2; ++k) \
;         acc[ai][bj][m][n] = __builtin_amdgcn_mfma_f32_16x16x32_bf16(Bt[n][k], At[m][k], acc[ai][bj][m][n], 0, 0, 0); __builtin_amdgcn_s_setprio(0); } while (0)
; #define PG8_WAIT_V(n) asm volatile("s_waitcnt vmcnt(" #n ")" ::: "memory")
; #define PG8_WAIT_L(n) asm volatile("s_waitcnt lgkmcnt(" #n ")" ::: "memory")
; #define PG8_BAR __builtin_amdgcn_s_barrier()
; #define PG8_SCHED __builtin_amdgcn_sched_barrier(0)
; template <class Epi, class Sched, bool STAMP = false>
; __device__ __forceinline__ void gemm_phase(PG8_LAS unsigned char* lds, const Gemm g, const Sched& S, const Epi& E, unsigned long long* stamps) {
;     ...
;             PG8_WAIT_V(6); PG8_BAR; PG8_MMA(1, 1, At, B1); PG8_BAR;
;             PG8_LDB(B0, 1, 0); PG8_SCHED; PG8_LDA(At, 1, 0); PG8_STAGE(PG8_SA(0, 1), a2 + hstep, voffA);
;             PG8_WAIT_L(8); PG8_BAR; PG8_WAIT_L(0); PG8_MMA(0, 0, At, B0); PG8_BAR; PG8_SCHED;
;             PG8_LDB(B1, 1, 1); PG8_STAGE(PG8_SB(1, 0), b3, voffB);
;             PG8_BAR; PG8_WAIT_L(0); PG8_MMA(0, 1, At, B1); PG8_BAR;
;             PG8_LDA(At, 1, 1); PG8_STAGE(PG8_SA(1, 0), a3, voffA);
;             PG8_BAR; PG8_WAIT_L(0); PG8_MMA(1, 0, At, B0); PG8_BAR; PG8_SCHED;
	s_setprio 1
	v_mfma_f32_16x16x32_bf16 v[44:47], v[218:221], v[186:189], v[44:47]
	v_mfma_f32_16x16x32_bf16 v[40:43], v[226:229], v[186:189], v[40:43]
	v_mfma_f32_16x16x32_bf16 v[28:31], v[218:221], v[194:197], v[28:31]
	v_mfma_f32_16x16x32_bf16 v[24:27], v[226:229], v[194:197], v[24:27]
	v_mfma_f32_16x16x32_bf16 v[12:15], v[218:221], v[202:205], v[12:15]
	v_mfma_f32_16x16x32_bf16 v[8:11], v[226:229], v[202:205], v[8:11]
	v_mfma_f32_16x16x32_bf16 v[4:7], v[218:221], v[210:213], v[4:7]
	v_mfma_f32_16x16x32_bf16 v[0:3], v[226:229], v[210:213], v[0:3]
	v_mfma_f32_16x16x32_bf16 v[44:47], v[222:225], v[190:193], v[44:47]
	v_mfma_f32_16x16x32_bf16 v[40:43], v[230:233], v[190:193], v[40:43]
	v_mfma_f32_16x16x32_bf16 v[28:31], v[222:225], v[198:201], v[28:31]
	v_mfma_f32_16x16x32_bf16 v[24:27], v[230:233], v[198:201], v[24:27]
	v_mfma_f32_16x16x32_bf16 v[12:15], v[222:225], v[206:209], v[12:15]
	v_mfma_f32_16x16x32_bf16 v[8:11], v[230:233], v[206:209], v[8:11]
	v_mfma_f32_16x16x32_bf16 v[4:7], v[222:225], v[214:217], v[4:7]
	v_mfma_f32_16x16x32_bf16 v[0:3], v[230:233], v[214:217], v[0:3]
	s_setprio 0
	s_barrier
	ds_read_b128 v[170:173], v155
	ds_read_b128 v[174:177], v156
	ds_read_b128 v[178:181], v157
	ds_read_b128 v[182:185], v165
	s_add_u32 s56, s62, 0xb4000
	s_addc_u32 s57, s63, 0
	s_mov_b32 m0, s76
	ds_read_b128 v[186:189], v145 offset:32768
	ds_read_b128 v[190:193], v145 offset:33792
	ds_read_b128 v[194:197], v145 offset:34816
	ds_read_b128 v[198:201], v145 offset:35840
	ds_read_b128 v[202:205], v145 offset:36864
	ds_read_b128 v[206:209], v145 offset:37888
	ds_read_b128 v[210:213], v145 offset:38912
	ds_read_b128 v[214:217], v145 offset:39936
	global_load_lds_dwordx4 v128, s[56:57]
	s_mov_b32 m0, s77
	s_nop 0
	global_load_lds_dwordx4 v132, s[56:57]
	s_waitcnt lgkmcnt(8)
	s_barrier
	s_waitcnt lgkmcnt(0)
	s_setprio 1
	s_waitcnt lgkmcnt(0)
	v_mfma_f32_16x16x32_bf16 v[124:127], v[170:173], v[186:189], v[124:127]
	v_mfma_f32_16x16x32_bf16 v[120:123], v[178:181], v[186:189], v[120:123]
	v_mfma_f32_16x16x32_bf16 v[116:119], v[170:173], v[194:197], v[116:119]
	v_mfma_f32_16x16x32_bf16 v[112:115], v[178:181], v[194:197], v[112:115]
	v_mfma_f32_16x16x32_bf16 v[100:103], v[170:173], v[202:205], v[100:103]
	v_mfma_f32_16x16x32_bf16 v[96:99], v[178:181], v[202:205], v[96:99]
	v_mfma_f32_16x16x32_bf16 v[84:87], v[170:173], v[210:213], v[84:87]
	v_mfma_f32_16x16x32_bf16 v[80:83], v[178:181], v[210:213], v[80:83]
	v_mfma_f32_16x16x32_bf16 v[124:127], v[174:177], v[190:193], v[124:127]
	v_mfma_f32_16x16x32_bf16 v[120:123], v[182:185], v[190:193], v[120:123]
	v_mfma_f32_16x16x32_bf16 v[116:119], v[174:177], v[198:201], v[116:119]
	v_mfma_f32_16x16x32_bf16 v[112:115], v[182:185], v[198:201], v[112:115]
	v_mfma_f32_16x16x32_bf16 v[100:103], v[174:177], v[206:209], v[100:103]
	v_mfma_f32_16x16x32_bf16 v[96:99], v[182:185], v[206:209], v[96:99]
	v_mfma_f32_16x16x32_bf16 v[84:87], v[174:177], v[214:217], v[84:87]
	v_mfma_f32_16x16x32_bf16 v[80:83], v[182:185], v[214:217], v[80:83]
	s_setprio 0
	s_barrier
	s_mov_b32 m0, s78
	ds_read_b128 v[218:221], v166
	ds_read_b128 v[222:225], v167
	ds_read_b128 v[226:229], v168
	ds_read_b128 v[230:233], v169
	s_add_u32 s100, s60, 0x80
	s_addc_u32 s101, s61, 0
	global_load_lds_dwordx4 v130, s[100:101]
	s_mov_b32 m0, s79
	s_nop 0
	global_load_lds_dwordx4 v134, s[100:101]
	s_barrier
	s_waitcnt lgkmcnt(0)
	s_setprio 1
	s_waitcnt lgkmcnt(0)
	v_mfma_f32_16x16x32_bf16 v[108:111], v[218:221], v[186:189], v[108:111]
	v_mfma_f32_16x16x32_bf16 v[104:107], v[226:229], v[186:189], v[104:107]
	v_mfma_f32_16x16x32_bf16 v[92:95], v[218:221], v[194:197], v[92:95]
	v_mfma_f32_16x16x32_bf16 v[88:91], v[226:229], v[194:197], v[88:91]
	v_mfma_f32_16x16x32_bf16 v[76:79], v[218:221], v[202:205], v[76:79]
	v_mfma_f32_16x16x32_bf16 v[72:75], v[226:229], v[202:205], v[72:75]
	v_mfma_f32_16x16x32_bf16 v[68:71], v[218:221], v[210:213], v[68:71]
	v_mfma_f32_16x16x32_bf16 v[64:67], v[226:229], v[210:213], v[64:67]
	v_mfma_f32_16x16x32_bf16 v[108:111], v[222:225], v[190:193], v[108:111]
	v_mfma_f32_16x16x32_bf16 v[104:107], v[230:233], v[190:193], v[104:107]
	v_mfma_f32_16x16x32_bf16 v[92:95], v[222:225], v[198:201], v[92:95]
	v_mfma_f32_16x16x32_bf16 v[88:91], v[230:233], v[198:201], v[88:91]
	v_mfma_f32_16x16x32_bf16 v[76:79], v[222:225], v[206:209], v[76:79]
	v_mfma_f32_16x16x32_bf16 v[72:75], v[230:233], v[206:209], v[72:75]
	v_mfma_f32_16x16x32_bf16 v[68:71], v[222:225], v[214:217], v[68:71]
	v_mfma_f32_16x16x32_bf16 v[64:67], v[230:233], v[214:217], v[64:67]
	s_setprio 0
	s_mov_b32 m0, s82
	s_barrier
	ds_read_b128 v[186:189], v145 offset:49152
	ds_read_b128 v[190:193], v145 offset:50176
	ds_read_b128 v[194:197], v145 offset:51200
	ds_read_b128 v[198:201], v145 offset:52224
	ds_read_b128 v[202:205], v145 offset:53248
	ds_read_b128 v[206:209], v145 offset:54272
	ds_read_b128 v[210:213], v145 offset:55296
	ds_read_b128 v[214:217], v145 offset:56320
	s_add_u32 s100, s62, 0x80
	s_addc_u32 s101, s63, 0
	global_load_lds_dwordx4 v128, s[100:101]
	s_mov_b32 m0, s83
	s_nop 0
	global_load_lds_dwordx4 v132, s[100:101]
	s_barrier
; #define PG8_STAGE(bufoff, gbase, voff) do { _Pragma("unroll") for (int _i = 0; _i < 2; ++_i) \
;         __builtin_amdgcn_global_load_lds((const unsigned*)((const char*)(gbase) + (voff)[_i]), (PG8_LAS unsigned*)(lds + (bufoff) + ldsw + _i * 8192), 16, 0, 0); } while (0)
; #define PG8_MMA(ai, bj, At, Bt) do { __builtin_amdgcn_s_setprio(1); _Pragma("unroll") for (int m = 0; m < 4; ++m) _Pragma("unroll") for (int n = 0; n < 2; ++n) _Pragma("unroll") for (int k = 0; k < 2; ++k) \
;         acc[ai][bj][m][n] = __builtin_amdgcn_mfma_f32_16x16x32_bf16(Bt[n][k], At[m][k], acc[ai][bj][m][n], 0, 0, 0); __builtin_amdgcn_s_setprio(0); } while (0)
; #define PG8_WAIT_V(n) asm volatile("s_waitcnt vmcnt(" #n ")" ::: "memory")
; #define PG8_WAIT_L(n) asm volatile("s_waitcnt lgkmcnt(" #n ")" ::: "memory")
; #define PG8_BAR __builtin_amdgcn_s_barrier()
; #define PG8_SCHED __builtin_amdgcn_sched_barrier(0)
; template <class Epi, class Sched, bool STAMP = false>
; __device__ __forceinline__ void gemm_phase(PG8_LAS unsigned char* lds, const Gemm g, const Sched& S, const Epi& E, unsigned long long* stamps) {
;     ...
;             PG8_BAR; PG8_WAIT_L(0); PG8_MMA(1, 0, At, B0); PG8_BAR; PG8_SCHED;
;             PG8_STAGE(PG8_SB(1, 1), b3 + hstep, voffB);
;             PG8_WAIT_V(6); PG8_BAR; PG8_MMA(1, 1, At, B1); PG8_BAR;
;         }
	s_waitcnt lgkmcnt(0)
	s_setprio 1
	s_waitcnt lgkmcnt(0)
	v_mfma_f32_16x16x32_bf16 v[60:63], v[170:173], v[186:189], v[60:63]
	v_mfma_f32_16x16x32_bf16 v[56:59], v[178:181], v[186:189], v[56:59]
	v_mfma_f32_16x16x32_bf16 v[52:55], v[170:173], v[194:197], v[52:55]
	v_mfma_f32_16x16x32_bf16 v[48:51], v[178:181], v[194:197], v[48:51]
	v_mfma_f32_16x16x32_bf16 v[36:39], v[170:173], v[202:205], v[36:39]
	v_mfma_f32_16x16x32_bf16 v[32:35], v[178:181], v[202:205], v[32:35]
	v_mfma_f32_16x16x32_bf16 v[20:23], v[170:173], v[210:213], v[20:23]
	v_mfma_f32_16x16x32_bf16 v[16:19], v[178:181], v[210:213], v[16:19]
	v_mfma_f32_16x16x32_bf16 v[60:63], v[174:177], v[190:193], v[60:63]
	v_mfma_f32_16x16x32_bf16 v[56:59], v[182:185], v[190:193], v[56:59]
	v_mfma_f32_16x16x32_bf16 v[52:55], v[174:177], v[198:201], v[52:55]
	v_mfma_f32_16x16x32_bf16 v[48:51], v[182:185], v[198:201], v[48:51]
	v_mfma_f32_16x16x32_bf16 v[36:39], v[174:177], v[206:209], v[36:39]
	v_mfma_f32_16x16x32_bf16 v[32:35], v[182:185], v[206:209], v[32:35]
	v_mfma_f32_16x16x32_bf16 v[20:23], v[174:177], v[214:217], v[20:23]
	v_mfma_f32_16x16x32_bf16 v[16:19], v[182:185], v[214:217], v[16:19]
	s_setprio 0
	s_barrier
	s_add_u32 s56, s60, 0xb4080
	s_addc_u32 s57, s61, 0
	s_mov_b32 m0, s84
	s_nop 0
	global_load_lds_dwordx4 v130, s[56:57]
	s_mov_b32 m0, s85
	s_nop 0
	global_load_lds_dwordx4 v134, s[56:57]
	s_waitcnt vmcnt(6)
	s_barrier
	s_setprio 1
	v_mfma_f32_16x16x32_bf16 v[44:47], v[218:221], v[186:189], v[44:47]
	v_mfma_f32_16x16x32_bf16 v[40:43], v[226:229], v[186:189], v[40:43]
	v_mfma_f32_16x16x32_bf16 v[28:31], v[218:221], v[194:197], v[28:31]
	v_mfma_f32_16x16x32_bf16 v[24:27], v[226:229], v[194:197], v[24:27]
	v_mfma_f32_16x16x32_bf16 v[12:15], v[218:221], v[202:205], v[12:15]
	v_mfma_f32_16x16x32_bf16 v[8:11], v[226:229], v[202:205], v[8:11]
	v_mfma_f32_16x16x32_bf16 v[4:7], v[218:221], v[210:213], v[4:7]
	v_mfma_f32_16x16x32_bf16 v[0:3], v[226:229], v[210:213], v[0:3]
	v_mfma_f32_16x16x32_bf16 v[44:47], v[222:225], v[190:193], v[44:47]
	v_mfma_f32_16x16x32_bf16 v[40:43], v[230:233], v[190:193], v[40:43]
	v_mfma_f32_16x16x32_bf16 v[28:31], v[222:225], v[198:201], v[28:31]
	v_mfma_f32_16x16x32_bf16 v[24:27], v[230:233], v[198:201], v[24:27]
	v_mfma_f32_16x16x32_bf16 v[12:15], v[222:225], v[206:209], v[12:15]
	v_mfma_f32_16x16x32_bf16 v[8:11], v[230:233], v[206:209], v[8:11]
	v_mfma_f32_16x16x32_bf16 v[4:7], v[222:225], v[214:217], v[4:7]
	v_mfma_f32_16x16x32_bf16 v[0:3], v[230:233], v[214:217], v[0:3]
	s_setprio 0
	s_add_i32 s10, s10, 2
	s_add_u32 vcc_lo, vcc_lo, 0x100
	s_addc_u32 vcc_hi, vcc_hi, 0
	s_cmp_gt_u32 s10, 41
	s_mov_b64 s[56:57], s[58:59]
	s_barrier
	s_cbranch_scc0 .LBB0_385
; #define PG8_WAIT_V(n) asm volatile("s_waitcnt vmcnt(" #n ")" ::: "memory")
; #define PG8_BAR __builtin_amdgcn_s_barrier()
;     DI void operator()(const f32x4 (&acc)[2][2][4][2], const Unit& u, int wr, int wc, int fr, int fq) const {
;         const int row0 = u.pm * BM + wr * 64 + fr, col0 = u.pn * BM + wc * 32 + 8 * fq;
; #pragma unroll
;         for (int ai = 0; ai < 2; ++ai)
; #pragma unroll
;             for (int m = 0; m < 4; ++m) { u16* rowp = O + (size_t)(row0 + ai * HALF + m * 16) * ldc + col0;
; #pragma unroll
;                 for (int bj = 0; bj < 2; ++bj) { const f32x4 v0 = acc[ai][bj][m][0], v1 = acc[ai][bj][m][1];
;                     uint4 w = {pack2(v0[0], v0[1]), pack2(v0[2], v0[3]), pack2(v1[0], v1[1]), pack2(v1[2], v1[3])}; *(uint4*)(rowp + bj * HALF) = w; } }
; template <class Epi, class Sched, bool STAMP = false>
; __device__ __forceinline__ void gemm_phase(PG8_LAS unsigned char* lds, const Gemm g, const Sched& S, const Epi& E, unsigned long long* stamps) {
;     ...
;         cur = nxt; cA = nA; cB = nB; ++ui;
;     }
;     PG8_WAIT_V(0);
;     if (wr == 0) PG8_BAR;
;     PG8_BAR;
	v_lshl_add_u32 v170, s94, 8, v144
	v_lshl_or_b32 v172, s97, 8, v146
	v_ashrrev_i32_e32 v171, 31, v170
	v_ashrrev_i32_e32 v173, 31, v172
	v_lshlrev_b64 v[174:175], 11, v[170:171]
	v_lshl_add_u64 v[174:175], s[14:15], 0, v[174:175]
	v_lshlrev_b64 v[172:173], 1, v[172:173]
	v_lshl_add_u64 v[174:175], v[174:175], 0, v[172:173]
	v_cvt_pk_bf16_f32 v60, v60, v61
	v_cvt_pk_bf16_f32 v61, v62, v63
	v_cvt_pk_bf16_f32 v62, v56, v57
	v_add_co_u32_e32 v56, vcc, s90, v174
	v_cvt_pk_bf16_f32 v68, v68, v69
	v_cvt_pk_bf16_f32 v69, v70, v71
	v_cvt_pk_bf16_f32 v70, v64, v65
	v_lshl_add_u64 v[64:65], v[174:175], 0, s[34:35]
	v_addc_co_u32_e32 v57, vcc, 0, v175, vcc
	v_cvt_pk_bf16_f32 v44, v44, v45
	v_cvt_pk_bf16_f32 v45, v46, v47
	v_cvt_pk_bf16_f32 v46, v40, v41
	v_cvt_pk_bf16_f32 v47, v42, v43
	v_cvt_pk_bf16_f32 v108, v108, v109
	v_cvt_pk_bf16_f32 v109, v110, v111
	v_cvt_pk_bf16_f32 v110, v104, v105
	v_or_b32_e32 v104, 16, v170
	global_store_dwordx4 v[64:65], v[44:47], off offset:256
	v_ashrrev_i32_e32 v105, 31, v104
	v_cvt_pk_bf16_f32 v92, v92, v93
	v_add_co_u32_e32 v46, vcc, s91, v174
	v_cvt_pk_bf16_f32 v93, v94, v95
	v_cvt_pk_bf16_f32 v94, v88, v89
	v_or_b32_e32 v88, 32, v170
	v_lshl_add_u64 v[44:45], v[174:175], 0, s[36:37]
	v_addc_co_u32_e32 v47, vcc, 0, v175, vcc
	v_cvt_pk_bf16_f32 v28, v28, v29
	v_cvt_pk_bf16_f32 v29, v30, v31
	v_cvt_pk_bf16_f32 v30, v24, v25
	v_cvt_pk_bf16_f32 v31, v26, v27
	v_lshlrev_b64 v[104:105], 11, v[104:105]
	v_ashrrev_i32_e32 v89, 31, v88
	v_cvt_pk_bf16_f32 v76, v76, v77
	v_cvt_pk_bf16_f32 v77, v78, v79
	v_cvt_pk_bf16_f32 v78, v72, v73
	v_or_b32_e32 v72, 48, v170
	global_store_dwordx4 v[44:45], v[28:31], off offset:256
	v_cvt_pk_bf16_f32 v111, v106, v107
	v_lshl_add_u64 v[104:105], s[14:15], 0, v[104:105]
	v_add_co_u32_e32 v30, vcc, s92, v174
	v_lshlrev_b64 v[88:89], 11, v[88:89]
	v_ashrrev_i32_e32 v73, 31, v72
	v_lshl_add_u64 v[28:29], v[174:175], 0, s[52:53]
	v_addc_co_u32_e32 v31, vcc, 0, v175, vcc
	v_cvt_pk_bf16_f32 v12, v12, v13
	v_cvt_pk_bf16_f32 v13, v14, v15
	v_cvt_pk_bf16_f32 v14, v8, v9
	v_cvt_pk_bf16_f32 v15, v10, v11
	global_store_dwordx4 v[174:175], v[108:111], off offset:256
	v_cvt_pk_bf16_f32 v95, v90, v91
	v_lshl_add_u64 v[88:89], s[14:15], 0, v[88:89]
	v_lshl_add_u64 v[108:109], v[104:105], 0, v[172:173]
	v_lshlrev_b64 v[72:73], 11, v[72:73]
	global_store_dwordx4 v[28:29], v[12:15], off offset:256
	global_store_dwordx4 v[108:109], v[92:95], off offset:256
	v_cvt_pk_bf16_f32 v79, v74, v75
	v_add_co_u32_e32 v14, vcc, s93, v174
	v_lshl_add_u64 v[92:93], v[88:89], 0, v[172:173]
	v_lshl_add_u64 v[72:73], s[14:15], 0, v[72:73]
	v_addc_co_u32_e32 v15, vcc, 0, v175, vcc
	v_cvt_pk_bf16_f32 v124, v124, v125
	v_cvt_pk_bf16_f32 v125, v126, v127
	v_cvt_pk_bf16_f32 v126, v120, v121
	v_cvt_pk_bf16_f32 v127, v122, v123
	v_cvt_pk_bf16_f32 v104, v116, v117
	v_cvt_pk_bf16_f32 v105, v118, v119
	v_cvt_pk_bf16_f32 v106, v112, v113
	v_cvt_pk_bf16_f32 v107, v114, v115
	v_cvt_pk_bf16_f32 v88, v100, v101
	v_cvt_pk_bf16_f32 v89, v102, v103
	v_cvt_pk_bf16_f32 v90, v96, v97
	v_cvt_pk_bf16_f32 v91, v98, v99
	global_store_dwordx4 v[92:93], v[76:79], off offset:256
	v_cvt_pk_bf16_f32 v74, v80, v81
	v_cvt_pk_bf16_f32 v75, v82, v83
	v_lshl_add_u64 v[76:77], v[72:73], 0, v[172:173]
	v_cvt_pk_bf16_f32 v72, v84, v85
	v_cvt_pk_bf16_f32 v73, v86, v87
	v_cvt_pk_bf16_f32 v71, v66, v67
	v_cvt_pk_bf16_f32 v63, v58, v59
	v_cvt_pk_bf16_f32 v40, v52, v53
	v_cvt_pk_bf16_f32 v41, v54, v55
	v_cvt_pk_bf16_f32 v42, v48, v49
	v_cvt_pk_bf16_f32 v43, v50, v51
	v_cvt_pk_bf16_f32 v24, v36, v37
	v_cvt_pk_bf16_f32 v25, v38, v39
	v_cvt_pk_bf16_f32 v26, v32, v33
	v_cvt_pk_bf16_f32 v27, v34, v35
	v_lshl_add_u64 v[12:13], v[174:175], 0, s[54:55]
	v_cvt_pk_bf16_f32 v8, v20, v21
	v_cvt_pk_bf16_f32 v9, v22, v23
	v_cvt_pk_bf16_f32 v10, v16, v17
	v_cvt_pk_bf16_f32 v11, v18, v19
	v_cvt_pk_bf16_f32 v4, v4, v5
	v_cvt_pk_bf16_f32 v5, v6, v7
	v_cvt_pk_bf16_f32 v6, v0, v1
	v_cvt_pk_bf16_f32 v7, v2, v3
	s_and_b64 vcc, exec, s[2:3]
	s_mov_b32 s97, s95
	s_mov_b32 s94, s96
	s_mov_b64 s[58:59], s[0:1]
	s_mov_b64 s[56:57], s[4:5]
	global_store_dwordx4 v[174:175], v[124:127], off
	global_store_dwordx4 v[108:109], v[104:107], off
	global_store_dwordx4 v[92:93], v[88:91], off
	global_store_dwordx4 v[76:77], v[72:75], off
	global_store_dwordx4 v[76:77], v[68:71], off offset:256
	global_store_dwordx4 v[56:57], v[60:63], off
	global_store_dwordx4 v[46:47], v[40:43], off
	global_store_dwordx4 v[30:31], v[24:27], off
	global_store_dwordx4 v[14:15], v[8:11], off
	global_store_dwordx4 v[12:13], v[4:7], off offset:256
	s_cbranch_vccz .LBB0_374
	s_waitcnt vmcnt(0)
	s_cmpk_gt_u32 s65, 0xff
	s_cbranch_scc1 .LBB0_389
	s_barrier

; #define PG8_STAGE(bufoff, gbase, voff) do { _Pragma("unroll") for (int _i = 0; _i < 2; ++_i) \
;         __builtin_amdgcn_global_load_lds((const unsigned*)((const char*)(gbase) + (voff)[_i]), (PG8_LAS unsigned*)(lds + (bufoff) + ldsw + _i * 8192), 16, 0, 0); } while (0)
; #define PG8_LDA(dst, b, h) do { _Pragma("unroll") for (int m = 0; m < 4; ++m) _Pragma("unroll") for (int k = 0; k < 2; ++k) dst[m][k] = *(const PG8_LAS bf16x8*)(lds + PG8_SA(b, h) + aoff + m * 2048 + k * 1024); } while (0)
; #define PG8_LDB(dst, b, h) do { _Pragma("unroll") for (int n = 0; n < 2; ++n) _Pragma("unroll") for (int k = 0; k < 2; ++k) dst[n][k] = *(const PG8_LAS bf16x8*)(lds + PG8_SB(b, h) + boff + n * 2048 + k * 1024); } while (0)
; #define PG8_MMA(ai, bj, At, Bt) do { __builtin_amdgcn_s_setprio(1); _Pragma("unroll") for (int m = 0; m < 4; ++m) _Pragma("unroll") for (int n = 0; n < 2; ++n) _Pragma("unroll") for (int k = 0; k < 2; ++k) \
;         acc[ai][bj][m][n] = __builtin_amdgcn_mfma_f32_16x16x32_bf16(Bt[n][k], At[m][k], acc[ai][bj][m][n], 0, 0, 0); __builtin_amdgcn_s_setprio(0); } while (0)
; #define PG8_WAIT_V(n) asm volatile("s_waitcnt vmcnt(" #n ")" ::: "memory")
; template <class Epi, class Sched, bool STAMP = false>
; __device__ __forceinline__ void gemm_phase(PG8_LAS unsigned char* lds, const Gemm g, const Sched& S, const Epi& E, unsigned long long* stamps) {
;     ...
;             const bool last = (t == nt - 2);
;             const char* a1 = cA + (size_t)(t + 1) * kstep;
;             const char* a2 = last ? nA : cA + (size_t)(t + 2) * kstep; const char* b2 = last ? nB : cB + (size_t)(t + 2) * kstep;
;             const char* a3 = a2 + kstep; const char* b3 = b2 + kstep;
;             if (last && has_next) S.a_ready(nxt);
;             PG8_LDB(B0, 0, 0); PG8_SCHED; PG8_LDA(At, 0, 0); PG8_STAGE(PG8_SA(1, 1), a1 + hstep, voffA);
;             PG8_WAIT_L(8); PG8_BAR; PG8_WAIT_L(0); PG8_MMA(0, 0, At, B0); PG8_BAR; PG8_SCHED;
;             PG8_LDB(B1, 0, 1); PG8_STAGE(PG8_SB(0, 0), b2, voffB);
;             PG8_BAR; PG8_WAIT_L(0); PG8_MMA(0, 1, At, B1); PG8_BAR;
;             PG8_LDA(At, 0, 1); PG8_STAGE(PG8_SA(0, 0), a2, voffA);
;             PG8_BAR; PG8_WAIT_L(0); PG8_MMA(1, 0, At, B0); PG8_BAR; PG8_SCHED;
;             PG8_STAGE(PG8_SB(0, 1), b2 + hstep, voffB);
;             PG8_WAIT_V(6); PG8_BAR; PG8_MMA(1, 1, At, B1); PG8_BAR;
.LBB0_439:
	ds_read_b128 v[140:143], v147
	ds_read_b128 v[170:173], v148
	ds_read_b128 v[174:177], v149
	ds_read_b128 v[178:181], v150
	s_add_u32 s36, s34, 0x100
	s_addc_u32 s37, s35, 0
	s_cmp_eq_u32 s10, 12
	s_cselect_b32 s43, s5, s37
	s_cselect_b32 s42, s4, s36
	s_cselect_b32 s41, s1, s78
	s_cselect_b32 s40, s0, s77
	s_mov_b32 m0, s67
	ds_read_b128 v[182:185], v145
	ds_read_b128 v[186:189], v145 offset:1024
	ds_read_b128 v[190:193], v145 offset:2048
	ds_read_b128 v[194:197], v145 offset:3072
	ds_read_b128 v[198:201], v145 offset:4096
	ds_read_b128 v[202:205], v145 offset:5120
	ds_read_b128 v[206:209], v145 offset:6144
	ds_read_b128 v[210:213], v145 offset:7168
	global_load_lds_dwordx4 v132, s[34:35]
	s_mov_b32 m0, s68
	s_nop 0
	global_load_lds_dwordx4 v134, s[34:35]
	s_waitcnt lgkmcnt(8)
	s_barrier
	s_waitcnt lgkmcnt(0)
	s_setprio 1
	s_waitcnt lgkmcnt(0)
	v_mfma_f32_16x16x32_bf16 v[124:127], v[140:143], v[182:185], v[124:127]
	v_mfma_f32_16x16x32_bf16 v[120:123], v[174:177], v[182:185], v[120:123]
	v_mfma_f32_16x16x32_bf16 v[108:111], v[140:143], v[190:193], v[108:111]
	v_mfma_f32_16x16x32_bf16 v[104:107], v[174:177], v[190:193], v[104:107]
	v_mfma_f32_16x16x32_bf16 v[92:95], v[140:143], v[198:201], v[92:95]
	v_mfma_f32_16x16x32_bf16 v[88:91], v[174:177], v[198:201], v[88:91]
	v_mfma_f32_16x16x32_bf16 v[76:79], v[140:143], v[206:209], v[76:79]
	v_mfma_f32_16x16x32_bf16 v[72:75], v[174:177], v[206:209], v[72:75]
	v_mfma_f32_16x16x32_bf16 v[124:127], v[170:173], v[186:189], v[124:127]
	v_mfma_f32_16x16x32_bf16 v[120:123], v[178:181], v[186:189], v[120:123]
	v_mfma_f32_16x16x32_bf16 v[108:111], v[170:173], v[194:197], v[108:111]
	v_mfma_f32_16x16x32_bf16 v[104:107], v[178:181], v[194:197], v[104:107]
	v_mfma_f32_16x16x32_bf16 v[92:95], v[170:173], v[202:205], v[92:95]
	v_mfma_f32_16x16x32_bf16 v[88:91], v[178:181], v[202:205], v[88:91]
	v_mfma_f32_16x16x32_bf16 v[76:79], v[170:173], v[210:213], v[76:79]
	v_mfma_f32_16x16x32_bf16 v[72:75], v[178:181], v[210:213], v[72:75]
	s_setprio 0
	s_barrier
	s_mov_b32 m0, s49
	ds_read_b128 v[214:217], v151
	ds_read_b128 v[218:221], v152
	ds_read_b128 v[222:225], v153
	ds_read_b128 v[226:229], v154
	global_load_lds_dwordx4 v130, s[40:41]
	s_mov_b32 m0, s52
	s_nop 0
	global_load_lds_dwordx4 v128, s[40:41]
	s_barrier
	s_waitcnt lgkmcnt(0)
	s_setprio 1
	s_waitcnt lgkmcnt(0)
	v_mfma_f32_16x16x32_bf16 v[116:119], v[214:217], v[182:185], v[116:119]
	v_mfma_f32_16x16x32_bf16 v[112:115], v[222:225], v[182:185], v[112:115]
	v_mfma_f32_16x16x32_bf16 v[100:103], v[214:217], v[190:193], v[100:103]
	v_mfma_f32_16x16x32_bf16 v[96:99], v[222:225], v[190:193], v[96:99]
	v_mfma_f32_16x16x32_bf16 v[84:87], v[214:217], v[198:201], v[84:87]
	v_mfma_f32_16x16x32_bf16 v[80:83], v[222:225], v[198:201], v[80:83]
	v_mfma_f32_16x16x32_bf16 v[68:71], v[214:217], v[206:209], v[68:71]
	v_mfma_f32_16x16x32_bf16 v[64:67], v[222:225], v[206:209], v[64:67]
	v_mfma_f32_16x16x32_bf16 v[116:119], v[218:221], v[186:189], v[116:119]
	v_mfma_f32_16x16x32_bf16 v[112:115], v[226:229], v[186:189], v[112:115]
	v_mfma_f32_16x16x32_bf16 v[100:103], v[218:221], v[194:197], v[100:103]
	v_mfma_f32_16x16x32_bf16 v[96:99], v[226:229], v[194:197], v[96:99]
	v_mfma_f32_16x16x32_bf16 v[84:87], v[218:221], v[202:205], v[84:87]
	v_mfma_f32_16x16x32_bf16 v[80:83], v[226:229], v[202:205], v[80:83]
	v_mfma_f32_16x16x32_bf16 v[68:71], v[218:221], v[210:213], v[68:71]
	v_mfma_f32_16x16x32_bf16 v[64:67], v[226:229], v[210:213], v[64:67]
	s_setprio 0
	s_mov_b32 m0, s46
	s_barrier
	ds_read_b128 v[182:185], v145 offset:16384
	ds_read_b128 v[186:189], v145 offset:17408
	ds_read_b128 v[190:193], v145 offset:18432
	ds_read_b128 v[194:197], v145 offset:19456
	ds_read_b128 v[198:201], v145 offset:20480
	ds_read_b128 v[202:205], v145 offset:21504
	ds_read_b128 v[206:209], v145 offset:22528
	ds_read_b128 v[210:213], v145 offset:23552
	global_load_lds_dwordx4 v130, s[42:43]
	s_mov_b32 m0, s53
	s_nop 0
	global_load_lds_dwordx4 v128, s[42:43]
	s_barrier
	s_waitcnt lgkmcnt(0)
	s_setprio 1
	s_waitcnt lgkmcnt(0)
	v_mfma_f32_16x16x32_bf16 v[60:63], v[140:143], v[182:185], v[60:63]
	v_mfma_f32_16x16x32_bf16 v[56:59], v[174:177], v[182:185], v[56:59]
	v_mfma_f32_16x16x32_bf16 v[44:47], v[140:143], v[190:193], v[44:47]
	v_mfma_f32_16x16x32_bf16 v[40:43], v[174:177], v[190:193], v[40:43]
	v_mfma_f32_16x16x32_bf16 v[28:31], v[140:143], v[198:201], v[28:31]
	v_mfma_f32_16x16x32_bf16 v[24:27], v[174:177], v[198:201], v[24:27]
	v_mfma_f32_16x16x32_bf16 v[12:15], v[140:143], v[206:209], v[12:15]
	v_mfma_f32_16x16x32_bf16 v[8:11], v[174:177], v[206:209], v[8:11]
	v_mfma_f32_16x16x32_bf16 v[60:63], v[170:173], v[186:189], v[60:63]
	v_mfma_f32_16x16x32_bf16 v[56:59], v[178:181], v[186:189], v[56:59]
	v_mfma_f32_16x16x32_bf16 v[44:47], v[170:173], v[194:197], v[44:47]
	v_mfma_f32_16x16x32_bf16 v[40:43], v[178:181], v[194:197], v[40:43]
	v_mfma_f32_16x16x32_bf16 v[28:31], v[170:173], v[202:205], v[28:31]
	v_mfma_f32_16x16x32_bf16 v[24:27], v[178:181], v[202:205], v[24:27]
	v_mfma_f32_16x16x32_bf16 v[12:15], v[170:173], v[210:213], v[12:15]
	v_mfma_f32_16x16x32_bf16 v[8:11], v[178:181], v[210:213], v[8:11]
	s_setprio 0
	s_barrier
	s_add_u32 s34, s40, 0x44000
	s_addc_u32 s35, s41, 0
	s_mov_b32 m0, s54
	s_nop 0
	global_load_lds_dwordx4 v130, s[34:35]
	s_mov_b32 m0, s55
	s_nop 0
	global_load_lds_dwordx4 v128, s[34:35]
	s_waitcnt vmcnt(6)
	s_barrier
; #define PG8_STAGE(bufoff, gbase, voff) do { _Pragma("unroll") for (int _i = 0; _i < 2; ++_i) \
;         __builtin_amdgcn_global_load_lds((const unsigned*)((const char*)(gbase) + (voff)[_i]), (PG8_LAS unsigned*)(lds + (bufoff) + ldsw + _i * 8192), 16, 0, 0); } while (0)
; #define PG8_LDA(dst, b, h) do { _Pragma("unroll") for (int m = 0; m < 4; ++m) _Pragma("unroll") for (int k = 0; k < 2; ++k) dst[m][k] = *(const PG8_LAS bf16x8*)(lds + PG8_SA(b, h) + aoff + m * 2048 + k * 1024); } while (0)
; #define PG8_LDB(dst, b, h) do { _Pragma("unroll") for (int n = 0; n < 2; ++n) _Pragma("unroll") for (int k = 0; k < 2; ++k) dst[n][k] = *(const PG8_LAS bf16x8*)(lds + PG8_SB(b, h) + boff + n * 2048 + k * 1024); } while (0)
; #define PG8_MMA(ai, bj, At, Bt) do { __builtin_amdgcn_s_setprio(1); _Pragma("unroll") for (int m = 0; m < 4; ++m) _Pragma("unroll") for (int n = 0; n < 2; ++n) _Pragma("unroll") for (int k = 0; k < 2; ++k) \
;         acc[ai][bj][m][n] = __builtin_amdgcn_mfma_f32_16x16x32_bf16(Bt[n][k], At[m][k], acc[ai][bj][m][n], 0, 0, 0); __builtin_amdgcn_s_setprio(0); } while (0)
; #define PG8_WAIT_V(n) asm volatile("s_waitcnt vmcnt(" #n ")" ::: "memory")
; #define PG8_WAIT_L(n) asm volatile("s_waitcnt lgkmcnt(" #n ")" ::: "memory")
; #define PG8_BAR __builtin_amdgcn_s_barrier()
; #define PG8_SCHED __builtin_amdgcn_sched_barrier(0)
; template <class Epi, class Sched, bool STAMP = false>
; __device__ __forceinline__ void gemm_phase(PG8_LAS unsigned char* lds, const Gemm g, const Sched& S, const Epi& E, unsigned long long* stamps) {
;     ...
;             PG8_WAIT_V(6); PG8_BAR; PG8_MMA(1, 1, At, B1); PG8_BAR;
;             PG8_LDB(B0, 1, 0); PG8_SCHED; PG8_LDA(At, 1, 0); PG8_STAGE(PG8_SA(0, 1), a2 + hstep, voffA);
;             PG8_WAIT_L(8); PG8_BAR; PG8_WAIT_L(0); PG8_MMA(0, 0, At, B0); PG8_BAR; PG8_SCHED;
;             PG8_LDB(B1, 1, 1); PG8_STAGE(PG8_SB(1, 0), b3, voffB);
;             PG8_BAR; PG8_WAIT_L(0); PG8_MMA(0, 1, At, B1); PG8_BAR;
;             PG8_LDA(At, 1, 1); PG8_STAGE(PG8_SA(1, 0), a3, voffA);
;             PG8_BAR; PG8_WAIT_L(0); PG8_MMA(1, 0, At, B0); PG8_BAR; PG8_SCHED;
	s_setprio 1
	v_mfma_f32_16x16x32_bf16 v[52:55], v[214:217], v[182:185], v[52:55]
	v_mfma_f32_16x16x32_bf16 v[48:51], v[222:225], v[182:185], v[48:51]
	v_mfma_f32_16x16x32_bf16 v[36:39], v[214:217], v[190:193], v[36:39]
	v_mfma_f32_16x16x32_bf16 v[32:35], v[222:225], v[190:193], v[32:35]
	v_mfma_f32_16x16x32_bf16 v[20:23], v[214:217], v[198:201], v[20:23]
	v_mfma_f32_16x16x32_bf16 v[16:19], v[222:225], v[198:201], v[16:19]
	v_mfma_f32_16x16x32_bf16 v[4:7], v[214:217], v[206:209], v[4:7]
	v_mfma_f32_16x16x32_bf16 v[0:3], v[222:225], v[206:209], v[0:3]
	v_mfma_f32_16x16x32_bf16 v[52:55], v[218:221], v[186:189], v[52:55]
	v_mfma_f32_16x16x32_bf16 v[48:51], v[226:229], v[186:189], v[48:51]
	v_mfma_f32_16x16x32_bf16 v[36:39], v[218:221], v[194:197], v[36:39]
	v_mfma_f32_16x16x32_bf16 v[32:35], v[226:229], v[194:197], v[32:35]
	v_mfma_f32_16x16x32_bf16 v[20:23], v[218:221], v[202:205], v[20:23]
	v_mfma_f32_16x16x32_bf16 v[16:19], v[226:229], v[202:205], v[16:19]
	v_mfma_f32_16x16x32_bf16 v[4:7], v[218:221], v[210:213], v[4:7]
	v_mfma_f32_16x16x32_bf16 v[0:3], v[226:229], v[210:213], v[0:3]
	s_setprio 0
	s_barrier
	ds_read_b128 v[140:143], v155
	ds_read_b128 v[170:173], v156
	ds_read_b128 v[174:177], v157
	ds_read_b128 v[178:181], v165
	s_add_u32 s34, s42, 0x44000
	s_addc_u32 s35, s43, 0
	s_mov_b32 m0, s56
	ds_read_b128 v[182:185], v145 offset:32768
	ds_read_b128 v[186:189], v145 offset:33792
	ds_read_b128 v[190:193], v145 offset:34816
	ds_read_b128 v[194:197], v145 offset:35840
	ds_read_b128 v[198:201], v145 offset:36864
	ds_read_b128 v[202:205], v145 offset:37888
	ds_read_b128 v[206:209], v145 offset:38912
	ds_read_b128 v[210:213], v145 offset:39936
	global_load_lds_dwordx4 v130, s[34:35]
	s_mov_b32 m0, s57
	s_nop 0
	global_load_lds_dwordx4 v128, s[34:35]
	s_waitcnt lgkmcnt(8)
	s_barrier
	s_waitcnt lgkmcnt(0)
	s_setprio 1
	s_waitcnt lgkmcnt(0)
	v_mfma_f32_16x16x32_bf16 v[124:127], v[140:143], v[182:185], v[124:127]
	v_mfma_f32_16x16x32_bf16 v[120:123], v[174:177], v[182:185], v[120:123]
	v_mfma_f32_16x16x32_bf16 v[108:111], v[140:143], v[190:193], v[108:111]
	v_mfma_f32_16x16x32_bf16 v[104:107], v[174:177], v[190:193], v[104:107]
	v_mfma_f32_16x16x32_bf16 v[92:95], v[140:143], v[198:201], v[92:95]
	v_mfma_f32_16x16x32_bf16 v[88:91], v[174:177], v[198:201], v[88:91]
	v_mfma_f32_16x16x32_bf16 v[76:79], v[140:143], v[206:209], v[76:79]
	v_mfma_f32_16x16x32_bf16 v[72:75], v[174:177], v[206:209], v[72:75]
	v_mfma_f32_16x16x32_bf16 v[124:127], v[170:173], v[186:189], v[124:127]
	v_mfma_f32_16x16x32_bf16 v[120:123], v[178:181], v[186:189], v[120:123]
	v_mfma_f32_16x16x32_bf16 v[108:111], v[170:173], v[194:197], v[108:111]
	v_mfma_f32_16x16x32_bf16 v[104:107], v[178:181], v[194:197], v[104:107]
	v_mfma_f32_16x16x32_bf16 v[92:95], v[170:173], v[202:205], v[92:95]
	v_mfma_f32_16x16x32_bf16 v[88:91], v[178:181], v[202:205], v[88:91]
	v_mfma_f32_16x16x32_bf16 v[76:79], v[170:173], v[210:213], v[76:79]
	v_mfma_f32_16x16x32_bf16 v[72:75], v[178:181], v[210:213], v[72:75]
	s_setprio 0
	s_barrier
	s_mov_b32 m0, s60
	ds_read_b128 v[214:217], v166
	ds_read_b128 v[218:221], v167
	ds_read_b128 v[222:225], v168
	ds_read_b128 v[226:229], v169
	s_add_u32 s100, s40, 0x80
	s_addc_u32 s101, s41, 0
	global_load_lds_dwordx4 v130, s[100:101]
	s_mov_b32 m0, s61
	s_nop 0
	global_load_lds_dwordx4 v128, s[100:101]
	s_barrier
	s_waitcnt lgkmcnt(0)
	s_setprio 1
	s_waitcnt lgkmcnt(0)
	v_mfma_f32_16x16x32_bf16 v[116:119], v[214:217], v[182:185], v[116:119]
	v_mfma_f32_16x16x32_bf16 v[112:115], v[222:225], v[182:185], v[112:115]
	v_mfma_f32_16x16x32_bf16 v[100:103], v[214:217], v[190:193], v[100:103]
	v_mfma_f32_16x16x32_bf16 v[96:99], v[222:225], v[190:193], v[96:99]
	v_mfma_f32_16x16x32_bf16 v[84:87], v[214:217], v[198:201], v[84:87]
	v_mfma_f32_16x16x32_bf16 v[80:83], v[222:225], v[198:201], v[80:83]
	v_mfma_f32_16x16x32_bf16 v[68:71], v[214:217], v[206:209], v[68:71]
	v_mfma_f32_16x16x32_bf16 v[64:67], v[222:225], v[206:209], v[64:67]
	v_mfma_f32_16x16x32_bf16 v[116:119], v[218:221], v[186:189], v[116:119]
	v_mfma_f32_16x16x32_bf16 v[112:115], v[226:229], v[186:189], v[112:115]
	v_mfma_f32_16x16x32_bf16 v[100:103], v[218:221], v[194:197], v[100:103]
	v_mfma_f32_16x16x32_bf16 v[96:99], v[226:229], v[194:197], v[96:99]
	v_mfma_f32_16x16x32_bf16 v[84:87], v[218:221], v[202:205], v[84:87]
	v_mfma_f32_16x16x32_bf16 v[80:83], v[226:229], v[202:205], v[80:83]
	v_mfma_f32_16x16x32_bf16 v[68:71], v[218:221], v[210:213], v[68:71]
	v_mfma_f32_16x16x32_bf16 v[64:67], v[226:229], v[210:213], v[64:67]
	s_setprio 0
	s_mov_b32 m0, s62
	s_barrier
	ds_read_b128 v[182:185], v145 offset:49152
	ds_read_b128 v[186:189], v145 offset:50176
	ds_read_b128 v[190:193], v145 offset:51200
	ds_read_b128 v[194:197], v145 offset:52224
	ds_read_b128 v[198:201], v145 offset:53248
	ds_read_b128 v[202:205], v145 offset:54272
	ds_read_b128 v[206:209], v145 offset:55296
	ds_read_b128 v[210:213], v145 offset:56320
	s_add_u32 s100, s42, 0x80
	s_addc_u32 s101, s43, 0
	global_load_lds_dwordx4 v130, s[100:101]
	s_mov_b32 m0, s63
	s_nop 0
	global_load_lds_dwordx4 v128, s[100:101]
	s_barrier
; DI float ex2(float x) { return __builtin_amdgcn_exp2f(x); }
; #define PG8_STAGE(bufoff, gbase, voff) do { _Pragma("unroll") for (int _i = 0; _i < 2; ++_i) \
;         __builtin_amdgcn_global_load_lds((const unsigned*)((const char*)(gbase) + (voff)[_i]), (PG8_LAS unsigned*)(lds + (bufoff) + ldsw + _i * 8192), 16, 0, 0); } while (0)
; #define PG8_MMA(ai, bj, At, Bt) do { __builtin_amdgcn_s_setprio(1); _Pragma("unroll") for (int m = 0; m < 4; ++m) _Pragma("unroll") for (int n = 0; n < 2; ++n) _Pragma("unroll") for (int k = 0; k < 2; ++k) \
;         acc[ai][bj][m][n] = __builtin_amdgcn_mfma_f32_16x16x32_bf16(Bt[n][k], At[m][k], acc[ai][bj][m][n], 0, 0, 0); __builtin_amdgcn_s_setprio(0); } while (0)
; #define PG8_WAIT_V(n) asm volatile("s_waitcnt vmcnt(" #n ")" ::: "memory")
; #define PG8_WAIT_L(n) asm volatile("s_waitcnt lgkmcnt(" #n ")" ::: "memory")
; #define PG8_BAR __builtin_amdgcn_s_barrier()
; #define PG8_SCHED __builtin_amdgcn_sched_barrier(0)
;     DI void operator()(const f32x4 (&acc)[2][2][4][2], const Unit& u, int wr, int wc, int fr, int fq) const {
;         const int row0 = u.pm * BM + wr * 64 + fr, hcol0 = ((u.pn * BM + wc * 32) >> 1) + 4 * fq;
; #pragma unroll
;         for (int ai = 0; ai < 2; ++ai)
; #pragma unroll
;             for (int m = 0; m < 4; ++m) { u16* rowp = O + (size_t)(row0 + ai * HALF + m * 16) * ldc + hcol0;
; #pragma unroll
;                 for (int bj = 0; bj < 2; ++bj) { const f32x4 g = acc[ai][bj][m][0], up = acc[ai][bj][m][1]; float r[4];
; #pragma unroll
;                     for (int j = 0; j < 4; ++j) r[j] = g[j] * up[j] * __builtin_amdgcn_rcpf(1.f + ex2(-LOG2E * g[j]));
;                     uint2 w = {pack2(r[0], r[1]), pack2(r[2], r[3])}; *(uint2*)(rowp + bj * (HALF / 2)) = w; } }
; template <class Epi, class Sched, bool STAMP = false>
; __device__ __forceinline__ void gemm_phase(PG8_LAS unsigned char* lds, const Gemm g, const Sched& S, const Epi& E, unsigned long long* stamps) {
;     ...
;             PG8_BAR; PG8_WAIT_L(0); PG8_MMA(1, 0, At, B0); PG8_BAR; PG8_SCHED;
;             PG8_STAGE(PG8_SB(1, 1), b3 + hstep, voffB);
;             PG8_WAIT_V(6); PG8_BAR; PG8_MMA(1, 1, At, B1); PG8_BAR;
;         }
	s_waitcnt lgkmcnt(0)
	s_setprio 1
	s_waitcnt lgkmcnt(0)
	v_mfma_f32_16x16x32_bf16 v[60:63], v[140:143], v[182:185], v[60:63]
	v_mfma_f32_16x16x32_bf16 v[56:59], v[174:177], v[182:185], v[56:59]
	v_mfma_f32_16x16x32_bf16 v[44:47], v[140:143], v[190:193], v[44:47]
	v_mfma_f32_16x16x32_bf16 v[40:43], v[174:177], v[190:193], v[40:43]
	v_mfma_f32_16x16x32_bf16 v[28:31], v[140:143], v[198:201], v[28:31]
	v_mfma_f32_16x16x32_bf16 v[24:27], v[174:177], v[198:201], v[24:27]
	v_mfma_f32_16x16x32_bf16 v[12:15], v[140:143], v[206:209], v[12:15]
	v_mfma_f32_16x16x32_bf16 v[8:11], v[174:177], v[206:209], v[8:11]
	v_mfma_f32_16x16x32_bf16 v[60:63], v[170:173], v[186:189], v[60:63]
	v_mfma_f32_16x16x32_bf16 v[56:59], v[178:181], v[186:189], v[56:59]
	v_mfma_f32_16x16x32_bf16 v[44:47], v[170:173], v[194:197], v[44:47]
	v_mfma_f32_16x16x32_bf16 v[40:43], v[178:181], v[194:197], v[40:43]
	v_mfma_f32_16x16x32_bf16 v[28:31], v[170:173], v[202:205], v[28:31]
	v_mfma_f32_16x16x32_bf16 v[24:27], v[178:181], v[202:205], v[24:27]
	v_mfma_f32_16x16x32_bf16 v[12:15], v[170:173], v[210:213], v[12:15]
	v_mfma_f32_16x16x32_bf16 v[8:11], v[178:181], v[210:213], v[8:11]
	s_setprio 0
	s_barrier
	s_add_u32 s34, s40, 0x44080
	s_addc_u32 s35, s41, 0
	s_mov_b32 m0, s64
	s_nop 0
	global_load_lds_dwordx4 v130, s[34:35]
	s_mov_b32 m0, s65
	s_nop 0
	global_load_lds_dwordx4 v128, s[34:35]
	s_waitcnt vmcnt(6)
	s_barrier
	s_setprio 1
	v_mfma_f32_16x16x32_bf16 v[52:55], v[214:217], v[182:185], v[52:55]
	v_mfma_f32_16x16x32_bf16 v[48:51], v[222:225], v[182:185], v[48:51]
	v_mfma_f32_16x16x32_bf16 v[36:39], v[214:217], v[190:193], v[36:39]
	v_mfma_f32_16x16x32_bf16 v[32:35], v[222:225], v[190:193], v[32:35]
	v_mfma_f32_16x16x32_bf16 v[20:23], v[214:217], v[198:201], v[20:23]
	v_mfma_f32_16x16x32_bf16 v[16:19], v[222:225], v[198:201], v[16:19]
	v_mfma_f32_16x16x32_bf16 v[4:7], v[214:217], v[206:209], v[4:7]
	v_mfma_f32_16x16x32_bf16 v[0:3], v[222:225], v[206:209], v[0:3]
	v_mfma_f32_16x16x32_bf16 v[52:55], v[218:221], v[186:189], v[52:55]
	v_mfma_f32_16x16x32_bf16 v[48:51], v[226:229], v[186:189], v[48:51]
	v_mfma_f32_16x16x32_bf16 v[36:39], v[218:221], v[194:197], v[36:39]
	v_mfma_f32_16x16x32_bf16 v[32:35], v[226:229], v[194:197], v[32:35]
	v_mfma_f32_16x16x32_bf16 v[20:23], v[218:221], v[202:205], v[20:23]
	v_mfma_f32_16x16x32_bf16 v[16:19], v[226:229], v[202:205], v[16:19]
	v_mfma_f32_16x16x32_bf16 v[4:7], v[218:221], v[210:213], v[4:7]
	v_mfma_f32_16x16x32_bf16 v[0:3], v[226:229], v[210:213], v[0:3]
	s_setprio 0
	s_add_i32 s10, s10, 2
	s_add_u32 s77, s77, 0x100
	s_addc_u32 s78, s78, 0
	s_cmp_gt_u32 s10, 13
	s_mov_b64 s[34:35], s[36:37]
	s_barrier
	s_cbranch_scc0 .LBB0_439
	v_mul_f32_e32 v171, 0xbfb8aa3b, v124
	v_exp_f32_e32 v171, v171
	v_mul_f32_e32 v174, 0xbfb8aa3b, v125
	v_exp_f32_e32 v175, v174
	s_lshl_b32 s10, s76, 8
	v_add_f32_e32 v171, 1.0, v171
	v_rcp_f32_e32 v174, v171
	v_add_f32_e32 v171, 1.0, v175
	v_mul_f32_e32 v175, 0xbfb8aa3b, v126
	v_exp_f32_e32 v176, v175
	v_mul_f32_e32 v175, 0xbfb8aa3b, v127
	v_exp_f32_e32 v177, v175
	v_rcp_f32_e32 v175, v171
	v_add_f32_e32 v171, 1.0, v176
	v_rcp_f32_e32 v176, v171
	v_add_f32_e32 v171, 1.0, v177
	v_rcp_f32_e32 v177, v171
	v_pk_mul_f32 v[122:123], v[126:127], v[122:123]
	v_pk_mul_f32 v[120:121], v[124:125], v[120:121]
	s_or_b32 s10, s10, s59
	v_pk_mul_f32 v[120:121], v[120:121], v[174:175]
	v_pk_mul_f32 v[122:123], v[122:123], v[176:177]
	s_ashr_i32 s10, s10, 1
	v_cvt_pk_bf16_f32 v120, v120, v121
	v_cvt_pk_bf16_f32 v121, v122, v123
	v_mul_f32_e32 v122, 0xbfb8aa3b, v116
	v_mul_f32_e32 v123, 0xbfb8aa3b, v117
	v_or_b32_e32 v140, s10, v146
	v_exp_f32_e32 v122, v122
	v_exp_f32_e32 v123, v123
	v_lshl_add_u32 v170, s75, 8, v144
	v_ashrrev_i32_e32 v141, 31, v140
	v_mov_b64_e32 v[142:143], s[12:13]
	v_mad_i64_i32 v[172:173], s[34:35], v170, s69, v[142:143]
	v_lshlrev_b64 v[140:141], 1, v[140:141]
	v_lshl_add_u64 v[172:173], v[172:173], 0, v[140:141]
	global_store_dwordx2 v[172:173], v[120:121], off
	v_add_f32_e32 v120, 1.0, v122
	v_add_f32_e32 v121, 1.0, v123
	v_mul_f32_e32 v122, 0xbfb8aa3b, v118
	v_mul_f32_e32 v123, 0xbfb8aa3b, v119
	v_exp_f32_e32 v122, v122
	v_exp_f32_e32 v123, v123
	v_rcp_f32_e32 v120, v120
	v_rcp_f32_e32 v121, v121
	v_add_f32_e32 v122, 1.0, v122
	v_add_f32_e32 v123, 1.0, v123
	v_rcp_f32_e32 v122, v122
	v_rcp_f32_e32 v123, v123
	v_pk_mul_f32 v[114:115], v[118:119], v[114:115]
	v_pk_mul_f32 v[112:113], v[116:117], v[112:113]
	v_mul_f32_e32 v116, 0xbfb8aa3b, v110
	v_pk_mul_f32 v[112:113], v[112:113], v[120:121]
	v_pk_mul_f32 v[114:115], v[114:115], v[122:123]
	v_cvt_pk_bf16_f32 v112, v112, v113
	v_cvt_pk_bf16_f32 v113, v114, v115
	v_mul_f32_e32 v114, 0xbfb8aa3b, v108
	v_mul_f32_e32 v115, 0xbfb8aa3b, v109
	v_mul_f32_e32 v117, 0xbfb8aa3b, v111
	v_exp_f32_e32 v114, v114
	v_exp_f32_e32 v115, v115
	v_exp_f32_e32 v116, v116
	v_exp_f32_e32 v117, v117
	v_add_f32_e32 v114, 1.0, v114
	v_add_f32_e32 v115, 1.0, v115
	v_add_f32_e32 v116, 1.0, v116
	v_add_f32_e32 v117, 1.0, v117
	v_rcp_f32_e32 v114, v114
	v_rcp_f32_e32 v115, v115
	v_rcp_f32_e32 v116, v116
	v_rcp_f32_e32 v117, v117
	v_pk_mul_f32 v[106:107], v[110:111], v[106:107]
	v_pk_mul_f32 v[104:105], v[108:109], v[104:105]
	global_store_dwordx2 v[172:173], v[112:113], off offset:128
	v_pk_mul_f32 v[104:105], v[104:105], v[114:115]
	v_pk_mul_f32 v[106:107], v[106:107], v[116:117]
	v_cvt_pk_bf16_f32 v104, v104, v105
	v_cvt_pk_bf16_f32 v105, v106, v107
	v_mul_f32_e32 v106, 0xbfb8aa3b, v100
	v_mul_f32_e32 v107, 0xbfb8aa3b, v101
	v_exp_f32_e32 v106, v106
	v_exp_f32_e32 v107, v107
	v_or_b32_e32 v112, 16, v170
	v_mad_i64_i32 v[112:113], s[34:35], v112, s69, v[142:143]
; DI float ex2(float x) { return __builtin_amdgcn_exp2f(x); }
;     DI void operator()(const f32x4 (&acc)[2][2][4][2], const Unit& u, int wr, int wc, int fr, int fq) const {
;         const int row0 = u.pm * BM + wr * 64 + fr, hcol0 = ((u.pn * BM + wc * 32) >> 1) + 4 * fq;
; #pragma unroll
;         for (int ai = 0; ai < 2; ++ai)
; #pragma unroll
;             for (int m = 0; m < 4; ++m) { u16* rowp = O + (size_t)(row0 + ai * HALF + m * 16) * ldc + hcol0;
; #pragma unroll
;                 for (int bj = 0; bj < 2; ++bj) { const f32x4 g = acc[ai][bj][m][0], up = acc[ai][bj][m][1]; float r[4];
; #pragma unroll
;                     for (int j = 0; j < 4; ++j) r[j] = g[j] * up[j] * __builtin_amdgcn_rcpf(1.f + ex2(-LOG2E * g[j]));
;                     uint2 w = {pack2(r[0], r[1]), pack2(r[2], r[3])}; *(uint2*)(rowp + bj * (HALF / 2)) = w; } }
	v_lshl_add_u64 v[112:113], v[112:113], 0, v[140:141]
	global_store_dwordx2 v[112:113], v[104:105], off
	v_add_f32_e32 v104, 1.0, v106
	v_add_f32_e32 v105, 1.0, v107
	v_mul_f32_e32 v106, 0xbfb8aa3b, v102
	v_mul_f32_e32 v107, 0xbfb8aa3b, v103
	v_exp_f32_e32 v106, v106
	v_exp_f32_e32 v107, v107
	v_rcp_f32_e32 v104, v104
	v_rcp_f32_e32 v105, v105
	v_add_f32_e32 v106, 1.0, v106
	v_add_f32_e32 v107, 1.0, v107
	v_rcp_f32_e32 v106, v106
	v_rcp_f32_e32 v107, v107
	v_pk_mul_f32 v[98:99], v[102:103], v[98:99]
	v_pk_mul_f32 v[96:97], v[100:101], v[96:97]
	v_mul_f32_e32 v100, 0xbfb8aa3b, v94
	v_pk_mul_f32 v[96:97], v[96:97], v[104:105]
	v_pk_mul_f32 v[98:99], v[98:99], v[106:107]
	v_cvt_pk_bf16_f32 v96, v96, v97
	v_cvt_pk_bf16_f32 v97, v98, v99
	v_mul_f32_e32 v98, 0xbfb8aa3b, v92
	v_mul_f32_e32 v99, 0xbfb8aa3b, v93
	v_mul_f32_e32 v101, 0xbfb8aa3b, v95
	v_exp_f32_e32 v98, v98
	v_exp_f32_e32 v99, v99
	v_exp_f32_e32 v100, v100
	v_exp_f32_e32 v101, v101
	v_add_f32_e32 v98, 1.0, v98
	v_add_f32_e32 v99, 1.0, v99
	v_add_f32_e32 v100, 1.0, v100
	v_add_f32_e32 v101, 1.0, v101
	v_rcp_f32_e32 v98, v98
	v_rcp_f32_e32 v99, v99
	v_rcp_f32_e32 v100, v100
	v_rcp_f32_e32 v101, v101
	v_pk_mul_f32 v[90:91], v[94:95], v[90:91]
	v_pk_mul_f32 v[88:89], v[92:93], v[88:89]
	global_store_dwordx2 v[112:113], v[96:97], off offset:128
	v_pk_mul_f32 v[88:89], v[88:89], v[98:99]
	v_pk_mul_f32 v[90:91], v[90:91], v[100:101]
	v_cvt_pk_bf16_f32 v88, v88, v89
	v_cvt_pk_bf16_f32 v89, v90, v91
	v_mul_f32_e32 v90, 0xbfb8aa3b, v84
	v_mul_f32_e32 v91, 0xbfb8aa3b, v85
	v_exp_f32_e32 v90, v90
	v_exp_f32_e32 v91, v91
	v_or_b32_e32 v96, 32, v170
	v_mad_i64_i32 v[96:97], s[34:35], v96, s69, v[142:143]
	v_lshl_add_u64 v[96:97], v[96:97], 0, v[140:141]
	global_store_dwordx2 v[96:97], v[88:89], off
	v_add_f32_e32 v88, 1.0, v90
	v_add_f32_e32 v89, 1.0, v91
	v_mul_f32_e32 v90, 0xbfb8aa3b, v86
	v_mul_f32_e32 v91, 0xbfb8aa3b, v87
	v_exp_f32_e32 v90, v90
	v_exp_f32_e32 v91, v91
	v_rcp_f32_e32 v88, v88
	v_rcp_f32_e32 v89, v89
	v_add_f32_e32 v90, 1.0, v90
	v_add_f32_e32 v91, 1.0, v91
	v_rcp_f32_e32 v90, v90
	v_rcp_f32_e32 v91, v91
	v_pk_mul_f32 v[82:83], v[86:87], v[82:83]
	v_pk_mul_f32 v[80:81], v[84:85], v[80:81]
	v_mul_f32_e32 v84, 0xbfb8aa3b, v78
	v_pk_mul_f32 v[80:81], v[80:81], v[88:89]
	v_pk_mul_f32 v[82:83], v[82:83], v[90:91]
	v_cvt_pk_bf16_f32 v80, v80, v81
	v_cvt_pk_bf16_f32 v81, v82, v83
	v_mul_f32_e32 v82, 0xbfb8aa3b, v76
	v_mul_f32_e32 v83, 0xbfb8aa3b, v77
	v_mul_f32_e32 v85, 0xbfb8aa3b, v79
	v_exp_f32_e32 v82, v82
	v_exp_f32_e32 v83, v83
	v_exp_f32_e32 v84, v84
	v_exp_f32_e32 v85, v85
	v_add_f32_e32 v82, 1.0, v82
	v_add_f32_e32 v83, 1.0, v83
	v_add_f32_e32 v84, 1.0, v84
	v_add_f32_e32 v85, 1.0, v85
	v_rcp_f32_e32 v82, v82
	v_rcp_f32_e32 v83, v83
	v_rcp_f32_e32 v84, v84
	v_rcp_f32_e32 v85, v85
	v_pk_mul_f32 v[74:75], v[78:79], v[74:75]
	v_pk_mul_f32 v[72:73], v[76:77], v[72:73]
	global_store_dwordx2 v[96:97], v[80:81], off offset:128
	v_pk_mul_f32 v[72:73], v[72:73], v[82:83]
	v_pk_mul_f32 v[74:75], v[74:75], v[84:85]
	v_cvt_pk_bf16_f32 v72, v72, v73
	v_cvt_pk_bf16_f32 v73, v74, v75
	v_mul_f32_e32 v74, 0xbfb8aa3b, v68
	v_mul_f32_e32 v75, 0xbfb8aa3b, v69
	v_exp_f32_e32 v74, v74
	v_exp_f32_e32 v75, v75
	v_or_b32_e32 v80, 48, v170
	v_mad_i64_i32 v[80:81], s[34:35], v80, s69, v[142:143]
	v_lshl_add_u64 v[80:81], v[80:81], 0, v[140:141]
	global_store_dwordx2 v[80:81], v[72:73], off
	v_add_f32_e32 v72, 1.0, v74
	v_add_f32_e32 v73, 1.0, v75
	v_mul_f32_e32 v74, 0xbfb8aa3b, v70
	v_mul_f32_e32 v75, 0xbfb8aa3b, v71
	v_exp_f32_e32 v74, v74
	v_exp_f32_e32 v75, v75
	v_rcp_f32_e32 v72, v72
	v_rcp_f32_e32 v73, v73
	v_add_f32_e32 v74, 1.0, v74
	v_add_f32_e32 v75, 1.0, v75
	v_rcp_f32_e32 v74, v74
	v_rcp_f32_e32 v75, v75
	v_pk_mul_f32 v[66:67], v[70:71], v[66:67]
	v_pk_mul_f32 v[64:65], v[68:69], v[64:65]
	v_mul_f32_e32 v68, 0xbfb8aa3b, v62
	v_pk_mul_f32 v[64:65], v[64:65], v[72:73]
	v_pk_mul_f32 v[66:67], v[66:67], v[74:75]
	v_cvt_pk_bf16_f32 v64, v64, v65
	v_cvt_pk_bf16_f32 v65, v66, v67
	v_mul_f32_e32 v66, 0xbfb8aa3b, v60
	v_mul_f32_e32 v67, 0xbfb8aa3b, v61
	v_mul_f32_e32 v69, 0xbfb8aa3b, v63
	v_exp_f32_e32 v66, v66
	v_exp_f32_e32 v67, v67
	v_exp_f32_e32 v68, v68
	v_exp_f32_e32 v69, v69
	v_add_f32_e32 v66, 1.0, v66
	v_add_f32_e32 v67, 1.0, v67
	v_add_f32_e32 v68, 1.0, v68
	v_add_f32_e32 v69, 1.0, v69
	v_rcp_f32_e32 v66, v66
	v_rcp_f32_e32 v67, v67
	v_rcp_f32_e32 v68, v68
	v_rcp_f32_e32 v69, v69
	v_pk_mul_f32 v[58:59], v[62:63], v[58:59]
	v_pk_mul_f32 v[56:57], v[60:61], v[56:57]
	global_store_dwordx2 v[80:81], v[64:65], off offset:128
	v_pk_mul_f32 v[56:57], v[56:57], v[66:67]
	v_pk_mul_f32 v[58:59], v[58:59], v[68:69]
	v_cvt_pk_bf16_f32 v56, v56, v57
	v_cvt_pk_bf16_f32 v57, v58, v59
	v_mul_f32_e32 v58, 0xbfb8aa3b, v52
	v_mul_f32_e32 v59, 0xbfb8aa3b, v53
	v_exp_f32_e32 v58, v58
	v_exp_f32_e32 v59, v59
	v_add_u32_e32 v64, 0x80, v170
	v_mad_i64_i32 v[64:65], s[34:35], v64, s69, v[142:143]
	v_lshl_add_u64 v[64:65], v[64:65], 0, v[140:141]
	global_store_dwordx2 v[64:65], v[56:57], off
	v_add_f32_e32 v56, 1.0, v58
	v_add_f32_e32 v57, 1.0, v59
	v_mul_f32_e32 v58, 0xbfb8aa3b, v54
	v_mul_f32_e32 v59, 0xbfb8aa3b, v55
	v_exp_f32_e32 v58, v58
	v_exp_f32_e32 v59, v59
	v_rcp_f32_e32 v56, v56
	v_rcp_f32_e32 v57, v57
	v_add_f32_e32 v58, 1.0, v58
	v_add_f32_e32 v59, 1.0, v59
	v_rcp_f32_e32 v58, v58
	v_rcp_f32_e32 v59, v59
	v_pk_mul_f32 v[50:51], v[54:55], v[50:51]
	v_pk_mul_f32 v[48:49], v[52:53], v[48:49]
	v_mul_f32_e32 v52, 0xbfb8aa3b, v46
	v_pk_mul_f32 v[48:49], v[48:49], v[56:57]
	v_pk_mul_f32 v[50:51], v[50:51], v[58:59]
	v_cvt_pk_bf16_f32 v48, v48, v49
	v_cvt_pk_bf16_f32 v49, v50, v51
	v_mul_f32_e32 v50, 0xbfb8aa3b, v44
; DI float ex2(float x) { return __builtin_amdgcn_exp2f(x); }
; #define PG8_STAMP() do { if (STAMP && wid == 0 && nts < 64) { const unsigned long long _c = 0ull; \
;         ts_lo = (lane == nts) ? (int)(unsigned)_c : ts_lo; ts_hi = (lane == nts) ? (int)(unsigned)(_c >> 32) : ts_hi; ++nts; } } while (0)
;     DI void operator()(const f32x4 (&acc)[2][2][4][2], const Unit& u, int wr, int wc, int fr, int fq) const {
;         const int row0 = u.pm * BM + wr * 64 + fr, hcol0 = ((u.pn * BM + wc * 32) >> 1) + 4 * fq;
; #pragma unroll
;         for (int ai = 0; ai < 2; ++ai)
; #pragma unroll
;             for (int m = 0; m < 4; ++m) { u16* rowp = O + (size_t)(row0 + ai * HALF + m * 16) * ldc + hcol0;
; #pragma unroll
;                 for (int bj = 0; bj < 2; ++bj) { const f32x4 g = acc[ai][bj][m][0], up = acc[ai][bj][m][1]; float r[4];
; #pragma unroll
;                     for (int j = 0; j < 4; ++j) r[j] = g[j] * up[j] * __builtin_amdgcn_rcpf(1.f + ex2(-LOG2E * g[j]));
;                     uint2 w = {pack2(r[0], r[1]), pack2(r[2], r[3])}; *(uint2*)(rowp + bj * (HALF / 2)) = w; } }
; template <class Epi, class Sched, bool STAMP = false>
; __device__ __forceinline__ void gemm_phase(PG8_LAS unsigned char* lds, const Gemm g, const Sched& S, const Epi& E, unsigned long long* stamps) {
;     ...
;         if constexpr (!Epi::AFTER_DRAIN) { E(acc, cur, wr, wc, fr, fq); S.done(cur); }
;         PG8_STAMP();
;         if (!has_next) break;
; #pragma unroll
;         for (int a = 0; a < 2; ++a)
	v_mul_f32_e32 v51, 0xbfb8aa3b, v45
	v_mul_f32_e32 v53, 0xbfb8aa3b, v47
	v_exp_f32_e32 v50, v50
	v_exp_f32_e32 v51, v51
	v_exp_f32_e32 v52, v52
	v_exp_f32_e32 v53, v53
	v_add_f32_e32 v50, 1.0, v50
	v_add_f32_e32 v51, 1.0, v51
	v_add_f32_e32 v52, 1.0, v52
	v_add_f32_e32 v53, 1.0, v53
	v_rcp_f32_e32 v50, v50
	v_rcp_f32_e32 v51, v51
	v_rcp_f32_e32 v52, v52
	v_rcp_f32_e32 v53, v53
	v_pk_mul_f32 v[42:43], v[46:47], v[42:43]
	v_pk_mul_f32 v[40:41], v[44:45], v[40:41]
	global_store_dwordx2 v[64:65], v[48:49], off offset:128
	v_pk_mul_f32 v[40:41], v[40:41], v[50:51]
	v_pk_mul_f32 v[42:43], v[42:43], v[52:53]
	v_cvt_pk_bf16_f32 v40, v40, v41
	v_cvt_pk_bf16_f32 v41, v42, v43
	v_mul_f32_e32 v42, 0xbfb8aa3b, v36
	v_mul_f32_e32 v43, 0xbfb8aa3b, v37
	v_exp_f32_e32 v42, v42
	v_exp_f32_e32 v43, v43
	v_add_u32_e32 v48, 0x90, v170
	v_mad_i64_i32 v[48:49], s[34:35], v48, s69, v[142:143]
	v_lshl_add_u64 v[48:49], v[48:49], 0, v[140:141]
	global_store_dwordx2 v[48:49], v[40:41], off
	v_add_f32_e32 v40, 1.0, v42
	v_add_f32_e32 v41, 1.0, v43
	v_mul_f32_e32 v42, 0xbfb8aa3b, v38
	v_mul_f32_e32 v43, 0xbfb8aa3b, v39
	v_exp_f32_e32 v42, v42
	v_exp_f32_e32 v43, v43
	v_rcp_f32_e32 v40, v40
	v_rcp_f32_e32 v41, v41
	v_add_f32_e32 v42, 1.0, v42
	v_add_f32_e32 v43, 1.0, v43
	v_rcp_f32_e32 v42, v42
	v_rcp_f32_e32 v43, v43
	v_pk_mul_f32 v[34:35], v[38:39], v[34:35]
	v_pk_mul_f32 v[32:33], v[36:37], v[32:33]
	v_mul_f32_e32 v36, 0xbfb8aa3b, v30
	v_pk_mul_f32 v[32:33], v[32:33], v[40:41]
	v_pk_mul_f32 v[34:35], v[34:35], v[42:43]
	v_cvt_pk_bf16_f32 v32, v32, v33
	v_cvt_pk_bf16_f32 v33, v34, v35
	v_mul_f32_e32 v34, 0xbfb8aa3b, v28
	v_mul_f32_e32 v35, 0xbfb8aa3b, v29
	v_mul_f32_e32 v37, 0xbfb8aa3b, v31
	v_exp_f32_e32 v34, v34
	v_exp_f32_e32 v35, v35
	v_exp_f32_e32 v36, v36
	v_exp_f32_e32 v37, v37
	v_add_f32_e32 v34, 1.0, v34
	v_add_f32_e32 v35, 1.0, v35
	v_add_f32_e32 v36, 1.0, v36
	v_add_f32_e32 v37, 1.0, v37
	v_rcp_f32_e32 v34, v34
	v_rcp_f32_e32 v35, v35
	v_rcp_f32_e32 v36, v36
	v_rcp_f32_e32 v37, v37
	v_pk_mul_f32 v[26:27], v[30:31], v[26:27]
	v_pk_mul_f32 v[24:25], v[28:29], v[24:25]
	global_store_dwordx2 v[48:49], v[32:33], off offset:128
	v_pk_mul_f32 v[24:25], v[24:25], v[34:35]
	v_pk_mul_f32 v[26:27], v[26:27], v[36:37]
	v_cvt_pk_bf16_f32 v24, v24, v25
	v_cvt_pk_bf16_f32 v25, v26, v27
	v_mul_f32_e32 v26, 0xbfb8aa3b, v20
	v_mul_f32_e32 v27, 0xbfb8aa3b, v21
	v_exp_f32_e32 v26, v26
	v_exp_f32_e32 v27, v27
	v_add_u32_e32 v32, 0xa0, v170
	v_mad_i64_i32 v[32:33], s[34:35], v32, s69, v[142:143]
	v_lshl_add_u64 v[32:33], v[32:33], 0, v[140:141]
	global_store_dwordx2 v[32:33], v[24:25], off
	v_add_f32_e32 v24, 1.0, v26
	v_add_f32_e32 v25, 1.0, v27
	v_mul_f32_e32 v26, 0xbfb8aa3b, v22
	v_mul_f32_e32 v27, 0xbfb8aa3b, v23
	v_exp_f32_e32 v26, v26
	v_exp_f32_e32 v27, v27
	v_rcp_f32_e32 v24, v24
	v_rcp_f32_e32 v25, v25
	v_add_f32_e32 v26, 1.0, v26
	v_add_f32_e32 v27, 1.0, v27
	v_rcp_f32_e32 v26, v26
	v_rcp_f32_e32 v27, v27
	v_pk_mul_f32 v[18:19], v[22:23], v[18:19]
	v_pk_mul_f32 v[16:17], v[20:21], v[16:17]
	v_mul_f32_e32 v20, 0xbfb8aa3b, v14
	v_pk_mul_f32 v[16:17], v[16:17], v[24:25]
	v_pk_mul_f32 v[18:19], v[18:19], v[26:27]
	v_cvt_pk_bf16_f32 v16, v16, v17
	v_cvt_pk_bf16_f32 v17, v18, v19
	v_mul_f32_e32 v18, 0xbfb8aa3b, v12
	v_mul_f32_e32 v19, 0xbfb8aa3b, v13
	v_mul_f32_e32 v21, 0xbfb8aa3b, v15
	v_exp_f32_e32 v18, v18
	v_exp_f32_e32 v19, v19
	v_exp_f32_e32 v20, v20
	v_exp_f32_e32 v21, v21
	v_add_f32_e32 v18, 1.0, v18
	v_add_f32_e32 v19, 1.0, v19
	v_add_f32_e32 v20, 1.0, v20
	v_add_f32_e32 v21, 1.0, v21
	v_rcp_f32_e32 v18, v18
	v_rcp_f32_e32 v19, v19
	v_rcp_f32_e32 v20, v20
	v_rcp_f32_e32 v21, v21
	v_pk_mul_f32 v[10:11], v[14:15], v[10:11]
	v_pk_mul_f32 v[8:9], v[12:13], v[8:9]
	global_store_dwordx2 v[32:33], v[16:17], off offset:128
	v_pk_mul_f32 v[8:9], v[8:9], v[18:19]
	v_pk_mul_f32 v[10:11], v[10:11], v[20:21]
	v_cvt_pk_bf16_f32 v8, v8, v9
	v_cvt_pk_bf16_f32 v9, v10, v11
	v_mul_f32_e32 v10, 0xbfb8aa3b, v4
	v_mul_f32_e32 v11, 0xbfb8aa3b, v5
	v_exp_f32_e32 v10, v10
	v_exp_f32_e32 v11, v11
	v_add_u32_e32 v16, 0xb0, v170
	v_mad_i64_i32 v[16:17], s[34:35], v16, s69, v[142:143]
	v_lshl_add_u64 v[16:17], v[16:17], 0, v[140:141]
	global_store_dwordx2 v[16:17], v[8:9], off
	v_add_f32_e32 v8, 1.0, v10
	v_add_f32_e32 v9, 1.0, v11
	v_mul_f32_e32 v10, 0xbfb8aa3b, v6
	v_mul_f32_e32 v11, 0xbfb8aa3b, v7
	v_exp_f32_e32 v10, v10
	v_exp_f32_e32 v11, v11
	v_rcp_f32_e32 v8, v8
	v_rcp_f32_e32 v9, v9
	v_add_f32_e32 v10, 1.0, v10
	v_add_f32_e32 v11, 1.0, v11
	v_rcp_f32_e32 v10, v10
	v_rcp_f32_e32 v11, v11
	v_pk_mul_f32 v[2:3], v[6:7], v[2:3]
	v_pk_mul_f32 v[0:1], v[4:5], v[0:1]
	s_and_b64 vcc, exec, s[2:3]
	v_pk_mul_f32 v[0:1], v[0:1], v[8:9]
	v_pk_mul_f32 v[2:3], v[2:3], v[10:11]
	v_cvt_pk_bf16_f32 v0, v0, v1
	v_cvt_pk_bf16_f32 v1, v2, v3
	s_mov_b32 s76, s70
	s_mov_b32 s75, s71
	s_mov_b64 s[36:37], s[0:1]
	s_mov_b64 s[34:35], s[4:5]
	global_store_dwordx2 v[16:17], v[0:1], off offset:128
	s_cbranch_vccz .LBB0_432
	s_branch .Lgu3_done
; #define PG8_STAGE(bufoff, gbase, voff) do { _Pragma("unroll") for (int _i = 0; _i < 2; ++_i) \
;         __builtin_amdgcn_global_load_lds((const unsigned*)((const char*)(gbase) + (voff)[_i]), (PG8_LAS unsigned*)(lds + (bufoff) + ldsw + _i * 8192), 16, 0, 0); } while (0)
; #define PG8_LDA(dst, b, h) do { _Pragma("unroll") for (int m = 0; m < 4; ++m) _Pragma("unroll") for (int k = 0; k < 2; ++k) dst[m][k] = *(const PG8_LAS bf16x8*)(lds + PG8_SA(b, h) + aoff + m * 2048 + k * 1024); } while (0)
; #define PG8_LDB(dst, b, h) do { _Pragma("unroll") for (int n = 0; n < 2; ++n) _Pragma("unroll") for (int k = 0; k < 2; ++k) dst[n][k] = *(const PG8_LAS bf16x8*)(lds + PG8_SB(b, h) + boff + n * 2048 + k * 1024); } while (0)
; #define PG8_WAIT_V(n) asm volatile("s_waitcnt vmcnt(" #n ")" ::: "memory")
; #define PG8_WAIT_L(n) asm volatile("s_waitcnt lgkmcnt(" #n ")" ::: "memory")
; #define PG8_BAR __builtin_amdgcn_s_barrier()
; #define PG8_SCHED __builtin_amdgcn_sched_barrier(0)
; template <class Epi, class Sched, bool STAMP = false>
; __device__ __forceinline__ void gemm_phase(PG8_LAS unsigned char* lds, const Gemm g, const Sched& S, const Epi& E, unsigned long long* stamps) {
;     ...
;             const bool last = (t == nt - 2);
;             const char* a1 = cA + (size_t)(t + 1) * kstep;
;             const char* a2 = last ? nA : cA + (size_t)(t + 2) * kstep; const char* b2 = last ? nB : cB + (size_t)(t + 2) * kstep;
;             const char* a3 = a2 + kstep; const char* b3 = b2 + kstep;
;             if (last && has_next) S.a_ready(nxt);
;             PG8_LDB(B0, 0, 0); PG8_SCHED; PG8_LDA(At, 0, 0); PG8_STAGE(PG8_SA(1, 1), a1 + hstep, voffA);
;             PG8_WAIT_L(8); PG8_BAR; PG8_WAIT_L(0); PG8_MMA(0, 0, At, B0); PG8_BAR; PG8_SCHED;
;             PG8_LDB(B1, 0, 1); PG8_STAGE(PG8_SB(0, 0), b2, voffB);
;             PG8_BAR; PG8_WAIT_L(0); PG8_MMA(0, 1, At, B1); PG8_BAR;
;             PG8_LDA(At, 0, 1); PG8_STAGE(PG8_SA(0, 0), a2, voffA);
;             PG8_BAR; PG8_WAIT_L(0); PG8_MMA(1, 0, At, B0); PG8_BAR; PG8_SCHED;
;             PG8_STAGE(PG8_SB(0, 1), b2 + hstep, voffB);
;             PG8_WAIT_V(6); PG8_BAR; PG8_MMA(1, 1, At, B1); PG8_BAR;
;             PG8_LDB(B0, 1, 0); PG8_SCHED; PG8_LDA(At, 1, 0); PG8_STAGE(PG8_SA(0, 1), a2 + hstep, voffA);
;             PG8_WAIT_L(8); PG8_BAR; PG8_WAIT_L(0); PG8_MMA(0, 0, At, B0); PG8_BAR; PG8_SCHED;
.Lgu3_half_loop:
	ds_read_b128 v[140:143], v147
	ds_read_b128 v[170:173], v148
	ds_read_b128 v[174:177], v149
	ds_read_b128 v[178:181], v150
	s_add_u32 s36, s34, 0x100
	s_addc_u32 s37, s35, 0
	s_cmp_eq_u32 s10, 12
	s_cselect_b32 s43, s5, s37
	s_cselect_b32 s42, s4, s36
	s_cselect_b32 s41, s1, s78
	s_cselect_b32 s40, s0, s77
	s_mov_b32 m0, s67
	ds_read_b128 v[182:185], v145
	ds_read_b128 v[186:189], v145 offset:1024
	ds_read_b128 v[190:193], v145 offset:2048
	ds_read_b128 v[194:197], v145 offset:3072
	ds_read_b128 v[198:201], v145 offset:4096
	ds_read_b128 v[202:205], v145 offset:5120
	ds_read_b128 v[206:209], v145 offset:6144
	ds_read_b128 v[210:213], v145 offset:7168
	global_load_lds_dwordx4 v132, s[34:35]
	s_mov_b32 m0, s68
	s_nop 0
	global_load_lds_dwordx4 v134, s[34:35]
	s_waitcnt lgkmcnt(8)
	s_barrier
	s_waitcnt lgkmcnt(0)
	s_setprio 1
	s_waitcnt lgkmcnt(0)
	v_mfma_f32_16x16x32_bf16 v[124:127], v[140:143], v[182:185], v[124:127]
	v_mfma_f32_16x16x32_bf16 v[120:123], v[174:177], v[182:185], v[120:123]
	v_mfma_f32_16x16x32_bf16 v[108:111], v[140:143], v[190:193], v[108:111]
	v_mfma_f32_16x16x32_bf16 v[104:107], v[174:177], v[190:193], v[104:107]
	v_mfma_f32_16x16x32_bf16 v[92:95], v[140:143], v[198:201], v[92:95]
	v_mfma_f32_16x16x32_bf16 v[88:91], v[174:177], v[198:201], v[88:91]
	v_mfma_f32_16x16x32_bf16 v[76:79], v[140:143], v[206:209], v[76:79]
	v_mfma_f32_16x16x32_bf16 v[72:75], v[174:177], v[206:209], v[72:75]
	v_mfma_f32_16x16x32_bf16 v[124:127], v[170:173], v[186:189], v[124:127]
	v_mfma_f32_16x16x32_bf16 v[120:123], v[178:181], v[186:189], v[120:123]
	v_mfma_f32_16x16x32_bf16 v[108:111], v[170:173], v[194:197], v[108:111]
	v_mfma_f32_16x16x32_bf16 v[104:107], v[178:181], v[194:197], v[104:107]
	v_mfma_f32_16x16x32_bf16 v[92:95], v[170:173], v[202:205], v[92:95]
	v_mfma_f32_16x16x32_bf16 v[88:91], v[178:181], v[202:205], v[88:91]
	v_mfma_f32_16x16x32_bf16 v[76:79], v[170:173], v[210:213], v[76:79]
	v_mfma_f32_16x16x32_bf16 v[72:75], v[178:181], v[210:213], v[72:75]
	s_setprio 0
	s_barrier
	s_mov_b32 m0, s49
	s_nop 0
	global_load_lds_dwordx4 v130, s[40:41]
	s_mov_b32 m0, s52
	s_nop 0
	global_load_lds_dwordx4 v128, s[40:41]
	s_barrier
	s_waitcnt lgkmcnt(0)
	s_setprio 1
	s_waitcnt lgkmcnt(0)
	s_setprio 0
	s_mov_b32 m0, s46
	s_barrier
	ds_read_b128 v[182:185], v145 offset:16384
	ds_read_b128 v[186:189], v145 offset:17408
	ds_read_b128 v[190:193], v145 offset:18432
	ds_read_b128 v[194:197], v145 offset:19456
	ds_read_b128 v[198:201], v145 offset:20480
	ds_read_b128 v[202:205], v145 offset:21504
	ds_read_b128 v[206:209], v145 offset:22528
	ds_read_b128 v[210:213], v145 offset:23552
	global_load_lds_dwordx4 v130, s[42:43]
	s_mov_b32 m0, s53
	s_nop 0
	global_load_lds_dwordx4 v128, s[42:43]
	s_barrier
	s_waitcnt lgkmcnt(0)
	s_setprio 1
	s_waitcnt lgkmcnt(0)
	v_mfma_f32_16x16x32_bf16 v[60:63], v[140:143], v[182:185], v[60:63]
	v_mfma_f32_16x16x32_bf16 v[56:59], v[174:177], v[182:185], v[56:59]
	v_mfma_f32_16x16x32_bf16 v[44:47], v[140:143], v[190:193], v[44:47]
	v_mfma_f32_16x16x32_bf16 v[40:43], v[174:177], v[190:193], v[40:43]
	v_mfma_f32_16x16x32_bf16 v[28:31], v[140:143], v[198:201], v[28:31]
	v_mfma_f32_16x16x32_bf16 v[24:27], v[174:177], v[198:201], v[24:27]
	v_mfma_f32_16x16x32_bf16 v[12:15], v[140:143], v[206:209], v[12:15]
	v_mfma_f32_16x16x32_bf16 v[8:11], v[174:177], v[206:209], v[8:11]
	v_mfma_f32_16x16x32_bf16 v[60:63], v[170:173], v[186:189], v[60:63]
	v_mfma_f32_16x16x32_bf16 v[56:59], v[178:181], v[186:189], v[56:59]
	v_mfma_f32_16x16x32_bf16 v[44:47], v[170:173], v[194:197], v[44:47]
	v_mfma_f32_16x16x32_bf16 v[40:43], v[178:181], v[194:197], v[40:43]
	v_mfma_f32_16x16x32_bf16 v[28:31], v[170:173], v[202:205], v[28:31]
	v_mfma_f32_16x16x32_bf16 v[24:27], v[178:181], v[202:205], v[24:27]
	v_mfma_f32_16x16x32_bf16 v[12:15], v[170:173], v[210:213], v[12:15]
	v_mfma_f32_16x16x32_bf16 v[8:11], v[178:181], v[210:213], v[8:11]
	s_setprio 0
	s_barrier
	s_add_u32 s34, s40, 0x44000
	s_addc_u32 s35, s41, 0
	s_mov_b32 m0, s54
	s_nop 0
	global_load_lds_dwordx4 v130, s[34:35]
	s_mov_b32 m0, s55
	s_nop 0
	global_load_lds_dwordx4 v128, s[34:35]
	s_waitcnt vmcnt(6)
	s_barrier
	s_setprio 1
	s_setprio 0
	s_barrier
	ds_read_b128 v[140:143], v155
	ds_read_b128 v[170:173], v156
	ds_read_b128 v[174:177], v157
	ds_read_b128 v[178:181], v165
	s_add_u32 s34, s42, 0x44000
	s_addc_u32 s35, s43, 0
	s_mov_b32 m0, s56
	ds_read_b128 v[182:185], v145 offset:32768
	ds_read_b128 v[186:189], v145 offset:33792
	ds_read_b128 v[190:193], v145 offset:34816
	ds_read_b128 v[194:197], v145 offset:35840
	ds_read_b128 v[198:201], v145 offset:36864
	ds_read_b128 v[202:205], v145 offset:37888
	ds_read_b128 v[206:209], v145 offset:38912
	ds_read_b128 v[210:213], v145 offset:39936
	global_load_lds_dwordx4 v130, s[34:35]
	s_mov_b32 m0, s57
	s_nop 0
	global_load_lds_dwordx4 v128, s[34:35]
	s_waitcnt lgkmcnt(8)
	s_barrier
	s_waitcnt lgkmcnt(0)
	s_setprio 1
	s_waitcnt lgkmcnt(0)
	v_mfma_f32_16x16x32_bf16 v[124:127], v[140:143], v[182:185], v[124:127]
	v_mfma_f32_16x16x32_bf16 v[120:123], v[174:177], v[182:185], v[120:123]
	v_mfma_f32_16x16x32_bf16 v[108:111], v[140:143], v[190:193], v[108:111]
	v_mfma_f32_16x16x32_bf16 v[104:107], v[174:177], v[190:193], v[104:107]
	v_mfma_f32_16x16x32_bf16 v[92:95], v[140:143], v[198:201], v[92:95]
	v_mfma_f32_16x16x32_bf16 v[88:91], v[174:177], v[198:201], v[88:91]
	v_mfma_f32_16x16x32_bf16 v[76:79], v[140:143], v[206:209], v[76:79]
	v_mfma_f32_16x16x32_bf16 v[72:75], v[174:177], v[206:209], v[72:75]
	v_mfma_f32_16x16x32_bf16 v[124:127], v[170:173], v[186:189], v[124:127]
	v_mfma_f32_16x16x32_bf16 v[120:123], v[178:181], v[186:189], v[120:123]
	v_mfma_f32_16x16x32_bf16 v[108:111], v[170:173], v[194:197], v[108:111]
	v_mfma_f32_16x16x32_bf16 v[104:107], v[178:181], v[194:197], v[104:107]
	v_mfma_f32_16x16x32_bf16 v[92:95], v[170:173], v[202:205], v[92:95]
	v_mfma_f32_16x16x32_bf16 v[88:91], v[178:181], v[202:205], v[88:91]
	v_mfma_f32_16x16x32_bf16 v[76:79], v[170:173], v[210:213], v[76:79]
	v_mfma_f32_16x16x32_bf16 v[72:75], v[178:181], v[210:213], v[72:75]
	s_setprio 0
	s_barrier
; DI float ex2(float x) { return __builtin_amdgcn_exp2f(x); }
; #define PG8_STAGE(bufoff, gbase, voff) do { _Pragma("unroll") for (int _i = 0; _i < 2; ++_i) \
;         __builtin_amdgcn_global_load_lds((const unsigned*)((const char*)(gbase) + (voff)[_i]), (PG8_LAS unsigned*)(lds + (bufoff) + ldsw + _i * 8192), 16, 0, 0); } while (0)
; #define PG8_LDA(dst, b, h) do { _Pragma("unroll") for (int m = 0; m < 4; ++m) _Pragma("unroll") for (int k = 0; k < 2; ++k) dst[m][k] = *(const PG8_LAS bf16x8*)(lds + PG8_SA(b, h) + aoff + m * 2048 + k * 1024); } while (0)
; #define PG8_LDB(dst, b, h) do { _Pragma("unroll") for (int n = 0; n < 2; ++n) _Pragma("unroll") for (int k = 0; k < 2; ++k) dst[n][k] = *(const PG8_LAS bf16x8*)(lds + PG8_SB(b, h) + boff + n * 2048 + k * 1024); } while (0)
; #define PG8_WAIT_V(n) asm volatile("s_waitcnt vmcnt(" #n ")" ::: "memory")
;     DI void operator()(const f32x4 (&acc)[2][2][4][2], const Unit& u, int wr, int wc, int fr, int fq) const {
;         const int row0 = u.pm * BM + wr * 64 + fr, hcol0 = ((u.pn * BM + wc * 32) >> 1) + 4 * fq;
; #pragma unroll
;         for (int ai = 0; ai < 2; ++ai)
; #pragma unroll
;             for (int m = 0; m < 4; ++m) { u16* rowp = O + (size_t)(row0 + ai * HALF + m * 16) * ldc + hcol0;
; #pragma unroll
;                 for (int bj = 0; bj < 2; ++bj) { const f32x4 g = acc[ai][bj][m][0], up = acc[ai][bj][m][1]; float r[4];
; #pragma unroll
;                     for (int j = 0; j < 4; ++j) r[j] = g[j] * up[j] * __builtin_amdgcn_rcpf(1.f + ex2(-LOG2E * g[j]));
;                     uint2 w = {pack2(r[0], r[1]), pack2(r[2], r[3])}; *(uint2*)(rowp + bj * (HALF / 2)) = w; } }
; template <class Epi, class Sched, bool STAMP = false>
; __device__ __forceinline__ void gemm_phase(PG8_LAS unsigned char* lds, const Gemm g, const Sched& S, const Epi& E, unsigned long long* stamps) {
;     ...
;             PG8_WAIT_L(8); PG8_BAR; PG8_WAIT_L(0); PG8_MMA(0, 0, At, B0); PG8_BAR; PG8_SCHED;
;             PG8_LDB(B1, 1, 1); PG8_STAGE(PG8_SB(1, 0), b3, voffB);
;             PG8_BAR; PG8_WAIT_L(0); PG8_MMA(0, 1, At, B1); PG8_BAR;
;             PG8_LDA(At, 1, 1); PG8_STAGE(PG8_SA(1, 0), a3, voffA);
;             PG8_BAR; PG8_WAIT_L(0); PG8_MMA(1, 0, At, B0); PG8_BAR; PG8_SCHED;
;             PG8_STAGE(PG8_SB(1, 1), b3 + hstep, voffB);
;             PG8_WAIT_V(6); PG8_BAR; PG8_MMA(1, 1, At, B1); PG8_BAR;
;         }
	s_mov_b32 m0, s60
	s_add_u32 s100, s40, 0x80
	s_addc_u32 s101, s41, 0
	global_load_lds_dwordx4 v130, s[100:101]
	s_mov_b32 m0, s61
	s_nop 0
	global_load_lds_dwordx4 v128, s[100:101]
	s_barrier
	s_waitcnt lgkmcnt(0)
	s_setprio 1
	s_waitcnt lgkmcnt(0)
	s_setprio 0
	s_mov_b32 m0, s62
	s_barrier
	ds_read_b128 v[182:185], v145 offset:49152
	ds_read_b128 v[186:189], v145 offset:50176
	ds_read_b128 v[190:193], v145 offset:51200
	ds_read_b128 v[194:197], v145 offset:52224
	ds_read_b128 v[198:201], v145 offset:53248
	ds_read_b128 v[202:205], v145 offset:54272
	ds_read_b128 v[206:209], v145 offset:55296
	ds_read_b128 v[210:213], v145 offset:56320
	s_add_u32 s100, s42, 0x80
	s_addc_u32 s101, s43, 0
	global_load_lds_dwordx4 v130, s[100:101]
	s_mov_b32 m0, s63
	s_nop 0
	global_load_lds_dwordx4 v128, s[100:101]
	s_barrier
	s_waitcnt lgkmcnt(0)
	s_setprio 1
	s_waitcnt lgkmcnt(0)
	v_mfma_f32_16x16x32_bf16 v[60:63], v[140:143], v[182:185], v[60:63]
	v_mfma_f32_16x16x32_bf16 v[56:59], v[174:177], v[182:185], v[56:59]
	v_mfma_f32_16x16x32_bf16 v[44:47], v[140:143], v[190:193], v[44:47]
	v_mfma_f32_16x16x32_bf16 v[40:43], v[174:177], v[190:193], v[40:43]
	v_mfma_f32_16x16x32_bf16 v[28:31], v[140:143], v[198:201], v[28:31]
	v_mfma_f32_16x16x32_bf16 v[24:27], v[174:177], v[198:201], v[24:27]
	v_mfma_f32_16x16x32_bf16 v[12:15], v[140:143], v[206:209], v[12:15]
	v_mfma_f32_16x16x32_bf16 v[8:11], v[174:177], v[206:209], v[8:11]
	v_mfma_f32_16x16x32_bf16 v[60:63], v[170:173], v[186:189], v[60:63]
	v_mfma_f32_16x16x32_bf16 v[56:59], v[178:181], v[186:189], v[56:59]
	v_mfma_f32_16x16x32_bf16 v[44:47], v[170:173], v[194:197], v[44:47]
	v_mfma_f32_16x16x32_bf16 v[40:43], v[178:181], v[194:197], v[40:43]
	v_mfma_f32_16x16x32_bf16 v[28:31], v[170:173], v[202:205], v[28:31]
	v_mfma_f32_16x16x32_bf16 v[24:27], v[178:181], v[202:205], v[24:27]
	v_mfma_f32_16x16x32_bf16 v[12:15], v[170:173], v[210:213], v[12:15]
	v_mfma_f32_16x16x32_bf16 v[8:11], v[178:181], v[210:213], v[8:11]
	s_setprio 0
	s_barrier
	s_add_u32 s34, s40, 0x44080
	s_addc_u32 s35, s41, 0
	s_mov_b32 m0, s64
	s_nop 0
	global_load_lds_dwordx4 v130, s[34:35]
	s_mov_b32 m0, s65
	s_nop 0
	global_load_lds_dwordx4 v128, s[34:35]
	s_waitcnt vmcnt(6)
	s_barrier
	s_setprio 1
	s_setprio 0
	s_add_i32 s10, s10, 2
	s_add_u32 s77, s77, 0x100
	s_addc_u32 s78, s78, 0
	s_cmp_gt_u32 s10, 13
	s_mov_b64 s[34:35], s[36:37]
	s_barrier
	s_cbranch_scc0 .Lgu3_half_loop
	v_mul_f32_e32 v171, 0xbfb8aa3b, v124
	v_exp_f32_e32 v171, v171
	v_mul_f32_e32 v174, 0xbfb8aa3b, v125
	v_exp_f32_e32 v175, v174
	s_lshl_b32 s10, s76, 8
	v_add_f32_e32 v171, 1.0, v171
	v_rcp_f32_e32 v174, v171
	v_add_f32_e32 v171, 1.0, v175
	v_mul_f32_e32 v175, 0xbfb8aa3b, v126
	v_exp_f32_e32 v176, v175
	v_mul_f32_e32 v175, 0xbfb8aa3b, v127
	v_exp_f32_e32 v177, v175
	v_rcp_f32_e32 v175, v171
	v_add_f32_e32 v171, 1.0, v176
	v_rcp_f32_e32 v176, v171
	v_add_f32_e32 v171, 1.0, v177
	v_rcp_f32_e32 v177, v171
	v_pk_mul_f32 v[122:123], v[126:127], v[122:123]
	v_pk_mul_f32 v[120:121], v[124:125], v[120:121]
	s_or_b32 s10, s10, s59
	s_or_b32 s10, s10, s98
	v_pk_mul_f32 v[120:121], v[120:121], v[174:175]
	v_pk_mul_f32 v[122:123], v[122:123], v[176:177]
	s_ashr_i32 s10, s10, 1
	v_cvt_pk_bf16_f32 v120, v120, v121
	v_cvt_pk_bf16_f32 v121, v122, v123
	v_or_b32_e32 v140, s10, v146
	v_lshl_add_u32 v170, s75, 8, v144
	v_ashrrev_i32_e32 v141, 31, v140
	v_mov_b64_e32 v[142:143], s[12:13]
	v_mad_i64_i32 v[172:173], s[34:35], v170, s69, v[142:143]
	v_lshlrev_b64 v[140:141], 1, v[140:141]
	v_lshl_add_u64 v[172:173], v[172:173], 0, v[140:141]
	global_store_dwordx2 v[172:173], v[120:121], off
	v_mul_f32_e32 v116, 0xbfb8aa3b, v110
	v_mul_f32_e32 v114, 0xbfb8aa3b, v108
	v_mul_f32_e32 v115, 0xbfb8aa3b, v109
	v_mul_f32_e32 v117, 0xbfb8aa3b, v111
	v_exp_f32_e32 v114, v114
	v_exp_f32_e32 v115, v115
	v_exp_f32_e32 v116, v116
	v_exp_f32_e32 v117, v117
	v_add_f32_e32 v114, 1.0, v114
	v_add_f32_e32 v115, 1.0, v115
	v_add_f32_e32 v116, 1.0, v116
	v_add_f32_e32 v117, 1.0, v117
	v_rcp_f32_e32 v114, v114
	v_rcp_f32_e32 v115, v115
	v_rcp_f32_e32 v116, v116
	v_rcp_f32_e32 v117, v117
	v_pk_mul_f32 v[106:107], v[110:111], v[106:107]
	v_pk_mul_f32 v[104:105], v[108:109], v[104:105]
	v_pk_mul_f32 v[104:105], v[104:105], v[114:115]
	v_pk_mul_f32 v[106:107], v[106:107], v[116:117]
	v_cvt_pk_bf16_f32 v104, v104, v105
	v_cvt_pk_bf16_f32 v105, v106, v107
	v_or_b32_e32 v112, 16, v170
	v_mad_i64_i32 v[112:113], s[34:35], v112, s69, v[142:143]
	v_lshl_add_u64 v[112:113], v[112:113], 0, v[140:141]
	global_store_dwordx2 v[112:113], v[104:105], off
	v_mul_f32_e32 v100, 0xbfb8aa3b, v94
	v_mul_f32_e32 v98, 0xbfb8aa3b, v92
	v_mul_f32_e32 v99, 0xbfb8aa3b, v93
	v_mul_f32_e32 v101, 0xbfb8aa3b, v95
	v_exp_f32_e32 v98, v98
	v_exp_f32_e32 v99, v99
	v_exp_f32_e32 v100, v100
	v_exp_f32_e32 v101, v101
	v_add_f32_e32 v98, 1.0, v98
	v_add_f32_e32 v99, 1.0, v99
	v_add_f32_e32 v100, 1.0, v100
	v_add_f32_e32 v101, 1.0, v101
	v_rcp_f32_e32 v98, v98
	v_rcp_f32_e32 v99, v99
; DI float ex2(float x) { return __builtin_amdgcn_exp2f(x); }
;     DI void operator()(const f32x4 (&acc)[2][2][4][2], const Unit& u, int wr, int wc, int fr, int fq) const {
;         const int row0 = u.pm * BM + wr * 64 + fr, hcol0 = ((u.pn * BM + wc * 32) >> 1) + 4 * fq;
; #pragma unroll
;         for (int ai = 0; ai < 2; ++ai)
; #pragma unroll
;             for (int m = 0; m < 4; ++m) { u16* rowp = O + (size_t)(row0 + ai * HALF + m * 16) * ldc + hcol0;
; #pragma unroll
;                 for (int bj = 0; bj < 2; ++bj) { const f32x4 g = acc[ai][bj][m][0], up = acc[ai][bj][m][1]; float r[4];
; #pragma unroll
;                     for (int j = 0; j < 4; ++j) r[j] = g[j] * up[j] * __builtin_amdgcn_rcpf(1.f + ex2(-LOG2E * g[j]));
;                     uint2 w = {pack2(r[0], r[1]), pack2(r[2], r[3])}; *(uint2*)(rowp + bj * (HALF / 2)) = w; } }
	v_rcp_f32_e32 v100, v100
	v_rcp_f32_e32 v101, v101
	v_pk_mul_f32 v[90:91], v[94:95], v[90:91]
	v_pk_mul_f32 v[88:89], v[92:93], v[88:89]
	v_pk_mul_f32 v[88:89], v[88:89], v[98:99]
	v_pk_mul_f32 v[90:91], v[90:91], v[100:101]
	v_cvt_pk_bf16_f32 v88, v88, v89
	v_cvt_pk_bf16_f32 v89, v90, v91
	v_or_b32_e32 v96, 32, v170
	v_mad_i64_i32 v[96:97], s[34:35], v96, s69, v[142:143]
	v_lshl_add_u64 v[96:97], v[96:97], 0, v[140:141]
	global_store_dwordx2 v[96:97], v[88:89], off
	v_mul_f32_e32 v84, 0xbfb8aa3b, v78
	v_mul_f32_e32 v82, 0xbfb8aa3b, v76
	v_mul_f32_e32 v83, 0xbfb8aa3b, v77
	v_mul_f32_e32 v85, 0xbfb8aa3b, v79
	v_exp_f32_e32 v82, v82
	v_exp_f32_e32 v83, v83
	v_exp_f32_e32 v84, v84
	v_exp_f32_e32 v85, v85
	v_add_f32_e32 v82, 1.0, v82
	v_add_f32_e32 v83, 1.0, v83
	v_add_f32_e32 v84, 1.0, v84
	v_add_f32_e32 v85, 1.0, v85
	v_rcp_f32_e32 v82, v82
	v_rcp_f32_e32 v83, v83
	v_rcp_f32_e32 v84, v84
	v_rcp_f32_e32 v85, v85
	v_pk_mul_f32 v[74:75], v[78:79], v[74:75]
	v_pk_mul_f32 v[72:73], v[76:77], v[72:73]
	v_pk_mul_f32 v[72:73], v[72:73], v[82:83]
	v_pk_mul_f32 v[74:75], v[74:75], v[84:85]
	v_cvt_pk_bf16_f32 v72, v72, v73
	v_cvt_pk_bf16_f32 v73, v74, v75
	v_or_b32_e32 v80, 48, v170
	v_mad_i64_i32 v[80:81], s[34:35], v80, s69, v[142:143]
	v_lshl_add_u64 v[80:81], v[80:81], 0, v[140:141]
	global_store_dwordx2 v[80:81], v[72:73], off
	v_mul_f32_e32 v68, 0xbfb8aa3b, v62
	v_mul_f32_e32 v66, 0xbfb8aa3b, v60
	v_mul_f32_e32 v67, 0xbfb8aa3b, v61
	v_mul_f32_e32 v69, 0xbfb8aa3b, v63
	v_exp_f32_e32 v66, v66
	v_exp_f32_e32 v67, v67
	v_exp_f32_e32 v68, v68
	v_exp_f32_e32 v69, v69
	v_add_f32_e32 v66, 1.0, v66
	v_add_f32_e32 v67, 1.0, v67
	v_add_f32_e32 v68, 1.0, v68
	v_add_f32_e32 v69, 1.0, v69
	v_rcp_f32_e32 v66, v66
	v_rcp_f32_e32 v67, v67
	v_rcp_f32_e32 v68, v68
	v_rcp_f32_e32 v69, v69
	v_pk_mul_f32 v[58:59], v[62:63], v[58:59]
	v_pk_mul_f32 v[56:57], v[60:61], v[56:57]
	v_pk_mul_f32 v[56:57], v[56:57], v[66:67]
	v_pk_mul_f32 v[58:59], v[58:59], v[68:69]
	v_cvt_pk_bf16_f32 v56, v56, v57
	v_cvt_pk_bf16_f32 v57, v58, v59
	v_add_u32_e32 v64, 0x80, v170
	v_mad_i64_i32 v[64:65], s[34:35], v64, s69, v[142:143]
	v_lshl_add_u64 v[64:65], v[64:65], 0, v[140:141]
	global_store_dwordx2 v[64:65], v[56:57], off
	v_mul_f32_e32 v52, 0xbfb8aa3b, v46
	v_mul_f32_e32 v50, 0xbfb8aa3b, v44
	v_mul_f32_e32 v51, 0xbfb8aa3b, v45
	v_mul_f32_e32 v53, 0xbfb8aa3b, v47
	v_exp_f32_e32 v50, v50
	v_exp_f32_e32 v51, v51
	v_exp_f32_e32 v52, v52
	v_exp_f32_e32 v53, v53
	v_add_f32_e32 v50, 1.0, v50
	v_add_f32_e32 v51, 1.0, v51
	v_add_f32_e32 v52, 1.0, v52
	v_add_f32_e32 v53, 1.0, v53
	v_rcp_f32_e32 v50, v50
	v_rcp_f32_e32 v51, v51
	v_rcp_f32_e32 v52, v52
	v_rcp_f32_e32 v53, v53
	v_pk_mul_f32 v[42:43], v[46:47], v[42:43]
	v_pk_mul_f32 v[40:41], v[44:45], v[40:41]
	v_pk_mul_f32 v[40:41], v[40:41], v[50:51]
	v_pk_mul_f32 v[42:43], v[42:43], v[52:53]
	v_cvt_pk_bf16_f32 v40, v40, v41
	v_cvt_pk_bf16_f32 v41, v42, v43
	v_add_u32_e32 v48, 0x90, v170
	v_mad_i64_i32 v[48:49], s[34:35], v48, s69, v[142:143]
	v_lshl_add_u64 v[48:49], v[48:49], 0, v[140:141]
	global_store_dwordx2 v[48:49], v[40:41], off
	v_mul_f32_e32 v36, 0xbfb8aa3b, v30
	v_mul_f32_e32 v34, 0xbfb8aa3b, v28
	v_mul_f32_e32 v35, 0xbfb8aa3b, v29
	v_mul_f32_e32 v37, 0xbfb8aa3b, v31
	v_exp_f32_e32 v34, v34
	v_exp_f32_e32 v35, v35
	v_exp_f32_e32 v36, v36
	v_exp_f32_e32 v37, v37
	v_add_f32_e32 v34, 1.0, v34
	v_add_f32_e32 v35, 1.0, v35
	v_add_f32_e32 v36, 1.0, v36
	v_add_f32_e32 v37, 1.0, v37
	v_rcp_f32_e32 v34, v34
	v_rcp_f32_e32 v35, v35
	v_rcp_f32_e32 v36, v36
	v_rcp_f32_e32 v37, v37
	v_pk_mul_f32 v[26:27], v[30:31], v[26:27]
	v_pk_mul_f32 v[24:25], v[28:29], v[24:25]
	v_pk_mul_f32 v[24:25], v[24:25], v[34:35]
	v_pk_mul_f32 v[26:27], v[26:27], v[36:37]
	v_cvt_pk_bf16_f32 v24, v24, v25
	v_cvt_pk_bf16_f32 v25, v26, v27
	v_add_u32_e32 v32, 0xa0, v170
	v_mad_i64_i32 v[32:33], s[34:35], v32, s69, v[142:143]
	v_lshl_add_u64 v[32:33], v[32:33], 0, v[140:141]
	global_store_dwordx2 v[32:33], v[24:25], off
	v_mul_f32_e32 v20, 0xbfb8aa3b, v14
	v_mul_f32_e32 v18, 0xbfb8aa3b, v12
	v_mul_f32_e32 v19, 0xbfb8aa3b, v13
	v_mul_f32_e32 v21, 0xbfb8aa3b, v15
	v_exp_f32_e32 v18, v18
	v_exp_f32_e32 v19, v19
	v_exp_f32_e32 v20, v20
	v_exp_f32_e32 v21, v21
	v_add_f32_e32 v18, 1.0, v18
	v_add_f32_e32 v19, 1.0, v19
	v_add_f32_e32 v20, 1.0, v20
	v_add_f32_e32 v21, 1.0, v21
	v_rcp_f32_e32 v18, v18
	v_rcp_f32_e32 v19, v19
	v_rcp_f32_e32 v20, v20
	v_rcp_f32_e32 v21, v21
	v_pk_mul_f32 v[10:11], v[14:15], v[10:11]
	v_pk_mul_f32 v[8:9], v[12:13], v[8:9]
	v_pk_mul_f32 v[8:9], v[8:9], v[18:19]
	v_pk_mul_f32 v[10:11], v[10:11], v[20:21]
	v_cvt_pk_bf16_f32 v8, v8, v9
	v_cvt_pk_bf16_f32 v9, v10, v11
	v_add_u32_e32 v16, 0xb0, v170
	v_mad_i64_i32 v[16:17], s[34:35], v16, s69, v[142:143]
	v_lshl_add_u64 v[16:17], v[16:17], 0, v[140:141]
	global_store_dwordx2 v[16:17], v[8:9], off
	s_and_b64 vcc, exec, s[2:3]
	s_mov_b32 s76, s70
	s_mov_b32 s75, s71
	s_mov_b64 s[36:37], s[0:1]
	s_mov_b64 s[34:35], s[4:5]

; #define PG8_STAGE(bufoff, gbase, voff) do { _Pragma("unroll") for (int _i = 0; _i < 2; ++_i) \
;         __builtin_amdgcn_global_load_lds((const unsigned*)((const char*)(gbase) + (voff)[_i]), (PG8_LAS unsigned*)(lds + (bufoff) + ldsw + _i * 8192), 16, 0, 0); } while (0)
; #define PG8_LDA(dst, b, h) do { _Pragma("unroll") for (int m = 0; m < 4; ++m) _Pragma("unroll") for (int k = 0; k < 2; ++k) dst[m][k] = *(const PG8_LAS bf16x8*)(lds + PG8_SA(b, h) + aoff + m * 2048 + k * 1024); } while (0)
; #define PG8_LDB(dst, b, h) do { _Pragma("unroll") for (int n = 0; n < 2; ++n) _Pragma("unroll") for (int k = 0; k < 2; ++k) dst[n][k] = *(const PG8_LAS bf16x8*)(lds + PG8_SB(b, h) + boff + n * 2048 + k * 1024); } while (0)
; #define PG8_MMA(ai, bj, At, Bt) do { __builtin_amdgcn_s_setprio(1); _Pragma("unroll") for (int m = 0; m < 4; ++m) _Pragma("unroll") for (int n = 0; n < 2; ++n) _Pragma("unroll") for (int k = 0; k < 2; ++k) \
;         acc[ai][bj][m][n] = __builtin_amdgcn_mfma_f32_16x16x32_bf16(Bt[n][k], At[m][k], acc[ai][bj][m][n], 0, 0, 0); __builtin_amdgcn_s_setprio(0); } while (0)
; #define PG8_WAIT_V(n) asm volatile("s_waitcnt vmcnt(" #n ")" ::: "memory")
; template <class Epi, class Sched, bool STAMP = false>
; __device__ __forceinline__ void gemm_phase(PG8_LAS unsigned char* lds, const Gemm g, const Sched& S, const Epi& E, unsigned long long* stamps) {
;     ...
;             const bool last = (t == nt - 2);
;             const char* a1 = cA + (size_t)(t + 1) * kstep;
;             const char* a2 = last ? nA : cA + (size_t)(t + 2) * kstep; const char* b2 = last ? nB : cB + (size_t)(t + 2) * kstep;
;             const char* a3 = a2 + kstep; const char* b3 = b2 + kstep;
;             if (last && has_next) S.a_ready(nxt);
;             PG8_LDB(B0, 0, 0); PG8_SCHED; PG8_LDA(At, 0, 0); PG8_STAGE(PG8_SA(1, 1), a1 + hstep, voffA);
;             PG8_WAIT_L(8); PG8_BAR; PG8_WAIT_L(0); PG8_MMA(0, 0, At, B0); PG8_BAR; PG8_SCHED;
;             PG8_LDB(B1, 0, 1); PG8_STAGE(PG8_SB(0, 0), b2, voffB);
;             PG8_BAR; PG8_WAIT_L(0); PG8_MMA(0, 1, At, B1); PG8_BAR;
;             PG8_LDA(At, 0, 1); PG8_STAGE(PG8_SA(0, 0), a2, voffA);
;             PG8_BAR; PG8_WAIT_L(0); PG8_MMA(1, 0, At, B0); PG8_BAR; PG8_SCHED;
;             PG8_STAGE(PG8_SB(0, 1), b2 + hstep, voffB);
;             PG8_WAIT_V(6); PG8_BAR; PG8_MMA(1, 1, At, B1); PG8_BAR;
.LBB0_473:
	ds_read_b128 v[170:173], v147
	ds_read_b128 v[174:177], v148
	ds_read_b128 v[178:181], v149
	ds_read_b128 v[182:185], v150
	s_add_u32 s46, s44, 0x100
	s_addc_u32 s47, s45, 0
	s_cmp_eq_u32 s10, 40
	s_cselect_b32 s53, s5, s47
	s_cselect_b32 s52, s4, s46
	s_cselect_b32 s49, s1, s89
	s_cselect_b32 s48, s0, s88
	s_mov_b32 m0, s76
	ds_read_b128 v[186:189], v145
	ds_read_b128 v[190:193], v145 offset:1024
	ds_read_b128 v[194:197], v145 offset:2048
	ds_read_b128 v[198:201], v145 offset:3072
	ds_read_b128 v[202:205], v145 offset:4096
	ds_read_b128 v[206:209], v145 offset:5120
	ds_read_b128 v[210:213], v145 offset:6144
	ds_read_b128 v[214:217], v145 offset:7168
	global_load_lds_dwordx4 v136, s[44:45]
	s_mov_b32 m0, s77
	s_nop 0
	global_load_lds_dwordx4 v138, s[44:45]
	s_waitcnt lgkmcnt(8)
	s_barrier
	s_waitcnt lgkmcnt(0)
	s_setprio 1
	s_waitcnt lgkmcnt(0)
	v_mfma_f32_16x16x32_bf16 v[124:127], v[170:173], v[186:189], v[124:127]
	v_mfma_f32_16x16x32_bf16 v[120:123], v[178:181], v[186:189], v[120:123]
	v_mfma_f32_16x16x32_bf16 v[116:119], v[170:173], v[194:197], v[116:119]
	v_mfma_f32_16x16x32_bf16 v[112:115], v[178:181], v[194:197], v[112:115]
	v_mfma_f32_16x16x32_bf16 v[100:103], v[170:173], v[202:205], v[100:103]
	v_mfma_f32_16x16x32_bf16 v[96:99], v[178:181], v[202:205], v[96:99]
	v_mfma_f32_16x16x32_bf16 v[84:87], v[170:173], v[210:213], v[84:87]
	v_mfma_f32_16x16x32_bf16 v[80:83], v[178:181], v[210:213], v[80:83]
	v_mfma_f32_16x16x32_bf16 v[124:127], v[174:177], v[190:193], v[124:127]
	v_mfma_f32_16x16x32_bf16 v[120:123], v[182:185], v[190:193], v[120:123]
	v_mfma_f32_16x16x32_bf16 v[116:119], v[174:177], v[198:201], v[116:119]
	v_mfma_f32_16x16x32_bf16 v[112:115], v[182:185], v[198:201], v[112:115]
	v_mfma_f32_16x16x32_bf16 v[100:103], v[174:177], v[206:209], v[100:103]
	v_mfma_f32_16x16x32_bf16 v[96:99], v[182:185], v[206:209], v[96:99]
	v_mfma_f32_16x16x32_bf16 v[84:87], v[174:177], v[214:217], v[84:87]
	v_mfma_f32_16x16x32_bf16 v[80:83], v[182:185], v[214:217], v[80:83]
	s_setprio 0
	s_barrier
	s_mov_b32 m0, s58
	ds_read_b128 v[218:221], v151
	ds_read_b128 v[222:225], v152
	ds_read_b128 v[226:229], v153
	ds_read_b128 v[230:233], v154
	global_load_lds_dwordx4 v130, s[48:49]
	s_mov_b32 m0, s59
	s_nop 0
	global_load_lds_dwordx4 v134, s[48:49]
	s_barrier
	s_waitcnt lgkmcnt(0)
	s_setprio 1
	s_waitcnt lgkmcnt(0)
	v_mfma_f32_16x16x32_bf16 v[108:111], v[218:221], v[186:189], v[108:111]
	v_mfma_f32_16x16x32_bf16 v[104:107], v[226:229], v[186:189], v[104:107]
	v_mfma_f32_16x16x32_bf16 v[92:95], v[218:221], v[194:197], v[92:95]
	v_mfma_f32_16x16x32_bf16 v[88:91], v[226:229], v[194:197], v[88:91]
	v_mfma_f32_16x16x32_bf16 v[76:79], v[218:221], v[202:205], v[76:79]
	v_mfma_f32_16x16x32_bf16 v[72:75], v[226:229], v[202:205], v[72:75]
	v_mfma_f32_16x16x32_bf16 v[68:71], v[218:221], v[210:213], v[68:71]
	v_mfma_f32_16x16x32_bf16 v[64:67], v[226:229], v[210:213], v[64:67]
	v_mfma_f32_16x16x32_bf16 v[108:111], v[222:225], v[190:193], v[108:111]
	v_mfma_f32_16x16x32_bf16 v[104:107], v[230:233], v[190:193], v[104:107]
	v_mfma_f32_16x16x32_bf16 v[92:95], v[222:225], v[198:201], v[92:95]
	v_mfma_f32_16x16x32_bf16 v[88:91], v[230:233], v[198:201], v[88:91]
	v_mfma_f32_16x16x32_bf16 v[76:79], v[222:225], v[206:209], v[76:79]
	v_mfma_f32_16x16x32_bf16 v[72:75], v[230:233], v[206:209], v[72:75]
	v_mfma_f32_16x16x32_bf16 v[68:71], v[222:225], v[214:217], v[68:71]
	v_mfma_f32_16x16x32_bf16 v[64:67], v[230:233], v[214:217], v[64:67]
	s_setprio 0
	s_mov_b32 m0, s57
	s_barrier
	ds_read_b128 v[186:189], v145 offset:16384
	ds_read_b128 v[190:193], v145 offset:17408
	ds_read_b128 v[194:197], v145 offset:18432
	ds_read_b128 v[198:201], v145 offset:19456
	ds_read_b128 v[202:205], v145 offset:20480
	ds_read_b128 v[206:209], v145 offset:21504
	ds_read_b128 v[210:213], v145 offset:22528
	ds_read_b128 v[214:217], v145 offset:23552
	global_load_lds_dwordx4 v128, s[52:53]
	s_mov_b32 m0, s60
	s_nop 0
	global_load_lds_dwordx4 v132, s[52:53]
	s_barrier
	s_waitcnt lgkmcnt(0)
	s_setprio 1
	s_waitcnt lgkmcnt(0)
	v_mfma_f32_16x16x32_bf16 v[60:63], v[170:173], v[186:189], v[60:63]
	v_mfma_f32_16x16x32_bf16 v[56:59], v[178:181], v[186:189], v[56:59]
	v_mfma_f32_16x16x32_bf16 v[52:55], v[170:173], v[194:197], v[52:55]
	v_mfma_f32_16x16x32_bf16 v[48:51], v[178:181], v[194:197], v[48:51]
	v_mfma_f32_16x16x32_bf16 v[36:39], v[170:173], v[202:205], v[36:39]
	v_mfma_f32_16x16x32_bf16 v[32:35], v[178:181], v[202:205], v[32:35]
	v_mfma_f32_16x16x32_bf16 v[20:23], v[170:173], v[210:213], v[20:23]
	v_mfma_f32_16x16x32_bf16 v[16:19], v[178:181], v[210:213], v[16:19]
	v_mfma_f32_16x16x32_bf16 v[60:63], v[174:177], v[190:193], v[60:63]
	v_mfma_f32_16x16x32_bf16 v[56:59], v[182:185], v[190:193], v[56:59]
	v_mfma_f32_16x16x32_bf16 v[52:55], v[174:177], v[198:201], v[52:55]
	v_mfma_f32_16x16x32_bf16 v[48:51], v[182:185], v[198:201], v[48:51]
	v_mfma_f32_16x16x32_bf16 v[36:39], v[174:177], v[206:209], v[36:39]
	v_mfma_f32_16x16x32_bf16 v[32:35], v[182:185], v[206:209], v[32:35]
	v_mfma_f32_16x16x32_bf16 v[20:23], v[174:177], v[214:217], v[20:23]
	v_mfma_f32_16x16x32_bf16 v[16:19], v[182:185], v[214:217], v[16:19]
	s_setprio 0
	s_barrier
	s_add_u32 s44, s48, 0xb4000
	s_addc_u32 s45, s49, 0
	s_mov_b32 m0, s61
	s_nop 0
	global_load_lds_dwordx4 v130, s[44:45]
	s_mov_b32 m0, s62
	s_nop 0
	global_load_lds_dwordx4 v134, s[44:45]
	s_waitcnt vmcnt(6)
	s_barrier
; #define PG8_STAGE(bufoff, gbase, voff) do { _Pragma("unroll") for (int _i = 0; _i < 2; ++_i) \
;         __builtin_amdgcn_global_load_lds((const unsigned*)((const char*)(gbase) + (voff)[_i]), (PG8_LAS unsigned*)(lds + (bufoff) + ldsw + _i * 8192), 16, 0, 0); } while (0)
; #define PG8_LDA(dst, b, h) do { _Pragma("unroll") for (int m = 0; m < 4; ++m) _Pragma("unroll") for (int k = 0; k < 2; ++k) dst[m][k] = *(const PG8_LAS bf16x8*)(lds + PG8_SA(b, h) + aoff + m * 2048 + k * 1024); } while (0)
; #define PG8_LDB(dst, b, h) do { _Pragma("unroll") for (int n = 0; n < 2; ++n) _Pragma("unroll") for (int k = 0; k < 2; ++k) dst[n][k] = *(const PG8_LAS bf16x8*)(lds + PG8_SB(b, h) + boff + n * 2048 + k * 1024); } while (0)
; #define PG8_MMA(ai, bj, At, Bt) do { __builtin_amdgcn_s_setprio(1); _Pragma("unroll") for (int m = 0; m < 4; ++m) _Pragma("unroll") for (int n = 0; n < 2; ++n) _Pragma("unroll") for (int k = 0; k < 2; ++k) \
;         acc[ai][bj][m][n] = __builtin_amdgcn_mfma_f32_16x16x32_bf16(Bt[n][k], At[m][k], acc[ai][bj][m][n], 0, 0, 0); __builtin_amdgcn_s_setprio(0); } while (0)
; #define PG8_WAIT_V(n) asm volatile("s_waitcnt vmcnt(" #n ")" ::: "memory")
; #define PG8_WAIT_L(n) asm volatile("s_waitcnt lgkmcnt(" #n ")" ::: "memory")
; #define PG8_BAR __builtin_amdgcn_s_barrier()
; #define PG8_SCHED __builtin_amdgcn_sched_barrier(0)
; template <class Epi, class Sched, bool STAMP = false>
; __device__ __forceinline__ void gemm_phase(PG8_LAS unsigned char* lds, const Gemm g, const Sched& S, const Epi& E, unsigned long long* stamps) {
;     ...
;             PG8_WAIT_V(6); PG8_BAR; PG8_MMA(1, 1, At, B1); PG8_BAR;
;             PG8_LDB(B0, 1, 0); PG8_SCHED; PG8_LDA(At, 1, 0); PG8_STAGE(PG8_SA(0, 1), a2 + hstep, voffA);
;             PG8_WAIT_L(8); PG8_BAR; PG8_WAIT_L(0); PG8_MMA(0, 0, At, B0); PG8_BAR; PG8_SCHED;
;             PG8_LDB(B1, 1, 1); PG8_STAGE(PG8_SB(1, 0), b3, voffB);
;             PG8_BAR; PG8_WAIT_L(0); PG8_MMA(0, 1, At, B1); PG8_BAR;
;             PG8_LDA(At, 1, 1); PG8_STAGE(PG8_SA(1, 0), a3, voffA);
	s_setprio 1
	v_mfma_f32_16x16x32_bf16 v[44:47], v[218:221], v[186:189], v[44:47]
	v_mfma_f32_16x16x32_bf16 v[40:43], v[226:229], v[186:189], v[40:43]
	v_mfma_f32_16x16x32_bf16 v[28:31], v[218:221], v[194:197], v[28:31]
	v_mfma_f32_16x16x32_bf16 v[24:27], v[226:229], v[194:197], v[24:27]
	v_mfma_f32_16x16x32_bf16 v[12:15], v[218:221], v[202:205], v[12:15]
	v_mfma_f32_16x16x32_bf16 v[8:11], v[226:229], v[202:205], v[8:11]
	v_mfma_f32_16x16x32_bf16 v[4:7], v[218:221], v[210:213], v[4:7]
	v_mfma_f32_16x16x32_bf16 v[0:3], v[226:229], v[210:213], v[0:3]
	v_mfma_f32_16x16x32_bf16 v[44:47], v[222:225], v[190:193], v[44:47]
	v_mfma_f32_16x16x32_bf16 v[40:43], v[230:233], v[190:193], v[40:43]
	v_mfma_f32_16x16x32_bf16 v[28:31], v[222:225], v[198:201], v[28:31]
	v_mfma_f32_16x16x32_bf16 v[24:27], v[230:233], v[198:201], v[24:27]
	v_mfma_f32_16x16x32_bf16 v[12:15], v[222:225], v[206:209], v[12:15]
	v_mfma_f32_16x16x32_bf16 v[8:11], v[230:233], v[206:209], v[8:11]
	v_mfma_f32_16x16x32_bf16 v[4:7], v[222:225], v[214:217], v[4:7]
	v_mfma_f32_16x16x32_bf16 v[0:3], v[230:233], v[214:217], v[0:3]
	s_setprio 0
	s_barrier
	ds_read_b128 v[170:173], v155
	ds_read_b128 v[174:177], v156
	ds_read_b128 v[178:181], v157
	ds_read_b128 v[182:185], v165
	s_add_u32 s44, s52, 0xb4000
	s_addc_u32 s45, s53, 0
	s_mov_b32 m0, s63
	ds_read_b128 v[186:189], v145 offset:32768
	ds_read_b128 v[190:193], v145 offset:33792
	ds_read_b128 v[194:197], v145 offset:34816
	ds_read_b128 v[198:201], v145 offset:35840
	ds_read_b128 v[202:205], v145 offset:36864
	ds_read_b128 v[206:209], v145 offset:37888
	ds_read_b128 v[210:213], v145 offset:38912
	ds_read_b128 v[214:217], v145 offset:39936
	global_load_lds_dwordx4 v128, s[44:45]
	s_mov_b32 m0, s64
	s_nop 0
	global_load_lds_dwordx4 v132, s[44:45]
	s_waitcnt lgkmcnt(8)
	s_barrier
	s_waitcnt lgkmcnt(0)
	s_setprio 1
	s_waitcnt lgkmcnt(0)
	v_mfma_f32_16x16x32_bf16 v[124:127], v[170:173], v[186:189], v[124:127]
	v_mfma_f32_16x16x32_bf16 v[120:123], v[178:181], v[186:189], v[120:123]
	v_mfma_f32_16x16x32_bf16 v[116:119], v[170:173], v[194:197], v[116:119]
	v_mfma_f32_16x16x32_bf16 v[112:115], v[178:181], v[194:197], v[112:115]
	v_mfma_f32_16x16x32_bf16 v[100:103], v[170:173], v[202:205], v[100:103]
	v_mfma_f32_16x16x32_bf16 v[96:99], v[178:181], v[202:205], v[96:99]
	v_mfma_f32_16x16x32_bf16 v[84:87], v[170:173], v[210:213], v[84:87]
	v_mfma_f32_16x16x32_bf16 v[80:83], v[178:181], v[210:213], v[80:83]
	v_mfma_f32_16x16x32_bf16 v[124:127], v[174:177], v[190:193], v[124:127]
	v_mfma_f32_16x16x32_bf16 v[120:123], v[182:185], v[190:193], v[120:123]
	v_mfma_f32_16x16x32_bf16 v[116:119], v[174:177], v[198:201], v[116:119]
	v_mfma_f32_16x16x32_bf16 v[112:115], v[182:185], v[198:201], v[112:115]
	v_mfma_f32_16x16x32_bf16 v[100:103], v[174:177], v[206:209], v[100:103]
	v_mfma_f32_16x16x32_bf16 v[96:99], v[182:185], v[206:209], v[96:99]
	v_mfma_f32_16x16x32_bf16 v[84:87], v[174:177], v[214:217], v[84:87]
	v_mfma_f32_16x16x32_bf16 v[80:83], v[182:185], v[214:217], v[80:83]
	s_setprio 0
	s_barrier
	s_mov_b32 m0, s65
	ds_read_b128 v[218:221], v166
	ds_read_b128 v[222:225], v167
	ds_read_b128 v[226:229], v168
	ds_read_b128 v[230:233], v169
	s_add_u32 s100, s48, 0x80
	s_addc_u32 s101, s49, 0
	global_load_lds_dwordx4 v130, s[100:101]
	s_mov_b32 m0, s66
	s_nop 0
	global_load_lds_dwordx4 v134, s[100:101]
	s_barrier
	s_waitcnt lgkmcnt(0)
	s_setprio 1
	s_waitcnt lgkmcnt(0)
	v_mfma_f32_16x16x32_bf16 v[108:111], v[218:221], v[186:189], v[108:111]
	v_mfma_f32_16x16x32_bf16 v[104:107], v[226:229], v[186:189], v[104:107]
	v_mfma_f32_16x16x32_bf16 v[92:95], v[218:221], v[194:197], v[92:95]
	v_mfma_f32_16x16x32_bf16 v[88:91], v[226:229], v[194:197], v[88:91]
	v_mfma_f32_16x16x32_bf16 v[76:79], v[218:221], v[202:205], v[76:79]
	v_mfma_f32_16x16x32_bf16 v[72:75], v[226:229], v[202:205], v[72:75]
	v_mfma_f32_16x16x32_bf16 v[68:71], v[218:221], v[210:213], v[68:71]
	v_mfma_f32_16x16x32_bf16 v[64:67], v[226:229], v[210:213], v[64:67]
	v_mfma_f32_16x16x32_bf16 v[108:111], v[222:225], v[190:193], v[108:111]
	v_mfma_f32_16x16x32_bf16 v[104:107], v[230:233], v[190:193], v[104:107]
	v_mfma_f32_16x16x32_bf16 v[92:95], v[222:225], v[198:201], v[92:95]
	v_mfma_f32_16x16x32_bf16 v[88:91], v[230:233], v[198:201], v[88:91]
	v_mfma_f32_16x16x32_bf16 v[76:79], v[222:225], v[206:209], v[76:79]
	v_mfma_f32_16x16x32_bf16 v[72:75], v[230:233], v[206:209], v[72:75]
	v_mfma_f32_16x16x32_bf16 v[68:71], v[222:225], v[214:217], v[68:71]
	v_mfma_f32_16x16x32_bf16 v[64:67], v[230:233], v[214:217], v[64:67]
	s_setprio 0
	s_mov_b32 m0, s67
	s_barrier
	ds_read_b128 v[186:189], v145 offset:49152
	ds_read_b128 v[190:193], v145 offset:50176
	ds_read_b128 v[194:197], v145 offset:51200
	ds_read_b128 v[198:201], v145 offset:52224
	ds_read_b128 v[202:205], v145 offset:53248
	ds_read_b128 v[206:209], v145 offset:54272
	ds_read_b128 v[210:213], v145 offset:55296
	ds_read_b128 v[214:217], v145 offset:56320
	s_add_u32 s100, s52, 0x80
	s_addc_u32 s101, s53, 0
	global_load_lds_dwordx4 v128, s[100:101]
	s_mov_b32 m0, s68
	s_nop 0
	global_load_lds_dwordx4 v132, s[100:101]
	s_barrier
; #define PG8_STAGE(bufoff, gbase, voff) do { _Pragma("unroll") for (int _i = 0; _i < 2; ++_i) \
;         __builtin_amdgcn_global_load_lds((const unsigned*)((const char*)(gbase) + (voff)[_i]), (PG8_LAS unsigned*)(lds + (bufoff) + ldsw + _i * 8192), 16, 0, 0); } while (0)
; #define PG8_MMA(ai, bj, At, Bt) do { __builtin_amdgcn_s_setprio(1); _Pragma("unroll") for (int m = 0; m < 4; ++m) _Pragma("unroll") for (int n = 0; n < 2; ++n) _Pragma("unroll") for (int k = 0; k < 2; ++k) \
;         acc[ai][bj][m][n] = __builtin_amdgcn_mfma_f32_16x16x32_bf16(Bt[n][k], At[m][k], acc[ai][bj][m][n], 0, 0, 0); __builtin_amdgcn_s_setprio(0); } while (0)
; #define PG8_WAIT_V(n) asm volatile("s_waitcnt vmcnt(" #n ")" ::: "memory")
; #define PG8_WAIT_L(n) asm volatile("s_waitcnt lgkmcnt(" #n ")" ::: "memory")
; #define PG8_BAR __builtin_amdgcn_s_barrier()
; #define PG8_SCHED __builtin_amdgcn_sched_barrier(0)
; template <class Epi, class Sched, bool STAMP = false>
; __device__ __forceinline__ void gemm_phase(PG8_LAS unsigned char* lds, const Gemm g, const Sched& S, const Epi& E, unsigned long long* stamps) {
;     ...
;             PG8_BAR; PG8_WAIT_L(0); PG8_MMA(1, 0, At, B0); PG8_BAR; PG8_SCHED;
;             PG8_STAGE(PG8_SB(1, 1), b3 + hstep, voffB);
;             PG8_WAIT_V(6); PG8_BAR; PG8_MMA(1, 1, At, B1); PG8_BAR;
;         }
	s_waitcnt lgkmcnt(0)
	s_setprio 1
	s_waitcnt lgkmcnt(0)
	v_mfma_f32_16x16x32_bf16 v[60:63], v[170:173], v[186:189], v[60:63]
	v_mfma_f32_16x16x32_bf16 v[56:59], v[178:181], v[186:189], v[56:59]
	v_mfma_f32_16x16x32_bf16 v[52:55], v[170:173], v[194:197], v[52:55]
	v_mfma_f32_16x16x32_bf16 v[48:51], v[178:181], v[194:197], v[48:51]
	v_mfma_f32_16x16x32_bf16 v[36:39], v[170:173], v[202:205], v[36:39]
	v_mfma_f32_16x16x32_bf16 v[32:35], v[178:181], v[202:205], v[32:35]
	v_mfma_f32_16x16x32_bf16 v[20:23], v[170:173], v[210:213], v[20:23]
	v_mfma_f32_16x16x32_bf16 v[16:19], v[178:181], v[210:213], v[16:19]
	v_mfma_f32_16x16x32_bf16 v[60:63], v[174:177], v[190:193], v[60:63]
	v_mfma_f32_16x16x32_bf16 v[56:59], v[182:185], v[190:193], v[56:59]
	v_mfma_f32_16x16x32_bf16 v[52:55], v[174:177], v[198:201], v[52:55]
	v_mfma_f32_16x16x32_bf16 v[48:51], v[182:185], v[198:201], v[48:51]
	v_mfma_f32_16x16x32_bf16 v[36:39], v[174:177], v[206:209], v[36:39]
	v_mfma_f32_16x16x32_bf16 v[32:35], v[182:185], v[206:209], v[32:35]
	v_mfma_f32_16x16x32_bf16 v[20:23], v[174:177], v[214:217], v[20:23]
	v_mfma_f32_16x16x32_bf16 v[16:19], v[182:185], v[214:217], v[16:19]
	s_setprio 0
	s_barrier
	s_add_u32 s44, s48, 0xb4080
	s_addc_u32 s45, s49, 0
	s_mov_b32 m0, s69
	s_nop 0
	global_load_lds_dwordx4 v130, s[44:45]
	s_mov_b32 m0, s70
	s_nop 0
	global_load_lds_dwordx4 v134, s[44:45]
	s_waitcnt vmcnt(6)
	s_barrier
	s_setprio 1
	v_mfma_f32_16x16x32_bf16 v[44:47], v[218:221], v[186:189], v[44:47]
	v_mfma_f32_16x16x32_bf16 v[40:43], v[226:229], v[186:189], v[40:43]
	v_mfma_f32_16x16x32_bf16 v[28:31], v[218:221], v[194:197], v[28:31]
	v_mfma_f32_16x16x32_bf16 v[24:27], v[226:229], v[194:197], v[24:27]
	v_mfma_f32_16x16x32_bf16 v[12:15], v[218:221], v[202:205], v[12:15]
	v_mfma_f32_16x16x32_bf16 v[8:11], v[226:229], v[202:205], v[8:11]
	v_mfma_f32_16x16x32_bf16 v[4:7], v[218:221], v[210:213], v[4:7]
	v_mfma_f32_16x16x32_bf16 v[0:3], v[226:229], v[210:213], v[0:3]
	v_mfma_f32_16x16x32_bf16 v[44:47], v[222:225], v[190:193], v[44:47]
	v_mfma_f32_16x16x32_bf16 v[40:43], v[230:233], v[190:193], v[40:43]
	v_mfma_f32_16x16x32_bf16 v[28:31], v[222:225], v[198:201], v[28:31]
	v_mfma_f32_16x16x32_bf16 v[24:27], v[230:233], v[198:201], v[24:27]
	v_mfma_f32_16x16x32_bf16 v[12:15], v[222:225], v[206:209], v[12:15]
	v_mfma_f32_16x16x32_bf16 v[8:11], v[230:233], v[206:209], v[8:11]
	v_mfma_f32_16x16x32_bf16 v[4:7], v[222:225], v[214:217], v[4:7]
	v_mfma_f32_16x16x32_bf16 v[0:3], v[230:233], v[214:217], v[0:3]
	s_setprio 0
	s_add_i32 s10, s10, 2
	s_add_u32 s88, s88, 0x100
	s_addc_u32 s89, s89, 0
	s_cmp_gt_u32 s10, 41
	s_mov_b64 s[44:45], s[46:47]
	s_barrier
	s_cbranch_scc0 .LBB0_473
; #define PG8_WAIT_V(n) asm volatile("s_waitcnt vmcnt(" #n ")" ::: "memory")
; #define PG8_BAR __builtin_amdgcn_s_barrier()
;     DI void operator()(const f32x4 (&acc)[2][2][4][2], const Unit& u, int wr, int wc, int fr, int fq) const {
;         const int row0 = u.pm * BM + wr * 64 + fr, col0 = u.pn * BM + wc * 32 + 8 * fq;
; #pragma unroll
;         for (int ai = 0; ai < 2; ++ai)
; #pragma unroll
;             for (int m = 0; m < 4; ++m) { u16* rowp = O + (size_t)(row0 + ai * HALF + m * 16) * ldc + col0;
; #pragma unroll
;                 for (int bj = 0; bj < 2; ++bj) { const f32x4 v0 = acc[ai][bj][m][0], v1 = acc[ai][bj][m][1];
;                     uint4 w = {pack2(v0[0], v0[1]), pack2(v0[2], v0[3]), pack2(v1[0], v1[1]), pack2(v1[2], v1[3])}; *(uint4*)(rowp + bj * HALF) = w; } }
; template <class Epi, class Sched, bool STAMP = false>
; __device__ __forceinline__ void gemm_phase(PG8_LAS unsigned char* lds, const Gemm g, const Sched& S, const Epi& E, unsigned long long* stamps) {
;     ...
;         if (!has_next) break;
; #pragma unroll
;         for (int a = 0; a < 2; ++a)
; #pragma unroll
;             for (int b = 0; b < 2; ++b)
; #pragma unroll
;                 for (int m = 0; m < 4; ++m)
; #pragma unroll
;                     for (int n = 0; n < 2; ++n) acc[a][b][m][n] = (f32x4){0.f, 0.f, 0.f, 0.f};
;         cur = nxt; cA = nA; cB = nB; ++ui;
;     }
;     PG8_WAIT_V(0);
;     if (wr == 0) PG8_BAR;
	v_lshl_add_u32 v170, s84, 8, v144
	v_lshl_or_b32 v172, s87, 8, v146
	v_ashrrev_i32_e32 v171, 31, v170
	v_ashrrev_i32_e32 v173, 31, v172
	v_lshlrev_b64 v[174:175], 11, v[170:171]
	v_lshl_add_u64 v[174:175], s[14:15], 0, v[174:175]
	v_lshlrev_b64 v[172:173], 1, v[172:173]
	v_lshl_add_u64 v[174:175], v[174:175], 0, v[172:173]
	v_cvt_pk_bf16_f32 v60, v60, v61
	v_cvt_pk_bf16_f32 v61, v62, v63
	v_cvt_pk_bf16_f32 v62, v56, v57
	v_add_co_u32_e32 v56, vcc, s78, v174
	v_cvt_pk_bf16_f32 v68, v68, v69
	v_cvt_pk_bf16_f32 v69, v70, v71
	v_cvt_pk_bf16_f32 v70, v64, v65
	v_lshl_add_u64 v[64:65], v[174:175], 0, s[34:35]
	v_addc_co_u32_e32 v57, vcc, 0, v175, vcc
	v_cvt_pk_bf16_f32 v44, v44, v45
	v_cvt_pk_bf16_f32 v45, v46, v47
	v_cvt_pk_bf16_f32 v46, v40, v41
	v_cvt_pk_bf16_f32 v47, v42, v43
	v_cvt_pk_bf16_f32 v108, v108, v109
	v_cvt_pk_bf16_f32 v109, v110, v111
	v_cvt_pk_bf16_f32 v110, v104, v105
	v_or_b32_e32 v104, 16, v170
	global_store_dwordx4 v[64:65], v[44:47], off offset:256
	v_ashrrev_i32_e32 v105, 31, v104
	v_cvt_pk_bf16_f32 v92, v92, v93
	v_add_co_u32_e32 v46, vcc, s79, v174
	v_cvt_pk_bf16_f32 v93, v94, v95
	v_cvt_pk_bf16_f32 v94, v88, v89
	v_or_b32_e32 v88, 32, v170
	v_lshl_add_u64 v[44:45], v[174:175], 0, s[36:37]
	v_addc_co_u32_e32 v47, vcc, 0, v175, vcc
	v_cvt_pk_bf16_f32 v28, v28, v29
	v_cvt_pk_bf16_f32 v29, v30, v31
	v_cvt_pk_bf16_f32 v30, v24, v25
	v_cvt_pk_bf16_f32 v31, v26, v27
	v_lshlrev_b64 v[104:105], 11, v[104:105]
	v_ashrrev_i32_e32 v89, 31, v88
	v_cvt_pk_bf16_f32 v76, v76, v77
	v_cvt_pk_bf16_f32 v77, v78, v79
	v_cvt_pk_bf16_f32 v78, v72, v73
	v_or_b32_e32 v72, 48, v170
	global_store_dwordx4 v[44:45], v[28:31], off offset:256
	v_cvt_pk_bf16_f32 v111, v106, v107
	v_lshl_add_u64 v[104:105], s[14:15], 0, v[104:105]
	v_add_co_u32_e32 v30, vcc, s82, v174
	v_lshlrev_b64 v[88:89], 11, v[88:89]
	v_ashrrev_i32_e32 v73, 31, v72
	v_lshl_add_u64 v[28:29], v[174:175], 0, s[40:41]
	v_addc_co_u32_e32 v31, vcc, 0, v175, vcc
	v_cvt_pk_bf16_f32 v12, v12, v13
	v_cvt_pk_bf16_f32 v13, v14, v15
	v_cvt_pk_bf16_f32 v14, v8, v9
	v_cvt_pk_bf16_f32 v15, v10, v11
	global_store_dwordx4 v[174:175], v[108:111], off offset:256
	v_cvt_pk_bf16_f32 v95, v90, v91
	v_lshl_add_u64 v[88:89], s[14:15], 0, v[88:89]
	v_lshl_add_u64 v[108:109], v[104:105], 0, v[172:173]
	v_lshlrev_b64 v[72:73], 11, v[72:73]
	global_store_dwordx4 v[28:29], v[12:15], off offset:256
	global_store_dwordx4 v[108:109], v[92:95], off offset:256
	v_cvt_pk_bf16_f32 v79, v74, v75
	v_add_co_u32_e32 v14, vcc, s83, v174
	v_lshl_add_u64 v[92:93], v[88:89], 0, v[172:173]
	v_lshl_add_u64 v[72:73], s[14:15], 0, v[72:73]
	v_addc_co_u32_e32 v15, vcc, 0, v175, vcc
	v_cvt_pk_bf16_f32 v124, v124, v125
	v_cvt_pk_bf16_f32 v125, v126, v127
	v_cvt_pk_bf16_f32 v126, v120, v121
	v_cvt_pk_bf16_f32 v127, v122, v123
	v_cvt_pk_bf16_f32 v104, v116, v117
	v_cvt_pk_bf16_f32 v105, v118, v119
	v_cvt_pk_bf16_f32 v106, v112, v113
	v_cvt_pk_bf16_f32 v107, v114, v115
	v_cvt_pk_bf16_f32 v88, v100, v101
	v_cvt_pk_bf16_f32 v89, v102, v103
	v_cvt_pk_bf16_f32 v90, v96, v97
	v_cvt_pk_bf16_f32 v91, v98, v99
	global_store_dwordx4 v[92:93], v[76:79], off offset:256
	v_cvt_pk_bf16_f32 v74, v80, v81
	v_cvt_pk_bf16_f32 v75, v82, v83
	v_lshl_add_u64 v[76:77], v[72:73], 0, v[172:173]
	v_cvt_pk_bf16_f32 v72, v84, v85
	v_cvt_pk_bf16_f32 v73, v86, v87
	v_cvt_pk_bf16_f32 v71, v66, v67
	v_cvt_pk_bf16_f32 v63, v58, v59
	v_cvt_pk_bf16_f32 v40, v52, v53
	v_cvt_pk_bf16_f32 v41, v54, v55
	v_cvt_pk_bf16_f32 v42, v48, v49
	v_cvt_pk_bf16_f32 v43, v50, v51
	v_cvt_pk_bf16_f32 v24, v36, v37
	v_cvt_pk_bf16_f32 v25, v38, v39
	v_cvt_pk_bf16_f32 v26, v32, v33
	v_cvt_pk_bf16_f32 v27, v34, v35
	v_lshl_add_u64 v[12:13], v[174:175], 0, s[42:43]
	v_cvt_pk_bf16_f32 v8, v20, v21
	v_cvt_pk_bf16_f32 v9, v22, v23
	v_cvt_pk_bf16_f32 v10, v16, v17
	v_cvt_pk_bf16_f32 v11, v18, v19
	v_cvt_pk_bf16_f32 v4, v4, v5
	v_cvt_pk_bf16_f32 v5, v6, v7
	v_cvt_pk_bf16_f32 v6, v0, v1
	v_cvt_pk_bf16_f32 v7, v2, v3
	s_and_b64 vcc, exec, s[2:3]
	s_mov_b32 s87, s85
	s_mov_b32 s84, s86
	s_mov_b64 s[46:47], s[0:1]
	s_mov_b64 s[44:45], s[4:5]
	global_store_dwordx4 v[174:175], v[124:127], off
	global_store_dwordx4 v[108:109], v[104:107], off
	global_store_dwordx4 v[92:93], v[88:91], off
	global_store_dwordx4 v[76:77], v[72:75], off
	global_store_dwordx4 v[76:77], v[68:71], off offset:256
	global_store_dwordx4 v[56:57], v[60:63], off
	global_store_dwordx4 v[46:47], v[40:43], off
	global_store_dwordx4 v[30:31], v[24:27], off
	global_store_dwordx4 v[14:15], v[8:11], off
	global_store_dwordx4 v[12:13], v[4:7], off offset:256
	s_cbranch_vccz .LBB0_462
	s_waitcnt vmcnt(0)
	s_cmpk_gt_u32 s55, 0xff
	s_cbranch_scc1 .LBB0_477
	s_barrier

; #define PG8_STAGE(bufoff, gbase, voff) do { _Pragma("unroll") for (int _i = 0; _i < 2; ++_i) \
;         __builtin_amdgcn_global_load_lds((const unsigned*)((const char*)(gbase) + (voff)[_i]), (PG8_LAS unsigned*)(lds + (bufoff) + ldsw + _i * 8192), 16, 0, 0); } while (0)
; #define PG8_LDA(dst, b, h) do { _Pragma("unroll") for (int m = 0; m < 4; ++m) _Pragma("unroll") for (int k = 0; k < 2; ++k) dst[m][k] = *(const PG8_LAS bf16x8*)(lds + PG8_SA(b, h) + aoff + m * 2048 + k * 1024); } while (0)
; #define PG8_LDB(dst, b, h) do { _Pragma("unroll") for (int n = 0; n < 2; ++n) _Pragma("unroll") for (int k = 0; k < 2; ++k) dst[n][k] = *(const PG8_LAS bf16x8*)(lds + PG8_SB(b, h) + boff + n * 2048 + k * 1024); } while (0)
; #define PG8_WAIT_V(n) asm volatile("s_waitcnt vmcnt(" #n ")" ::: "memory")
; #define PG8_WAIT_L(n) asm volatile("s_waitcnt lgkmcnt(" #n ")" ::: "memory")
; #define PG8_BAR __builtin_amdgcn_s_barrier()
; template <class Epi, class Sched, bool STAMP = false>
; __device__ __forceinline__ void gemm_phase(PG8_LAS unsigned char* lds, const Gemm g, const Sched& S, const Epi& E, unsigned long long* stamps) {
;     ...
;         const bool has_next = S.next(ui + 1, nxt);
;         const char* nA = has_next ? (const char*)g.A + (size_t)nxt.pm * tstep : cA; const char* nB = has_next ? (const char*)g.Bt + (size_t)nxt.pn * tstep : cB;
;         for (int t = 0; t < nt; t += 2) {
;             const bool last = (t == nt - 2);
;             const char* a1 = cA + (size_t)(t + 1) * kstep;
;             const char* a2 = last ? nA : cA + (size_t)(t + 2) * kstep; const char* b2 = last ? nB : cB + (size_t)(t + 2) * kstep;
;             const char* a3 = a2 + kstep; const char* b3 = b2 + kstep;
;             if (last && has_next) S.a_ready(nxt);
;             PG8_LDB(B0, 0, 0); PG8_SCHED; PG8_LDA(At, 0, 0); PG8_STAGE(PG8_SA(1, 1), a1 + hstep, voffA);
;             PG8_WAIT_L(8); PG8_BAR; PG8_WAIT_L(0); PG8_MMA(0, 0, At, B0); PG8_BAR; PG8_SCHED;
;             PG8_LDB(B1, 0, 1); PG8_STAGE(PG8_SB(0, 0), b2, voffB);
;             PG8_BAR; PG8_WAIT_L(0); PG8_MMA(0, 1, At, B1); PG8_BAR;
;             PG8_LDA(At, 0, 1); PG8_STAGE(PG8_SA(0, 0), a2, voffA);
;             PG8_BAR; PG8_WAIT_L(0); PG8_MMA(1, 0, At, B0); PG8_BAR; PG8_SCHED;
;             PG8_STAGE(PG8_SB(0, 1), b2 + hstep, voffB);
;             PG8_WAIT_V(6); PG8_BAR; PG8_MMA(1, 1, At, B1); PG8_BAR;
.LBB0_514:
	ds_read_b128 v[170:173], v147
	ds_read_b128 v[174:177], v148
	ds_read_b128 v[178:181], v149
	ds_read_b128 v[182:185], v150
	s_add_u32 s42, s40, 0x100
	s_addc_u32 s43, s41, 0
	s_cmp_eq_u32 s10, 12
	s_cselect_b32 s47, s7, s43
	s_cselect_b32 s46, s6, s42
	s_cselect_b32 s45, s1, s82
	s_cselect_b32 s44, s0, s81
	s_mov_b32 m0, s71
	ds_read_b128 v[186:189], v145
	ds_read_b128 v[190:193], v145 offset:1024
	ds_read_b128 v[194:197], v145 offset:2048
	ds_read_b128 v[198:201], v145 offset:3072
	ds_read_b128 v[202:205], v145 offset:4096
	ds_read_b128 v[206:209], v145 offset:5120
	ds_read_b128 v[210:213], v145 offset:6144
	ds_read_b128 v[214:217], v145 offset:7168
	global_load_lds_dwordx4 v136, s[40:41]
	s_mov_b32 m0, s75
	s_nop 0
	global_load_lds_dwordx4 v138, s[40:41]
	s_waitcnt lgkmcnt(8)
	s_barrier
	s_waitcnt lgkmcnt(0)
	s_setprio 1
	s_waitcnt lgkmcnt(0)
	v_mfma_f32_16x16x32_bf16 v[124:127], v[170:173], v[186:189], v[124:127]
	v_mfma_f32_16x16x32_bf16 v[120:123], v[178:181], v[186:189], v[120:123]
	v_mfma_f32_16x16x32_bf16 v[116:119], v[170:173], v[194:197], v[116:119]
	v_mfma_f32_16x16x32_bf16 v[112:115], v[178:181], v[194:197], v[112:115]
	v_mfma_f32_16x16x32_bf16 v[108:111], v[170:173], v[202:205], v[108:111]
	v_mfma_f32_16x16x32_bf16 v[104:107], v[178:181], v[202:205], v[104:107]
	v_mfma_f32_16x16x32_bf16 v[100:103], v[170:173], v[210:213], v[100:103]
	v_mfma_f32_16x16x32_bf16 v[96:99], v[178:181], v[210:213], v[96:99]
	v_mfma_f32_16x16x32_bf16 v[124:127], v[174:177], v[190:193], v[124:127]
	v_mfma_f32_16x16x32_bf16 v[120:123], v[182:185], v[190:193], v[120:123]
	v_mfma_f32_16x16x32_bf16 v[116:119], v[174:177], v[198:201], v[116:119]
	v_mfma_f32_16x16x32_bf16 v[112:115], v[182:185], v[198:201], v[112:115]
	v_mfma_f32_16x16x32_bf16 v[108:111], v[174:177], v[206:209], v[108:111]
	v_mfma_f32_16x16x32_bf16 v[104:107], v[182:185], v[206:209], v[104:107]
	v_mfma_f32_16x16x32_bf16 v[100:103], v[174:177], v[214:217], v[100:103]
	v_mfma_f32_16x16x32_bf16 v[96:99], v[182:185], v[214:217], v[96:99]
	s_setprio 0
	s_barrier
	s_mov_b32 m0, s55
	ds_read_b128 v[218:221], v151
	ds_read_b128 v[222:225], v152
	ds_read_b128 v[226:229], v153
	ds_read_b128 v[230:233], v154
	global_load_lds_dwordx4 v132, s[44:45]
	s_mov_b32 m0, s56
	s_nop 0
	global_load_lds_dwordx4 v128, s[44:45]
	s_barrier
	s_waitcnt lgkmcnt(0)
	s_setprio 1
	s_waitcnt lgkmcnt(0)
	v_mfma_f32_16x16x32_bf16 v[60:63], v[218:221], v[186:189], v[60:63]
	v_mfma_f32_16x16x32_bf16 v[56:59], v[226:229], v[186:189], v[56:59]
	v_mfma_f32_16x16x32_bf16 v[52:55], v[218:221], v[194:197], v[52:55]
	v_mfma_f32_16x16x32_bf16 v[48:51], v[226:229], v[194:197], v[48:51]
	v_mfma_f32_16x16x32_bf16 v[44:47], v[218:221], v[202:205], v[44:47]
	v_mfma_f32_16x16x32_bf16 v[40:43], v[226:229], v[202:205], v[40:43]
	v_mfma_f32_16x16x32_bf16 v[36:39], v[218:221], v[210:213], v[36:39]
	v_mfma_f32_16x16x32_bf16 v[32:35], v[226:229], v[210:213], v[32:35]
	v_mfma_f32_16x16x32_bf16 v[60:63], v[222:225], v[190:193], v[60:63]
	v_mfma_f32_16x16x32_bf16 v[56:59], v[230:233], v[190:193], v[56:59]
	v_mfma_f32_16x16x32_bf16 v[52:55], v[222:225], v[198:201], v[52:55]
	v_mfma_f32_16x16x32_bf16 v[48:51], v[230:233], v[198:201], v[48:51]
	v_mfma_f32_16x16x32_bf16 v[44:47], v[222:225], v[206:209], v[44:47]
	v_mfma_f32_16x16x32_bf16 v[40:43], v[230:233], v[206:209], v[40:43]
	v_mfma_f32_16x16x32_bf16 v[36:39], v[222:225], v[214:217], v[36:39]
	v_mfma_f32_16x16x32_bf16 v[32:35], v[230:233], v[214:217], v[32:35]
	s_setprio 0
	s_mov_b32 m0, s52
	s_barrier
	ds_read_b128 v[186:189], v145 offset:16384
	ds_read_b128 v[190:193], v145 offset:17408
	ds_read_b128 v[194:197], v145 offset:18432
	ds_read_b128 v[198:201], v145 offset:19456
	ds_read_b128 v[202:205], v145 offset:20480
	ds_read_b128 v[206:209], v145 offset:21504
	ds_read_b128 v[210:213], v145 offset:22528
	ds_read_b128 v[214:217], v145 offset:23552
	global_load_lds_dwordx4 v134, s[46:47]
	s_mov_b32 m0, s57
	s_nop 0
	global_load_lds_dwordx4 v130, s[46:47]
	s_barrier
	s_waitcnt lgkmcnt(0)
	s_setprio 1
	s_waitcnt lgkmcnt(0)
	v_mfma_f32_16x16x32_bf16 v[92:95], v[170:173], v[186:189], v[92:95]
	v_mfma_f32_16x16x32_bf16 v[88:91], v[178:181], v[186:189], v[88:91]
	v_mfma_f32_16x16x32_bf16 v[84:87], v[170:173], v[194:197], v[84:87]
	v_mfma_f32_16x16x32_bf16 v[80:83], v[178:181], v[194:197], v[80:83]
	v_mfma_f32_16x16x32_bf16 v[76:79], v[170:173], v[202:205], v[76:79]
	v_mfma_f32_16x16x32_bf16 v[72:75], v[178:181], v[202:205], v[72:75]
	v_mfma_f32_16x16x32_bf16 v[68:71], v[170:173], v[210:213], v[68:71]
	v_mfma_f32_16x16x32_bf16 v[64:67], v[178:181], v[210:213], v[64:67]
	v_mfma_f32_16x16x32_bf16 v[92:95], v[174:177], v[190:193], v[92:95]
	v_mfma_f32_16x16x32_bf16 v[88:91], v[182:185], v[190:193], v[88:91]
	v_mfma_f32_16x16x32_bf16 v[84:87], v[174:177], v[198:201], v[84:87]
	v_mfma_f32_16x16x32_bf16 v[80:83], v[182:185], v[198:201], v[80:83]
	v_mfma_f32_16x16x32_bf16 v[76:79], v[174:177], v[206:209], v[76:79]
	v_mfma_f32_16x16x32_bf16 v[72:75], v[182:185], v[206:209], v[72:75]
	v_mfma_f32_16x16x32_bf16 v[68:71], v[174:177], v[214:217], v[68:71]
	v_mfma_f32_16x16x32_bf16 v[64:67], v[182:185], v[214:217], v[64:67]
	s_setprio 0
	s_barrier
	s_add_u32 s40, s44, 0x44000
	s_addc_u32 s41, s45, 0
	s_mov_b32 m0, s58
	s_nop 0
	global_load_lds_dwordx4 v132, s[40:41]
	s_mov_b32 m0, s59
	s_nop 0
	global_load_lds_dwordx4 v128, s[40:41]
	s_waitcnt vmcnt(6)
	s_barrier
; #define PG8_STAGE(bufoff, gbase, voff) do { _Pragma("unroll") for (int _i = 0; _i < 2; ++_i) \
;         __builtin_amdgcn_global_load_lds((const unsigned*)((const char*)(gbase) + (voff)[_i]), (PG8_LAS unsigned*)(lds + (bufoff) + ldsw + _i * 8192), 16, 0, 0); } while (0)
; #define PG8_LDA(dst, b, h) do { _Pragma("unroll") for (int m = 0; m < 4; ++m) _Pragma("unroll") for (int k = 0; k < 2; ++k) dst[m][k] = *(const PG8_LAS bf16x8*)(lds + PG8_SA(b, h) + aoff + m * 2048 + k * 1024); } while (0)
; #define PG8_LDB(dst, b, h) do { _Pragma("unroll") for (int n = 0; n < 2; ++n) _Pragma("unroll") for (int k = 0; k < 2; ++k) dst[n][k] = *(const PG8_LAS bf16x8*)(lds + PG8_SB(b, h) + boff + n * 2048 + k * 1024); } while (0)
; #define PG8_MMA(ai, bj, At, Bt) do { __builtin_amdgcn_s_setprio(1); _Pragma("unroll") for (int m = 0; m < 4; ++m) _Pragma("unroll") for (int n = 0; n < 2; ++n) _Pragma("unroll") for (int k = 0; k < 2; ++k) \
;         acc[ai][bj][m][n] = __builtin_amdgcn_mfma_f32_16x16x32_bf16(Bt[n][k], At[m][k], acc[ai][bj][m][n], 0, 0, 0); __builtin_amdgcn_s_setprio(0); } while (0)
; #define PG8_WAIT_V(n) asm volatile("s_waitcnt vmcnt(" #n ")" ::: "memory")
; #define PG8_WAIT_L(n) asm volatile("s_waitcnt lgkmcnt(" #n ")" ::: "memory")
; #define PG8_BAR __builtin_amdgcn_s_barrier()
; #define PG8_SCHED __builtin_amdgcn_sched_barrier(0)
; template <class Epi, class Sched, bool STAMP = false>
; __device__ __forceinline__ void gemm_phase(PG8_LAS unsigned char* lds, const Gemm g, const Sched& S, const Epi& E, unsigned long long* stamps) {
;     ...
;             PG8_WAIT_V(6); PG8_BAR; PG8_MMA(1, 1, At, B1); PG8_BAR;
;             PG8_LDB(B0, 1, 0); PG8_SCHED; PG8_LDA(At, 1, 0); PG8_STAGE(PG8_SA(0, 1), a2 + hstep, voffA);
;             PG8_WAIT_L(8); PG8_BAR; PG8_WAIT_L(0); PG8_MMA(0, 0, At, B0); PG8_BAR; PG8_SCHED;
;             PG8_LDB(B1, 1, 1); PG8_STAGE(PG8_SB(1, 0), b3, voffB);
;             PG8_BAR; PG8_WAIT_L(0); PG8_MMA(0, 1, At, B1); PG8_BAR;
;             PG8_LDA(At, 1, 1); PG8_STAGE(PG8_SA(1, 0), a3, voffA);
	s_setprio 1
	v_mfma_f32_16x16x32_bf16 v[28:31], v[218:221], v[186:189], v[28:31]
	v_mfma_f32_16x16x32_bf16 v[24:27], v[226:229], v[186:189], v[24:27]
	v_mfma_f32_16x16x32_bf16 v[20:23], v[218:221], v[194:197], v[20:23]
	v_mfma_f32_16x16x32_bf16 v[16:19], v[226:229], v[194:197], v[16:19]
	v_mfma_f32_16x16x32_bf16 v[12:15], v[218:221], v[202:205], v[12:15]
	v_mfma_f32_16x16x32_bf16 v[8:11], v[226:229], v[202:205], v[8:11]
	v_mfma_f32_16x16x32_bf16 v[4:7], v[218:221], v[210:213], v[4:7]
	v_mfma_f32_16x16x32_bf16 v[0:3], v[226:229], v[210:213], v[0:3]
	v_mfma_f32_16x16x32_bf16 v[28:31], v[222:225], v[190:193], v[28:31]
	v_mfma_f32_16x16x32_bf16 v[24:27], v[230:233], v[190:193], v[24:27]
	v_mfma_f32_16x16x32_bf16 v[20:23], v[222:225], v[198:201], v[20:23]
	v_mfma_f32_16x16x32_bf16 v[16:19], v[230:233], v[198:201], v[16:19]
	v_mfma_f32_16x16x32_bf16 v[12:15], v[222:225], v[206:209], v[12:15]
	v_mfma_f32_16x16x32_bf16 v[8:11], v[230:233], v[206:209], v[8:11]
	v_mfma_f32_16x16x32_bf16 v[4:7], v[222:225], v[214:217], v[4:7]
	v_mfma_f32_16x16x32_bf16 v[0:3], v[230:233], v[214:217], v[0:3]
	s_setprio 0
	s_barrier
	ds_read_b128 v[170:173], v155
	ds_read_b128 v[174:177], v156
	ds_read_b128 v[178:181], v157
	ds_read_b128 v[182:185], v165
	s_add_u32 s40, s46, 0x44000
	s_addc_u32 s41, s47, 0
	s_mov_b32 m0, s60
	ds_read_b128 v[186:189], v145 offset:32768
	ds_read_b128 v[190:193], v145 offset:33792
	ds_read_b128 v[194:197], v145 offset:34816
	ds_read_b128 v[198:201], v145 offset:35840
	ds_read_b128 v[202:205], v145 offset:36864
	ds_read_b128 v[206:209], v145 offset:37888
	ds_read_b128 v[210:213], v145 offset:38912
	ds_read_b128 v[214:217], v145 offset:39936
	global_load_lds_dwordx4 v134, s[40:41]
	s_mov_b32 m0, s61
	s_nop 0
	global_load_lds_dwordx4 v130, s[40:41]
	s_waitcnt lgkmcnt(8)
	s_barrier
	s_waitcnt lgkmcnt(0)
	s_setprio 1
	s_waitcnt lgkmcnt(0)
	v_mfma_f32_16x16x32_bf16 v[124:127], v[170:173], v[186:189], v[124:127]
	v_mfma_f32_16x16x32_bf16 v[120:123], v[178:181], v[186:189], v[120:123]
	v_mfma_f32_16x16x32_bf16 v[116:119], v[170:173], v[194:197], v[116:119]
	v_mfma_f32_16x16x32_bf16 v[112:115], v[178:181], v[194:197], v[112:115]
	v_mfma_f32_16x16x32_bf16 v[108:111], v[170:173], v[202:205], v[108:111]
	v_mfma_f32_16x16x32_bf16 v[104:107], v[178:181], v[202:205], v[104:107]
	v_mfma_f32_16x16x32_bf16 v[100:103], v[170:173], v[210:213], v[100:103]
	v_mfma_f32_16x16x32_bf16 v[96:99], v[178:181], v[210:213], v[96:99]
	v_mfma_f32_16x16x32_bf16 v[124:127], v[174:177], v[190:193], v[124:127]
	v_mfma_f32_16x16x32_bf16 v[120:123], v[182:185], v[190:193], v[120:123]
	v_mfma_f32_16x16x32_bf16 v[116:119], v[174:177], v[198:201], v[116:119]
	v_mfma_f32_16x16x32_bf16 v[112:115], v[182:185], v[198:201], v[112:115]
	v_mfma_f32_16x16x32_bf16 v[108:111], v[174:177], v[206:209], v[108:111]
	v_mfma_f32_16x16x32_bf16 v[104:107], v[182:185], v[206:209], v[104:107]
	v_mfma_f32_16x16x32_bf16 v[100:103], v[174:177], v[214:217], v[100:103]
	v_mfma_f32_16x16x32_bf16 v[96:99], v[182:185], v[214:217], v[96:99]
	s_setprio 0
	s_barrier
	s_mov_b32 m0, s64
	ds_read_b128 v[218:221], v166
	ds_read_b128 v[222:225], v167
	ds_read_b128 v[226:229], v168
	ds_read_b128 v[230:233], v169
	s_add_u32 s100, s44, 0x80
	s_addc_u32 s101, s45, 0
	global_load_lds_dwordx4 v132, s[100:101]
	s_mov_b32 m0, s65
	s_nop 0
	global_load_lds_dwordx4 v128, s[100:101]
	s_barrier
	s_waitcnt lgkmcnt(0)
	s_setprio 1
	s_waitcnt lgkmcnt(0)
	v_mfma_f32_16x16x32_bf16 v[60:63], v[218:221], v[186:189], v[60:63]
	v_mfma_f32_16x16x32_bf16 v[56:59], v[226:229], v[186:189], v[56:59]
	v_mfma_f32_16x16x32_bf16 v[52:55], v[218:221], v[194:197], v[52:55]
	v_mfma_f32_16x16x32_bf16 v[48:51], v[226:229], v[194:197], v[48:51]
	v_mfma_f32_16x16x32_bf16 v[44:47], v[218:221], v[202:205], v[44:47]
	v_mfma_f32_16x16x32_bf16 v[40:43], v[226:229], v[202:205], v[40:43]
	v_mfma_f32_16x16x32_bf16 v[36:39], v[218:221], v[210:213], v[36:39]
	v_mfma_f32_16x16x32_bf16 v[32:35], v[226:229], v[210:213], v[32:35]
	v_mfma_f32_16x16x32_bf16 v[60:63], v[222:225], v[190:193], v[60:63]
	v_mfma_f32_16x16x32_bf16 v[56:59], v[230:233], v[190:193], v[56:59]
	v_mfma_f32_16x16x32_bf16 v[52:55], v[222:225], v[198:201], v[52:55]
	v_mfma_f32_16x16x32_bf16 v[48:51], v[230:233], v[198:201], v[48:51]
	v_mfma_f32_16x16x32_bf16 v[44:47], v[222:225], v[206:209], v[44:47]
	v_mfma_f32_16x16x32_bf16 v[40:43], v[230:233], v[206:209], v[40:43]
	v_mfma_f32_16x16x32_bf16 v[36:39], v[222:225], v[214:217], v[36:39]
	v_mfma_f32_16x16x32_bf16 v[32:35], v[230:233], v[214:217], v[32:35]
	s_setprio 0
	s_mov_b32 m0, s66
	s_barrier
	ds_read_b128 v[186:189], v145 offset:49152
	ds_read_b128 v[190:193], v145 offset:50176
	ds_read_b128 v[194:197], v145 offset:51200
	ds_read_b128 v[198:201], v145 offset:52224
	ds_read_b128 v[202:205], v145 offset:53248
	ds_read_b128 v[206:209], v145 offset:54272
	ds_read_b128 v[210:213], v145 offset:55296
	ds_read_b128 v[214:217], v145 offset:56320
	s_add_u32 s100, s46, 0x80
	s_addc_u32 s101, s47, 0
	global_load_lds_dwordx4 v134, s[100:101]
	s_mov_b32 m0, s67
	s_nop 0
	global_load_lds_dwordx4 v130, s[100:101]
	s_barrier
; #define PG8_STAGE(bufoff, gbase, voff) do { _Pragma("unroll") for (int _i = 0; _i < 2; ++_i) \
;         __builtin_amdgcn_global_load_lds((const unsigned*)((const char*)(gbase) + (voff)[_i]), (PG8_LAS unsigned*)(lds + (bufoff) + ldsw + _i * 8192), 16, 0, 0); } while (0)
; #define PG8_MMA(ai, bj, At, Bt) do { __builtin_amdgcn_s_setprio(1); _Pragma("unroll") for (int m = 0; m < 4; ++m) _Pragma("unroll") for (int n = 0; n < 2; ++n) _Pragma("unroll") for (int k = 0; k < 2; ++k) \
;         acc[ai][bj][m][n] = __builtin_amdgcn_mfma_f32_16x16x32_bf16(Bt[n][k], At[m][k], acc[ai][bj][m][n], 0, 0, 0); __builtin_amdgcn_s_setprio(0); } while (0)
; #define PG8_WAIT_V(n) asm volatile("s_waitcnt vmcnt(" #n ")" ::: "memory")
; #define PG8_WAIT_L(n) asm volatile("s_waitcnt lgkmcnt(" #n ")" ::: "memory")
; #define PG8_BAR __builtin_amdgcn_s_barrier()
; #define PG8_SCHED __builtin_amdgcn_sched_barrier(0)
;     DI void operator()(const f32x4 (&acc)[2][2][4][2], const Unit& u, int wr, int wc, int fr, int fq) const {
;         const int row0 = u.pm * BM + wr * 64 + fr, col0 = u.pn * BM + wc * 32 + 8 * fq;
; #pragma unroll
;         for (int ai = 0; ai < 2; ++ai)
; #pragma unroll
;             for (int m = 0; m < 4; ++m) { u16* rowp = O + (size_t)(row0 + ai * HALF + m * 16) * ldc + col0;
; #pragma unroll
;                 for (int bj = 0; bj < 2; ++bj) { const f32x4 v0 = acc[ai][bj][m][0], v1 = acc[ai][bj][m][1];
;                     uint4 w = {pack2(v0[0], v0[1]), pack2(v0[2], v0[3]), pack2(v1[0], v1[1]), pack2(v1[2], v1[3])}; *(uint4*)(rowp + bj * HALF) = w; } }
; template <class Epi, class Sched, bool STAMP = false>
; __device__ __forceinline__ void gemm_phase(PG8_LAS unsigned char* lds, const Gemm g, const Sched& S, const Epi& E, unsigned long long* stamps) {
;     ...
;             PG8_BAR; PG8_WAIT_L(0); PG8_MMA(1, 0, At, B0); PG8_BAR; PG8_SCHED;
;             PG8_STAGE(PG8_SB(1, 1), b3 + hstep, voffB);
;             PG8_WAIT_V(6); PG8_BAR; PG8_MMA(1, 1, At, B1); PG8_BAR;
	s_waitcnt lgkmcnt(0)
	s_setprio 1
	s_waitcnt lgkmcnt(0)
	v_mfma_f32_16x16x32_bf16 v[92:95], v[170:173], v[186:189], v[92:95]
	v_mfma_f32_16x16x32_bf16 v[88:91], v[178:181], v[186:189], v[88:91]
	v_mfma_f32_16x16x32_bf16 v[84:87], v[170:173], v[194:197], v[84:87]
	v_mfma_f32_16x16x32_bf16 v[80:83], v[178:181], v[194:197], v[80:83]
	v_mfma_f32_16x16x32_bf16 v[76:79], v[170:173], v[202:205], v[76:79]
	v_mfma_f32_16x16x32_bf16 v[72:75], v[178:181], v[202:205], v[72:75]
	v_mfma_f32_16x16x32_bf16 v[68:71], v[170:173], v[210:213], v[68:71]
	v_mfma_f32_16x16x32_bf16 v[64:67], v[178:181], v[210:213], v[64:67]
	v_mfma_f32_16x16x32_bf16 v[92:95], v[174:177], v[190:193], v[92:95]
	v_mfma_f32_16x16x32_bf16 v[88:91], v[182:185], v[190:193], v[88:91]
	v_mfma_f32_16x16x32_bf16 v[84:87], v[174:177], v[198:201], v[84:87]
	v_mfma_f32_16x16x32_bf16 v[80:83], v[182:185], v[198:201], v[80:83]
	v_mfma_f32_16x16x32_bf16 v[76:79], v[174:177], v[206:209], v[76:79]
	v_mfma_f32_16x16x32_bf16 v[72:75], v[182:185], v[206:209], v[72:75]
	v_mfma_f32_16x16x32_bf16 v[68:71], v[174:177], v[214:217], v[68:71]
	v_mfma_f32_16x16x32_bf16 v[64:67], v[182:185], v[214:217], v[64:67]
	s_setprio 0
	s_barrier
	s_add_u32 s40, s44, 0x44080
	s_addc_u32 s41, s45, 0
	s_mov_b32 m0, s68
	s_nop 0
	global_load_lds_dwordx4 v132, s[40:41]
	s_mov_b32 m0, s69
	s_nop 0
	global_load_lds_dwordx4 v128, s[40:41]
	s_waitcnt vmcnt(6)
	s_barrier
	s_setprio 1
	v_mfma_f32_16x16x32_bf16 v[28:31], v[218:221], v[186:189], v[28:31]
	v_mfma_f32_16x16x32_bf16 v[24:27], v[226:229], v[186:189], v[24:27]
	v_mfma_f32_16x16x32_bf16 v[20:23], v[218:221], v[194:197], v[20:23]
	v_mfma_f32_16x16x32_bf16 v[16:19], v[226:229], v[194:197], v[16:19]
	v_mfma_f32_16x16x32_bf16 v[12:15], v[218:221], v[202:205], v[12:15]
	v_mfma_f32_16x16x32_bf16 v[8:11], v[226:229], v[202:205], v[8:11]
	v_mfma_f32_16x16x32_bf16 v[4:7], v[218:221], v[210:213], v[4:7]
	v_mfma_f32_16x16x32_bf16 v[0:3], v[226:229], v[210:213], v[0:3]
	v_mfma_f32_16x16x32_bf16 v[28:31], v[222:225], v[190:193], v[28:31]
	v_mfma_f32_16x16x32_bf16 v[24:27], v[230:233], v[190:193], v[24:27]
	v_mfma_f32_16x16x32_bf16 v[20:23], v[222:225], v[198:201], v[20:23]
	v_mfma_f32_16x16x32_bf16 v[16:19], v[230:233], v[198:201], v[16:19]
	v_mfma_f32_16x16x32_bf16 v[12:15], v[222:225], v[206:209], v[12:15]
	v_mfma_f32_16x16x32_bf16 v[8:11], v[230:233], v[206:209], v[8:11]
	v_mfma_f32_16x16x32_bf16 v[4:7], v[222:225], v[214:217], v[4:7]
	v_mfma_f32_16x16x32_bf16 v[0:3], v[230:233], v[214:217], v[0:3]
	s_setprio 0
	s_add_i32 s10, s10, 2
	s_add_u32 s81, s81, 0x100
	s_addc_u32 s82, s82, 0
	s_cmp_gt_u32 s10, 13
	s_mov_b64 s[40:41], s[42:43]
	s_barrier
	s_cbranch_scc0 .LBB0_514
	s_lshl_b32 s46, s79, 8
	v_or_b32_e32 v170, s46, v146
	v_lshl_add_u32 v180, s80, 8, v144
	v_ashrrev_i32_e32 v171, 31, v170
	v_mov_b64_e32 v[174:175], s[12:13]
	v_mad_i64_i32 v[172:173], s[40:41], v180, s76, v[174:175]
	v_lshlrev_b64 v[176:177], 1, v[170:171]
	v_lshl_add_u64 v[178:179], v[172:173], 0, v[176:177]
	v_cvt_pk_bf16_f32 v170, v124, v125
	v_cvt_pk_bf16_f32 v171, v126, v127
	v_cvt_pk_bf16_f32 v172, v120, v121
	v_cvt_pk_bf16_f32 v173, v122, v123
	global_store_dwordx4 v[178:179], v[170:173], off
	s_or_b32 s10, s46, s63
	s_nop 0
	v_cvt_pk_bf16_f32 v170, v60, v61
	v_cvt_pk_bf16_f32 v171, v62, v63
	v_cvt_pk_bf16_f32 v172, v56, v57
	v_cvt_pk_bf16_f32 v173, v58, v59
	global_store_dwordx4 v[178:179], v[170:173], off offset:256
	s_nop 1
	v_or_b32_e32 v170, 16, v180
	v_mad_i64_i32 v[170:171], s[40:41], v170, s76, v[174:175]
	v_lshl_add_u64 v[178:179], v[170:171], 0, v[176:177]
	v_cvt_pk_bf16_f32 v170, v116, v117
	v_cvt_pk_bf16_f32 v171, v118, v119
	v_cvt_pk_bf16_f32 v172, v112, v113
	v_cvt_pk_bf16_f32 v173, v114, v115
	global_store_dwordx4 v[178:179], v[170:173], off
	s_nop 1
	v_cvt_pk_bf16_f32 v170, v52, v53
	v_cvt_pk_bf16_f32 v171, v54, v55
	v_cvt_pk_bf16_f32 v172, v48, v49
	v_cvt_pk_bf16_f32 v173, v50, v51
	global_store_dwordx4 v[178:179], v[170:173], off offset:256
	s_nop 1
	v_or_b32_e32 v170, 32, v180
	v_mad_i64_i32 v[170:171], s[40:41], v170, s76, v[174:175]
	v_lshl_add_u64 v[178:179], v[170:171], 0, v[176:177]
	v_cvt_pk_bf16_f32 v170, v108, v109
	v_cvt_pk_bf16_f32 v171, v110, v111
	v_cvt_pk_bf16_f32 v172, v104, v105
	v_cvt_pk_bf16_f32 v173, v106, v107
	global_store_dwordx4 v[178:179], v[170:173], off
	s_nop 1
	v_cvt_pk_bf16_f32 v170, v44, v45
	v_cvt_pk_bf16_f32 v171, v46, v47
	v_cvt_pk_bf16_f32 v172, v40, v41
	v_cvt_pk_bf16_f32 v173, v42, v43
	global_store_dwordx4 v[178:179], v[170:173], off offset:256
	s_nop 1
	v_or_b32_e32 v170, 48, v180
	v_mad_i64_i32 v[170:171], s[40:41], v170, s76, v[174:175]
	v_lshl_add_u64 v[178:179], v[170:171], 0, v[176:177]
	v_cvt_pk_bf16_f32 v170, v100, v101
	v_cvt_pk_bf16_f32 v171, v102, v103
	v_cvt_pk_bf16_f32 v172, v96, v97
	v_cvt_pk_bf16_f32 v173, v98, v99
	global_store_dwordx4 v[178:179], v[170:173], off
	s_nop 1
	v_cvt_pk_bf16_f32 v170, v36, v37
	v_cvt_pk_bf16_f32 v171, v38, v39
	v_cvt_pk_bf16_f32 v172, v32, v33
	v_cvt_pk_bf16_f32 v173, v34, v35
	global_store_dwordx4 v[178:179], v[170:173], off offset:256
	s_nop 1
	v_add_u32_e32 v170, 0x80, v180
	v_mad_i64_i32 v[170:171], s[40:41], v170, s76, v[174:175]
	v_lshl_add_u64 v[178:179], v[170:171], 0, v[176:177]
	v_cvt_pk_bf16_f32 v170, v92, v93
	v_cvt_pk_bf16_f32 v171, v94, v95
	v_cvt_pk_bf16_f32 v172, v88, v89
	v_cvt_pk_bf16_f32 v173, v90, v91
	global_store_dwordx4 v[178:179], v[170:173], off
	s_nop 1
	v_cvt_pk_bf16_f32 v170, v28, v29
	v_cvt_pk_bf16_f32 v171, v30, v31
	v_cvt_pk_bf16_f32 v172, v24, v25
	v_cvt_pk_bf16_f32 v173, v26, v27
	global_store_dwordx4 v[178:179], v[170:173], off offset:256
	s_nop 1
	v_add_u32_e32 v170, 0x90, v180
;     DI void operator()(const f32x4 (&acc)[2][2][4][2], const Unit& u, int wr, int wc, int fr, int fq) const {
;     ...
;             for (int m = 0; m < 4; ++m) { u16* rowp = O + (size_t)(row0 + ai * HALF + m * 16) * ldc + col0;
; #pragma unroll
;                 for (int bj = 0; bj < 2; ++bj) { const f32x4 v0 = acc[ai][bj][m][0], v1 = acc[ai][bj][m][1];
;                     uint4 w = {pack2(v0[0], v0[1]), pack2(v0[2], v0[3]), pack2(v1[0], v1[1]), pack2(v1[2], v1[3])}; *(uint4*)(rowp + bj * HALF) = w; } }
;         if (kmaxp) {
; #pragma unroll
;             for (int bj = 0; bj < 2; ++bj) {
;                 const int cb = u.pn * BM + bj * HALF + wc * 32;
;                 const bool isA = (cb >= 384 && cb < 768), isB = (cb >= 1408 && cb < 1664);
;                 if (isA || isB) {
;                     float mx = 0.f;
; #pragma unroll
;                     for (int ai = 0; ai < 2; ++ai)
; #pragma unroll
;                         for (int m = 0; m < 4; ++m) {
;                             const f32x4 a = acc[ai][bj][m][0], b = acc[ai][bj][m][1];
;                             float s0 = a[0] * a[0] + a[1] * a[1] + a[2] * a[2] + a[3] * a[3] + b[0] * b[0] + b[1] * b[1] + b[2] * b[2] + b[3] * b[3];
;                             s0 += __shfl_xor(s0, 16);
;                             s0 += __shfl_xor(s0, 32);
;                             mx = fmaxf(mx, s0);
;                         }
; #pragma unroll
;                     for (int o = 1; o <= 8; o <<= 1) mx = fmaxf(mx, __shfl_xor(mx, o));
;                     if ((threadIdx.x & 63) == 0) atomicMax((unsigned*)kmaxp + (isA ? ((cb - 384) >> 5) : (12 + ((cb - 1408) >> 5))), __float_as_uint(mx));
	v_mad_i64_i32 v[170:171], s[40:41], v170, s76, v[174:175]
	v_lshl_add_u64 v[178:179], v[170:171], 0, v[176:177]
	v_cvt_pk_bf16_f32 v170, v84, v85
	v_cvt_pk_bf16_f32 v171, v86, v87
	v_cvt_pk_bf16_f32 v172, v80, v81
	v_cvt_pk_bf16_f32 v173, v82, v83
	global_store_dwordx4 v[178:179], v[170:173], off
	s_nop 1
	v_cvt_pk_bf16_f32 v170, v20, v21
	v_cvt_pk_bf16_f32 v171, v22, v23
	v_cvt_pk_bf16_f32 v172, v16, v17
	v_cvt_pk_bf16_f32 v173, v18, v19
	global_store_dwordx4 v[178:179], v[170:173], off offset:256
	s_nop 1
	v_add_u32_e32 v170, 0xa0, v180
	v_mad_i64_i32 v[170:171], s[40:41], v170, s76, v[174:175]
	v_lshl_add_u64 v[178:179], v[170:171], 0, v[176:177]
	v_cvt_pk_bf16_f32 v170, v76, v77
	v_cvt_pk_bf16_f32 v171, v78, v79
	v_cvt_pk_bf16_f32 v172, v72, v73
	v_cvt_pk_bf16_f32 v173, v74, v75
	global_store_dwordx4 v[178:179], v[170:173], off
	s_nop 1
	v_cvt_pk_bf16_f32 v170, v12, v13
	v_cvt_pk_bf16_f32 v171, v14, v15
	v_cvt_pk_bf16_f32 v172, v8, v9
	v_cvt_pk_bf16_f32 v173, v10, v11
	global_store_dwordx4 v[178:179], v[170:173], off offset:256
	s_nop 1
	v_add_u32_e32 v170, 0xb0, v180
	v_mad_i64_i32 v[170:171], s[40:41], v170, s76, v[174:175]
	s_add_i32 s40, s46, 0xfffffe80
	s_cmpk_gt_u32 s40, 0x17f
	s_cselect_b64 s[40:41], -1, 0
	s_add_i32 s42, s46, 0xfffffa80
	s_cmpk_gt_u32 s42, 0xff
	s_cselect_b64 s[42:43], -1, 0
	v_lshl_add_u64 v[174:175], v[170:171], 0, v[176:177]
	v_cvt_pk_bf16_f32 v170, v68, v69
	v_cvt_pk_bf16_f32 v171, v70, v71
	v_cvt_pk_bf16_f32 v172, v64, v65
	v_cvt_pk_bf16_f32 v173, v66, v67
	s_and_b64 s[42:43], s[40:41], s[42:43]
	global_store_dwordx4 v[174:175], v[170:173], off
	s_and_b64 vcc, exec, s[42:43]
	s_nop 0
	v_cvt_pk_bf16_f32 v170, v4, v5
	v_cvt_pk_bf16_f32 v171, v6, v7
	v_cvt_pk_bf16_f32 v172, v0, v1
	v_cvt_pk_bf16_f32 v173, v2, v3
	global_store_dwordx4 v[174:175], v[170:173], off offset:256
	s_cbranch_vccnz .LBB0_526
	v_mul_f32_e32 v125, v125, v125
	v_mul_f32_e32 v117, v117, v117
	v_fmac_f32_e32 v125, v124, v124
	v_fmac_f32_e32 v117, v116, v116
	v_mul_f32_e32 v109, v109, v109
	v_mul_f32_e32 v101, v101, v101
	v_fmac_f32_e32 v125, v126, v126
	v_fmac_f32_e32 v117, v118, v118
	v_fmac_f32_e32 v109, v108, v108
	v_fmac_f32_e32 v101, v100, v100
	v_fmac_f32_e32 v125, v127, v127
	v_fmac_f32_e32 v117, v119, v119
	v_fmac_f32_e32 v109, v110, v110
	v_fmac_f32_e32 v101, v102, v102
	v_fmac_f32_e32 v125, v120, v120
	v_fmac_f32_e32 v117, v112, v112
	v_fmac_f32_e32 v109, v111, v111
	v_fmac_f32_e32 v101, v103, v103
	v_fmac_f32_e32 v125, v121, v121
	v_fmac_f32_e32 v117, v113, v113
	v_fmac_f32_e32 v109, v104, v104
	v_fmac_f32_e32 v101, v96, v96
	v_fmac_f32_e32 v125, v122, v122
	v_fmac_f32_e32 v117, v114, v114
	v_fmac_f32_e32 v109, v105, v105
	v_fmac_f32_e32 v101, v97, v97
	v_fmac_f32_e32 v125, v123, v123
	v_fmac_f32_e32 v117, v115, v115
	v_fmac_f32_e32 v109, v106, v106
	v_fmac_f32_e32 v101, v98, v98
	v_mul_f32_e32 v93, v93, v93
	v_mul_f32_e32 v85, v85, v85
	ds_bpermute_b32 v120, v160, v125
	ds_bpermute_b32 v112, v160, v117
	v_fmac_f32_e32 v109, v107, v107
	v_fmac_f32_e32 v101, v99, v99
	v_fmac_f32_e32 v93, v92, v92
	v_fmac_f32_e32 v85, v84, v84
	v_mul_f32_e32 v77, v77, v77
	v_mul_f32_e32 v69, v69, v69
	ds_bpermute_b32 v104, v160, v109
	ds_bpermute_b32 v96, v160, v101
	v_fmac_f32_e32 v93, v94, v94
	v_fmac_f32_e32 v85, v86, v86
	v_fmac_f32_e32 v77, v76, v76
	v_fmac_f32_e32 v69, v68, v68
	v_fmac_f32_e32 v93, v95, v95
	v_fmac_f32_e32 v85, v87, v87
	v_fmac_f32_e32 v77, v78, v78
	v_fmac_f32_e32 v69, v70, v70
	v_fmac_f32_e32 v93, v88, v88
	v_fmac_f32_e32 v85, v80, v80
	v_fmac_f32_e32 v77, v79, v79
	v_fmac_f32_e32 v69, v71, v71
	v_fmac_f32_e32 v93, v89, v89
	v_fmac_f32_e32 v85, v81, v81
	v_fmac_f32_e32 v77, v72, v72
	v_fmac_f32_e32 v69, v64, v64
	s_waitcnt lgkmcnt(0)
	v_add_f32_e32 v113, v125, v120
	v_add_f32_e32 v112, v117, v112
	v_fmac_f32_e32 v93, v90, v90
	v_fmac_f32_e32 v85, v82, v82
	v_fmac_f32_e32 v77, v73, v73
	v_fmac_f32_e32 v69, v65, v65
	ds_bpermute_b32 v114, v159, v113
	ds_bpermute_b32 v115, v159, v112
	v_add_f32_e32 v99, v109, v104
	v_add_f32_e32 v96, v101, v96
	v_fmac_f32_e32 v93, v91, v91
	v_fmac_f32_e32 v85, v83, v83
	v_fmac_f32_e32 v77, v74, v74
	v_fmac_f32_e32 v69, v66, v66
	ds_bpermute_b32 v100, v159, v99
	ds_bpermute_b32 v101, v159, v96
	ds_bpermute_b32 v88, v160, v93
	ds_bpermute_b32 v80, v160, v85
	v_fmac_f32_e32 v77, v75, v75
	v_fmac_f32_e32 v69, v67, v67
	ds_bpermute_b32 v72, v160, v77
	ds_bpermute_b32 v64, v160, v69
	s_waitcnt lgkmcnt(0)
	v_add_f32_e32 v97, v113, v114
	v_add_f32_e32 v98, v112, v115
	v_max3_f32 v89, v97, 0, v98
	v_add_f32_e32 v90, v99, v100
	v_add_f32_e32 v91, v96, v101
	v_add_f32_e32 v88, v93, v88
	v_add_f32_e32 v65, v85, v80
	v_max3_f32 v89, v89, v90, v91
	ds_bpermute_b32 v90, v159, v88
	ds_bpermute_b32 v66, v159, v65
	v_add_f32_e32 v67, v77, v72
	v_add_f32_e32 v64, v69, v64
	ds_bpermute_b32 v68, v159, v67
	ds_bpermute_b32 v69, v159, v64
	s_waitcnt lgkmcnt(0)
	v_add_f32_e32 v70, v88, v90
	v_add_f32_e32 v65, v65, v66
	v_max3_f32 v65, v89, v70, v65
	v_add_f32_e32 v66, v67, v68
	v_add_f32_e32 v64, v64, v69
	v_max3_f32 v64, v65, v66, v64
	ds_bpermute_b32 v65, v164, v64
	s_waitcnt lgkmcnt(0)
	v_max_f32_e32 v65, v65, v65
	v_max_f32_e32 v64, v64, v65
	ds_bpermute_b32 v65, v163, v64
	s_waitcnt lgkmcnt(0)
	v_max_f32_e32 v65, v65, v65
	v_max_f32_e32 v64, v64, v65
	ds_bpermute_b32 v65, v162, v64
	s_waitcnt lgkmcnt(0)
	v_max_f32_e32 v65, v65, v65
	v_max_f32_e32 v64, v64, v65
	ds_bpermute_b32 v65, v161, v64
	s_and_saveexec_b64 s[42:43], s[2:3]
	s_cbranch_execz .LBB0_525
	s_mov_b64 s[44:45], -1
	s_and_b64 vcc, exec, s[40:41]
	s_cbranch_vccz .LBB0_519
	s_add_i32 s40, s10, 0xfffffa80
	s_ashr_i32 s40, s40, 5
	s_add_i32 s40, s40, 12
	s_mov_b64 s[44:45], 0

; #define PG8_STAGE(bufoff, gbase, voff) do { _Pragma("unroll") for (int _i = 0; _i < 2; ++_i) \
;         __builtin_amdgcn_global_load_lds((const unsigned*)((const char*)(gbase) + (voff)[_i]), (PG8_LAS unsigned*)(lds + (bufoff) + ldsw + _i * 8192), 16, 0, 0); } while (0)
; #define PG8_LDA(dst, b, h) do { _Pragma("unroll") for (int m = 0; m < 4; ++m) _Pragma("unroll") for (int k = 0; k < 2; ++k) dst[m][k] = *(const PG8_LAS bf16x8*)(lds + PG8_SA(b, h) + aoff + m * 2048 + k * 1024); } while (0)
; #define PG8_LDB(dst, b, h) do { _Pragma("unroll") for (int n = 0; n < 2; ++n) _Pragma("unroll") for (int k = 0; k < 2; ++k) dst[n][k] = *(const PG8_LAS bf16x8*)(lds + PG8_SB(b, h) + boff + n * 2048 + k * 1024); } while (0)
; #define PG8_MMA(ai, bj, At, Bt) do { __builtin_amdgcn_s_setprio(1); _Pragma("unroll") for (int m = 0; m < 4; ++m) _Pragma("unroll") for (int n = 0; n < 2; ++n) _Pragma("unroll") for (int k = 0; k < 2; ++k) \
;         acc[ai][bj][m][n] = __builtin_amdgcn_mfma_f32_16x16x32_bf16(Bt[n][k], At[m][k], acc[ai][bj][m][n], 0, 0, 0); __builtin_amdgcn_s_setprio(0); } while (0)
; #define PG8_WAIT_V(n) asm volatile("s_waitcnt vmcnt(" #n ")" ::: "memory")
; template <class Epi, class Sched, bool STAMP = false>
; __device__ __forceinline__ void gemm_phase(PG8_LAS unsigned char* lds, const Gemm g, const Sched& S, const Epi& E, unsigned long long* stamps) {
;     ...
;             const bool last = (t == nt - 2);
;             const char* a1 = cA + (size_t)(t + 1) * kstep;
;             const char* a2 = last ? nA : cA + (size_t)(t + 2) * kstep; const char* b2 = last ? nB : cB + (size_t)(t + 2) * kstep;
;             const char* a3 = a2 + kstep; const char* b3 = b2 + kstep;
;             if (last && has_next) S.a_ready(nxt);
;             PG8_LDB(B0, 0, 0); PG8_SCHED; PG8_LDA(At, 0, 0); PG8_STAGE(PG8_SA(1, 1), a1 + hstep, voffA);
;             PG8_WAIT_L(8); PG8_BAR; PG8_WAIT_L(0); PG8_MMA(0, 0, At, B0); PG8_BAR; PG8_SCHED;
;             PG8_LDB(B1, 0, 1); PG8_STAGE(PG8_SB(0, 0), b2, voffB);
;             PG8_BAR; PG8_WAIT_L(0); PG8_MMA(0, 1, At, B1); PG8_BAR;
;             PG8_LDA(At, 0, 1); PG8_STAGE(PG8_SA(0, 0), a2, voffA);
;             PG8_BAR; PG8_WAIT_L(0); PG8_MMA(1, 0, At, B0); PG8_BAR; PG8_SCHED;
;             PG8_STAGE(PG8_SB(0, 1), b2 + hstep, voffB);
;             PG8_WAIT_V(6); PG8_BAR; PG8_MMA(1, 1, At, B1); PG8_BAR;
.LBB0_688:
	ds_read_b128 v[170:173], v147
	ds_read_b128 v[174:177], v148
	ds_read_b128 v[178:181], v149
	ds_read_b128 v[182:185], v150
	s_add_u32 s36, s34, 0x100
	s_addc_u32 s37, s35, 0
	s_cmp_eq_u32 s10, 12
	s_cselect_b32 s43, s5, s37
	s_cselect_b32 s42, s4, s36
	s_cselect_b32 s41, s1, s77
	s_cselect_b32 s40, s0, s76
	s_mov_b32 m0, s63
	ds_read_b128 v[186:189], v145
	ds_read_b128 v[190:193], v145 offset:1024
	ds_read_b128 v[194:197], v145 offset:2048
	ds_read_b128 v[198:201], v145 offset:3072
	ds_read_b128 v[202:205], v145 offset:4096
	ds_read_b128 v[206:209], v145 offset:5120
	ds_read_b128 v[210:213], v145 offset:6144
	ds_read_b128 v[214:217], v145 offset:7168
	global_load_lds_dwordx4 v136, s[34:35]
	s_mov_b32 m0, s64
	s_nop 0
	global_load_lds_dwordx4 v138, s[34:35]
	s_waitcnt lgkmcnt(8)
	s_barrier
	s_waitcnt lgkmcnt(0)
	s_setprio 1
	s_waitcnt lgkmcnt(0)
	v_mfma_f32_16x16x32_bf16 v[124:127], v[170:173], v[186:189], v[124:127]
	v_mfma_f32_16x16x32_bf16 v[120:123], v[178:181], v[186:189], v[120:123]
	v_mfma_f32_16x16x32_bf16 v[116:119], v[170:173], v[194:197], v[116:119]
	v_mfma_f32_16x16x32_bf16 v[112:115], v[178:181], v[194:197], v[112:115]
	v_mfma_f32_16x16x32_bf16 v[100:103], v[170:173], v[202:205], v[100:103]
	v_mfma_f32_16x16x32_bf16 v[96:99], v[178:181], v[202:205], v[96:99]
	v_mfma_f32_16x16x32_bf16 v[84:87], v[170:173], v[210:213], v[84:87]
	v_mfma_f32_16x16x32_bf16 v[80:83], v[178:181], v[210:213], v[80:83]
	v_mfma_f32_16x16x32_bf16 v[124:127], v[174:177], v[190:193], v[124:127]
	v_mfma_f32_16x16x32_bf16 v[120:123], v[182:185], v[190:193], v[120:123]
	v_mfma_f32_16x16x32_bf16 v[116:119], v[174:177], v[198:201], v[116:119]
	v_mfma_f32_16x16x32_bf16 v[112:115], v[182:185], v[198:201], v[112:115]
	v_mfma_f32_16x16x32_bf16 v[100:103], v[174:177], v[206:209], v[100:103]
	v_mfma_f32_16x16x32_bf16 v[96:99], v[182:185], v[206:209], v[96:99]
	v_mfma_f32_16x16x32_bf16 v[84:87], v[174:177], v[214:217], v[84:87]
	v_mfma_f32_16x16x32_bf16 v[80:83], v[182:185], v[214:217], v[80:83]
	s_setprio 0
	s_barrier
	s_mov_b32 m0, s48
	ds_read_b128 v[218:221], v151
	ds_read_b128 v[222:225], v152
	ds_read_b128 v[226:229], v153
	ds_read_b128 v[230:233], v154
	global_load_lds_dwordx4 v130, s[40:41]
	s_mov_b32 m0, s49
	s_nop 0
	global_load_lds_dwordx4 v134, s[40:41]
	s_barrier
	s_waitcnt lgkmcnt(0)
	s_setprio 1
	s_waitcnt lgkmcnt(0)
	v_mfma_f32_16x16x32_bf16 v[108:111], v[218:221], v[186:189], v[108:111]
	v_mfma_f32_16x16x32_bf16 v[104:107], v[226:229], v[186:189], v[104:107]
	v_mfma_f32_16x16x32_bf16 v[92:95], v[218:221], v[194:197], v[92:95]
	v_mfma_f32_16x16x32_bf16 v[88:91], v[226:229], v[194:197], v[88:91]
	v_mfma_f32_16x16x32_bf16 v[76:79], v[218:221], v[202:205], v[76:79]
	v_mfma_f32_16x16x32_bf16 v[72:75], v[226:229], v[202:205], v[72:75]
	v_mfma_f32_16x16x32_bf16 v[68:71], v[218:221], v[210:213], v[68:71]
	v_mfma_f32_16x16x32_bf16 v[64:67], v[226:229], v[210:213], v[64:67]
	v_mfma_f32_16x16x32_bf16 v[108:111], v[222:225], v[190:193], v[108:111]
	v_mfma_f32_16x16x32_bf16 v[104:107], v[230:233], v[190:193], v[104:107]
	v_mfma_f32_16x16x32_bf16 v[92:95], v[222:225], v[198:201], v[92:95]
	v_mfma_f32_16x16x32_bf16 v[88:91], v[230:233], v[198:201], v[88:91]
	v_mfma_f32_16x16x32_bf16 v[76:79], v[222:225], v[206:209], v[76:79]
	v_mfma_f32_16x16x32_bf16 v[72:75], v[230:233], v[206:209], v[72:75]
	v_mfma_f32_16x16x32_bf16 v[68:71], v[222:225], v[214:217], v[68:71]
	v_mfma_f32_16x16x32_bf16 v[64:67], v[230:233], v[214:217], v[64:67]
	s_setprio 0
	s_mov_b32 m0, s47
	s_barrier
	ds_read_b128 v[186:189], v145 offset:16384
	ds_read_b128 v[190:193], v145 offset:17408
	ds_read_b128 v[194:197], v145 offset:18432
	ds_read_b128 v[198:201], v145 offset:19456
	ds_read_b128 v[202:205], v145 offset:20480
	ds_read_b128 v[206:209], v145 offset:21504
	ds_read_b128 v[210:213], v145 offset:22528
	ds_read_b128 v[214:217], v145 offset:23552
	global_load_lds_dwordx4 v128, s[42:43]
	s_mov_b32 m0, s50
	s_nop 0
	global_load_lds_dwordx4 v132, s[42:43]
	s_barrier
	s_waitcnt lgkmcnt(0)
	s_setprio 1
	s_waitcnt lgkmcnt(0)
	v_mfma_f32_16x16x32_bf16 v[60:63], v[170:173], v[186:189], v[60:63]
	v_mfma_f32_16x16x32_bf16 v[56:59], v[178:181], v[186:189], v[56:59]
	v_mfma_f32_16x16x32_bf16 v[52:55], v[170:173], v[194:197], v[52:55]
	v_mfma_f32_16x16x32_bf16 v[48:51], v[178:181], v[194:197], v[48:51]
	v_mfma_f32_16x16x32_bf16 v[36:39], v[170:173], v[202:205], v[36:39]
	v_mfma_f32_16x16x32_bf16 v[32:35], v[178:181], v[202:205], v[32:35]
	v_mfma_f32_16x16x32_bf16 v[20:23], v[170:173], v[210:213], v[20:23]
	v_mfma_f32_16x16x32_bf16 v[16:19], v[178:181], v[210:213], v[16:19]
	v_mfma_f32_16x16x32_bf16 v[60:63], v[174:177], v[190:193], v[60:63]
	v_mfma_f32_16x16x32_bf16 v[56:59], v[182:185], v[190:193], v[56:59]
	v_mfma_f32_16x16x32_bf16 v[52:55], v[174:177], v[198:201], v[52:55]
	v_mfma_f32_16x16x32_bf16 v[48:51], v[182:185], v[198:201], v[48:51]
	v_mfma_f32_16x16x32_bf16 v[36:39], v[174:177], v[206:209], v[36:39]
	v_mfma_f32_16x16x32_bf16 v[32:35], v[182:185], v[206:209], v[32:35]
	v_mfma_f32_16x16x32_bf16 v[20:23], v[174:177], v[214:217], v[20:23]
	v_mfma_f32_16x16x32_bf16 v[16:19], v[182:185], v[214:217], v[16:19]
	s_setprio 0
	s_barrier
	s_add_u32 s34, s40, 0x44000
	s_addc_u32 s35, s41, 0
	s_mov_b32 m0, s51
	s_nop 0
	global_load_lds_dwordx4 v130, s[34:35]
	s_mov_b32 m0, s52
	s_nop 0
	global_load_lds_dwordx4 v134, s[34:35]
	s_waitcnt vmcnt(6)
	s_barrier
; #define PG8_STAGE(bufoff, gbase, voff) do { _Pragma("unroll") for (int _i = 0; _i < 2; ++_i) \
;         __builtin_amdgcn_global_load_lds((const unsigned*)((const char*)(gbase) + (voff)[_i]), (PG8_LAS unsigned*)(lds + (bufoff) + ldsw + _i * 8192), 16, 0, 0); } while (0)
; #define PG8_LDA(dst, b, h) do { _Pragma("unroll") for (int m = 0; m < 4; ++m) _Pragma("unroll") for (int k = 0; k < 2; ++k) dst[m][k] = *(const PG8_LAS bf16x8*)(lds + PG8_SA(b, h) + aoff + m * 2048 + k * 1024); } while (0)
; #define PG8_LDB(dst, b, h) do { _Pragma("unroll") for (int n = 0; n < 2; ++n) _Pragma("unroll") for (int k = 0; k < 2; ++k) dst[n][k] = *(const PG8_LAS bf16x8*)(lds + PG8_SB(b, h) + boff + n * 2048 + k * 1024); } while (0)
; #define PG8_MMA(ai, bj, At, Bt) do { __builtin_amdgcn_s_setprio(1); _Pragma("unroll") for (int m = 0; m < 4; ++m) _Pragma("unroll") for (int n = 0; n < 2; ++n) _Pragma("unroll") for (int k = 0; k < 2; ++k) \
;         acc[ai][bj][m][n] = __builtin_amdgcn_mfma_f32_16x16x32_bf16(Bt[n][k], At[m][k], acc[ai][bj][m][n], 0, 0, 0); __builtin_amdgcn_s_setprio(0); } while (0)
; #define PG8_WAIT_V(n) asm volatile("s_waitcnt vmcnt(" #n ")" ::: "memory")
; #define PG8_WAIT_L(n) asm volatile("s_waitcnt lgkmcnt(" #n ")" ::: "memory")
; #define PG8_BAR __builtin_amdgcn_s_barrier()
; #define PG8_SCHED __builtin_amdgcn_sched_barrier(0)
; template <class Epi, class Sched, bool STAMP = false>
; __device__ __forceinline__ void gemm_phase(PG8_LAS unsigned char* lds, const Gemm g, const Sched& S, const Epi& E, unsigned long long* stamps) {
;     ...
;             PG8_WAIT_V(6); PG8_BAR; PG8_MMA(1, 1, At, B1); PG8_BAR;
;             PG8_LDB(B0, 1, 0); PG8_SCHED; PG8_LDA(At, 1, 0); PG8_STAGE(PG8_SA(0, 1), a2 + hstep, voffA);
;             PG8_WAIT_L(8); PG8_BAR; PG8_WAIT_L(0); PG8_MMA(0, 0, At, B0); PG8_BAR; PG8_SCHED;
;             PG8_LDB(B1, 1, 1); PG8_STAGE(PG8_SB(1, 0), b3, voffB);
;             PG8_BAR; PG8_WAIT_L(0); PG8_MMA(0, 1, At, B1); PG8_BAR;
;             PG8_LDA(At, 1, 1); PG8_STAGE(PG8_SA(1, 0), a3, voffA);
	s_setprio 1
	v_mfma_f32_16x16x32_bf16 v[44:47], v[218:221], v[186:189], v[44:47]
	v_mfma_f32_16x16x32_bf16 v[40:43], v[226:229], v[186:189], v[40:43]
	v_mfma_f32_16x16x32_bf16 v[28:31], v[218:221], v[194:197], v[28:31]
	v_mfma_f32_16x16x32_bf16 v[24:27], v[226:229], v[194:197], v[24:27]
	v_mfma_f32_16x16x32_bf16 v[12:15], v[218:221], v[202:205], v[12:15]
	v_mfma_f32_16x16x32_bf16 v[8:11], v[226:229], v[202:205], v[8:11]
	v_mfma_f32_16x16x32_bf16 v[4:7], v[218:221], v[210:213], v[4:7]
	v_mfma_f32_16x16x32_bf16 v[0:3], v[226:229], v[210:213], v[0:3]
	v_mfma_f32_16x16x32_bf16 v[44:47], v[222:225], v[190:193], v[44:47]
	v_mfma_f32_16x16x32_bf16 v[40:43], v[230:233], v[190:193], v[40:43]
	v_mfma_f32_16x16x32_bf16 v[28:31], v[222:225], v[198:201], v[28:31]
	v_mfma_f32_16x16x32_bf16 v[24:27], v[230:233], v[198:201], v[24:27]
	v_mfma_f32_16x16x32_bf16 v[12:15], v[222:225], v[206:209], v[12:15]
	v_mfma_f32_16x16x32_bf16 v[8:11], v[230:233], v[206:209], v[8:11]
	v_mfma_f32_16x16x32_bf16 v[4:7], v[222:225], v[214:217], v[4:7]
	v_mfma_f32_16x16x32_bf16 v[0:3], v[230:233], v[214:217], v[0:3]
	s_setprio 0
	s_barrier
	ds_read_b128 v[170:173], v155
	ds_read_b128 v[174:177], v156
	ds_read_b128 v[178:181], v157
	ds_read_b128 v[182:185], v165
	s_add_u32 s34, s42, 0x44000
	s_addc_u32 s35, s43, 0
	s_mov_b32 m0, s53
	ds_read_b128 v[186:189], v145 offset:32768
	ds_read_b128 v[190:193], v145 offset:33792
	ds_read_b128 v[194:197], v145 offset:34816
	ds_read_b128 v[198:201], v145 offset:35840
	ds_read_b128 v[202:205], v145 offset:36864
	ds_read_b128 v[206:209], v145 offset:37888
	ds_read_b128 v[210:213], v145 offset:38912
	ds_read_b128 v[214:217], v145 offset:39936
	global_load_lds_dwordx4 v128, s[34:35]
	s_mov_b32 m0, s54
	s_nop 0
	global_load_lds_dwordx4 v132, s[34:35]
	s_waitcnt lgkmcnt(8)
	s_barrier
	s_waitcnt lgkmcnt(0)
	s_setprio 1
	s_waitcnt lgkmcnt(0)
	v_mfma_f32_16x16x32_bf16 v[124:127], v[170:173], v[186:189], v[124:127]
	v_mfma_f32_16x16x32_bf16 v[120:123], v[178:181], v[186:189], v[120:123]
	v_mfma_f32_16x16x32_bf16 v[116:119], v[170:173], v[194:197], v[116:119]
	v_mfma_f32_16x16x32_bf16 v[112:115], v[178:181], v[194:197], v[112:115]
	v_mfma_f32_16x16x32_bf16 v[100:103], v[170:173], v[202:205], v[100:103]
	v_mfma_f32_16x16x32_bf16 v[96:99], v[178:181], v[202:205], v[96:99]
	v_mfma_f32_16x16x32_bf16 v[84:87], v[170:173], v[210:213], v[84:87]
	v_mfma_f32_16x16x32_bf16 v[80:83], v[178:181], v[210:213], v[80:83]
	v_mfma_f32_16x16x32_bf16 v[124:127], v[174:177], v[190:193], v[124:127]
	v_mfma_f32_16x16x32_bf16 v[120:123], v[182:185], v[190:193], v[120:123]
	v_mfma_f32_16x16x32_bf16 v[116:119], v[174:177], v[198:201], v[116:119]
	v_mfma_f32_16x16x32_bf16 v[112:115], v[182:185], v[198:201], v[112:115]
	v_mfma_f32_16x16x32_bf16 v[100:103], v[174:177], v[206:209], v[100:103]
	v_mfma_f32_16x16x32_bf16 v[96:99], v[182:185], v[206:209], v[96:99]
	v_mfma_f32_16x16x32_bf16 v[84:87], v[174:177], v[214:217], v[84:87]
	v_mfma_f32_16x16x32_bf16 v[80:83], v[182:185], v[214:217], v[80:83]
	s_setprio 0
	s_barrier
	s_mov_b32 m0, s55
	ds_read_b128 v[218:221], v166
	ds_read_b128 v[222:225], v167
	ds_read_b128 v[226:229], v168
	ds_read_b128 v[230:233], v169
	s_add_u32 s100, s40, 0x80
	s_addc_u32 s101, s41, 0
	global_load_lds_dwordx4 v130, s[100:101]
	s_mov_b32 m0, s56
	s_nop 0
	global_load_lds_dwordx4 v134, s[100:101]
	s_barrier
	s_waitcnt lgkmcnt(0)
	s_setprio 1
	s_waitcnt lgkmcnt(0)
	v_mfma_f32_16x16x32_bf16 v[108:111], v[218:221], v[186:189], v[108:111]
	v_mfma_f32_16x16x32_bf16 v[104:107], v[226:229], v[186:189], v[104:107]
	v_mfma_f32_16x16x32_bf16 v[92:95], v[218:221], v[194:197], v[92:95]
	v_mfma_f32_16x16x32_bf16 v[88:91], v[226:229], v[194:197], v[88:91]
	v_mfma_f32_16x16x32_bf16 v[76:79], v[218:221], v[202:205], v[76:79]
	v_mfma_f32_16x16x32_bf16 v[72:75], v[226:229], v[202:205], v[72:75]
	v_mfma_f32_16x16x32_bf16 v[68:71], v[218:221], v[210:213], v[68:71]
	v_mfma_f32_16x16x32_bf16 v[64:67], v[226:229], v[210:213], v[64:67]
	v_mfma_f32_16x16x32_bf16 v[108:111], v[222:225], v[190:193], v[108:111]
	v_mfma_f32_16x16x32_bf16 v[104:107], v[230:233], v[190:193], v[104:107]
	v_mfma_f32_16x16x32_bf16 v[92:95], v[222:225], v[198:201], v[92:95]
	v_mfma_f32_16x16x32_bf16 v[88:91], v[230:233], v[198:201], v[88:91]
	v_mfma_f32_16x16x32_bf16 v[76:79], v[222:225], v[206:209], v[76:79]
	v_mfma_f32_16x16x32_bf16 v[72:75], v[230:233], v[206:209], v[72:75]
	v_mfma_f32_16x16x32_bf16 v[68:71], v[222:225], v[214:217], v[68:71]
	v_mfma_f32_16x16x32_bf16 v[64:67], v[230:233], v[214:217], v[64:67]
	s_setprio 0
	s_mov_b32 m0, s57
	s_barrier
	ds_read_b128 v[186:189], v145 offset:49152
	ds_read_b128 v[190:193], v145 offset:50176
	ds_read_b128 v[194:197], v145 offset:51200
	ds_read_b128 v[198:201], v145 offset:52224
	ds_read_b128 v[202:205], v145 offset:53248
	ds_read_b128 v[206:209], v145 offset:54272
	ds_read_b128 v[210:213], v145 offset:55296
	ds_read_b128 v[214:217], v145 offset:56320
	s_add_u32 s100, s42, 0x80
	s_addc_u32 s101, s43, 0
	global_load_lds_dwordx4 v128, s[100:101]
	s_mov_b32 m0, s58
	s_nop 0
	global_load_lds_dwordx4 v132, s[100:101]
	s_barrier
; #define PG8_STAGE(bufoff, gbase, voff) do { _Pragma("unroll") for (int _i = 0; _i < 2; ++_i) \
;         __builtin_amdgcn_global_load_lds((const unsigned*)((const char*)(gbase) + (voff)[_i]), (PG8_LAS unsigned*)(lds + (bufoff) + ldsw + _i * 8192), 16, 0, 0); } while (0)
; #define PG8_MMA(ai, bj, At, Bt) do { __builtin_amdgcn_s_setprio(1); _Pragma("unroll") for (int m = 0; m < 4; ++m) _Pragma("unroll") for (int n = 0; n < 2; ++n) _Pragma("unroll") for (int k = 0; k < 2; ++k) \
;         acc[ai][bj][m][n] = __builtin_amdgcn_mfma_f32_16x16x32_bf16(Bt[n][k], At[m][k], acc[ai][bj][m][n], 0, 0, 0); __builtin_amdgcn_s_setprio(0); } while (0)
; #define PG8_WAIT_V(n) asm volatile("s_waitcnt vmcnt(" #n ")" ::: "memory")
; #define PG8_WAIT_L(n) asm volatile("s_waitcnt lgkmcnt(" #n ")" ::: "memory")
; #define PG8_BAR __builtin_amdgcn_s_barrier()
; #define PG8_SCHED __builtin_amdgcn_sched_barrier(0)
; template <class Epi, class Sched, bool STAMP = false>
; __device__ __forceinline__ void gemm_phase(PG8_LAS unsigned char* lds, const Gemm g, const Sched& S, const Epi& E, unsigned long long* stamps) {
;     ...
;             PG8_BAR; PG8_WAIT_L(0); PG8_MMA(1, 0, At, B0); PG8_BAR; PG8_SCHED;
;             PG8_STAGE(PG8_SB(1, 1), b3 + hstep, voffB);
;             PG8_WAIT_V(6); PG8_BAR; PG8_MMA(1, 1, At, B1); PG8_BAR;
;         }
	s_waitcnt lgkmcnt(0)
	s_setprio 1
	s_waitcnt lgkmcnt(0)
	v_mfma_f32_16x16x32_bf16 v[60:63], v[170:173], v[186:189], v[60:63]
	v_mfma_f32_16x16x32_bf16 v[56:59], v[178:181], v[186:189], v[56:59]
	v_mfma_f32_16x16x32_bf16 v[52:55], v[170:173], v[194:197], v[52:55]
	v_mfma_f32_16x16x32_bf16 v[48:51], v[178:181], v[194:197], v[48:51]
	v_mfma_f32_16x16x32_bf16 v[36:39], v[170:173], v[202:205], v[36:39]
	v_mfma_f32_16x16x32_bf16 v[32:35], v[178:181], v[202:205], v[32:35]
	v_mfma_f32_16x16x32_bf16 v[20:23], v[170:173], v[210:213], v[20:23]
	v_mfma_f32_16x16x32_bf16 v[16:19], v[178:181], v[210:213], v[16:19]
	v_mfma_f32_16x16x32_bf16 v[60:63], v[174:177], v[190:193], v[60:63]
	v_mfma_f32_16x16x32_bf16 v[56:59], v[182:185], v[190:193], v[56:59]
	v_mfma_f32_16x16x32_bf16 v[52:55], v[174:177], v[198:201], v[52:55]
	v_mfma_f32_16x16x32_bf16 v[48:51], v[182:185], v[198:201], v[48:51]
	v_mfma_f32_16x16x32_bf16 v[36:39], v[174:177], v[206:209], v[36:39]
	v_mfma_f32_16x16x32_bf16 v[32:35], v[182:185], v[206:209], v[32:35]
	v_mfma_f32_16x16x32_bf16 v[20:23], v[174:177], v[214:217], v[20:23]
	v_mfma_f32_16x16x32_bf16 v[16:19], v[182:185], v[214:217], v[16:19]
	s_setprio 0
	s_barrier
	s_add_u32 s34, s40, 0x44080
	s_addc_u32 s35, s41, 0
	s_mov_b32 m0, s59
	s_nop 0
	global_load_lds_dwordx4 v130, s[34:35]
	s_mov_b32 m0, s60
	s_nop 0
	global_load_lds_dwordx4 v134, s[34:35]
	s_waitcnt vmcnt(6)
	s_barrier
	s_setprio 1
	v_mfma_f32_16x16x32_bf16 v[44:47], v[218:221], v[186:189], v[44:47]
	v_mfma_f32_16x16x32_bf16 v[40:43], v[226:229], v[186:189], v[40:43]
	v_mfma_f32_16x16x32_bf16 v[28:31], v[218:221], v[194:197], v[28:31]
	v_mfma_f32_16x16x32_bf16 v[24:27], v[226:229], v[194:197], v[24:27]
	v_mfma_f32_16x16x32_bf16 v[12:15], v[218:221], v[202:205], v[12:15]
	v_mfma_f32_16x16x32_bf16 v[8:11], v[226:229], v[202:205], v[8:11]
	v_mfma_f32_16x16x32_bf16 v[4:7], v[218:221], v[210:213], v[4:7]
	v_mfma_f32_16x16x32_bf16 v[0:3], v[226:229], v[210:213], v[0:3]
	v_mfma_f32_16x16x32_bf16 v[44:47], v[222:225], v[190:193], v[44:47]
	v_mfma_f32_16x16x32_bf16 v[40:43], v[230:233], v[190:193], v[40:43]
	v_mfma_f32_16x16x32_bf16 v[28:31], v[222:225], v[198:201], v[28:31]
	v_mfma_f32_16x16x32_bf16 v[24:27], v[230:233], v[198:201], v[24:27]
	v_mfma_f32_16x16x32_bf16 v[12:15], v[222:225], v[206:209], v[12:15]
	v_mfma_f32_16x16x32_bf16 v[8:11], v[230:233], v[206:209], v[8:11]
	v_mfma_f32_16x16x32_bf16 v[4:7], v[222:225], v[214:217], v[4:7]
	v_mfma_f32_16x16x32_bf16 v[0:3], v[230:233], v[214:217], v[0:3]
	s_setprio 0
	s_add_i32 s10, s10, 2
	s_add_u32 s76, s76, 0x100
	s_addc_u32 s77, s77, 0
	s_cmp_gt_u32 s10, 13
	s_mov_b64 s[34:35], s[36:37]
	s_barrier
	s_cbranch_scc0 .LBB0_688
; #define PG8_WAIT_V(n) asm volatile("s_waitcnt vmcnt(" #n ")" ::: "memory")
; #define PG8_BAR __builtin_amdgcn_s_barrier()
;     DI void operator()(const f32x4 (&acc)[2][2][4][2], const Unit& u, int wr, int wc, int fr, int fq) const {
;         const int row0 = u.pm * BM + wr * 64 + fr, col0 = u.pn * BM + wc * 32 + 8 * fq;
; #pragma unroll
;         for (int ai = 0; ai < 2; ++ai)
; #pragma unroll
;             for (int m = 0; m < 4; ++m) { u16* rowp = O + (size_t)(row0 + ai * HALF + m * 16) * ldc + col0;
; #pragma unroll
;                 for (int bj = 0; bj < 2; ++bj) { const f32x4 v0 = acc[ai][bj][m][0], v1 = acc[ai][bj][m][1];
;                     uint4 w = {pack2(v0[0], v0[1]), pack2(v0[2], v0[3]), pack2(v1[0], v1[1]), pack2(v1[2], v1[3])}; *(uint4*)(rowp + bj * HALF) = w; } }
; template <class Epi, class Sched, bool STAMP = false>
; __device__ __forceinline__ void gemm_phase(PG8_LAS unsigned char* lds, const Gemm g, const Sched& S, const Epi& E, unsigned long long* stamps) {
;     ...
;         if (!has_next) break;
; #pragma unroll
;         for (int a = 0; a < 2; ++a)
; #pragma unroll
;             for (int b = 0; b < 2; ++b)
; #pragma unroll
;                 for (int m = 0; m < 4; ++m)
; #pragma unroll
;                     for (int n = 0; n < 2; ++n) acc[a][b][m][n] = (f32x4){0.f, 0.f, 0.f, 0.f};
;         cur = nxt; cA = nA; cB = nB; ++ui;
;     }
;     PG8_WAIT_V(0);
;     if (wr == 0) PG8_BAR;
	v_lshl_add_u32 v170, s69, 8, v144
	v_lshl_or_b32 v172, s75, 8, v146
	v_ashrrev_i32_e32 v171, 31, v170
	v_ashrrev_i32_e32 v173, 31, v172
	v_lshlrev_b64 v[174:175], 11, v[170:171]
	v_lshl_add_u64 v[174:175], s[14:15], 0, v[174:175]
	v_lshlrev_b64 v[172:173], 1, v[172:173]
	v_lshl_add_u64 v[174:175], v[174:175], 0, v[172:173]
	v_cvt_pk_bf16_f32 v60, v60, v61
	v_cvt_pk_bf16_f32 v61, v62, v63
	v_cvt_pk_bf16_f32 v62, v56, v57
	v_add_co_u32_e32 v56, vcc, s65, v174
	v_cvt_pk_bf16_f32 v68, v68, v69
	v_cvt_pk_bf16_f32 v69, v70, v71
	v_cvt_pk_bf16_f32 v70, v64, v65
	v_lshl_add_u64 v[64:65], v[174:175], 0, s[16:17]
	v_addc_co_u32_e32 v57, vcc, 0, v175, vcc
	v_cvt_pk_bf16_f32 v44, v44, v45
	v_cvt_pk_bf16_f32 v45, v46, v47
	v_cvt_pk_bf16_f32 v46, v40, v41
	v_cvt_pk_bf16_f32 v47, v42, v43
	v_cvt_pk_bf16_f32 v108, v108, v109
	v_cvt_pk_bf16_f32 v109, v110, v111
	v_cvt_pk_bf16_f32 v110, v104, v105
	v_or_b32_e32 v104, 16, v170
	global_store_dwordx4 v[64:65], v[44:47], off offset:256
	v_ashrrev_i32_e32 v105, 31, v104
	v_cvt_pk_bf16_f32 v92, v92, v93
	v_add_co_u32_e32 v46, vcc, s66, v174
	v_cvt_pk_bf16_f32 v93, v94, v95
	v_cvt_pk_bf16_f32 v94, v88, v89
	v_or_b32_e32 v88, 32, v170
	v_lshl_add_u64 v[44:45], v[174:175], 0, s[18:19]
	v_addc_co_u32_e32 v47, vcc, 0, v175, vcc
	v_cvt_pk_bf16_f32 v28, v28, v29
	v_cvt_pk_bf16_f32 v29, v30, v31
	v_cvt_pk_bf16_f32 v30, v24, v25
	v_cvt_pk_bf16_f32 v31, v26, v27
	v_lshlrev_b64 v[104:105], 11, v[104:105]
	v_ashrrev_i32_e32 v89, 31, v88
	v_cvt_pk_bf16_f32 v76, v76, v77
	v_cvt_pk_bf16_f32 v77, v78, v79
	v_cvt_pk_bf16_f32 v78, v72, v73
	v_or_b32_e32 v72, 48, v170
	global_store_dwordx4 v[44:45], v[28:31], off offset:256
	v_cvt_pk_bf16_f32 v111, v106, v107
	v_lshl_add_u64 v[104:105], s[14:15], 0, v[104:105]
	v_add_co_u32_e32 v30, vcc, s67, v174
	v_lshlrev_b64 v[88:89], 11, v[88:89]
	v_ashrrev_i32_e32 v73, 31, v72
	v_lshl_add_u64 v[28:29], v[174:175], 0, s[20:21]
	v_addc_co_u32_e32 v31, vcc, 0, v175, vcc
	v_cvt_pk_bf16_f32 v12, v12, v13
	v_cvt_pk_bf16_f32 v13, v14, v15
	v_cvt_pk_bf16_f32 v14, v8, v9
	v_cvt_pk_bf16_f32 v15, v10, v11
	global_store_dwordx4 v[174:175], v[108:111], off offset:256
	v_cvt_pk_bf16_f32 v95, v90, v91
	v_lshl_add_u64 v[88:89], s[14:15], 0, v[88:89]
	v_lshl_add_u64 v[108:109], v[104:105], 0, v[172:173]
	v_lshlrev_b64 v[72:73], 11, v[72:73]
	global_store_dwordx4 v[28:29], v[12:15], off offset:256
	global_store_dwordx4 v[108:109], v[92:95], off offset:256
	v_cvt_pk_bf16_f32 v79, v74, v75
	v_add_co_u32_e32 v14, vcc, s68, v174
	v_lshl_add_u64 v[92:93], v[88:89], 0, v[172:173]
	v_lshl_add_u64 v[72:73], s[14:15], 0, v[72:73]
	v_addc_co_u32_e32 v15, vcc, 0, v175, vcc
	v_cvt_pk_bf16_f32 v124, v124, v125
	v_cvt_pk_bf16_f32 v125, v126, v127
	v_cvt_pk_bf16_f32 v126, v120, v121
	v_cvt_pk_bf16_f32 v127, v122, v123
	v_cvt_pk_bf16_f32 v104, v116, v117
	v_cvt_pk_bf16_f32 v105, v118, v119
	v_cvt_pk_bf16_f32 v106, v112, v113
	v_cvt_pk_bf16_f32 v107, v114, v115
	v_cvt_pk_bf16_f32 v88, v100, v101
	v_cvt_pk_bf16_f32 v89, v102, v103
	v_cvt_pk_bf16_f32 v90, v96, v97
	v_cvt_pk_bf16_f32 v91, v98, v99
	global_store_dwordx4 v[92:93], v[76:79], off offset:256
	v_cvt_pk_bf16_f32 v74, v80, v81
	v_cvt_pk_bf16_f32 v75, v82, v83
	v_lshl_add_u64 v[76:77], v[72:73], 0, v[172:173]
	v_cvt_pk_bf16_f32 v72, v84, v85
	v_cvt_pk_bf16_f32 v73, v86, v87
	v_cvt_pk_bf16_f32 v71, v66, v67
	v_cvt_pk_bf16_f32 v63, v58, v59
	v_cvt_pk_bf16_f32 v40, v52, v53
	v_cvt_pk_bf16_f32 v41, v54, v55
	v_cvt_pk_bf16_f32 v42, v48, v49
	v_cvt_pk_bf16_f32 v43, v50, v51
	v_cvt_pk_bf16_f32 v24, v36, v37
	v_cvt_pk_bf16_f32 v25, v38, v39
	v_cvt_pk_bf16_f32 v26, v32, v33
	v_cvt_pk_bf16_f32 v27, v34, v35
	v_lshl_add_u64 v[12:13], v[174:175], 0, s[28:29]
	v_cvt_pk_bf16_f32 v8, v20, v21
	v_cvt_pk_bf16_f32 v9, v22, v23
	v_cvt_pk_bf16_f32 v10, v16, v17
	v_cvt_pk_bf16_f32 v11, v18, v19
	v_cvt_pk_bf16_f32 v4, v4, v5
	v_cvt_pk_bf16_f32 v5, v6, v7
	v_cvt_pk_bf16_f32 v6, v0, v1
	v_cvt_pk_bf16_f32 v7, v2, v3
	s_and_b64 vcc, exec, s[2:3]
	s_mov_b32 s75, s70
	s_mov_b32 s69, s71
	s_mov_b64 s[36:37], s[0:1]
	s_mov_b64 s[34:35], s[4:5]
	global_store_dwordx4 v[174:175], v[124:127], off
	global_store_dwordx4 v[108:109], v[104:107], off
	global_store_dwordx4 v[92:93], v[88:91], off
	global_store_dwordx4 v[76:77], v[72:75], off
	global_store_dwordx4 v[76:77], v[68:71], off offset:256
	global_store_dwordx4 v[56:57], v[60:63], off
	global_store_dwordx4 v[46:47], v[40:43], off
	global_store_dwordx4 v[30:31], v[24:27], off
	global_store_dwordx4 v[14:15], v[8:11], off
	global_store_dwordx4 v[12:13], v[4:7], off offset:256
	s_cbranch_vccz .LBB0_677
	s_waitcnt vmcnt(0)
	s_cmpk_gt_u32 s45, 0xff
	s_cbranch_scc1 .LBB0_692
	s_barrier

; #define PG8_STAGE(bufoff, gbase, voff) do { _Pragma("unroll") for (int _i = 0; _i < 2; ++_i) \
;         __builtin_amdgcn_global_load_lds((const unsigned*)((const char*)(gbase) + (voff)[_i]), (PG8_LAS unsigned*)(lds + (bufoff) + ldsw + _i * 8192), 16, 0, 0); } while (0)
; #define PG8_LDA(dst, b, h) do { _Pragma("unroll") for (int m = 0; m < 4; ++m) _Pragma("unroll") for (int k = 0; k < 2; ++k) dst[m][k] = *(const PG8_LAS bf16x8*)(lds + PG8_SA(b, h) + aoff + m * 2048 + k * 1024); } while (0)
; #define PG8_LDB(dst, b, h) do { _Pragma("unroll") for (int n = 0; n < 2; ++n) _Pragma("unroll") for (int k = 0; k < 2; ++k) dst[n][k] = *(const PG8_LAS bf16x8*)(lds + PG8_SB(b, h) + boff + n * 2048 + k * 1024); } while (0)
; #define PG8_MMA(ai, bj, At, Bt) do { __builtin_amdgcn_s_setprio(1); _Pragma("unroll") for (int m = 0; m < 4; ++m) _Pragma("unroll") for (int n = 0; n < 2; ++n) _Pragma("unroll") for (int k = 0; k < 2; ++k) \
;         acc[ai][bj][m][n] = __builtin_amdgcn_mfma_f32_16x16x32_bf16(Bt[n][k], At[m][k], acc[ai][bj][m][n], 0, 0, 0); __builtin_amdgcn_s_setprio(0); } while (0)
; #define PG8_WAIT_V(n) asm volatile("s_waitcnt vmcnt(" #n ")" ::: "memory")
; template <class Epi, class Sched, bool STAMP = false>
; __device__ __forceinline__ void gemm_phase(PG8_LAS unsigned char* lds, const Gemm g, const Sched& S, const Epi& E, unsigned long long* stamps) {
;     ...
;             const bool last = (t == nt - 2);
;             const char* a1 = cA + (size_t)(t + 1) * kstep;
;             const char* a2 = last ? nA : cA + (size_t)(t + 2) * kstep; const char* b2 = last ? nB : cB + (size_t)(t + 2) * kstep;
;             const char* a3 = a2 + kstep; const char* b3 = b2 + kstep;
;             if (last && has_next) S.a_ready(nxt);
;             PG8_LDB(B0, 0, 0); PG8_SCHED; PG8_LDA(At, 0, 0); PG8_STAGE(PG8_SA(1, 1), a1 + hstep, voffA);
;             PG8_WAIT_L(8); PG8_BAR; PG8_WAIT_L(0); PG8_MMA(0, 0, At, B0); PG8_BAR; PG8_SCHED;
;             PG8_LDB(B1, 0, 1); PG8_STAGE(PG8_SB(0, 0), b2, voffB);
;             PG8_BAR; PG8_WAIT_L(0); PG8_MMA(0, 1, At, B1); PG8_BAR;
;             PG8_LDA(At, 0, 1); PG8_STAGE(PG8_SA(0, 0), a2, voffA);
;             PG8_BAR; PG8_WAIT_L(0); PG8_MMA(1, 0, At, B0); PG8_BAR; PG8_SCHED;
;             PG8_STAGE(PG8_SB(0, 1), b2 + hstep, voffB);
;             PG8_WAIT_V(6); PG8_BAR; PG8_MMA(1, 1, At, B1); PG8_BAR;
.LBB0_727:
	ds_read_b128 v[140:143], v147
	ds_read_b128 v[170:173], v148
	ds_read_b128 v[174:177], v149
	ds_read_b128 v[178:181], v150
	s_add_u32 s18, s16, 0x100
	s_addc_u32 s19, s17, 0
	s_cmp_eq_u32 s10, 12
	s_cselect_b32 s29, s5, s19
	s_cselect_b32 s28, s4, s18
	s_cselect_b32 s21, s1, s63
	s_cselect_b32 s20, s0, s62
	s_mov_b32 m0, s55
	ds_read_b128 v[182:185], v145
	ds_read_b128 v[186:189], v145 offset:1024
	ds_read_b128 v[190:193], v145 offset:2048
	ds_read_b128 v[194:197], v145 offset:3072
	ds_read_b128 v[198:201], v145 offset:4096
	ds_read_b128 v[202:205], v145 offset:5120
	ds_read_b128 v[206:209], v145 offset:6144
	ds_read_b128 v[210:213], v145 offset:7168
	global_load_lds_dwordx4 v132, s[16:17]
	s_mov_b32 m0, s56
	s_nop 0
	global_load_lds_dwordx4 v134, s[16:17]
	s_waitcnt lgkmcnt(8)
	s_barrier
	s_waitcnt lgkmcnt(0)
	s_setprio 1
	s_waitcnt lgkmcnt(0)
	v_mfma_f32_16x16x32_bf16 v[124:127], v[140:143], v[182:185], v[124:127]
	v_mfma_f32_16x16x32_bf16 v[120:123], v[174:177], v[182:185], v[120:123]
	v_mfma_f32_16x16x32_bf16 v[108:111], v[140:143], v[190:193], v[108:111]
	v_mfma_f32_16x16x32_bf16 v[104:107], v[174:177], v[190:193], v[104:107]
	v_mfma_f32_16x16x32_bf16 v[92:95], v[140:143], v[198:201], v[92:95]
	v_mfma_f32_16x16x32_bf16 v[88:91], v[174:177], v[198:201], v[88:91]
	v_mfma_f32_16x16x32_bf16 v[76:79], v[140:143], v[206:209], v[76:79]
	v_mfma_f32_16x16x32_bf16 v[72:75], v[174:177], v[206:209], v[72:75]
	v_mfma_f32_16x16x32_bf16 v[124:127], v[170:173], v[186:189], v[124:127]
	v_mfma_f32_16x16x32_bf16 v[120:123], v[178:181], v[186:189], v[120:123]
	v_mfma_f32_16x16x32_bf16 v[108:111], v[170:173], v[194:197], v[108:111]
	v_mfma_f32_16x16x32_bf16 v[104:107], v[178:181], v[194:197], v[104:107]
	v_mfma_f32_16x16x32_bf16 v[92:95], v[170:173], v[202:205], v[92:95]
	v_mfma_f32_16x16x32_bf16 v[88:91], v[178:181], v[202:205], v[88:91]
	v_mfma_f32_16x16x32_bf16 v[76:79], v[170:173], v[210:213], v[76:79]
	v_mfma_f32_16x16x32_bf16 v[72:75], v[178:181], v[210:213], v[72:75]
	s_setprio 0
	s_barrier
	s_mov_b32 m0, s37
	ds_read_b128 v[214:217], v151
	ds_read_b128 v[218:221], v152
	ds_read_b128 v[222:225], v153
	ds_read_b128 v[226:229], v154
	global_load_lds_dwordx4 v130, s[20:21]
	s_mov_b32 m0, s40
	s_nop 0
	global_load_lds_dwordx4 v128, s[20:21]
	s_barrier
	s_waitcnt lgkmcnt(0)
	s_setprio 1
	s_waitcnt lgkmcnt(0)
	v_mfma_f32_16x16x32_bf16 v[116:119], v[214:217], v[182:185], v[116:119]
	v_mfma_f32_16x16x32_bf16 v[112:115], v[222:225], v[182:185], v[112:115]
	v_mfma_f32_16x16x32_bf16 v[100:103], v[214:217], v[190:193], v[100:103]
	v_mfma_f32_16x16x32_bf16 v[96:99], v[222:225], v[190:193], v[96:99]
	v_mfma_f32_16x16x32_bf16 v[84:87], v[214:217], v[198:201], v[84:87]
	v_mfma_f32_16x16x32_bf16 v[80:83], v[222:225], v[198:201], v[80:83]
	v_mfma_f32_16x16x32_bf16 v[68:71], v[214:217], v[206:209], v[68:71]
	v_mfma_f32_16x16x32_bf16 v[64:67], v[222:225], v[206:209], v[64:67]
	v_mfma_f32_16x16x32_bf16 v[116:119], v[218:221], v[186:189], v[116:119]
	v_mfma_f32_16x16x32_bf16 v[112:115], v[226:229], v[186:189], v[112:115]
	v_mfma_f32_16x16x32_bf16 v[100:103], v[218:221], v[194:197], v[100:103]
	v_mfma_f32_16x16x32_bf16 v[96:99], v[226:229], v[194:197], v[96:99]
	v_mfma_f32_16x16x32_bf16 v[84:87], v[218:221], v[202:205], v[84:87]
	v_mfma_f32_16x16x32_bf16 v[80:83], v[226:229], v[202:205], v[80:83]
	v_mfma_f32_16x16x32_bf16 v[68:71], v[218:221], v[210:213], v[68:71]
	v_mfma_f32_16x16x32_bf16 v[64:67], v[226:229], v[210:213], v[64:67]
	s_setprio 0
	s_mov_b32 m0, s34
	s_barrier
	ds_read_b128 v[182:185], v145 offset:16384
	ds_read_b128 v[186:189], v145 offset:17408
	ds_read_b128 v[190:193], v145 offset:18432
	ds_read_b128 v[194:197], v145 offset:19456
	ds_read_b128 v[198:201], v145 offset:20480
	ds_read_b128 v[202:205], v145 offset:21504
	ds_read_b128 v[206:209], v145 offset:22528
	ds_read_b128 v[210:213], v145 offset:23552
	global_load_lds_dwordx4 v130, s[28:29]
	s_mov_b32 m0, s41
	s_nop 0
	global_load_lds_dwordx4 v128, s[28:29]
	s_barrier
	s_waitcnt lgkmcnt(0)
	s_setprio 1
	s_waitcnt lgkmcnt(0)
	v_mfma_f32_16x16x32_bf16 v[60:63], v[140:143], v[182:185], v[60:63]
	v_mfma_f32_16x16x32_bf16 v[56:59], v[174:177], v[182:185], v[56:59]
	v_mfma_f32_16x16x32_bf16 v[44:47], v[140:143], v[190:193], v[44:47]
	v_mfma_f32_16x16x32_bf16 v[40:43], v[174:177], v[190:193], v[40:43]
	v_mfma_f32_16x16x32_bf16 v[28:31], v[140:143], v[198:201], v[28:31]
	v_mfma_f32_16x16x32_bf16 v[24:27], v[174:177], v[198:201], v[24:27]
	v_mfma_f32_16x16x32_bf16 v[12:15], v[140:143], v[206:209], v[12:15]
	v_mfma_f32_16x16x32_bf16 v[8:11], v[174:177], v[206:209], v[8:11]
	v_mfma_f32_16x16x32_bf16 v[60:63], v[170:173], v[186:189], v[60:63]
	v_mfma_f32_16x16x32_bf16 v[56:59], v[178:181], v[186:189], v[56:59]
	v_mfma_f32_16x16x32_bf16 v[44:47], v[170:173], v[194:197], v[44:47]
	v_mfma_f32_16x16x32_bf16 v[40:43], v[178:181], v[194:197], v[40:43]
	v_mfma_f32_16x16x32_bf16 v[28:31], v[170:173], v[202:205], v[28:31]
	v_mfma_f32_16x16x32_bf16 v[24:27], v[178:181], v[202:205], v[24:27]
	v_mfma_f32_16x16x32_bf16 v[12:15], v[170:173], v[210:213], v[12:15]
	v_mfma_f32_16x16x32_bf16 v[8:11], v[178:181], v[210:213], v[8:11]
	s_setprio 0
	s_barrier
	s_add_u32 s16, s20, 0x44000
	s_addc_u32 s17, s21, 0
	s_mov_b32 m0, s42
	s_nop 0
	global_load_lds_dwordx4 v130, s[16:17]
	s_mov_b32 m0, s43
	s_nop 0
	global_load_lds_dwordx4 v128, s[16:17]
	s_waitcnt vmcnt(6)
	s_barrier
; #define PG8_STAGE(bufoff, gbase, voff) do { _Pragma("unroll") for (int _i = 0; _i < 2; ++_i) \
;         __builtin_amdgcn_global_load_lds((const unsigned*)((const char*)(gbase) + (voff)[_i]), (PG8_LAS unsigned*)(lds + (bufoff) + ldsw + _i * 8192), 16, 0, 0); } while (0)
; #define PG8_LDA(dst, b, h) do { _Pragma("unroll") for (int m = 0; m < 4; ++m) _Pragma("unroll") for (int k = 0; k < 2; ++k) dst[m][k] = *(const PG8_LAS bf16x8*)(lds + PG8_SA(b, h) + aoff + m * 2048 + k * 1024); } while (0)
; #define PG8_LDB(dst, b, h) do { _Pragma("unroll") for (int n = 0; n < 2; ++n) _Pragma("unroll") for (int k = 0; k < 2; ++k) dst[n][k] = *(const PG8_LAS bf16x8*)(lds + PG8_SB(b, h) + boff + n * 2048 + k * 1024); } while (0)
; #define PG8_MMA(ai, bj, At, Bt) do { __builtin_amdgcn_s_setprio(1); _Pragma("unroll") for (int m = 0; m < 4; ++m) _Pragma("unroll") for (int n = 0; n < 2; ++n) _Pragma("unroll") for (int k = 0; k < 2; ++k) \
;         acc[ai][bj][m][n] = __builtin_amdgcn_mfma_f32_16x16x32_bf16(Bt[n][k], At[m][k], acc[ai][bj][m][n], 0, 0, 0); __builtin_amdgcn_s_setprio(0); } while (0)
; #define PG8_WAIT_V(n) asm volatile("s_waitcnt vmcnt(" #n ")" ::: "memory")
; #define PG8_WAIT_L(n) asm volatile("s_waitcnt lgkmcnt(" #n ")" ::: "memory")
; #define PG8_BAR __builtin_amdgcn_s_barrier()
; #define PG8_SCHED __builtin_amdgcn_sched_barrier(0)
; template <class Epi, class Sched, bool STAMP = false>
; __device__ __forceinline__ void gemm_phase(PG8_LAS unsigned char* lds, const Gemm g, const Sched& S, const Epi& E, unsigned long long* stamps) {
;     ...
;             PG8_WAIT_V(6); PG8_BAR; PG8_MMA(1, 1, At, B1); PG8_BAR;
;             PG8_LDB(B0, 1, 0); PG8_SCHED; PG8_LDA(At, 1, 0); PG8_STAGE(PG8_SA(0, 1), a2 + hstep, voffA);
;             PG8_WAIT_L(8); PG8_BAR; PG8_WAIT_L(0); PG8_MMA(0, 0, At, B0); PG8_BAR; PG8_SCHED;
;             PG8_LDB(B1, 1, 1); PG8_STAGE(PG8_SB(1, 0), b3, voffB);
;             PG8_BAR; PG8_WAIT_L(0); PG8_MMA(0, 1, At, B1); PG8_BAR;
;             PG8_LDA(At, 1, 1); PG8_STAGE(PG8_SA(1, 0), a3, voffA);
	s_setprio 1
	v_mfma_f32_16x16x32_bf16 v[52:55], v[214:217], v[182:185], v[52:55]
	v_mfma_f32_16x16x32_bf16 v[48:51], v[222:225], v[182:185], v[48:51]
	v_mfma_f32_16x16x32_bf16 v[36:39], v[214:217], v[190:193], v[36:39]
	v_mfma_f32_16x16x32_bf16 v[32:35], v[222:225], v[190:193], v[32:35]
	v_mfma_f32_16x16x32_bf16 v[20:23], v[214:217], v[198:201], v[20:23]
	v_mfma_f32_16x16x32_bf16 v[16:19], v[222:225], v[198:201], v[16:19]
	v_mfma_f32_16x16x32_bf16 v[4:7], v[214:217], v[206:209], v[4:7]
	v_mfma_f32_16x16x32_bf16 v[0:3], v[222:225], v[206:209], v[0:3]
	v_mfma_f32_16x16x32_bf16 v[52:55], v[218:221], v[186:189], v[52:55]
	v_mfma_f32_16x16x32_bf16 v[48:51], v[226:229], v[186:189], v[48:51]
	v_mfma_f32_16x16x32_bf16 v[36:39], v[218:221], v[194:197], v[36:39]
	v_mfma_f32_16x16x32_bf16 v[32:35], v[226:229], v[194:197], v[32:35]
	v_mfma_f32_16x16x32_bf16 v[20:23], v[218:221], v[202:205], v[20:23]
	v_mfma_f32_16x16x32_bf16 v[16:19], v[226:229], v[202:205], v[16:19]
	v_mfma_f32_16x16x32_bf16 v[4:7], v[218:221], v[210:213], v[4:7]
	v_mfma_f32_16x16x32_bf16 v[0:3], v[226:229], v[210:213], v[0:3]
	s_setprio 0
	s_barrier
	ds_read_b128 v[140:143], v155
	ds_read_b128 v[170:173], v156
	ds_read_b128 v[174:177], v157
	ds_read_b128 v[178:181], v165
	s_add_u32 s16, s28, 0x44000
	s_addc_u32 s17, s29, 0
	s_mov_b32 m0, s44
	ds_read_b128 v[182:185], v145 offset:32768
	ds_read_b128 v[186:189], v145 offset:33792
	ds_read_b128 v[190:193], v145 offset:34816
	ds_read_b128 v[194:197], v145 offset:35840
	ds_read_b128 v[198:201], v145 offset:36864
	ds_read_b128 v[202:205], v145 offset:37888
	ds_read_b128 v[206:209], v145 offset:38912
	ds_read_b128 v[210:213], v145 offset:39936
	global_load_lds_dwordx4 v130, s[16:17]
	s_mov_b32 m0, s45
	s_nop 0
	global_load_lds_dwordx4 v128, s[16:17]
	s_waitcnt lgkmcnt(8)
	s_barrier
	s_waitcnt lgkmcnt(0)
	s_setprio 1
	s_waitcnt lgkmcnt(0)
	v_mfma_f32_16x16x32_bf16 v[124:127], v[140:143], v[182:185], v[124:127]
	v_mfma_f32_16x16x32_bf16 v[120:123], v[174:177], v[182:185], v[120:123]
	v_mfma_f32_16x16x32_bf16 v[108:111], v[140:143], v[190:193], v[108:111]
	v_mfma_f32_16x16x32_bf16 v[104:107], v[174:177], v[190:193], v[104:107]
	v_mfma_f32_16x16x32_bf16 v[92:95], v[140:143], v[198:201], v[92:95]
	v_mfma_f32_16x16x32_bf16 v[88:91], v[174:177], v[198:201], v[88:91]
	v_mfma_f32_16x16x32_bf16 v[76:79], v[140:143], v[206:209], v[76:79]
	v_mfma_f32_16x16x32_bf16 v[72:75], v[174:177], v[206:209], v[72:75]
	v_mfma_f32_16x16x32_bf16 v[124:127], v[170:173], v[186:189], v[124:127]
	v_mfma_f32_16x16x32_bf16 v[120:123], v[178:181], v[186:189], v[120:123]
	v_mfma_f32_16x16x32_bf16 v[108:111], v[170:173], v[194:197], v[108:111]
	v_mfma_f32_16x16x32_bf16 v[104:107], v[178:181], v[194:197], v[104:107]
	v_mfma_f32_16x16x32_bf16 v[92:95], v[170:173], v[202:205], v[92:95]
	v_mfma_f32_16x16x32_bf16 v[88:91], v[178:181], v[202:205], v[88:91]
	v_mfma_f32_16x16x32_bf16 v[76:79], v[170:173], v[210:213], v[76:79]
	v_mfma_f32_16x16x32_bf16 v[72:75], v[178:181], v[210:213], v[72:75]
	s_setprio 0
	s_barrier
	s_mov_b32 m0, s48
	ds_read_b128 v[214:217], v166
	ds_read_b128 v[218:221], v167
	ds_read_b128 v[222:225], v168
	ds_read_b128 v[226:229], v169
	s_add_u32 s100, s20, 0x80
	s_addc_u32 s101, s21, 0
	global_load_lds_dwordx4 v130, s[100:101]
	s_mov_b32 m0, s49
	s_nop 0
	global_load_lds_dwordx4 v128, s[100:101]
	s_barrier
	s_waitcnt lgkmcnt(0)
	s_setprio 1
	s_waitcnt lgkmcnt(0)
	v_mfma_f32_16x16x32_bf16 v[116:119], v[214:217], v[182:185], v[116:119]
	v_mfma_f32_16x16x32_bf16 v[112:115], v[222:225], v[182:185], v[112:115]
	v_mfma_f32_16x16x32_bf16 v[100:103], v[214:217], v[190:193], v[100:103]
	v_mfma_f32_16x16x32_bf16 v[96:99], v[222:225], v[190:193], v[96:99]
	v_mfma_f32_16x16x32_bf16 v[84:87], v[214:217], v[198:201], v[84:87]
	v_mfma_f32_16x16x32_bf16 v[80:83], v[222:225], v[198:201], v[80:83]
	v_mfma_f32_16x16x32_bf16 v[68:71], v[214:217], v[206:209], v[68:71]
	v_mfma_f32_16x16x32_bf16 v[64:67], v[222:225], v[206:209], v[64:67]
	v_mfma_f32_16x16x32_bf16 v[116:119], v[218:221], v[186:189], v[116:119]
	v_mfma_f32_16x16x32_bf16 v[112:115], v[226:229], v[186:189], v[112:115]
	v_mfma_f32_16x16x32_bf16 v[100:103], v[218:221], v[194:197], v[100:103]
	v_mfma_f32_16x16x32_bf16 v[96:99], v[226:229], v[194:197], v[96:99]
	v_mfma_f32_16x16x32_bf16 v[84:87], v[218:221], v[202:205], v[84:87]
	v_mfma_f32_16x16x32_bf16 v[80:83], v[226:229], v[202:205], v[80:83]
	v_mfma_f32_16x16x32_bf16 v[68:71], v[218:221], v[210:213], v[68:71]
	v_mfma_f32_16x16x32_bf16 v[64:67], v[226:229], v[210:213], v[64:67]
	s_setprio 0
	s_mov_b32 m0, s50
	s_barrier
	ds_read_b128 v[182:185], v145 offset:49152
	ds_read_b128 v[186:189], v145 offset:50176
	ds_read_b128 v[190:193], v145 offset:51200
	ds_read_b128 v[194:197], v145 offset:52224
	ds_read_b128 v[198:201], v145 offset:53248
	ds_read_b128 v[202:205], v145 offset:54272
	ds_read_b128 v[206:209], v145 offset:55296
	ds_read_b128 v[210:213], v145 offset:56320
	s_add_u32 s100, s28, 0x80
	s_addc_u32 s101, s29, 0
	global_load_lds_dwordx4 v130, s[100:101]
	s_mov_b32 m0, s51
	s_nop 0
	global_load_lds_dwordx4 v128, s[100:101]
	s_barrier
; DI float ex2(float x) { return __builtin_amdgcn_exp2f(x); }
; #define PG8_STAGE(bufoff, gbase, voff) do { _Pragma("unroll") for (int _i = 0; _i < 2; ++_i) \
;         __builtin_amdgcn_global_load_lds((const unsigned*)((const char*)(gbase) + (voff)[_i]), (PG8_LAS unsigned*)(lds + (bufoff) + ldsw + _i * 8192), 16, 0, 0); } while (0)
; #define PG8_MMA(ai, bj, At, Bt) do { __builtin_amdgcn_s_setprio(1); _Pragma("unroll") for (int m = 0; m < 4; ++m) _Pragma("unroll") for (int n = 0; n < 2; ++n) _Pragma("unroll") for (int k = 0; k < 2; ++k) \
;         acc[ai][bj][m][n] = __builtin_amdgcn_mfma_f32_16x16x32_bf16(Bt[n][k], At[m][k], acc[ai][bj][m][n], 0, 0, 0); __builtin_amdgcn_s_setprio(0); } while (0)
; #define PG8_WAIT_V(n) asm volatile("s_waitcnt vmcnt(" #n ")" ::: "memory")
; #define PG8_WAIT_L(n) asm volatile("s_waitcnt lgkmcnt(" #n ")" ::: "memory")
; #define PG8_BAR __builtin_amdgcn_s_barrier()
; #define PG8_SCHED __builtin_amdgcn_sched_barrier(0)
;     DI void operator()(const f32x4 (&acc)[2][2][4][2], const Unit& u, int wr, int wc, int fr, int fq) const {
;         const int row0 = u.pm * BM + wr * 64 + fr, hcol0 = ((u.pn * BM + wc * 32) >> 1) + 4 * fq;
; #pragma unroll
;         for (int ai = 0; ai < 2; ++ai)
; #pragma unroll
;             for (int m = 0; m < 4; ++m) { u16* rowp = O + (size_t)(row0 + ai * HALF + m * 16) * ldc + hcol0;
; #pragma unroll
;                 for (int bj = 0; bj < 2; ++bj) { const f32x4 g = acc[ai][bj][m][0], up = acc[ai][bj][m][1]; float r[4];
; #pragma unroll
;                     for (int j = 0; j < 4; ++j) r[j] = g[j] * up[j] * __builtin_amdgcn_rcpf(1.f + ex2(-LOG2E * g[j]));
;                     uint2 w = {pack2(r[0], r[1]), pack2(r[2], r[3])}; *(uint2*)(rowp + bj * (HALF / 2)) = w; } }
; template <class Epi, class Sched, bool STAMP = false>
; __device__ __forceinline__ void gemm_phase(PG8_LAS unsigned char* lds, const Gemm g, const Sched& S, const Epi& E, unsigned long long* stamps) {
;     ...
;             PG8_BAR; PG8_WAIT_L(0); PG8_MMA(1, 0, At, B0); PG8_BAR; PG8_SCHED;
;             PG8_STAGE(PG8_SB(1, 1), b3 + hstep, voffB);
;             PG8_WAIT_V(6); PG8_BAR; PG8_MMA(1, 1, At, B1); PG8_BAR;
	s_waitcnt lgkmcnt(0)
	s_setprio 1
	s_waitcnt lgkmcnt(0)
	v_mfma_f32_16x16x32_bf16 v[60:63], v[140:143], v[182:185], v[60:63]
	v_mfma_f32_16x16x32_bf16 v[56:59], v[174:177], v[182:185], v[56:59]
	v_mfma_f32_16x16x32_bf16 v[44:47], v[140:143], v[190:193], v[44:47]
	v_mfma_f32_16x16x32_bf16 v[40:43], v[174:177], v[190:193], v[40:43]
	v_mfma_f32_16x16x32_bf16 v[28:31], v[140:143], v[198:201], v[28:31]
	v_mfma_f32_16x16x32_bf16 v[24:27], v[174:177], v[198:201], v[24:27]
	v_mfma_f32_16x16x32_bf16 v[12:15], v[140:143], v[206:209], v[12:15]
	v_mfma_f32_16x16x32_bf16 v[8:11], v[174:177], v[206:209], v[8:11]
	v_mfma_f32_16x16x32_bf16 v[60:63], v[170:173], v[186:189], v[60:63]
	v_mfma_f32_16x16x32_bf16 v[56:59], v[178:181], v[186:189], v[56:59]
	v_mfma_f32_16x16x32_bf16 v[44:47], v[170:173], v[194:197], v[44:47]
	v_mfma_f32_16x16x32_bf16 v[40:43], v[178:181], v[194:197], v[40:43]
	v_mfma_f32_16x16x32_bf16 v[28:31], v[170:173], v[202:205], v[28:31]
	v_mfma_f32_16x16x32_bf16 v[24:27], v[178:181], v[202:205], v[24:27]
	v_mfma_f32_16x16x32_bf16 v[12:15], v[170:173], v[210:213], v[12:15]
	v_mfma_f32_16x16x32_bf16 v[8:11], v[178:181], v[210:213], v[8:11]
	s_setprio 0
	s_barrier
	s_add_u32 s16, s20, 0x44080
	s_addc_u32 s17, s21, 0
	s_mov_b32 m0, s52
	s_nop 0
	global_load_lds_dwordx4 v130, s[16:17]
	s_mov_b32 m0, s53
	s_nop 0
	global_load_lds_dwordx4 v128, s[16:17]
	s_waitcnt vmcnt(6)
	s_barrier
	s_setprio 1
	v_mfma_f32_16x16x32_bf16 v[52:55], v[214:217], v[182:185], v[52:55]
	v_mfma_f32_16x16x32_bf16 v[48:51], v[222:225], v[182:185], v[48:51]
	v_mfma_f32_16x16x32_bf16 v[36:39], v[214:217], v[190:193], v[36:39]
	v_mfma_f32_16x16x32_bf16 v[32:35], v[222:225], v[190:193], v[32:35]
	v_mfma_f32_16x16x32_bf16 v[20:23], v[214:217], v[198:201], v[20:23]
	v_mfma_f32_16x16x32_bf16 v[16:19], v[222:225], v[198:201], v[16:19]
	v_mfma_f32_16x16x32_bf16 v[4:7], v[214:217], v[206:209], v[4:7]
	v_mfma_f32_16x16x32_bf16 v[0:3], v[222:225], v[206:209], v[0:3]
	v_mfma_f32_16x16x32_bf16 v[52:55], v[218:221], v[186:189], v[52:55]
	v_mfma_f32_16x16x32_bf16 v[48:51], v[226:229], v[186:189], v[48:51]
	v_mfma_f32_16x16x32_bf16 v[36:39], v[218:221], v[194:197], v[36:39]
	v_mfma_f32_16x16x32_bf16 v[32:35], v[226:229], v[194:197], v[32:35]
	v_mfma_f32_16x16x32_bf16 v[20:23], v[218:221], v[202:205], v[20:23]
	v_mfma_f32_16x16x32_bf16 v[16:19], v[226:229], v[202:205], v[16:19]
	v_mfma_f32_16x16x32_bf16 v[4:7], v[218:221], v[210:213], v[4:7]
	v_mfma_f32_16x16x32_bf16 v[0:3], v[226:229], v[210:213], v[0:3]
	s_setprio 0
	s_add_i32 s10, s10, 2
	s_add_u32 s62, s62, 0x100
	s_addc_u32 s63, s63, 0
	s_cmp_gt_u32 s10, 13
	s_mov_b64 s[16:17], s[18:19]
	s_barrier
	s_cbranch_scc0 .LBB0_727
	v_mul_f32_e32 v171, 0xbfb8aa3b, v124
	v_exp_f32_e32 v171, v171
	v_mul_f32_e32 v174, 0xbfb8aa3b, v125
	v_exp_f32_e32 v175, v174
	s_lshl_b32 s10, s61, 8
	v_add_f32_e32 v171, 1.0, v171
	v_rcp_f32_e32 v174, v171
	v_add_f32_e32 v171, 1.0, v175
	v_mul_f32_e32 v175, 0xbfb8aa3b, v126
	v_exp_f32_e32 v176, v175
	v_mul_f32_e32 v175, 0xbfb8aa3b, v127
	v_exp_f32_e32 v177, v175
	v_rcp_f32_e32 v175, v171
	v_add_f32_e32 v171, 1.0, v176
	v_rcp_f32_e32 v176, v171
	v_add_f32_e32 v171, 1.0, v177
	v_rcp_f32_e32 v177, v171
	v_pk_mul_f32 v[122:123], v[126:127], v[122:123]
	v_pk_mul_f32 v[120:121], v[124:125], v[120:121]
	s_or_b32 s10, s10, s47
	v_pk_mul_f32 v[120:121], v[120:121], v[174:175]
	v_pk_mul_f32 v[122:123], v[122:123], v[176:177]
	s_ashr_i32 s10, s10, 1
	v_cvt_pk_bf16_f32 v120, v120, v121
	v_cvt_pk_bf16_f32 v121, v122, v123
	v_mul_f32_e32 v122, 0xbfb8aa3b, v116
	v_mul_f32_e32 v123, 0xbfb8aa3b, v117
	v_or_b32_e32 v140, s10, v146
	v_exp_f32_e32 v122, v122
	v_exp_f32_e32 v123, v123
	v_lshl_add_u32 v170, s60, 8, v144
	v_ashrrev_i32_e32 v141, 31, v140
	v_mov_b64_e32 v[142:143], s[12:13]
	v_mad_i64_i32 v[172:173], s[16:17], v170, s57, v[142:143]
	v_lshlrev_b64 v[140:141], 1, v[140:141]
	v_lshl_add_u64 v[172:173], v[172:173], 0, v[140:141]
	global_store_dwordx2 v[172:173], v[120:121], off
	v_add_f32_e32 v120, 1.0, v122
	v_add_f32_e32 v121, 1.0, v123
	v_mul_f32_e32 v122, 0xbfb8aa3b, v118
	v_mul_f32_e32 v123, 0xbfb8aa3b, v119
	v_exp_f32_e32 v122, v122
	v_exp_f32_e32 v123, v123
	v_rcp_f32_e32 v120, v120
	v_rcp_f32_e32 v121, v121
	v_add_f32_e32 v122, 1.0, v122
	v_add_f32_e32 v123, 1.0, v123
	v_rcp_f32_e32 v122, v122
	v_rcp_f32_e32 v123, v123
	v_pk_mul_f32 v[114:115], v[118:119], v[114:115]
	v_pk_mul_f32 v[112:113], v[116:117], v[112:113]
	v_mul_f32_e32 v116, 0xbfb8aa3b, v110
	v_pk_mul_f32 v[112:113], v[112:113], v[120:121]
	v_pk_mul_f32 v[114:115], v[114:115], v[122:123]
	v_cvt_pk_bf16_f32 v112, v112, v113
	v_cvt_pk_bf16_f32 v113, v114, v115
	v_mul_f32_e32 v114, 0xbfb8aa3b, v108
	v_mul_f32_e32 v115, 0xbfb8aa3b, v109
	v_mul_f32_e32 v117, 0xbfb8aa3b, v111
	v_exp_f32_e32 v114, v114
	v_exp_f32_e32 v115, v115
	v_exp_f32_e32 v116, v116
	v_exp_f32_e32 v117, v117
	v_add_f32_e32 v114, 1.0, v114
	v_add_f32_e32 v115, 1.0, v115
	v_add_f32_e32 v116, 1.0, v116
	v_add_f32_e32 v117, 1.0, v117
	v_rcp_f32_e32 v114, v114
	v_rcp_f32_e32 v115, v115
	v_rcp_f32_e32 v116, v116
	v_rcp_f32_e32 v117, v117
	v_pk_mul_f32 v[106:107], v[110:111], v[106:107]
	v_pk_mul_f32 v[104:105], v[108:109], v[104:105]
	global_store_dwordx2 v[172:173], v[112:113], off offset:128
	v_pk_mul_f32 v[104:105], v[104:105], v[114:115]
	v_pk_mul_f32 v[106:107], v[106:107], v[116:117]
	v_cvt_pk_bf16_f32 v104, v104, v105
	v_cvt_pk_bf16_f32 v105, v106, v107
	v_mul_f32_e32 v106, 0xbfb8aa3b, v100
	v_mul_f32_e32 v107, 0xbfb8aa3b, v101
	v_exp_f32_e32 v106, v106
	v_exp_f32_e32 v107, v107
	v_or_b32_e32 v112, 16, v170
	v_mad_i64_i32 v[112:113], s[16:17], v112, s57, v[142:143]
; DI float ex2(float x) { return __builtin_amdgcn_exp2f(x); }
;     DI void operator()(const f32x4 (&acc)[2][2][4][2], const Unit& u, int wr, int wc, int fr, int fq) const {
;     ...
;             for (int m = 0; m < 4; ++m) { u16* rowp = O + (size_t)(row0 + ai * HALF + m * 16) * ldc + hcol0;
; #pragma unroll
;                 for (int bj = 0; bj < 2; ++bj) { const f32x4 g = acc[ai][bj][m][0], up = acc[ai][bj][m][1]; float r[4];
; #pragma unroll
;                     for (int j = 0; j < 4; ++j) r[j] = g[j] * up[j] * __builtin_amdgcn_rcpf(1.f + ex2(-LOG2E * g[j]));
;                     uint2 w = {pack2(r[0], r[1]), pack2(r[2], r[3])}; *(uint2*)(rowp + bj * (HALF / 2)) = w; } }
	v_lshl_add_u64 v[112:113], v[112:113], 0, v[140:141]
	global_store_dwordx2 v[112:113], v[104:105], off
	v_add_f32_e32 v104, 1.0, v106
	v_add_f32_e32 v105, 1.0, v107
	v_mul_f32_e32 v106, 0xbfb8aa3b, v102
	v_mul_f32_e32 v107, 0xbfb8aa3b, v103
	v_exp_f32_e32 v106, v106
	v_exp_f32_e32 v107, v107
	v_rcp_f32_e32 v104, v104
	v_rcp_f32_e32 v105, v105
	v_add_f32_e32 v106, 1.0, v106
	v_add_f32_e32 v107, 1.0, v107
	v_rcp_f32_e32 v106, v106
	v_rcp_f32_e32 v107, v107
	v_pk_mul_f32 v[98:99], v[102:103], v[98:99]
	v_pk_mul_f32 v[96:97], v[100:101], v[96:97]
	v_mul_f32_e32 v100, 0xbfb8aa3b, v94
	v_pk_mul_f32 v[96:97], v[96:97], v[104:105]
	v_pk_mul_f32 v[98:99], v[98:99], v[106:107]
	v_cvt_pk_bf16_f32 v96, v96, v97
	v_cvt_pk_bf16_f32 v97, v98, v99
	v_mul_f32_e32 v98, 0xbfb8aa3b, v92
	v_mul_f32_e32 v99, 0xbfb8aa3b, v93
	v_mul_f32_e32 v101, 0xbfb8aa3b, v95
	v_exp_f32_e32 v98, v98
	v_exp_f32_e32 v99, v99
	v_exp_f32_e32 v100, v100
	v_exp_f32_e32 v101, v101
	v_add_f32_e32 v98, 1.0, v98
	v_add_f32_e32 v99, 1.0, v99
	v_add_f32_e32 v100, 1.0, v100
	v_add_f32_e32 v101, 1.0, v101
	v_rcp_f32_e32 v98, v98
	v_rcp_f32_e32 v99, v99
	v_rcp_f32_e32 v100, v100
	v_rcp_f32_e32 v101, v101
	v_pk_mul_f32 v[90:91], v[94:95], v[90:91]
	v_pk_mul_f32 v[88:89], v[92:93], v[88:89]
	global_store_dwordx2 v[112:113], v[96:97], off offset:128
	v_pk_mul_f32 v[88:89], v[88:89], v[98:99]
	v_pk_mul_f32 v[90:91], v[90:91], v[100:101]
	v_cvt_pk_bf16_f32 v88, v88, v89
	v_cvt_pk_bf16_f32 v89, v90, v91
	v_mul_f32_e32 v90, 0xbfb8aa3b, v84
	v_mul_f32_e32 v91, 0xbfb8aa3b, v85
	v_exp_f32_e32 v90, v90
	v_exp_f32_e32 v91, v91
	v_or_b32_e32 v96, 32, v170
	v_mad_i64_i32 v[96:97], s[16:17], v96, s57, v[142:143]
	v_lshl_add_u64 v[96:97], v[96:97], 0, v[140:141]
	global_store_dwordx2 v[96:97], v[88:89], off
	v_add_f32_e32 v88, 1.0, v90
	v_add_f32_e32 v89, 1.0, v91
	v_mul_f32_e32 v90, 0xbfb8aa3b, v86
	v_mul_f32_e32 v91, 0xbfb8aa3b, v87
	v_exp_f32_e32 v90, v90
	v_exp_f32_e32 v91, v91
	v_rcp_f32_e32 v88, v88
	v_rcp_f32_e32 v89, v89
	v_add_f32_e32 v90, 1.0, v90
	v_add_f32_e32 v91, 1.0, v91
	v_rcp_f32_e32 v90, v90
	v_rcp_f32_e32 v91, v91
	v_pk_mul_f32 v[82:83], v[86:87], v[82:83]
	v_pk_mul_f32 v[80:81], v[84:85], v[80:81]
	v_mul_f32_e32 v84, 0xbfb8aa3b, v78
	v_pk_mul_f32 v[80:81], v[80:81], v[88:89]
	v_pk_mul_f32 v[82:83], v[82:83], v[90:91]
	v_cvt_pk_bf16_f32 v80, v80, v81
	v_cvt_pk_bf16_f32 v81, v82, v83
	v_mul_f32_e32 v82, 0xbfb8aa3b, v76
	v_mul_f32_e32 v83, 0xbfb8aa3b, v77
	v_mul_f32_e32 v85, 0xbfb8aa3b, v79
	v_exp_f32_e32 v82, v82
	v_exp_f32_e32 v83, v83
	v_exp_f32_e32 v84, v84
	v_exp_f32_e32 v85, v85
	v_add_f32_e32 v82, 1.0, v82
	v_add_f32_e32 v83, 1.0, v83
	v_add_f32_e32 v84, 1.0, v84
	v_add_f32_e32 v85, 1.0, v85
	v_rcp_f32_e32 v82, v82
	v_rcp_f32_e32 v83, v83
	v_rcp_f32_e32 v84, v84
	v_rcp_f32_e32 v85, v85
	v_pk_mul_f32 v[74:75], v[78:79], v[74:75]
	v_pk_mul_f32 v[72:73], v[76:77], v[72:73]
	global_store_dwordx2 v[96:97], v[80:81], off offset:128
	v_pk_mul_f32 v[72:73], v[72:73], v[82:83]
	v_pk_mul_f32 v[74:75], v[74:75], v[84:85]
	v_cvt_pk_bf16_f32 v72, v72, v73
	v_cvt_pk_bf16_f32 v73, v74, v75
	v_mul_f32_e32 v74, 0xbfb8aa3b, v68
	v_mul_f32_e32 v75, 0xbfb8aa3b, v69
	v_exp_f32_e32 v74, v74
	v_exp_f32_e32 v75, v75
	v_or_b32_e32 v80, 48, v170
	v_mad_i64_i32 v[80:81], s[16:17], v80, s57, v[142:143]
	v_lshl_add_u64 v[80:81], v[80:81], 0, v[140:141]
	global_store_dwordx2 v[80:81], v[72:73], off
	v_add_f32_e32 v72, 1.0, v74
	v_add_f32_e32 v73, 1.0, v75
	v_mul_f32_e32 v74, 0xbfb8aa3b, v70
	v_mul_f32_e32 v75, 0xbfb8aa3b, v71
	v_exp_f32_e32 v74, v74
	v_exp_f32_e32 v75, v75
	v_rcp_f32_e32 v72, v72
	v_rcp_f32_e32 v73, v73
	v_add_f32_e32 v74, 1.0, v74
	v_add_f32_e32 v75, 1.0, v75
	v_rcp_f32_e32 v74, v74
	v_rcp_f32_e32 v75, v75
	v_pk_mul_f32 v[66:67], v[70:71], v[66:67]
	v_pk_mul_f32 v[64:65], v[68:69], v[64:65]
	v_mul_f32_e32 v68, 0xbfb8aa3b, v62
	v_pk_mul_f32 v[64:65], v[64:65], v[72:73]
	v_pk_mul_f32 v[66:67], v[66:67], v[74:75]
	v_cvt_pk_bf16_f32 v64, v64, v65
	v_cvt_pk_bf16_f32 v65, v66, v67
	v_mul_f32_e32 v66, 0xbfb8aa3b, v60
	v_mul_f32_e32 v67, 0xbfb8aa3b, v61
	v_mul_f32_e32 v69, 0xbfb8aa3b, v63
	v_exp_f32_e32 v66, v66
	v_exp_f32_e32 v67, v67
	v_exp_f32_e32 v68, v68
	v_exp_f32_e32 v69, v69
	v_add_f32_e32 v66, 1.0, v66
	v_add_f32_e32 v67, 1.0, v67
	v_add_f32_e32 v68, 1.0, v68
	v_add_f32_e32 v69, 1.0, v69
	v_rcp_f32_e32 v66, v66
	v_rcp_f32_e32 v67, v67
	v_rcp_f32_e32 v68, v68
	v_rcp_f32_e32 v69, v69
	v_pk_mul_f32 v[58:59], v[62:63], v[58:59]
	v_pk_mul_f32 v[56:57], v[60:61], v[56:57]
	global_store_dwordx2 v[80:81], v[64:65], off offset:128
	v_pk_mul_f32 v[56:57], v[56:57], v[66:67]
	v_pk_mul_f32 v[58:59], v[58:59], v[68:69]
	v_cvt_pk_bf16_f32 v56, v56, v57
	v_cvt_pk_bf16_f32 v57, v58, v59
	v_mul_f32_e32 v58, 0xbfb8aa3b, v52
	v_mul_f32_e32 v59, 0xbfb8aa3b, v53
	v_exp_f32_e32 v58, v58
	v_exp_f32_e32 v59, v59
	v_add_u32_e32 v64, 0x80, v170
	v_mad_i64_i32 v[64:65], s[16:17], v64, s57, v[142:143]
	v_lshl_add_u64 v[64:65], v[64:65], 0, v[140:141]
	global_store_dwordx2 v[64:65], v[56:57], off
	v_add_f32_e32 v56, 1.0, v58
	v_add_f32_e32 v57, 1.0, v59
	v_mul_f32_e32 v58, 0xbfb8aa3b, v54
	v_mul_f32_e32 v59, 0xbfb8aa3b, v55
	v_exp_f32_e32 v58, v58
	v_exp_f32_e32 v59, v59
	v_rcp_f32_e32 v56, v56
	v_rcp_f32_e32 v57, v57
	v_add_f32_e32 v58, 1.0, v58
	v_add_f32_e32 v59, 1.0, v59
	v_rcp_f32_e32 v58, v58
	v_rcp_f32_e32 v59, v59
	v_pk_mul_f32 v[50:51], v[54:55], v[50:51]
	v_pk_mul_f32 v[48:49], v[52:53], v[48:49]
	v_mul_f32_e32 v52, 0xbfb8aa3b, v46
	v_pk_mul_f32 v[48:49], v[48:49], v[56:57]
	v_pk_mul_f32 v[50:51], v[50:51], v[58:59]
	v_cvt_pk_bf16_f32 v48, v48, v49
	v_cvt_pk_bf16_f32 v49, v50, v51
	v_mul_f32_e32 v50, 0xbfb8aa3b, v44
; DI float ex2(float x) { return __builtin_amdgcn_exp2f(x); }
;     DI void operator()(const f32x4 (&acc)[2][2][4][2], const Unit& u, int wr, int wc, int fr, int fq) const {
;     ...
;             for (int m = 0; m < 4; ++m) { u16* rowp = O + (size_t)(row0 + ai * HALF + m * 16) * ldc + hcol0;
; #pragma unroll
;                 for (int bj = 0; bj < 2; ++bj) { const f32x4 g = acc[ai][bj][m][0], up = acc[ai][bj][m][1]; float r[4];
; #pragma unroll
;                     for (int j = 0; j < 4; ++j) r[j] = g[j] * up[j] * __builtin_amdgcn_rcpf(1.f + ex2(-LOG2E * g[j]));
;                     uint2 w = {pack2(r[0], r[1]), pack2(r[2], r[3])}; *(uint2*)(rowp + bj * (HALF / 2)) = w; } }
; template <class Epi, class Sched, bool STAMP = false>
; __device__ __forceinline__ void gemm_phase(PG8_LAS unsigned char* lds, const Gemm g, const Sched& S, const Epi& E, unsigned long long* stamps) {
;     ...
;         if (!has_next) break;
; #pragma unroll
;         for (int a = 0; a < 2; ++a)
; #pragma unroll
;             for (int b = 0; b < 2; ++b)
; #pragma unroll
;                 for (int m = 0; m < 4; ++m)
; #pragma unroll
;                     for (int n = 0; n < 2; ++n) acc[a][b][m][n] = (f32x4){0.f, 0.f, 0.f, 0.f};
;         cur = nxt; cA = nA; cB = nB; ++ui;
	v_mul_f32_e32 v51, 0xbfb8aa3b, v45
	v_mul_f32_e32 v53, 0xbfb8aa3b, v47
	v_exp_f32_e32 v50, v50
	v_exp_f32_e32 v51, v51
	v_exp_f32_e32 v52, v52
	v_exp_f32_e32 v53, v53
	v_add_f32_e32 v50, 1.0, v50
	v_add_f32_e32 v51, 1.0, v51
	v_add_f32_e32 v52, 1.0, v52
	v_add_f32_e32 v53, 1.0, v53
	v_rcp_f32_e32 v50, v50
	v_rcp_f32_e32 v51, v51
	v_rcp_f32_e32 v52, v52
	v_rcp_f32_e32 v53, v53
	v_pk_mul_f32 v[42:43], v[46:47], v[42:43]
	v_pk_mul_f32 v[40:41], v[44:45], v[40:41]
	global_store_dwordx2 v[64:65], v[48:49], off offset:128
	v_pk_mul_f32 v[40:41], v[40:41], v[50:51]
	v_pk_mul_f32 v[42:43], v[42:43], v[52:53]
	v_cvt_pk_bf16_f32 v40, v40, v41
	v_cvt_pk_bf16_f32 v41, v42, v43
	v_mul_f32_e32 v42, 0xbfb8aa3b, v36
	v_mul_f32_e32 v43, 0xbfb8aa3b, v37
	v_exp_f32_e32 v42, v42
	v_exp_f32_e32 v43, v43
	v_add_u32_e32 v48, 0x90, v170
	v_mad_i64_i32 v[48:49], s[16:17], v48, s57, v[142:143]
	v_lshl_add_u64 v[48:49], v[48:49], 0, v[140:141]
	global_store_dwordx2 v[48:49], v[40:41], off
	v_add_f32_e32 v40, 1.0, v42
	v_add_f32_e32 v41, 1.0, v43
	v_mul_f32_e32 v42, 0xbfb8aa3b, v38
	v_mul_f32_e32 v43, 0xbfb8aa3b, v39
	v_exp_f32_e32 v42, v42
	v_exp_f32_e32 v43, v43
	v_rcp_f32_e32 v40, v40
	v_rcp_f32_e32 v41, v41
	v_add_f32_e32 v42, 1.0, v42
	v_add_f32_e32 v43, 1.0, v43
	v_rcp_f32_e32 v42, v42
	v_rcp_f32_e32 v43, v43
	v_pk_mul_f32 v[34:35], v[38:39], v[34:35]
	v_pk_mul_f32 v[32:33], v[36:37], v[32:33]
	v_mul_f32_e32 v36, 0xbfb8aa3b, v30
	v_pk_mul_f32 v[32:33], v[32:33], v[40:41]
	v_pk_mul_f32 v[34:35], v[34:35], v[42:43]
	v_cvt_pk_bf16_f32 v32, v32, v33
	v_cvt_pk_bf16_f32 v33, v34, v35
	v_mul_f32_e32 v34, 0xbfb8aa3b, v28
	v_mul_f32_e32 v35, 0xbfb8aa3b, v29
	v_mul_f32_e32 v37, 0xbfb8aa3b, v31
	v_exp_f32_e32 v34, v34
	v_exp_f32_e32 v35, v35
	v_exp_f32_e32 v36, v36
	v_exp_f32_e32 v37, v37
	v_add_f32_e32 v34, 1.0, v34
	v_add_f32_e32 v35, 1.0, v35
	v_add_f32_e32 v36, 1.0, v36
	v_add_f32_e32 v37, 1.0, v37
	v_rcp_f32_e32 v34, v34
	v_rcp_f32_e32 v35, v35
	v_rcp_f32_e32 v36, v36
	v_rcp_f32_e32 v37, v37
	v_pk_mul_f32 v[26:27], v[30:31], v[26:27]
	v_pk_mul_f32 v[24:25], v[28:29], v[24:25]
	global_store_dwordx2 v[48:49], v[32:33], off offset:128
	v_pk_mul_f32 v[24:25], v[24:25], v[34:35]
	v_pk_mul_f32 v[26:27], v[26:27], v[36:37]
	v_cvt_pk_bf16_f32 v24, v24, v25
	v_cvt_pk_bf16_f32 v25, v26, v27
	v_mul_f32_e32 v26, 0xbfb8aa3b, v20
	v_mul_f32_e32 v27, 0xbfb8aa3b, v21
	v_exp_f32_e32 v26, v26
	v_exp_f32_e32 v27, v27
	v_add_u32_e32 v32, 0xa0, v170
	v_mad_i64_i32 v[32:33], s[16:17], v32, s57, v[142:143]
	v_lshl_add_u64 v[32:33], v[32:33], 0, v[140:141]
	global_store_dwordx2 v[32:33], v[24:25], off
	v_add_f32_e32 v24, 1.0, v26
	v_add_f32_e32 v25, 1.0, v27
	v_mul_f32_e32 v26, 0xbfb8aa3b, v22
	v_mul_f32_e32 v27, 0xbfb8aa3b, v23
	v_exp_f32_e32 v26, v26
	v_exp_f32_e32 v27, v27
	v_rcp_f32_e32 v24, v24
	v_rcp_f32_e32 v25, v25
	v_add_f32_e32 v26, 1.0, v26
	v_add_f32_e32 v27, 1.0, v27
	v_rcp_f32_e32 v26, v26
	v_rcp_f32_e32 v27, v27
	v_pk_mul_f32 v[18:19], v[22:23], v[18:19]
	v_pk_mul_f32 v[16:17], v[20:21], v[16:17]
	v_mul_f32_e32 v20, 0xbfb8aa3b, v14
	v_pk_mul_f32 v[16:17], v[16:17], v[24:25]
	v_pk_mul_f32 v[18:19], v[18:19], v[26:27]
	v_cvt_pk_bf16_f32 v16, v16, v17
	v_cvt_pk_bf16_f32 v17, v18, v19
	v_mul_f32_e32 v18, 0xbfb8aa3b, v12
	v_mul_f32_e32 v19, 0xbfb8aa3b, v13
	v_mul_f32_e32 v21, 0xbfb8aa3b, v15
	v_exp_f32_e32 v18, v18
	v_exp_f32_e32 v19, v19
	v_exp_f32_e32 v20, v20
	v_exp_f32_e32 v21, v21
	v_add_f32_e32 v18, 1.0, v18
	v_add_f32_e32 v19, 1.0, v19
	v_add_f32_e32 v20, 1.0, v20
	v_add_f32_e32 v21, 1.0, v21
	v_rcp_f32_e32 v18, v18
	v_rcp_f32_e32 v19, v19
	v_rcp_f32_e32 v20, v20
	v_rcp_f32_e32 v21, v21
	v_pk_mul_f32 v[10:11], v[14:15], v[10:11]
	v_pk_mul_f32 v[8:9], v[12:13], v[8:9]
	global_store_dwordx2 v[32:33], v[16:17], off offset:128
	v_pk_mul_f32 v[8:9], v[8:9], v[18:19]
	v_pk_mul_f32 v[10:11], v[10:11], v[20:21]
	v_cvt_pk_bf16_f32 v8, v8, v9
	v_cvt_pk_bf16_f32 v9, v10, v11
	v_mul_f32_e32 v10, 0xbfb8aa3b, v4
	v_mul_f32_e32 v11, 0xbfb8aa3b, v5
	v_exp_f32_e32 v10, v10
	v_exp_f32_e32 v11, v11
	v_add_u32_e32 v16, 0xb0, v170
	v_mad_i64_i32 v[16:17], s[16:17], v16, s57, v[142:143]
	v_lshl_add_u64 v[16:17], v[16:17], 0, v[140:141]
	global_store_dwordx2 v[16:17], v[8:9], off
	v_add_f32_e32 v8, 1.0, v10
	v_add_f32_e32 v9, 1.0, v11
	v_mul_f32_e32 v10, 0xbfb8aa3b, v6
	v_mul_f32_e32 v11, 0xbfb8aa3b, v7
	v_exp_f32_e32 v10, v10
	v_exp_f32_e32 v11, v11
	v_rcp_f32_e32 v8, v8
	v_rcp_f32_e32 v9, v9
	v_add_f32_e32 v10, 1.0, v10
	v_add_f32_e32 v11, 1.0, v11
	v_rcp_f32_e32 v10, v10
	v_rcp_f32_e32 v11, v11
	v_pk_mul_f32 v[2:3], v[6:7], v[2:3]
	v_pk_mul_f32 v[0:1], v[4:5], v[0:1]
	s_and_b64 vcc, exec, s[2:3]
	v_pk_mul_f32 v[0:1], v[0:1], v[8:9]
	v_pk_mul_f32 v[2:3], v[2:3], v[10:11]
	v_cvt_pk_bf16_f32 v0, v0, v1
	v_cvt_pk_bf16_f32 v1, v2, v3
	s_mov_b32 s61, s58
	s_mov_b32 s60, s59
	s_mov_b64 s[18:19], s[0:1]
	s_mov_b64 s[16:17], s[4:5]
	global_store_dwordx2 v[16:17], v[0:1], off offset:128
	s_cbranch_vccz .LBB0_720
	s_branch .Lgu4_done
; #define PG8_STAGE(bufoff, gbase, voff) do { _Pragma("unroll") for (int _i = 0; _i < 2; ++_i) \
;         __builtin_amdgcn_global_load_lds((const unsigned*)((const char*)(gbase) + (voff)[_i]), (PG8_LAS unsigned*)(lds + (bufoff) + ldsw + _i * 8192), 16, 0, 0); } while (0)
; #define PG8_LDA(dst, b, h) do { _Pragma("unroll") for (int m = 0; m < 4; ++m) _Pragma("unroll") for (int k = 0; k < 2; ++k) dst[m][k] = *(const PG8_LAS bf16x8*)(lds + PG8_SA(b, h) + aoff + m * 2048 + k * 1024); } while (0)
; #define PG8_WAIT_V(n) asm volatile("s_waitcnt vmcnt(" #n ")" ::: "memory")
; #define PG8_WAIT_L(n) asm volatile("s_waitcnt lgkmcnt(" #n ")" ::: "memory")
; #define PG8_BAR __builtin_amdgcn_s_barrier()
; template <class Epi, class Sched, bool STAMP = false>
; __device__ __forceinline__ void gemm_phase(PG8_LAS unsigned char* lds, const Gemm g, const Sched& S, const Epi& E, unsigned long long* stamps) {
;     ...
;             const bool last = (t == nt - 2);
;             const char* a1 = cA + (size_t)(t + 1) * kstep;
;             const char* a2 = last ? nA : cA + (size_t)(t + 2) * kstep; const char* b2 = last ? nB : cB + (size_t)(t + 2) * kstep;
;             const char* a3 = a2 + kstep; const char* b3 = b2 + kstep;
;             if (last && has_next) S.a_ready(nxt);
;             PG8_LDB(B0, 0, 0); PG8_SCHED; PG8_LDA(At, 0, 0); PG8_STAGE(PG8_SA(1, 1), a1 + hstep, voffA);
;             PG8_WAIT_L(8); PG8_BAR; PG8_WAIT_L(0); PG8_MMA(0, 0, At, B0); PG8_BAR; PG8_SCHED;
;             PG8_LDB(B1, 0, 1); PG8_STAGE(PG8_SB(0, 0), b2, voffB);
;             PG8_BAR; PG8_WAIT_L(0); PG8_MMA(0, 1, At, B1); PG8_BAR;
;             PG8_LDA(At, 0, 1); PG8_STAGE(PG8_SA(0, 0), a2, voffA);
;             PG8_BAR; PG8_WAIT_L(0); PG8_MMA(1, 0, At, B0); PG8_BAR; PG8_SCHED;
;             PG8_STAGE(PG8_SB(0, 1), b2 + hstep, voffB);
;             PG8_WAIT_V(6); PG8_BAR; PG8_MMA(1, 1, At, B1); PG8_BAR;
;             PG8_LDB(B0, 1, 0); PG8_SCHED; PG8_LDA(At, 1, 0); PG8_STAGE(PG8_SA(0, 1), a2 + hstep, voffA);
;             PG8_WAIT_L(8); PG8_BAR; PG8_WAIT_L(0); PG8_MMA(0, 0, At, B0); PG8_BAR; PG8_SCHED;
;             PG8_LDB(B1, 1, 1); PG8_STAGE(PG8_SB(1, 0), b3, voffB);
;             PG8_BAR; PG8_WAIT_L(0); PG8_MMA(0, 1, At, B1); PG8_BAR;
;             PG8_LDA(At, 1, 1); PG8_STAGE(PG8_SA(1, 0), a3, voffA);
;             PG8_BAR; PG8_WAIT_L(0); PG8_MMA(1, 0, At, B0); PG8_BAR; PG8_SCHED;
.Lgu4_half_loop:
	ds_read_b128 v[140:143], v147
	ds_read_b128 v[170:173], v148
	ds_read_b128 v[174:177], v149
	ds_read_b128 v[178:181], v150
	s_add_u32 s18, s16, 0x100
	s_addc_u32 s19, s17, 0
	s_cmp_eq_u32 s10, 12
	s_cselect_b32 s29, s5, s19
	s_cselect_b32 s28, s4, s18
	s_cselect_b32 s21, s1, s63
	s_cselect_b32 s20, s0, s62
	s_mov_b32 m0, s55
	ds_read_b128 v[182:185], v145
	ds_read_b128 v[186:189], v145 offset:1024
	ds_read_b128 v[190:193], v145 offset:2048
	ds_read_b128 v[194:197], v145 offset:3072
	ds_read_b128 v[198:201], v145 offset:4096
	ds_read_b128 v[202:205], v145 offset:5120
	ds_read_b128 v[206:209], v145 offset:6144
	ds_read_b128 v[210:213], v145 offset:7168
	global_load_lds_dwordx4 v132, s[16:17]
	s_mov_b32 m0, s56
	s_nop 0
	global_load_lds_dwordx4 v134, s[16:17]
	s_waitcnt lgkmcnt(8)
	s_barrier
	s_waitcnt lgkmcnt(0)
	s_setprio 1
	s_waitcnt lgkmcnt(0)
	v_mfma_f32_16x16x32_bf16 v[124:127], v[140:143], v[182:185], v[124:127]
	v_mfma_f32_16x16x32_bf16 v[120:123], v[174:177], v[182:185], v[120:123]
	v_mfma_f32_16x16x32_bf16 v[108:111], v[140:143], v[190:193], v[108:111]
	v_mfma_f32_16x16x32_bf16 v[104:107], v[174:177], v[190:193], v[104:107]
	v_mfma_f32_16x16x32_bf16 v[92:95], v[140:143], v[198:201], v[92:95]
	v_mfma_f32_16x16x32_bf16 v[88:91], v[174:177], v[198:201], v[88:91]
	v_mfma_f32_16x16x32_bf16 v[76:79], v[140:143], v[206:209], v[76:79]
	v_mfma_f32_16x16x32_bf16 v[72:75], v[174:177], v[206:209], v[72:75]
	v_mfma_f32_16x16x32_bf16 v[124:127], v[170:173], v[186:189], v[124:127]
	v_mfma_f32_16x16x32_bf16 v[120:123], v[178:181], v[186:189], v[120:123]
	v_mfma_f32_16x16x32_bf16 v[108:111], v[170:173], v[194:197], v[108:111]
	v_mfma_f32_16x16x32_bf16 v[104:107], v[178:181], v[194:197], v[104:107]
	v_mfma_f32_16x16x32_bf16 v[92:95], v[170:173], v[202:205], v[92:95]
	v_mfma_f32_16x16x32_bf16 v[88:91], v[178:181], v[202:205], v[88:91]
	v_mfma_f32_16x16x32_bf16 v[76:79], v[170:173], v[210:213], v[76:79]
	v_mfma_f32_16x16x32_bf16 v[72:75], v[178:181], v[210:213], v[72:75]
	s_setprio 0
	s_barrier
	s_mov_b32 m0, s37
	s_nop 0
	global_load_lds_dwordx4 v130, s[20:21]
	s_mov_b32 m0, s40
	s_nop 0
	global_load_lds_dwordx4 v128, s[20:21]
	s_barrier
	s_waitcnt lgkmcnt(0)
	s_setprio 1
	s_waitcnt lgkmcnt(0)
	s_setprio 0
	s_mov_b32 m0, s34
	s_barrier
	ds_read_b128 v[182:185], v145 offset:16384
	ds_read_b128 v[186:189], v145 offset:17408
	ds_read_b128 v[190:193], v145 offset:18432
	ds_read_b128 v[194:197], v145 offset:19456
	ds_read_b128 v[198:201], v145 offset:20480
	ds_read_b128 v[202:205], v145 offset:21504
	ds_read_b128 v[206:209], v145 offset:22528
	ds_read_b128 v[210:213], v145 offset:23552
	global_load_lds_dwordx4 v130, s[28:29]
	s_mov_b32 m0, s41
	s_nop 0
	global_load_lds_dwordx4 v128, s[28:29]
	s_barrier
	s_waitcnt lgkmcnt(0)
	s_setprio 1
	s_waitcnt lgkmcnt(0)
	v_mfma_f32_16x16x32_bf16 v[60:63], v[140:143], v[182:185], v[60:63]
	v_mfma_f32_16x16x32_bf16 v[56:59], v[174:177], v[182:185], v[56:59]
	v_mfma_f32_16x16x32_bf16 v[44:47], v[140:143], v[190:193], v[44:47]
	v_mfma_f32_16x16x32_bf16 v[40:43], v[174:177], v[190:193], v[40:43]
	v_mfma_f32_16x16x32_bf16 v[28:31], v[140:143], v[198:201], v[28:31]
	v_mfma_f32_16x16x32_bf16 v[24:27], v[174:177], v[198:201], v[24:27]
	v_mfma_f32_16x16x32_bf16 v[12:15], v[140:143], v[206:209], v[12:15]
	v_mfma_f32_16x16x32_bf16 v[8:11], v[174:177], v[206:209], v[8:11]
	v_mfma_f32_16x16x32_bf16 v[60:63], v[170:173], v[186:189], v[60:63]
	v_mfma_f32_16x16x32_bf16 v[56:59], v[178:181], v[186:189], v[56:59]
	v_mfma_f32_16x16x32_bf16 v[44:47], v[170:173], v[194:197], v[44:47]
	v_mfma_f32_16x16x32_bf16 v[40:43], v[178:181], v[194:197], v[40:43]
	v_mfma_f32_16x16x32_bf16 v[28:31], v[170:173], v[202:205], v[28:31]
	v_mfma_f32_16x16x32_bf16 v[24:27], v[178:181], v[202:205], v[24:27]
	v_mfma_f32_16x16x32_bf16 v[12:15], v[170:173], v[210:213], v[12:15]
	v_mfma_f32_16x16x32_bf16 v[8:11], v[178:181], v[210:213], v[8:11]
	s_setprio 0
	s_barrier
	s_add_u32 s16, s20, 0x44000
	s_addc_u32 s17, s21, 0
	s_mov_b32 m0, s42
	s_nop 0
	global_load_lds_dwordx4 v130, s[16:17]
	s_mov_b32 m0, s43
	s_nop 0
	global_load_lds_dwordx4 v128, s[16:17]
	s_waitcnt vmcnt(6)
	s_barrier
	s_setprio 1
	s_setprio 0
	s_barrier
	ds_read_b128 v[140:143], v155
	ds_read_b128 v[170:173], v156
	ds_read_b128 v[174:177], v157
	ds_read_b128 v[178:181], v165
	s_add_u32 s16, s28, 0x44000
	s_addc_u32 s17, s29, 0
	s_mov_b32 m0, s44
	ds_read_b128 v[182:185], v145 offset:32768
	ds_read_b128 v[186:189], v145 offset:33792
	ds_read_b128 v[190:193], v145 offset:34816
	ds_read_b128 v[194:197], v145 offset:35840
	ds_read_b128 v[198:201], v145 offset:36864
	ds_read_b128 v[202:205], v145 offset:37888
	ds_read_b128 v[206:209], v145 offset:38912
	ds_read_b128 v[210:213], v145 offset:39936
	global_load_lds_dwordx4 v130, s[16:17]
	s_mov_b32 m0, s45
	s_nop 0
	global_load_lds_dwordx4 v128, s[16:17]
	s_waitcnt lgkmcnt(8)
	s_barrier
	s_waitcnt lgkmcnt(0)
	s_setprio 1
	s_waitcnt lgkmcnt(0)
	v_mfma_f32_16x16x32_bf16 v[124:127], v[140:143], v[182:185], v[124:127]
	v_mfma_f32_16x16x32_bf16 v[120:123], v[174:177], v[182:185], v[120:123]
	v_mfma_f32_16x16x32_bf16 v[108:111], v[140:143], v[190:193], v[108:111]
	v_mfma_f32_16x16x32_bf16 v[104:107], v[174:177], v[190:193], v[104:107]
	v_mfma_f32_16x16x32_bf16 v[92:95], v[140:143], v[198:201], v[92:95]
	v_mfma_f32_16x16x32_bf16 v[88:91], v[174:177], v[198:201], v[88:91]
	v_mfma_f32_16x16x32_bf16 v[76:79], v[140:143], v[206:209], v[76:79]
	v_mfma_f32_16x16x32_bf16 v[72:75], v[174:177], v[206:209], v[72:75]
	v_mfma_f32_16x16x32_bf16 v[124:127], v[170:173], v[186:189], v[124:127]
	v_mfma_f32_16x16x32_bf16 v[120:123], v[178:181], v[186:189], v[120:123]
	v_mfma_f32_16x16x32_bf16 v[108:111], v[170:173], v[194:197], v[108:111]
	v_mfma_f32_16x16x32_bf16 v[104:107], v[178:181], v[194:197], v[104:107]
	v_mfma_f32_16x16x32_bf16 v[92:95], v[170:173], v[202:205], v[92:95]
	v_mfma_f32_16x16x32_bf16 v[88:91], v[178:181], v[202:205], v[88:91]
	v_mfma_f32_16x16x32_bf16 v[76:79], v[170:173], v[210:213], v[76:79]
	v_mfma_f32_16x16x32_bf16 v[72:75], v[178:181], v[210:213], v[72:75]
	s_setprio 0
	s_barrier
; DI float ex2(float x) { return __builtin_amdgcn_exp2f(x); }
; #define PG8_STAGE(bufoff, gbase, voff) do { _Pragma("unroll") for (int _i = 0; _i < 2; ++_i) \
;         __builtin_amdgcn_global_load_lds((const unsigned*)((const char*)(gbase) + (voff)[_i]), (PG8_LAS unsigned*)(lds + (bufoff) + ldsw + _i * 8192), 16, 0, 0); } while (0)
; #define PG8_MMA(ai, bj, At, Bt) do { __builtin_amdgcn_s_setprio(1); _Pragma("unroll") for (int m = 0; m < 4; ++m) _Pragma("unroll") for (int n = 0; n < 2; ++n) _Pragma("unroll") for (int k = 0; k < 2; ++k) \
;         acc[ai][bj][m][n] = __builtin_amdgcn_mfma_f32_16x16x32_bf16(Bt[n][k], At[m][k], acc[ai][bj][m][n], 0, 0, 0); __builtin_amdgcn_s_setprio(0); } while (0)
; #define PG8_WAIT_V(n) asm volatile("s_waitcnt vmcnt(" #n ")" ::: "memory")
; #define PG8_WAIT_L(n) asm volatile("s_waitcnt lgkmcnt(" #n ")" ::: "memory")
; #define PG8_BAR __builtin_amdgcn_s_barrier()
; #define PG8_SCHED __builtin_amdgcn_sched_barrier(0)
;     DI void operator()(const f32x4 (&acc)[2][2][4][2], const Unit& u, int wr, int wc, int fr, int fq) const {
;         const int row0 = u.pm * BM + wr * 64 + fr, hcol0 = ((u.pn * BM + wc * 32) >> 1) + 4 * fq;
; #pragma unroll
;         for (int ai = 0; ai < 2; ++ai)
; #pragma unroll
;             for (int m = 0; m < 4; ++m) { u16* rowp = O + (size_t)(row0 + ai * HALF + m * 16) * ldc + hcol0;
; #pragma unroll
;                 for (int bj = 0; bj < 2; ++bj) { const f32x4 g = acc[ai][bj][m][0], up = acc[ai][bj][m][1]; float r[4];
; #pragma unroll
;                     for (int j = 0; j < 4; ++j) r[j] = g[j] * up[j] * __builtin_amdgcn_rcpf(1.f + ex2(-LOG2E * g[j]));
;                     uint2 w = {pack2(r[0], r[1]), pack2(r[2], r[3])}; *(uint2*)(rowp + bj * (HALF / 2)) = w; } }
; template <class Epi, class Sched, bool STAMP = false>
; __device__ __forceinline__ void gemm_phase(PG8_LAS unsigned char* lds, const Gemm g, const Sched& S, const Epi& E, unsigned long long* stamps) {
;     ...
;             PG8_BAR; PG8_WAIT_L(0); PG8_MMA(1, 0, At, B0); PG8_BAR; PG8_SCHED;
;             PG8_STAGE(PG8_SB(1, 1), b3 + hstep, voffB);
;             PG8_WAIT_V(6); PG8_BAR; PG8_MMA(1, 1, At, B1); PG8_BAR;
	s_mov_b32 m0, s48
	s_add_u32 s100, s20, 0x80
	s_addc_u32 s101, s21, 0
	global_load_lds_dwordx4 v130, s[100:101]
	s_mov_b32 m0, s49
	s_nop 0
	global_load_lds_dwordx4 v128, s[100:101]
	s_barrier
	s_waitcnt lgkmcnt(0)
	s_setprio 1
	s_waitcnt lgkmcnt(0)
	s_setprio 0
	s_mov_b32 m0, s50
	s_barrier
	ds_read_b128 v[182:185], v145 offset:49152
	ds_read_b128 v[186:189], v145 offset:50176
	ds_read_b128 v[190:193], v145 offset:51200
	ds_read_b128 v[194:197], v145 offset:52224
	ds_read_b128 v[198:201], v145 offset:53248
	ds_read_b128 v[202:205], v145 offset:54272
	ds_read_b128 v[206:209], v145 offset:55296
	ds_read_b128 v[210:213], v145 offset:56320
	s_add_u32 s100, s28, 0x80
	s_addc_u32 s101, s29, 0
	global_load_lds_dwordx4 v130, s[100:101]
	s_mov_b32 m0, s51
	s_nop 0
	global_load_lds_dwordx4 v128, s[100:101]
	s_barrier
	s_waitcnt lgkmcnt(0)
	s_setprio 1
	s_waitcnt lgkmcnt(0)
	v_mfma_f32_16x16x32_bf16 v[60:63], v[140:143], v[182:185], v[60:63]
	v_mfma_f32_16x16x32_bf16 v[56:59], v[174:177], v[182:185], v[56:59]
	v_mfma_f32_16x16x32_bf16 v[44:47], v[140:143], v[190:193], v[44:47]
	v_mfma_f32_16x16x32_bf16 v[40:43], v[174:177], v[190:193], v[40:43]
	v_mfma_f32_16x16x32_bf16 v[28:31], v[140:143], v[198:201], v[28:31]
	v_mfma_f32_16x16x32_bf16 v[24:27], v[174:177], v[198:201], v[24:27]
	v_mfma_f32_16x16x32_bf16 v[12:15], v[140:143], v[206:209], v[12:15]
	v_mfma_f32_16x16x32_bf16 v[8:11], v[174:177], v[206:209], v[8:11]
	v_mfma_f32_16x16x32_bf16 v[60:63], v[170:173], v[186:189], v[60:63]
	v_mfma_f32_16x16x32_bf16 v[56:59], v[178:181], v[186:189], v[56:59]
	v_mfma_f32_16x16x32_bf16 v[44:47], v[170:173], v[194:197], v[44:47]
	v_mfma_f32_16x16x32_bf16 v[40:43], v[178:181], v[194:197], v[40:43]
	v_mfma_f32_16x16x32_bf16 v[28:31], v[170:173], v[202:205], v[28:31]
	v_mfma_f32_16x16x32_bf16 v[24:27], v[178:181], v[202:205], v[24:27]
	v_mfma_f32_16x16x32_bf16 v[12:15], v[170:173], v[210:213], v[12:15]
	v_mfma_f32_16x16x32_bf16 v[8:11], v[178:181], v[210:213], v[8:11]
	s_setprio 0
	s_barrier
	s_add_u32 s16, s20, 0x44080
	s_addc_u32 s17, s21, 0
	s_mov_b32 m0, s52
	s_nop 0
	global_load_lds_dwordx4 v130, s[16:17]
	s_mov_b32 m0, s53
	s_nop 0
	global_load_lds_dwordx4 v128, s[16:17]
	s_waitcnt vmcnt(6)
	s_barrier
	s_setprio 1
	s_setprio 0
	s_add_i32 s10, s10, 2
	s_add_u32 s62, s62, 0x100
	s_addc_u32 s63, s63, 0
	s_cmp_gt_u32 s10, 13
	s_mov_b64 s[16:17], s[18:19]
	s_barrier
	s_cbranch_scc0 .Lgu4_half_loop
	v_mul_f32_e32 v171, 0xbfb8aa3b, v124
	v_exp_f32_e32 v171, v171
	v_mul_f32_e32 v174, 0xbfb8aa3b, v125
	v_exp_f32_e32 v175, v174
	s_lshl_b32 s10, s61, 8
	v_add_f32_e32 v171, 1.0, v171
	v_rcp_f32_e32 v174, v171
	v_add_f32_e32 v171, 1.0, v175
	v_mul_f32_e32 v175, 0xbfb8aa3b, v126
	v_exp_f32_e32 v176, v175
	v_mul_f32_e32 v175, 0xbfb8aa3b, v127
	v_exp_f32_e32 v177, v175
	v_rcp_f32_e32 v175, v171
	v_add_f32_e32 v171, 1.0, v176
	v_rcp_f32_e32 v176, v171
	v_add_f32_e32 v171, 1.0, v177
	v_rcp_f32_e32 v177, v171
	v_pk_mul_f32 v[122:123], v[126:127], v[122:123]
	v_pk_mul_f32 v[120:121], v[124:125], v[120:121]
	s_or_b32 s10, s10, s47
	s_or_b32 s10, s10, s98
	v_pk_mul_f32 v[120:121], v[120:121], v[174:175]
	v_pk_mul_f32 v[122:123], v[122:123], v[176:177]
	s_ashr_i32 s10, s10, 1
	v_cvt_pk_bf16_f32 v120, v120, v121
	v_cvt_pk_bf16_f32 v121, v122, v123
	v_or_b32_e32 v140, s10, v146
	v_lshl_add_u32 v170, s60, 8, v144
	v_ashrrev_i32_e32 v141, 31, v140
	v_mov_b64_e32 v[142:143], s[12:13]
	v_mad_i64_i32 v[172:173], s[16:17], v170, s57, v[142:143]
	v_lshlrev_b64 v[140:141], 1, v[140:141]
	v_lshl_add_u64 v[172:173], v[172:173], 0, v[140:141]
	global_store_dwordx2 v[172:173], v[120:121], off
	v_mul_f32_e32 v116, 0xbfb8aa3b, v110
	v_mul_f32_e32 v114, 0xbfb8aa3b, v108
	v_mul_f32_e32 v115, 0xbfb8aa3b, v109
	v_mul_f32_e32 v117, 0xbfb8aa3b, v111
	v_exp_f32_e32 v114, v114
	v_exp_f32_e32 v115, v115
	v_exp_f32_e32 v116, v116
	v_exp_f32_e32 v117, v117
	v_add_f32_e32 v114, 1.0, v114
	v_add_f32_e32 v115, 1.0, v115
	v_add_f32_e32 v116, 1.0, v116
	v_add_f32_e32 v117, 1.0, v117
	v_rcp_f32_e32 v114, v114
	v_rcp_f32_e32 v115, v115
	v_rcp_f32_e32 v116, v116
	v_rcp_f32_e32 v117, v117
	v_pk_mul_f32 v[106:107], v[110:111], v[106:107]
	v_pk_mul_f32 v[104:105], v[108:109], v[104:105]
	v_pk_mul_f32 v[104:105], v[104:105], v[114:115]
	v_pk_mul_f32 v[106:107], v[106:107], v[116:117]
	v_cvt_pk_bf16_f32 v104, v104, v105
	v_cvt_pk_bf16_f32 v105, v106, v107
	v_or_b32_e32 v112, 16, v170
	v_mad_i64_i32 v[112:113], s[16:17], v112, s57, v[142:143]
	v_lshl_add_u64 v[112:113], v[112:113], 0, v[140:141]
	global_store_dwordx2 v[112:113], v[104:105], off
	v_mul_f32_e32 v100, 0xbfb8aa3b, v94
	v_mul_f32_e32 v98, 0xbfb8aa3b, v92
	v_mul_f32_e32 v99, 0xbfb8aa3b, v93
	v_mul_f32_e32 v101, 0xbfb8aa3b, v95
	v_exp_f32_e32 v98, v98
	v_exp_f32_e32 v99, v99
	v_exp_f32_e32 v100, v100
	v_exp_f32_e32 v101, v101
	v_add_f32_e32 v98, 1.0, v98
	v_add_f32_e32 v99, 1.0, v99
	v_add_f32_e32 v100, 1.0, v100
	v_add_f32_e32 v101, 1.0, v101
	v_rcp_f32_e32 v98, v98
	v_rcp_f32_e32 v99, v99
; DI float ex2(float x) { return __builtin_amdgcn_exp2f(x); }
;     DI void operator()(const f32x4 (&acc)[2][2][4][2], const Unit& u, int wr, int wc, int fr, int fq) const {
;         const int row0 = u.pm * BM + wr * 64 + fr, hcol0 = ((u.pn * BM + wc * 32) >> 1) + 4 * fq;
; #pragma unroll
;         for (int ai = 0; ai < 2; ++ai)
; #pragma unroll
;             for (int m = 0; m < 4; ++m) { u16* rowp = O + (size_t)(row0 + ai * HALF + m * 16) * ldc + hcol0;
; #pragma unroll
;                 for (int bj = 0; bj < 2; ++bj) { const f32x4 g = acc[ai][bj][m][0], up = acc[ai][bj][m][1]; float r[4];
; #pragma unroll
;                     for (int j = 0; j < 4; ++j) r[j] = g[j] * up[j] * __builtin_amdgcn_rcpf(1.f + ex2(-LOG2E * g[j]));
;                     uint2 w = {pack2(r[0], r[1]), pack2(r[2], r[3])}; *(uint2*)(rowp + bj * (HALF / 2)) = w; } }
	v_rcp_f32_e32 v100, v100
	v_rcp_f32_e32 v101, v101
	v_pk_mul_f32 v[90:91], v[94:95], v[90:91]
	v_pk_mul_f32 v[88:89], v[92:93], v[88:89]
	v_pk_mul_f32 v[88:89], v[88:89], v[98:99]
	v_pk_mul_f32 v[90:91], v[90:91], v[100:101]
	v_cvt_pk_bf16_f32 v88, v88, v89
	v_cvt_pk_bf16_f32 v89, v90, v91
	v_or_b32_e32 v96, 32, v170
	v_mad_i64_i32 v[96:97], s[16:17], v96, s57, v[142:143]
	v_lshl_add_u64 v[96:97], v[96:97], 0, v[140:141]
	global_store_dwordx2 v[96:97], v[88:89], off
	v_mul_f32_e32 v84, 0xbfb8aa3b, v78
	v_mul_f32_e32 v82, 0xbfb8aa3b, v76
	v_mul_f32_e32 v83, 0xbfb8aa3b, v77
	v_mul_f32_e32 v85, 0xbfb8aa3b, v79
	v_exp_f32_e32 v82, v82
	v_exp_f32_e32 v83, v83
	v_exp_f32_e32 v84, v84
	v_exp_f32_e32 v85, v85
	v_add_f32_e32 v82, 1.0, v82
	v_add_f32_e32 v83, 1.0, v83
	v_add_f32_e32 v84, 1.0, v84
	v_add_f32_e32 v85, 1.0, v85
	v_rcp_f32_e32 v82, v82
	v_rcp_f32_e32 v83, v83
	v_rcp_f32_e32 v84, v84
	v_rcp_f32_e32 v85, v85
	v_pk_mul_f32 v[74:75], v[78:79], v[74:75]
	v_pk_mul_f32 v[72:73], v[76:77], v[72:73]
	v_pk_mul_f32 v[72:73], v[72:73], v[82:83]
	v_pk_mul_f32 v[74:75], v[74:75], v[84:85]
	v_cvt_pk_bf16_f32 v72, v72, v73
	v_cvt_pk_bf16_f32 v73, v74, v75
	v_or_b32_e32 v80, 48, v170
	v_mad_i64_i32 v[80:81], s[16:17], v80, s57, v[142:143]
	v_lshl_add_u64 v[80:81], v[80:81], 0, v[140:141]
	global_store_dwordx2 v[80:81], v[72:73], off
	v_mul_f32_e32 v68, 0xbfb8aa3b, v62
	v_mul_f32_e32 v66, 0xbfb8aa3b, v60
	v_mul_f32_e32 v67, 0xbfb8aa3b, v61
	v_mul_f32_e32 v69, 0xbfb8aa3b, v63
	v_exp_f32_e32 v66, v66
	v_exp_f32_e32 v67, v67
	v_exp_f32_e32 v68, v68
	v_exp_f32_e32 v69, v69
	v_add_f32_e32 v66, 1.0, v66
	v_add_f32_e32 v67, 1.0, v67
	v_add_f32_e32 v68, 1.0, v68
	v_add_f32_e32 v69, 1.0, v69
	v_rcp_f32_e32 v66, v66
	v_rcp_f32_e32 v67, v67
	v_rcp_f32_e32 v68, v68
	v_rcp_f32_e32 v69, v69
	v_pk_mul_f32 v[58:59], v[62:63], v[58:59]
	v_pk_mul_f32 v[56:57], v[60:61], v[56:57]
	v_pk_mul_f32 v[56:57], v[56:57], v[66:67]
	v_pk_mul_f32 v[58:59], v[58:59], v[68:69]
	v_cvt_pk_bf16_f32 v56, v56, v57
	v_cvt_pk_bf16_f32 v57, v58, v59
	v_add_u32_e32 v64, 0x80, v170
	v_mad_i64_i32 v[64:65], s[16:17], v64, s57, v[142:143]
	v_lshl_add_u64 v[64:65], v[64:65], 0, v[140:141]
	global_store_dwordx2 v[64:65], v[56:57], off
	v_mul_f32_e32 v52, 0xbfb8aa3b, v46
	v_mul_f32_e32 v50, 0xbfb8aa3b, v44
	v_mul_f32_e32 v51, 0xbfb8aa3b, v45
	v_mul_f32_e32 v53, 0xbfb8aa3b, v47
	v_exp_f32_e32 v50, v50
	v_exp_f32_e32 v51, v51
	v_exp_f32_e32 v52, v52
	v_exp_f32_e32 v53, v53
	v_add_f32_e32 v50, 1.0, v50
	v_add_f32_e32 v51, 1.0, v51
	v_add_f32_e32 v52, 1.0, v52
	v_add_f32_e32 v53, 1.0, v53
	v_rcp_f32_e32 v50, v50
	v_rcp_f32_e32 v51, v51
	v_rcp_f32_e32 v52, v52
	v_rcp_f32_e32 v53, v53
	v_pk_mul_f32 v[42:43], v[46:47], v[42:43]
	v_pk_mul_f32 v[40:41], v[44:45], v[40:41]
	v_pk_mul_f32 v[40:41], v[40:41], v[50:51]
	v_pk_mul_f32 v[42:43], v[42:43], v[52:53]
	v_cvt_pk_bf16_f32 v40, v40, v41
	v_cvt_pk_bf16_f32 v41, v42, v43
	v_add_u32_e32 v48, 0x90, v170
	v_mad_i64_i32 v[48:49], s[16:17], v48, s57, v[142:143]
	v_lshl_add_u64 v[48:49], v[48:49], 0, v[140:141]
	global_store_dwordx2 v[48:49], v[40:41], off
	v_mul_f32_e32 v36, 0xbfb8aa3b, v30
	v_mul_f32_e32 v34, 0xbfb8aa3b, v28
	v_mul_f32_e32 v35, 0xbfb8aa3b, v29
	v_mul_f32_e32 v37, 0xbfb8aa3b, v31
	v_exp_f32_e32 v34, v34
	v_exp_f32_e32 v35, v35
	v_exp_f32_e32 v36, v36
	v_exp_f32_e32 v37, v37
	v_add_f32_e32 v34, 1.0, v34
	v_add_f32_e32 v35, 1.0, v35
	v_add_f32_e32 v36, 1.0, v36
	v_add_f32_e32 v37, 1.0, v37
	v_rcp_f32_e32 v34, v34
	v_rcp_f32_e32 v35, v35
	v_rcp_f32_e32 v36, v36
	v_rcp_f32_e32 v37, v37
	v_pk_mul_f32 v[26:27], v[30:31], v[26:27]
	v_pk_mul_f32 v[24:25], v[28:29], v[24:25]
	v_pk_mul_f32 v[24:25], v[24:25], v[34:35]
	v_pk_mul_f32 v[26:27], v[26:27], v[36:37]
	v_cvt_pk_bf16_f32 v24, v24, v25
	v_cvt_pk_bf16_f32 v25, v26, v27
	v_add_u32_e32 v32, 0xa0, v170
	v_mad_i64_i32 v[32:33], s[16:17], v32, s57, v[142:143]
	v_lshl_add_u64 v[32:33], v[32:33], 0, v[140:141]
	global_store_dwordx2 v[32:33], v[24:25], off
	v_mul_f32_e32 v20, 0xbfb8aa3b, v14
	v_mul_f32_e32 v18, 0xbfb8aa3b, v12
	v_mul_f32_e32 v19, 0xbfb8aa3b, v13
	v_mul_f32_e32 v21, 0xbfb8aa3b, v15
	v_exp_f32_e32 v18, v18
	v_exp_f32_e32 v19, v19
	v_exp_f32_e32 v20, v20
	v_exp_f32_e32 v21, v21
	v_add_f32_e32 v18, 1.0, v18
	v_add_f32_e32 v19, 1.0, v19
	v_add_f32_e32 v20, 1.0, v20
	v_add_f32_e32 v21, 1.0, v21
	v_rcp_f32_e32 v18, v18
	v_rcp_f32_e32 v19, v19
	v_rcp_f32_e32 v20, v20
	v_rcp_f32_e32 v21, v21
	v_pk_mul_f32 v[10:11], v[14:15], v[10:11]
	v_pk_mul_f32 v[8:9], v[12:13], v[8:9]
	v_pk_mul_f32 v[8:9], v[8:9], v[18:19]
	v_pk_mul_f32 v[10:11], v[10:11], v[20:21]
	v_cvt_pk_bf16_f32 v8, v8, v9
	v_cvt_pk_bf16_f32 v9, v10, v11
	v_add_u32_e32 v16, 0xb0, v170
	v_mad_i64_i32 v[16:17], s[16:17], v16, s57, v[142:143]
	v_lshl_add_u64 v[16:17], v[16:17], 0, v[140:141]
	global_store_dwordx2 v[16:17], v[8:9], off
	s_and_b64 vcc, exec, s[2:3]
	s_mov_b32 s61, s58
	s_mov_b32 s60, s59
	s_mov_b64 s[18:19], s[0:1]
	s_mov_b64 s[16:17], s[4:5]

; #define PG8_STAGE(bufoff, gbase, voff) do { _Pragma("unroll") for (int _i = 0; _i < 2; ++_i) \
;         __builtin_amdgcn_global_load_lds((const unsigned*)((const char*)(gbase) + (voff)[_i]), (PG8_LAS unsigned*)(lds + (bufoff) + ldsw + _i * 8192), 16, 0, 0); } while (0)
; #define PG8_LDA(dst, b, h) do { _Pragma("unroll") for (int m = 0; m < 4; ++m) _Pragma("unroll") for (int k = 0; k < 2; ++k) dst[m][k] = *(const PG8_LAS bf16x8*)(lds + PG8_SA(b, h) + aoff + m * 2048 + k * 1024); } while (0)
; #define PG8_LDB(dst, b, h) do { _Pragma("unroll") for (int n = 0; n < 2; ++n) _Pragma("unroll") for (int k = 0; k < 2; ++k) dst[n][k] = *(const PG8_LAS bf16x8*)(lds + PG8_SB(b, h) + boff + n * 2048 + k * 1024); } while (0)
; #define PG8_MMA(ai, bj, At, Bt) do { __builtin_amdgcn_s_setprio(1); _Pragma("unroll") for (int m = 0; m < 4; ++m) _Pragma("unroll") for (int n = 0; n < 2; ++n) _Pragma("unroll") for (int k = 0; k < 2; ++k) \
;         acc[ai][bj][m][n] = __builtin_amdgcn_mfma_f32_16x16x32_bf16(Bt[n][k], At[m][k], acc[ai][bj][m][n], 0, 0, 0); __builtin_amdgcn_s_setprio(0); } while (0)
; #define PG8_WAIT_V(n) asm volatile("s_waitcnt vmcnt(" #n ")" ::: "memory")
; template <class Epi, class Sched, bool STAMP = false>
; __device__ __forceinline__ void gemm_phase(PG8_LAS unsigned char* lds, const Gemm g, const Sched& S, const Epi& E, unsigned long long* stamps) {
;     ...
;             const bool last = (t == nt - 2);
;             const char* a1 = cA + (size_t)(t + 1) * kstep;
;             const char* a2 = last ? nA : cA + (size_t)(t + 2) * kstep; const char* b2 = last ? nB : cB + (size_t)(t + 2) * kstep;
;             const char* a3 = a2 + kstep; const char* b3 = b2 + kstep;
;             if (last && has_next) S.a_ready(nxt);
;             PG8_LDB(B0, 0, 0); PG8_SCHED; PG8_LDA(At, 0, 0); PG8_STAGE(PG8_SA(1, 1), a1 + hstep, voffA);
;             PG8_WAIT_L(8); PG8_BAR; PG8_WAIT_L(0); PG8_MMA(0, 0, At, B0); PG8_BAR; PG8_SCHED;
;             PG8_LDB(B1, 0, 1); PG8_STAGE(PG8_SB(0, 0), b2, voffB);
;             PG8_BAR; PG8_WAIT_L(0); PG8_MMA(0, 1, At, B1); PG8_BAR;
;             PG8_LDA(At, 0, 1); PG8_STAGE(PG8_SA(0, 0), a2, voffA);
;             PG8_BAR; PG8_WAIT_L(0); PG8_MMA(1, 0, At, B0); PG8_BAR; PG8_SCHED;
;             PG8_STAGE(PG8_SB(0, 1), b2 + hstep, voffB);
;             PG8_WAIT_V(6); PG8_BAR; PG8_MMA(1, 1, At, B1); PG8_BAR;
.LBB0_761:
	ds_read_b128 v[170:173], v147
	ds_read_b128 v[174:177], v148
	ds_read_b128 v[178:181], v149
	ds_read_b128 v[182:185], v150
	s_add_u32 s30, s28, 0x100
	s_addc_u32 s31, s29, 0
	s_cmp_eq_u32 s10, 40
	s_cselect_b32 s37, s5, s31
	s_cselect_b32 s36, s4, s30
	s_cselect_b32 s35, s1, s69
	s_cselect_b32 s34, s0, s68
	s_mov_b32 m0, s58
	ds_read_b128 v[186:189], v145
	ds_read_b128 v[190:193], v145 offset:1024
	ds_read_b128 v[194:197], v145 offset:2048
	ds_read_b128 v[198:201], v145 offset:3072
	ds_read_b128 v[202:205], v145 offset:4096
	ds_read_b128 v[206:209], v145 offset:5120
	ds_read_b128 v[210:213], v145 offset:6144
	ds_read_b128 v[214:217], v145 offset:7168
	global_load_lds_dwordx4 v136, s[28:29]
	s_mov_b32 m0, s59
	s_nop 0
	global_load_lds_dwordx4 v138, s[28:29]
	s_waitcnt lgkmcnt(8)
	s_barrier
	s_waitcnt lgkmcnt(0)
	s_setprio 1
	s_waitcnt lgkmcnt(0)
	v_mfma_f32_16x16x32_bf16 v[124:127], v[170:173], v[186:189], v[124:127]
	v_mfma_f32_16x16x32_bf16 v[120:123], v[178:181], v[186:189], v[120:123]
	v_mfma_f32_16x16x32_bf16 v[116:119], v[170:173], v[194:197], v[116:119]
	v_mfma_f32_16x16x32_bf16 v[112:115], v[178:181], v[194:197], v[112:115]
	v_mfma_f32_16x16x32_bf16 v[100:103], v[170:173], v[202:205], v[100:103]
	v_mfma_f32_16x16x32_bf16 v[96:99], v[178:181], v[202:205], v[96:99]
	v_mfma_f32_16x16x32_bf16 v[84:87], v[170:173], v[210:213], v[84:87]
	v_mfma_f32_16x16x32_bf16 v[80:83], v[178:181], v[210:213], v[80:83]
	v_mfma_f32_16x16x32_bf16 v[124:127], v[174:177], v[190:193], v[124:127]
	v_mfma_f32_16x16x32_bf16 v[120:123], v[182:185], v[190:193], v[120:123]
	v_mfma_f32_16x16x32_bf16 v[116:119], v[174:177], v[198:201], v[116:119]
	v_mfma_f32_16x16x32_bf16 v[112:115], v[182:185], v[198:201], v[112:115]
	v_mfma_f32_16x16x32_bf16 v[100:103], v[174:177], v[206:209], v[100:103]
	v_mfma_f32_16x16x32_bf16 v[96:99], v[182:185], v[206:209], v[96:99]
	v_mfma_f32_16x16x32_bf16 v[84:87], v[174:177], v[214:217], v[84:87]
	v_mfma_f32_16x16x32_bf16 v[80:83], v[182:185], v[214:217], v[80:83]
	s_setprio 0
	s_barrier
	s_mov_b32 m0, s43
	ds_read_b128 v[218:221], v151
	ds_read_b128 v[222:225], v152
	ds_read_b128 v[226:229], v153
	ds_read_b128 v[230:233], v154
	global_load_lds_dwordx4 v130, s[34:35]
	s_mov_b32 m0, s44
	s_nop 0
	global_load_lds_dwordx4 v134, s[34:35]
	s_barrier
	s_waitcnt lgkmcnt(0)
	s_setprio 1
	s_waitcnt lgkmcnt(0)
	v_mfma_f32_16x16x32_bf16 v[108:111], v[218:221], v[186:189], v[108:111]
	v_mfma_f32_16x16x32_bf16 v[104:107], v[226:229], v[186:189], v[104:107]
	v_mfma_f32_16x16x32_bf16 v[92:95], v[218:221], v[194:197], v[92:95]
	v_mfma_f32_16x16x32_bf16 v[88:91], v[226:229], v[194:197], v[88:91]
	v_mfma_f32_16x16x32_bf16 v[76:79], v[218:221], v[202:205], v[76:79]
	v_mfma_f32_16x16x32_bf16 v[72:75], v[226:229], v[202:205], v[72:75]
	v_mfma_f32_16x16x32_bf16 v[68:71], v[218:221], v[210:213], v[68:71]
	v_mfma_f32_16x16x32_bf16 v[64:67], v[226:229], v[210:213], v[64:67]
	v_mfma_f32_16x16x32_bf16 v[108:111], v[222:225], v[190:193], v[108:111]
	v_mfma_f32_16x16x32_bf16 v[104:107], v[230:233], v[190:193], v[104:107]
	v_mfma_f32_16x16x32_bf16 v[92:95], v[222:225], v[198:201], v[92:95]
	v_mfma_f32_16x16x32_bf16 v[88:91], v[230:233], v[198:201], v[88:91]
	v_mfma_f32_16x16x32_bf16 v[76:79], v[222:225], v[206:209], v[76:79]
	v_mfma_f32_16x16x32_bf16 v[72:75], v[230:233], v[206:209], v[72:75]
	v_mfma_f32_16x16x32_bf16 v[68:71], v[222:225], v[214:217], v[68:71]
	v_mfma_f32_16x16x32_bf16 v[64:67], v[230:233], v[214:217], v[64:67]
	s_setprio 0
	s_mov_b32 m0, s42
	s_barrier
	ds_read_b128 v[186:189], v145 offset:16384
	ds_read_b128 v[190:193], v145 offset:17408
	ds_read_b128 v[194:197], v145 offset:18432
	ds_read_b128 v[198:201], v145 offset:19456
	ds_read_b128 v[202:205], v145 offset:20480
	ds_read_b128 v[206:209], v145 offset:21504
	ds_read_b128 v[210:213], v145 offset:22528
	ds_read_b128 v[214:217], v145 offset:23552
	global_load_lds_dwordx4 v128, s[36:37]
	s_mov_b32 m0, s45
	s_nop 0
	global_load_lds_dwordx4 v132, s[36:37]
	s_barrier
	s_waitcnt lgkmcnt(0)
	s_setprio 1
	s_waitcnt lgkmcnt(0)
	v_mfma_f32_16x16x32_bf16 v[60:63], v[170:173], v[186:189], v[60:63]
	v_mfma_f32_16x16x32_bf16 v[56:59], v[178:181], v[186:189], v[56:59]
	v_mfma_f32_16x16x32_bf16 v[52:55], v[170:173], v[194:197], v[52:55]
	v_mfma_f32_16x16x32_bf16 v[48:51], v[178:181], v[194:197], v[48:51]
	v_mfma_f32_16x16x32_bf16 v[36:39], v[170:173], v[202:205], v[36:39]
	v_mfma_f32_16x16x32_bf16 v[32:35], v[178:181], v[202:205], v[32:35]
	v_mfma_f32_16x16x32_bf16 v[20:23], v[170:173], v[210:213], v[20:23]
	v_mfma_f32_16x16x32_bf16 v[16:19], v[178:181], v[210:213], v[16:19]
	v_mfma_f32_16x16x32_bf16 v[60:63], v[174:177], v[190:193], v[60:63]
	v_mfma_f32_16x16x32_bf16 v[56:59], v[182:185], v[190:193], v[56:59]
	v_mfma_f32_16x16x32_bf16 v[52:55], v[174:177], v[198:201], v[52:55]
	v_mfma_f32_16x16x32_bf16 v[48:51], v[182:185], v[198:201], v[48:51]
	v_mfma_f32_16x16x32_bf16 v[36:39], v[174:177], v[206:209], v[36:39]
	v_mfma_f32_16x16x32_bf16 v[32:35], v[182:185], v[206:209], v[32:35]
	v_mfma_f32_16x16x32_bf16 v[20:23], v[174:177], v[214:217], v[20:23]
	v_mfma_f32_16x16x32_bf16 v[16:19], v[182:185], v[214:217], v[16:19]
	s_setprio 0
	s_barrier
	s_add_u32 s28, s34, 0xb4000
	s_addc_u32 s29, s35, 0
	s_mov_b32 m0, s46
	s_nop 0
	global_load_lds_dwordx4 v130, s[28:29]
	s_mov_b32 m0, s47
	s_nop 0
	global_load_lds_dwordx4 v134, s[28:29]
	s_waitcnt vmcnt(6)
	s_barrier
; #define PG8_STAGE(bufoff, gbase, voff) do { _Pragma("unroll") for (int _i = 0; _i < 2; ++_i) \
;         __builtin_amdgcn_global_load_lds((const unsigned*)((const char*)(gbase) + (voff)[_i]), (PG8_LAS unsigned*)(lds + (bufoff) + ldsw + _i * 8192), 16, 0, 0); } while (0)
; #define PG8_LDA(dst, b, h) do { _Pragma("unroll") for (int m = 0; m < 4; ++m) _Pragma("unroll") for (int k = 0; k < 2; ++k) dst[m][k] = *(const PG8_LAS bf16x8*)(lds + PG8_SA(b, h) + aoff + m * 2048 + k * 1024); } while (0)
; #define PG8_LDB(dst, b, h) do { _Pragma("unroll") for (int n = 0; n < 2; ++n) _Pragma("unroll") for (int k = 0; k < 2; ++k) dst[n][k] = *(const PG8_LAS bf16x8*)(lds + PG8_SB(b, h) + boff + n * 2048 + k * 1024); } while (0)
; #define PG8_MMA(ai, bj, At, Bt) do { __builtin_amdgcn_s_setprio(1); _Pragma("unroll") for (int m = 0; m < 4; ++m) _Pragma("unroll") for (int n = 0; n < 2; ++n) _Pragma("unroll") for (int k = 0; k < 2; ++k) \
;         acc[ai][bj][m][n] = __builtin_amdgcn_mfma_f32_16x16x32_bf16(Bt[n][k], At[m][k], acc[ai][bj][m][n], 0, 0, 0); __builtin_amdgcn_s_setprio(0); } while (0)
; #define PG8_WAIT_V(n) asm volatile("s_waitcnt vmcnt(" #n ")" ::: "memory")
; #define PG8_WAIT_L(n) asm volatile("s_waitcnt lgkmcnt(" #n ")" ::: "memory")
; #define PG8_BAR __builtin_amdgcn_s_barrier()
; #define PG8_SCHED __builtin_amdgcn_sched_barrier(0)
; template <class Epi, class Sched, bool STAMP = false>
; __device__ __forceinline__ void gemm_phase(PG8_LAS unsigned char* lds, const Gemm g, const Sched& S, const Epi& E, unsigned long long* stamps) {
;     ...
;             PG8_WAIT_V(6); PG8_BAR; PG8_MMA(1, 1, At, B1); PG8_BAR;
;             PG8_LDB(B0, 1, 0); PG8_SCHED; PG8_LDA(At, 1, 0); PG8_STAGE(PG8_SA(0, 1), a2 + hstep, voffA);
;             PG8_WAIT_L(8); PG8_BAR; PG8_WAIT_L(0); PG8_MMA(0, 0, At, B0); PG8_BAR; PG8_SCHED;
;             PG8_LDB(B1, 1, 1); PG8_STAGE(PG8_SB(1, 0), b3, voffB);
;             PG8_BAR; PG8_WAIT_L(0); PG8_MMA(0, 1, At, B1); PG8_BAR;
;             PG8_LDA(At, 1, 1); PG8_STAGE(PG8_SA(1, 0), a3, voffA);
	s_setprio 1
	v_mfma_f32_16x16x32_bf16 v[44:47], v[218:221], v[186:189], v[44:47]
	v_mfma_f32_16x16x32_bf16 v[40:43], v[226:229], v[186:189], v[40:43]
	v_mfma_f32_16x16x32_bf16 v[28:31], v[218:221], v[194:197], v[28:31]
	v_mfma_f32_16x16x32_bf16 v[24:27], v[226:229], v[194:197], v[24:27]
	v_mfma_f32_16x16x32_bf16 v[12:15], v[218:221], v[202:205], v[12:15]
	v_mfma_f32_16x16x32_bf16 v[8:11], v[226:229], v[202:205], v[8:11]
	v_mfma_f32_16x16x32_bf16 v[4:7], v[218:221], v[210:213], v[4:7]
	v_mfma_f32_16x16x32_bf16 v[0:3], v[226:229], v[210:213], v[0:3]
	v_mfma_f32_16x16x32_bf16 v[44:47], v[222:225], v[190:193], v[44:47]
	v_mfma_f32_16x16x32_bf16 v[40:43], v[230:233], v[190:193], v[40:43]
	v_mfma_f32_16x16x32_bf16 v[28:31], v[222:225], v[198:201], v[28:31]
	v_mfma_f32_16x16x32_bf16 v[24:27], v[230:233], v[198:201], v[24:27]
	v_mfma_f32_16x16x32_bf16 v[12:15], v[222:225], v[206:209], v[12:15]
	v_mfma_f32_16x16x32_bf16 v[8:11], v[230:233], v[206:209], v[8:11]
	v_mfma_f32_16x16x32_bf16 v[4:7], v[222:225], v[214:217], v[4:7]
	v_mfma_f32_16x16x32_bf16 v[0:3], v[230:233], v[214:217], v[0:3]
	s_setprio 0
	s_barrier
	ds_read_b128 v[170:173], v155
	ds_read_b128 v[174:177], v156
	ds_read_b128 v[178:181], v157
	ds_read_b128 v[182:185], v165
	s_add_u32 s28, s36, 0xb4000
	s_addc_u32 s29, s37, 0
	s_mov_b32 m0, s48
	ds_read_b128 v[186:189], v145 offset:32768
	ds_read_b128 v[190:193], v145 offset:33792
	ds_read_b128 v[194:197], v145 offset:34816
	ds_read_b128 v[198:201], v145 offset:35840
	ds_read_b128 v[202:205], v145 offset:36864
	ds_read_b128 v[206:209], v145 offset:37888
	ds_read_b128 v[210:213], v145 offset:38912
	ds_read_b128 v[214:217], v145 offset:39936
	global_load_lds_dwordx4 v128, s[28:29]
	s_mov_b32 m0, s49
	s_nop 0
	global_load_lds_dwordx4 v132, s[28:29]
	s_waitcnt lgkmcnt(8)
	s_barrier
	s_waitcnt lgkmcnt(0)
	s_setprio 1
	s_waitcnt lgkmcnt(0)
	v_mfma_f32_16x16x32_bf16 v[124:127], v[170:173], v[186:189], v[124:127]
	v_mfma_f32_16x16x32_bf16 v[120:123], v[178:181], v[186:189], v[120:123]
	v_mfma_f32_16x16x32_bf16 v[116:119], v[170:173], v[194:197], v[116:119]
	v_mfma_f32_16x16x32_bf16 v[112:115], v[178:181], v[194:197], v[112:115]
	v_mfma_f32_16x16x32_bf16 v[100:103], v[170:173], v[202:205], v[100:103]
	v_mfma_f32_16x16x32_bf16 v[96:99], v[178:181], v[202:205], v[96:99]
	v_mfma_f32_16x16x32_bf16 v[84:87], v[170:173], v[210:213], v[84:87]
	v_mfma_f32_16x16x32_bf16 v[80:83], v[178:181], v[210:213], v[80:83]
	v_mfma_f32_16x16x32_bf16 v[124:127], v[174:177], v[190:193], v[124:127]
	v_mfma_f32_16x16x32_bf16 v[120:123], v[182:185], v[190:193], v[120:123]
	v_mfma_f32_16x16x32_bf16 v[116:119], v[174:177], v[198:201], v[116:119]
	v_mfma_f32_16x16x32_bf16 v[112:115], v[182:185], v[198:201], v[112:115]
	v_mfma_f32_16x16x32_bf16 v[100:103], v[174:177], v[206:209], v[100:103]
	v_mfma_f32_16x16x32_bf16 v[96:99], v[182:185], v[206:209], v[96:99]
	v_mfma_f32_16x16x32_bf16 v[84:87], v[174:177], v[214:217], v[84:87]
	v_mfma_f32_16x16x32_bf16 v[80:83], v[182:185], v[214:217], v[80:83]
	s_setprio 0
	s_barrier
	s_mov_b32 m0, s50
	ds_read_b128 v[218:221], v166
	ds_read_b128 v[222:225], v167
	ds_read_b128 v[226:229], v168
	ds_read_b128 v[230:233], v169
	s_add_u32 s100, s34, 0x80
	s_addc_u32 s101, s35, 0
	global_load_lds_dwordx4 v130, s[100:101]
	s_mov_b32 m0, s51
	s_nop 0
	global_load_lds_dwordx4 v134, s[100:101]
	s_barrier
	s_waitcnt lgkmcnt(0)
	s_setprio 1
	s_waitcnt lgkmcnt(0)
	v_mfma_f32_16x16x32_bf16 v[108:111], v[218:221], v[186:189], v[108:111]
	v_mfma_f32_16x16x32_bf16 v[104:107], v[226:229], v[186:189], v[104:107]
	v_mfma_f32_16x16x32_bf16 v[92:95], v[218:221], v[194:197], v[92:95]
	v_mfma_f32_16x16x32_bf16 v[88:91], v[226:229], v[194:197], v[88:91]
	v_mfma_f32_16x16x32_bf16 v[76:79], v[218:221], v[202:205], v[76:79]
	v_mfma_f32_16x16x32_bf16 v[72:75], v[226:229], v[202:205], v[72:75]
	v_mfma_f32_16x16x32_bf16 v[68:71], v[218:221], v[210:213], v[68:71]
	v_mfma_f32_16x16x32_bf16 v[64:67], v[226:229], v[210:213], v[64:67]
	v_mfma_f32_16x16x32_bf16 v[108:111], v[222:225], v[190:193], v[108:111]
	v_mfma_f32_16x16x32_bf16 v[104:107], v[230:233], v[190:193], v[104:107]
	v_mfma_f32_16x16x32_bf16 v[92:95], v[222:225], v[198:201], v[92:95]
	v_mfma_f32_16x16x32_bf16 v[88:91], v[230:233], v[198:201], v[88:91]
	v_mfma_f32_16x16x32_bf16 v[76:79], v[222:225], v[206:209], v[76:79]
	v_mfma_f32_16x16x32_bf16 v[72:75], v[230:233], v[206:209], v[72:75]
	v_mfma_f32_16x16x32_bf16 v[68:71], v[222:225], v[214:217], v[68:71]
	v_mfma_f32_16x16x32_bf16 v[64:67], v[230:233], v[214:217], v[64:67]
	s_setprio 0
	s_mov_b32 m0, s52
	s_barrier
	ds_read_b128 v[186:189], v145 offset:49152
	ds_read_b128 v[190:193], v145 offset:50176
	ds_read_b128 v[194:197], v145 offset:51200
	ds_read_b128 v[198:201], v145 offset:52224
	ds_read_b128 v[202:205], v145 offset:53248
	ds_read_b128 v[206:209], v145 offset:54272
	ds_read_b128 v[210:213], v145 offset:55296
	ds_read_b128 v[214:217], v145 offset:56320
	s_add_u32 s100, s36, 0x80
	s_addc_u32 s101, s37, 0
	global_load_lds_dwordx4 v128, s[100:101]
	s_mov_b32 m0, s53
	s_nop 0
	global_load_lds_dwordx4 v132, s[100:101]
	s_barrier
; #define PG8_STAGE(bufoff, gbase, voff) do { _Pragma("unroll") for (int _i = 0; _i < 2; ++_i) \
;         __builtin_amdgcn_global_load_lds((const unsigned*)((const char*)(gbase) + (voff)[_i]), (PG8_LAS unsigned*)(lds + (bufoff) + ldsw + _i * 8192), 16, 0, 0); } while (0)
; #define PG8_MMA(ai, bj, At, Bt) do { __builtin_amdgcn_s_setprio(1); _Pragma("unroll") for (int m = 0; m < 4; ++m) _Pragma("unroll") for (int n = 0; n < 2; ++n) _Pragma("unroll") for (int k = 0; k < 2; ++k) \
;         acc[ai][bj][m][n] = __builtin_amdgcn_mfma_f32_16x16x32_bf16(Bt[n][k], At[m][k], acc[ai][bj][m][n], 0, 0, 0); __builtin_amdgcn_s_setprio(0); } while (0)
; #define PG8_WAIT_V(n) asm volatile("s_waitcnt vmcnt(" #n ")" ::: "memory")
; #define PG8_WAIT_L(n) asm volatile("s_waitcnt lgkmcnt(" #n ")" ::: "memory")
; #define PG8_BAR __builtin_amdgcn_s_barrier()
; #define PG8_SCHED __builtin_amdgcn_sched_barrier(0)
; template <class Epi, class Sched, bool STAMP = false>
; __device__ __forceinline__ void gemm_phase(PG8_LAS unsigned char* lds, const Gemm g, const Sched& S, const Epi& E, unsigned long long* stamps) {
;     ...
;             PG8_BAR; PG8_WAIT_L(0); PG8_MMA(1, 0, At, B0); PG8_BAR; PG8_SCHED;
;             PG8_STAGE(PG8_SB(1, 1), b3 + hstep, voffB);
;             PG8_WAIT_V(6); PG8_BAR; PG8_MMA(1, 1, At, B1); PG8_BAR;
;         }
	s_waitcnt lgkmcnt(0)
	s_setprio 1
	s_waitcnt lgkmcnt(0)
	v_mfma_f32_16x16x32_bf16 v[60:63], v[170:173], v[186:189], v[60:63]
	v_mfma_f32_16x16x32_bf16 v[56:59], v[178:181], v[186:189], v[56:59]
	v_mfma_f32_16x16x32_bf16 v[52:55], v[170:173], v[194:197], v[52:55]
	v_mfma_f32_16x16x32_bf16 v[48:51], v[178:181], v[194:197], v[48:51]
	v_mfma_f32_16x16x32_bf16 v[36:39], v[170:173], v[202:205], v[36:39]
	v_mfma_f32_16x16x32_bf16 v[32:35], v[178:181], v[202:205], v[32:35]
	v_mfma_f32_16x16x32_bf16 v[20:23], v[170:173], v[210:213], v[20:23]
	v_mfma_f32_16x16x32_bf16 v[16:19], v[178:181], v[210:213], v[16:19]
	v_mfma_f32_16x16x32_bf16 v[60:63], v[174:177], v[190:193], v[60:63]
	v_mfma_f32_16x16x32_bf16 v[56:59], v[182:185], v[190:193], v[56:59]
	v_mfma_f32_16x16x32_bf16 v[52:55], v[174:177], v[198:201], v[52:55]
	v_mfma_f32_16x16x32_bf16 v[48:51], v[182:185], v[198:201], v[48:51]
	v_mfma_f32_16x16x32_bf16 v[36:39], v[174:177], v[206:209], v[36:39]
	v_mfma_f32_16x16x32_bf16 v[32:35], v[182:185], v[206:209], v[32:35]
	v_mfma_f32_16x16x32_bf16 v[20:23], v[174:177], v[214:217], v[20:23]
	v_mfma_f32_16x16x32_bf16 v[16:19], v[182:185], v[214:217], v[16:19]
	s_setprio 0
	s_barrier
	s_add_u32 s28, s34, 0xb4080
	s_addc_u32 s29, s35, 0
	s_mov_b32 m0, s54
	s_nop 0
	global_load_lds_dwordx4 v130, s[28:29]
	s_mov_b32 m0, s55
	s_nop 0
	global_load_lds_dwordx4 v134, s[28:29]
	s_waitcnt vmcnt(6)
	s_barrier
	s_setprio 1
	v_mfma_f32_16x16x32_bf16 v[44:47], v[218:221], v[186:189], v[44:47]
	v_mfma_f32_16x16x32_bf16 v[40:43], v[226:229], v[186:189], v[40:43]
	v_mfma_f32_16x16x32_bf16 v[28:31], v[218:221], v[194:197], v[28:31]
	v_mfma_f32_16x16x32_bf16 v[24:27], v[226:229], v[194:197], v[24:27]
	v_mfma_f32_16x16x32_bf16 v[12:15], v[218:221], v[202:205], v[12:15]
	v_mfma_f32_16x16x32_bf16 v[8:11], v[226:229], v[202:205], v[8:11]
	v_mfma_f32_16x16x32_bf16 v[4:7], v[218:221], v[210:213], v[4:7]
	v_mfma_f32_16x16x32_bf16 v[0:3], v[226:229], v[210:213], v[0:3]
	v_mfma_f32_16x16x32_bf16 v[44:47], v[222:225], v[190:193], v[44:47]
	v_mfma_f32_16x16x32_bf16 v[40:43], v[230:233], v[190:193], v[40:43]
	v_mfma_f32_16x16x32_bf16 v[28:31], v[222:225], v[198:201], v[28:31]
	v_mfma_f32_16x16x32_bf16 v[24:27], v[230:233], v[198:201], v[24:27]
	v_mfma_f32_16x16x32_bf16 v[12:15], v[222:225], v[206:209], v[12:15]
	v_mfma_f32_16x16x32_bf16 v[8:11], v[230:233], v[206:209], v[8:11]
	v_mfma_f32_16x16x32_bf16 v[4:7], v[222:225], v[214:217], v[4:7]
	v_mfma_f32_16x16x32_bf16 v[0:3], v[230:233], v[214:217], v[0:3]
	s_setprio 0
	s_add_i32 s10, s10, 2
	s_add_u32 s68, s68, 0x100
	s_addc_u32 s69, s69, 0
	s_cmp_gt_u32 s10, 41
	s_mov_b64 s[28:29], s[30:31]
	s_barrier
	s_cbranch_scc0 .LBB0_761
; #define PG8_WAIT_V(n) asm volatile("s_waitcnt vmcnt(" #n ")" ::: "memory")
; #define PG8_BAR __builtin_amdgcn_s_barrier()
;     DI void operator()(const f32x4 (&acc)[2][2][4][2], const Unit& u, int wr, int wc, int fr, int fq) const {
;         const int row0 = u.pm * BM + wr * 64 + fr, col0 = u.pn * BM + wc * 32 + 8 * fq;
; #pragma unroll
;         for (int ai = 0; ai < 2; ++ai)
; #pragma unroll
;             for (int m = 0; m < 4; ++m) { u16* rowp = O + (size_t)(row0 + ai * HALF + m * 16) * ldc + col0;
; #pragma unroll
;                 for (int bj = 0; bj < 2; ++bj) { const f32x4 v0 = acc[ai][bj][m][0], v1 = acc[ai][bj][m][1];
;                     uint4 w = {pack2(v0[0], v0[1]), pack2(v0[2], v0[3]), pack2(v1[0], v1[1]), pack2(v1[2], v1[3])}; *(uint4*)(rowp + bj * HALF) = w; } }
; template <class Epi, class Sched, bool STAMP = false>
; __device__ __forceinline__ void gemm_phase(PG8_LAS unsigned char* lds, const Gemm g, const Sched& S, const Epi& E, unsigned long long* stamps) {
;     ...
;         if (!has_next) break;
; #pragma unroll
;         for (int a = 0; a < 2; ++a)
; #pragma unroll
;             for (int b = 0; b < 2; ++b)
; #pragma unroll
;                 for (int m = 0; m < 4; ++m)
; #pragma unroll
;                     for (int n = 0; n < 2; ++n) acc[a][b][m][n] = (f32x4){0.f, 0.f, 0.f, 0.f};
;         cur = nxt; cA = nA; cB = nB; ++ui;
;     }
;     PG8_WAIT_V(0);
;     if (wr == 0) PG8_BAR;
	v_lshl_add_u32 v170, s64, 8, v144
	v_lshl_or_b32 v172, s67, 8, v146
	v_ashrrev_i32_e32 v171, 31, v170
	v_ashrrev_i32_e32 v173, 31, v172
	v_lshlrev_b64 v[174:175], 11, v[170:171]
	v_lshl_add_u64 v[174:175], s[14:15], 0, v[174:175]
	v_lshlrev_b64 v[172:173], 1, v[172:173]
	v_lshl_add_u64 v[174:175], v[174:175], 0, v[172:173]
	v_cvt_pk_bf16_f32 v60, v60, v61
	v_cvt_pk_bf16_f32 v61, v62, v63
	v_cvt_pk_bf16_f32 v62, v56, v57
	v_add_co_u32_e32 v56, vcc, s60, v174
	v_cvt_pk_bf16_f32 v68, v68, v69
	v_cvt_pk_bf16_f32 v69, v70, v71
	v_cvt_pk_bf16_f32 v70, v64, v65
	v_lshl_add_u64 v[64:65], v[174:175], 0, s[16:17]
	v_addc_co_u32_e32 v57, vcc, 0, v175, vcc
	v_cvt_pk_bf16_f32 v44, v44, v45
	v_cvt_pk_bf16_f32 v45, v46, v47
	v_cvt_pk_bf16_f32 v46, v40, v41
	v_cvt_pk_bf16_f32 v47, v42, v43
	v_cvt_pk_bf16_f32 v108, v108, v109
	v_cvt_pk_bf16_f32 v109, v110, v111
	v_cvt_pk_bf16_f32 v110, v104, v105
	v_or_b32_e32 v104, 16, v170
	global_store_dwordx4 v[64:65], v[44:47], off offset:256
	v_ashrrev_i32_e32 v105, 31, v104
	v_cvt_pk_bf16_f32 v92, v92, v93
	v_add_co_u32_e32 v46, vcc, s61, v174
	v_cvt_pk_bf16_f32 v93, v94, v95
	v_cvt_pk_bf16_f32 v94, v88, v89
	v_or_b32_e32 v88, 32, v170
	v_lshl_add_u64 v[44:45], v[174:175], 0, s[18:19]
	v_addc_co_u32_e32 v47, vcc, 0, v175, vcc
	v_cvt_pk_bf16_f32 v28, v28, v29
	v_cvt_pk_bf16_f32 v29, v30, v31
	v_cvt_pk_bf16_f32 v30, v24, v25
	v_cvt_pk_bf16_f32 v31, v26, v27
	v_lshlrev_b64 v[104:105], 11, v[104:105]
	v_ashrrev_i32_e32 v89, 31, v88
	v_cvt_pk_bf16_f32 v76, v76, v77
	v_cvt_pk_bf16_f32 v77, v78, v79
	v_cvt_pk_bf16_f32 v78, v72, v73
	v_or_b32_e32 v72, 48, v170
	global_store_dwordx4 v[44:45], v[28:31], off offset:256
	v_cvt_pk_bf16_f32 v111, v106, v107
	v_lshl_add_u64 v[104:105], s[14:15], 0, v[104:105]
	v_add_co_u32_e32 v30, vcc, s62, v174
	v_lshlrev_b64 v[88:89], 11, v[88:89]
	v_ashrrev_i32_e32 v73, 31, v72
	v_lshl_add_u64 v[28:29], v[174:175], 0, s[20:21]
	v_addc_co_u32_e32 v31, vcc, 0, v175, vcc
	v_cvt_pk_bf16_f32 v12, v12, v13
	v_cvt_pk_bf16_f32 v13, v14, v15
	v_cvt_pk_bf16_f32 v14, v8, v9
	v_cvt_pk_bf16_f32 v15, v10, v11
	global_store_dwordx4 v[174:175], v[108:111], off offset:256
	v_cvt_pk_bf16_f32 v95, v90, v91
	v_lshl_add_u64 v[88:89], s[14:15], 0, v[88:89]
	v_lshl_add_u64 v[108:109], v[104:105], 0, v[172:173]
	v_lshlrev_b64 v[72:73], 11, v[72:73]
	global_store_dwordx4 v[28:29], v[12:15], off offset:256
	global_store_dwordx4 v[108:109], v[92:95], off offset:256
	v_cvt_pk_bf16_f32 v79, v74, v75
	v_add_co_u32_e32 v14, vcc, s63, v174
	v_lshl_add_u64 v[92:93], v[88:89], 0, v[172:173]
	v_lshl_add_u64 v[72:73], s[14:15], 0, v[72:73]
	v_addc_co_u32_e32 v15, vcc, 0, v175, vcc
	v_cvt_pk_bf16_f32 v124, v124, v125
	v_cvt_pk_bf16_f32 v125, v126, v127
	v_cvt_pk_bf16_f32 v126, v120, v121
	v_cvt_pk_bf16_f32 v127, v122, v123
	v_cvt_pk_bf16_f32 v104, v116, v117
	v_cvt_pk_bf16_f32 v105, v118, v119
	v_cvt_pk_bf16_f32 v106, v112, v113
	v_cvt_pk_bf16_f32 v107, v114, v115
	v_cvt_pk_bf16_f32 v88, v100, v101
	v_cvt_pk_bf16_f32 v89, v102, v103
	v_cvt_pk_bf16_f32 v90, v96, v97
	v_cvt_pk_bf16_f32 v91, v98, v99
	global_store_dwordx4 v[92:93], v[76:79], off offset:256
	v_cvt_pk_bf16_f32 v74, v80, v81
	v_cvt_pk_bf16_f32 v75, v82, v83
	v_lshl_add_u64 v[76:77], v[72:73], 0, v[172:173]
	v_cvt_pk_bf16_f32 v72, v84, v85
	v_cvt_pk_bf16_f32 v73, v86, v87
	v_cvt_pk_bf16_f32 v71, v66, v67
	v_cvt_pk_bf16_f32 v63, v58, v59
	v_cvt_pk_bf16_f32 v40, v52, v53
	v_cvt_pk_bf16_f32 v41, v54, v55
	v_cvt_pk_bf16_f32 v42, v48, v49
	v_cvt_pk_bf16_f32 v43, v50, v51
	v_cvt_pk_bf16_f32 v24, v36, v37
	v_cvt_pk_bf16_f32 v25, v38, v39
	v_cvt_pk_bf16_f32 v26, v32, v33
	v_cvt_pk_bf16_f32 v27, v34, v35
	v_lshl_add_u64 v[12:13], v[174:175], 0, s[26:27]
	v_cvt_pk_bf16_f32 v8, v20, v21
	v_cvt_pk_bf16_f32 v9, v22, v23
	v_cvt_pk_bf16_f32 v10, v16, v17
	v_cvt_pk_bf16_f32 v11, v18, v19
	v_cvt_pk_bf16_f32 v4, v4, v5
	v_cvt_pk_bf16_f32 v5, v6, v7
	v_cvt_pk_bf16_f32 v6, v0, v1
	v_cvt_pk_bf16_f32 v7, v2, v3
	s_and_b64 vcc, exec, s[2:3]
	s_mov_b32 s67, s65
	s_mov_b32 s64, s66
	s_mov_b64 s[30:31], s[0:1]
	s_mov_b64 s[28:29], s[4:5]
	global_store_dwordx4 v[174:175], v[124:127], off
	global_store_dwordx4 v[108:109], v[104:107], off
	global_store_dwordx4 v[92:93], v[88:91], off
	global_store_dwordx4 v[76:77], v[72:75], off
	global_store_dwordx4 v[76:77], v[68:71], off offset:256
	global_store_dwordx4 v[56:57], v[60:63], off
	global_store_dwordx4 v[46:47], v[40:43], off
	global_store_dwordx4 v[30:31], v[24:27], off
	global_store_dwordx4 v[14:15], v[8:11], off
	global_store_dwordx4 v[12:13], v[4:7], off offset:256
	s_cbranch_vccz .LBB0_750
	s_waitcnt vmcnt(0)
	s_cmpk_gt_u32 s40, 0xff
	s_cbranch_scc1 .LBB0_765
	s_barrier

; __global__ void __launch_bounds__(NTHR, 2) k_mega(Params p, int ph0, int ph1) {
;   __shared__ __attribute__((aligned(16))) char smem[SMEM_BYTES];
	.amdhsa_kernel _Z6k_mega6Paramsii
		.amdhsa_group_segment_fixed_size 147584
		.amdhsa_private_segment_fixed_size 0
		.amdhsa_kernarg_size 352
		.amdhsa_user_sgpr_count 2
		.amdhsa_user_sgpr_dispatch_ptr 0
		.amdhsa_user_sgpr_queue_ptr 0
		.amdhsa_user_sgpr_kernarg_segment_ptr 1
		.amdhsa_user_sgpr_dispatch_id 0
		.amdhsa_user_sgpr_kernarg_preload_length 0
		.amdhsa_user_sgpr_kernarg_preload_offset 0
		.amdhsa_user_sgpr_private_segment_size 0
		.amdhsa_uses_dynamic_stack 0
		.amdhsa_enable_private_segment 0
		.amdhsa_system_sgpr_workgroup_id_x 1
		.amdhsa_system_sgpr_workgroup_id_y 0
		.amdhsa_system_sgpr_workgroup_id_z 0
		.amdhsa_system_sgpr_workgroup_info 0
		.amdhsa_system_vgpr_workitem_id 2
		.amdhsa_next_free_vgpr 243
		.amdhsa_next_free_sgpr 102
		.amdhsa_accum_offset 244
		.amdhsa_reserve_vcc 1
		.amdhsa_float_round_mode_32 0
		.amdhsa_float_round_mode_16_64 0
		.amdhsa_float_denorm_mode_32 3
		.amdhsa_float_denorm_mode_16_64 3
		.amdhsa_dx10_clamp 1
		.amdhsa_ieee_mode 1
		.amdhsa_fp16_overflow 0
		.amdhsa_tg_split 0
		.amdhsa_exception_fp_ieee_invalid_op 0
		.amdhsa_exception_fp_denorm_src 0
		.amdhsa_exception_fp_ieee_div_zero 0
		.amdhsa_exception_fp_ieee_overflow 0
		.amdhsa_exception_fp_ieee_underflow 0
		.amdhsa_exception_fp_ieee_inexact 0
		.amdhsa_exception_int_div_zero 0
	.end_amdhsa_kernel

; __global__ void __launch_bounds__(NTHR, 2) k_mega(Params p, int ph0, int ph1) {
;   __shared__ __attribute__((aligned(16))) char smem[SMEM_BYTES];
amdhsa.kernels:
  - .agpr_count:     0
    .args:
      - .offset:         0
        .size:           88
        .value_kind:     by_value
      - .offset:         88
        .size:           4
        .value_kind:     by_value
      - .offset:         92
        .size:           4
        .value_kind:     by_value
      - .offset:         96
        .size:           4
        .value_kind:     hidden_block_count_x
      - .offset:         100
        .size:           4
        .value_kind:     hidden_block_count_y
      - .offset:         104
        .size:           4
        .value_kind:     hidden_block_count_z
      - .offset:         108
        .size:           2
        .value_kind:     hidden_group_size_x
      - .offset:         110
        .size:           2
        .value_kind:     hidden_group_size_y
      - .offset:         112
        .size:           2
        .value_kind:     hidden_group_size_z
      - .offset:         114
        .size:           2
        .value_kind:     hidden_remainder_x
      - .offset:         116
        .size:           2
        .value_kind:     hidden_remainder_y
      - .offset:         118
        .size:           2
        .value_kind:     hidden_remainder_z
      - .offset:         136
        .size:           8
        .value_kind:     hidden_global_offset_x
      - .offset:         144
        .size:           8
        .value_kind:     hidden_global_offset_y
      - .offset:         152
        .size:           8
        .value_kind:     hidden_global_offset_z
      - .offset:         160
        .size:           2
        .value_kind:     hidden_grid_dims
      - .offset:         184
        .size:           8
        .value_kind:     hidden_multigrid_sync_arg
    .group_segment_fixed_size: 147584
    .kernarg_segment_align: 8
    .kernarg_segment_size: 352
    .language:       OpenCL C
    .language_version:
      - 2
      - 0
    .max_flat_workgroup_size: 512
    .name:           _Z6k_mega6Paramsii
    .private_segment_fixed_size: 0
    .sgpr_count:     108
    .sgpr_spill_count: 1
    .symbol:         _Z6k_mega6Paramsii.kd
    .uniform_work_group_size: 1
    .uses_dynamic_stack: false
    .vgpr_count:     243
    .vgpr_spill_count: 0
    .wavefront_size: 64
